# A+Q+P2+S + EpiResidNorm Hn stores: exec-masked half-wave store pairs merged into one full-wave store with v_cndmask-selected address/data (78 sites)
# speedup vs baseline: 1.0059x; 1.0059x over previous
; #define LAS __attribute__((address_space(3)))
;     __device__ __forceinline__ void operator()(const f32x4 (&acc)[2][2][4][2], const Unit& u, int wr, int wc, int fr, int fq) const {
;         const int s = u.pm >> 5, lane = fq * 16 + fr, rr = lane >> 3, pc = lane & 7;
;         const float* __restrict__ xi = xin + (size_t)u.pm * BM * DM; float* __restrict__ xo = xout + (size_t)u.pm * BM * DM; bf16_t* __restrict__ ho = Hn + (size_t)u.pm * BM * DM;
;         LAS unsigned char* st = lds_epi + (wr * 4 + wc) * 2304;
;         LAS float* sst = (LAS float*)(lds_epi + 18432 + (wr * 4 + wc) * 512);
;         const int colr = u.pn * BM + wc * 64 + 4 * pc;
;         const unsigned eb = (unsigned)((wr * 64 + rr) * DM + colr);
;         f32x4 gv[2], gsn[2];
; #pragma unroll
;         for (int bj = 0; bj < 2; ++bj) { gv[bj] = *(const f32x4*)(gate + (size_t)s * MODW + colr + bj * 32) * (0.5f * GS2);
;             if (!PLAIN) gsn[bj] = *(const f32x4*)(gnext + colr + bj * 32) * (*(const f32x4*)(scnext + (size_t)s * MODW + colr + bj * 32) + 1.0f); else gsn[bj] = gv[bj]; }
;         const unsigned wr_off = (unsigned)(fr * 144 + 16 * fq), rd_off = (unsigned)(rr * 144 + pc * 16);
;         const bool odd = (rr & 1) != 0;
;         f32x4 xb[2][2][2];
;     ...
;         ERN_LOADX(0);
; #pragma unroll
;         for (int g = 0; g < 8; ++g) { const int ai = g >> 2, m = g & 3;
;             if (g + 1 < 8) ERN_LOADX(g + 1);
;             float sq0 = 0.f, sq1 = 0.f; u32x2 hw[2][2];
; #pragma unroll
;             for (int bj = 0; bj < 2; ++bj) {
;                 *(LAS f32x4*)(st + wr_off) = acc[ai][bj][m][0]; *(LAS f32x4*)(st + wr_off + 64) = acc[ai][bj][m][1];
;                 const f32x4 a0 = *(const LAS f32x4*)(st + rd_off), a1 = *(const LAS f32x4*)(st + rd_off + 8 * 144);
;                 { const f32x4 xv = xb[g & 1][bj][0] + gv[bj] * a0; __builtin_nontemporal_store(xv, (f32x4*)((char*)xo + 4u * ERN_EOFF(g, bj, 0)));
;                   sq0 += (xv.x * xv.x + xv.y * xv.y) + (xv.z * xv.z + xv.w * xv.w);
;                   const f32x4 hv = xv * gsn[bj]; hw[bj][0].x = cvt_pk_bf16(hv.x, hv.y); hw[bj][0].y = cvt_pk_bf16(hv.z, hv.w); }
;                 { const f32x4 xv = xb[g & 1][bj][1] + gv[bj] * a1; __builtin_nontemporal_store(xv, (f32x4*)((char*)xo + 4u * ERN_EOFF(g, bj, 1)));
;                   sq1 += (xv.x * xv.x + xv.y * xv.y) + (xv.z * xv.z + xv.w * xv.w);
.LBB0_320:
	s_ashr_i32 s12, s4, 5
	s_ashr_i32 s5, s4, 31
	v_lshl_or_b32 v130, s0, 8, v192
	s_mul_i32 s14, s12, 0x12000
	s_mul_hi_i32 s0, s12, 0x12000
	s_add_u32 s12, s35, s14
	v_ashrrev_i32_e32 v131, 31, v130
	s_addc_u32 s13, s36, s0
	v_lshlrev_b64 v[132:133], 2, v[130:131]
	v_lshl_add_u64 v[134:135], s[12:13], 0, v[132:133]
	s_add_u32 s12, s37, s14
	s_addc_u32 s13, s60, s0
	v_lshl_add_u64 v[136:137], s[46:47], 0, v[132:133]
	v_lshl_add_u64 v[132:133], s[12:13], 0, v[132:133]
	s_lshl_b64 s[54:55], s[4:5], 21
	v_readlane_b32 s12, v253, 2
	v_readlane_b32 s13, v253, 3
	s_add_u32 s58, s12, s54
	v_add_u32_e32 v202, v130, v193
	s_addc_u32 s59, s13, s55
	v_lshlrev_b32_e32 v207, 2, v202
	global_load_dwordx4 v[170:173], v[136:137], off
	global_load_dwordx4 v[166:169], v[134:135], off
	global_load_dwordx4 v[174:177], v[134:135], off offset:128
	global_load_dwordx4 v[186:189], v[132:133], off
	global_load_dwordx4 v[208:211], v[132:133], off offset:128
	global_load_dwordx4 v[212:215], v207, s[58:59]
	v_add_u32_e32 v130, 0x10000, v207
	global_load_dwordx4 v[216:219], v130, s[58:59]
	global_load_dwordx4 v[220:223], v[136:137], off offset:128
	global_load_dwordx4 v[224:227], v207, s[58:59] offset:128
	v_add_u32_e32 v206, 0x10080, v207
	v_add_u32_e32 v130, 0x20000, v207
	global_load_dwordx4 v[228:231], v206, s[58:59]
	v_add_u32_e32 v154, 0x30000, v207
	v_add_u32_e32 v184, 0x20080, v207
	v_add_u32_e32 v182, 0x30080, v207
	global_load_dwordx4 v[142:145], v130, s[58:59]
	global_load_dwordx4 v[138:141], v154, s[58:59]
	global_load_dwordx4 v[134:137], v184, s[58:59]
	s_nop 0
	global_load_dwordx4 v[130:133], v182, s[58:59]
	ds_write_b128 v200, v[126:129]
	ds_write_b128 v200, v[122:125] offset:64
	v_and_b32_e32 v127, 64, v199
	ds_read_b128 v[122:125], v201
	ds_read_b128 v[232:235], v201 offset:1152
	v_xor_b32_e32 v126, 8, v199
	v_add_u32_e32 v183, 64, v127
	v_cmp_lt_i32_e32 vcc, v126, v183
	v_add_u32_e32 v185, 0x4000, v202
	s_add_u32 s56, s90, s54
	v_cndmask_b32_e32 v126, v199, v126, vcc
	v_lshlrev_b32_e32 v203, 2, v126
	v_lshlrev_b32_e32 v236, 2, v185
	s_addc_u32 s57, s91, s55
	s_lshl_b64 s[12:13], s[4:5], 20
	s_add_u32 s54, s93, s12
	v_readlane_b32 s16, v253, 6
	v_readlane_b32 s17, v253, 7
	s_addc_u32 s55, s92, s13
	v_readlane_b32 s14, v253, 4
	v_readlane_b32 s15, v253, 5
	v_readlane_b32 s18, v253, 8
	v_readlane_b32 s19, v253, 9
	v_readlane_b32 s20, v253, 10
	v_readlane_b32 s21, v253, 11
	v_readlane_b32 s22, v253, 12
	v_readlane_b32 s23, v253, 13
	v_readlane_b32 s24, v253, 14
	v_readlane_b32 s25, v253, 15
	v_readlane_b32 s26, v253, 16
	v_readlane_b32 s27, v253, 17
	s_waitcnt vmcnt(0)
	v_pk_mul_f32 v[180:181], v[166:167], 0.5 op_sel_hi:[1,0]
	v_pk_mul_f32 v[178:179], v[168:169], 0.5 op_sel_hi:[1,0]
	v_pk_add_f32 v[126:127], v[188:189], 1.0 op_sel_hi:[1,0]
	v_pk_add_f32 v[128:129], v[186:187], 1.0 op_sel_hi:[1,0]
	v_pk_mul_f32 v[166:167], v[176:177], 0.5 op_sel_hi:[1,0]
	v_pk_mul_f32 v[168:169], v[174:175], 0.5 op_sel_hi:[1,0]
	v_pk_mul_f32 v[174:175], v[172:173], v[126:127]
	v_pk_mul_f32 v[176:177], v[170:171], v[128:129]
	s_waitcnt lgkmcnt(1)
	v_pk_fma_f32 v[126:127], v[180:181], v[122:123], v[212:213]
	s_waitcnt lgkmcnt(0)
	v_pk_fma_f32 v[122:123], v[180:181], v[232:233], v[216:217]
	v_pk_fma_f32 v[128:129], v[178:179], v[124:125], v[214:215]
	v_pk_fma_f32 v[124:125], v[178:179], v[234:235], v[218:219]
	v_pk_mul_f32 v[186:187], v[176:177], v[122:123]
	global_store_dwordx4 v207, v[126:129], s[56:57] nt
	v_pk_mul_f32 v[170:171], v[174:175], v[128:129]
	v_pk_mul_f32 v[172:173], v[176:177], v[126:127]
	v_pk_mul_f32 v[204:205], v[174:175], v[124:125]
	v_cvt_pk_bf16_f32 v188, v172, v173
	v_cvt_pk_bf16_f32 v189, v170, v171
	global_store_dwordx4 v236, v[122:125], s[56:57] nt
	v_cvt_pk_bf16_f32 v186, v186, v187
	v_cvt_pk_bf16_f32 v187, v204, v205
	ds_write_b128 v200, v[118:121]
	ds_write_b128 v200, v[114:117] offset:64
	ds_read_b128 v[114:117], v201
	v_pk_add_f32 v[190:191], v[210:211], 1.0 op_sel_hi:[1,0]
	v_pk_add_f32 v[118:119], v[208:209], 1.0 op_sel_hi:[1,0]
	ds_read_b128 v[208:211], v201 offset:1152
	v_pk_mul_f32 v[170:171], v[222:223], v[190:191]
	v_pk_mul_f32 v[172:173], v[220:221], v[118:119]
	s_waitcnt lgkmcnt(1)
	v_pk_fma_f32 v[120:121], v[166:167], v[116:117], v[226:227]
	v_pk_fma_f32 v[118:119], v[168:169], v[114:115], v[224:225]
	v_pk_mul_f32 v[190:191], v[170:171], v[120:121]
	v_pk_mul_f32 v[204:205], v[172:173], v[118:119]
	global_store_dwordx4 v207, v[118:121], s[56:57] offset:128 nt
	v_cvt_pk_bf16_f32 v204, v204, v205
	v_cvt_pk_bf16_f32 v191, v190, v191
	ds_bpermute_b32 v190, v203, v204
	ds_bpermute_b32 v191, v203, v191
	s_waitcnt lgkmcnt(2)
	v_pk_fma_f32 v[116:117], v[166:167], v[210:211], v[230:231]
	v_pk_fma_f32 v[114:115], v[168:169], v[208:209], v[228:229]
	global_store_dwordx4 v206, v[114:117], s[56:57] nt
	v_pk_mul_f32 v[204:205], v[172:173], v[114:115]
	v_lshlrev_b32_e32 v206, 1, v202
	v_pk_mul_f32 v[208:209], v[170:171], v[116:117]
	v_cvt_pk_bf16_f32 v204, v204, v205
	s_nop 0
	v_cvt_pk_bf16_f32 v205, v208, v209
	s_waitcnt lgkmcnt(0)
	v_add_u32_e32 v250, 0xfffff040, v206
	v_cndmask_b32_e64 v250, v206, v250, s[40:41]
	v_cndmask_b32_e64 v248, v188, v190, s[40:41]
	v_cndmask_b32_e64 v249, v189, v191, s[40:41]
	global_store_dwordx2 v250, v[248:249], s[54:55]
	v_cndmask_b32_e64 v246, v190, v188, s[40:41]
	v_cndmask_b32_e64 v247, v191, v189, s[40:41]
	s_waitcnt lgkmcnt(1)
	v_add_u32_e32 v190, 0x1040, v206
	v_cndmask_b32_e64 v190, v206, v190, s[38:39]
	global_store_dwordx2 v190, v[246:247], s[54:55]
	ds_bpermute_b32 v188, v203, v204
	ds_bpermute_b32 v189, v203, v205
	v_lshlrev_b32_e32 v190, 1, v185
	s_waitcnt lgkmcnt(0)
; #define LAS __attribute__((address_space(3)))
; #define ERN_EOFF(q, m) (eb + (unsigned)((((q) & 1) * HALF + (m) * 16) * DM + ERN_COL((q) >> 1)))
;     __device__ __forceinline__ void operator()(const f32x4 (&acc)[2][2][4][2], const Unit& u, int wr, int wc, int fr, int fq) const {
;     ...
;         for (int g = 0; g < 8; ++g) { const int ai = g >> 2, m = g & 3;
;             if (g + 1 < 8) ERN_LOADX(g + 1);
;             float sq0 = 0.f, sq1 = 0.f; u32x2 hw[2][2];
; #pragma unroll
;             for (int bj = 0; bj < 2; ++bj) {
;                 *(LAS f32x4*)(st + wr_off) = acc[ai][bj][m][0]; *(LAS f32x4*)(st + wr_off + 64) = acc[ai][bj][m][1];
;                 const f32x4 a0 = *(const LAS f32x4*)(st + rd_off), a1 = *(const LAS f32x4*)(st + rd_off + 8 * 144);
;                 { const f32x4 xv = xb[g & 1][bj][0] + gv[bj] * a0; __builtin_nontemporal_store(xv, (f32x4*)((char*)xo + 4u * ERN_EOFF(g, bj, 0)));
;                   sq0 += (xv.x * xv.x + xv.y * xv.y) + (xv.z * xv.z + xv.w * xv.w);
;                   const f32x4 hv = xv * gsn[bj]; hw[bj][0].x = cvt_pk_bf16(hv.x, hv.y); hw[bj][0].y = cvt_pk_bf16(hv.z, hv.w); }
;                 { const f32x4 xv = xb[g & 1][bj][1] + gv[bj] * a1; __builtin_nontemporal_store(xv, (f32x4*)((char*)xo + 4u * ERN_EOFF(g, bj, 1)));
;                   sq1 += (xv.x * xv.x + xv.y * xv.y) + (xv.z * xv.z + xv.w * xv.w);
;                   const f32x4 hv = xv * gsn[bj]; hw[bj][1].x = cvt_pk_bf16(hv.x, hv.y); hw[bj][1].y = cvt_pk_bf16(hv.z, hv.w); }
;             }
;             if (!NOH && !PLAIN) {
; #pragma unroll
;                 for (int rh = 0; rh < 2; ++rh) { u32x2 rv; rv.x = __shfl_xor(hw[1][rh].x, 8); rv.y = __shfl_xor(hw[1][rh].y, 8);
;                     const unsigned e0 = ERN_EOFF(g, 0, rh);
;                     const unsigned ee = odd ? (e0 - DM + 32) : e0, eo2 = odd ? e0 : (e0 + DM + 32);
;                     *(u32x2*)((char*)ho + 2u * ee) = odd ? rv : hw[0][rh];
;                     *(u32x2*)((char*)ho + 2u * eo2) = odd ? hw[0][rh] : rv; }
;             }
;             if (!PLAIN) { sq0 += __shfl_xor(sq0, 1); sq0 += __shfl_xor(sq0, 2); sq0 += __shfl_xor(sq0, 4);
;             sq1 += __shfl_xor(sq1, 1); sq1 += __shfl_xor(sq1, 2); sq1 += __shfl_xor(sq1, 4); }
;             if (!PLAIN && pc == 0) { sst[g * 16 + rr] = sq0; sst[g * 16 + 8 + rr] = sq1; }
	v_add_u32_e32 v250, 0xfffff040, v190
	v_cndmask_b32_e64 v250, v190, v250, s[40:41]
	v_cndmask_b32_e64 v248, v186, v188, s[40:41]
	v_cndmask_b32_e64 v249, v187, v189, s[40:41]
	global_store_dwordx2 v250, v[248:249], s[54:55]
	v_cndmask_b32_e64 v246, v188, v186, s[40:41]
	v_cndmask_b32_e64 v247, v189, v187, s[40:41]
	v_mul_f32_e32 v119, v119, v119
	v_mul_f32_e32 v127, v127, v127
	v_mul_f32_e32 v129, v129, v129
	v_fmac_f32_e32 v119, v118, v118
	v_mul_f32_e32 v118, v121, v121
	v_fmac_f32_e32 v129, v128, v128
	v_fmac_f32_e32 v118, v120, v120
	v_mul_f32_e32 v115, v115, v115
	v_fmac_f32_e32 v127, v126, v126
	v_add_f32_e32 v118, v119, v118
	v_fmac_f32_e32 v115, v114, v114
	v_mul_f32_e32 v114, v117, v117
	v_add_f32_e32 v117, v127, v129
	v_add_f32_e32 v117, v117, v118
	v_xor_b32_e32 v118, 1, v199
	v_cmp_lt_i32_e32 vcc, v118, v183
	v_mul_f32_e32 v123, v123, v123
	v_mul_f32_e32 v125, v125, v125
	v_cndmask_b32_e32 v118, v199, v118, vcc
	v_lshlrev_b32_e32 v204, 2, v118
	ds_bpermute_b32 v118, v204, v117
	v_fmac_f32_e32 v114, v116, v116
	v_fmac_f32_e32 v125, v124, v124
	v_fmac_f32_e32 v123, v122, v122
	v_add_f32_e32 v114, v115, v114
	s_waitcnt lgkmcnt(0)
	v_add_f32_e32 v116, v117, v118
	v_xor_b32_e32 v117, 2, v199
	v_cmp_lt_i32_e32 vcc, v117, v183
	v_add_f32_e32 v115, v123, v125
	v_add_f32_e32 v115, v115, v114
	v_cndmask_b32_e32 v117, v199, v117, vcc
	v_lshlrev_b32_e32 v205, 2, v117
	ds_bpermute_b32 v117, v205, v116
	ds_bpermute_b32 v118, v204, v115
	s_waitcnt lgkmcnt(1)
	v_add_f32_e32 v114, v116, v117
	s_waitcnt lgkmcnt(0)
	v_add_f32_e32 v117, v115, v118
	ds_bpermute_b32 v118, v205, v117
	v_xor_b32_e32 v116, 4, v199
	v_cmp_lt_i32_e32 vcc, v116, v183
	s_nop 1
	v_cndmask_b32_e32 v115, v199, v116, vcc
	v_lshlrev_b32_e32 v206, 2, v115
	s_waitcnt lgkmcnt(0)
	v_add_f32_e32 v116, v117, v118
	ds_bpermute_b32 v115, v206, v114
	ds_bpermute_b32 v117, v206, v116
	v_add_u32_e32 v118, 0x1040, v190
	v_cndmask_b32_e64 v118, v190, v118, s[38:39]
	global_store_dwordx2 v118, v[246:247], s[54:55]
	s_and_saveexec_b64 s[16:17], s[42:43]
	s_cbranch_execz .LBB0_330
	s_waitcnt lgkmcnt(1)
	v_add_f32_e32 v114, v114, v115
	s_waitcnt lgkmcnt(0)
	v_add_f32_e32 v115, v116, v117
	ds_write2_b32 v194, v114, v115 offset1:8
.LBB0_330:
	s_or_b64 exec, exec, s[16:17]
	v_add_u32_e32 v114, 0x40000, v207
	v_add_u32_e32 v190, 0x50000, v207
	v_add_u32_e32 v188, 0x40080, v207
	global_load_dwordx4 v[122:125], v190, s[58:59]
	global_load_dwordx4 v[118:121], v188, s[58:59]
	v_add_u32_e32 v186, 0x50080, v207
	global_load_dwordx4 v[126:129], v114, s[58:59]
	s_waitcnt lgkmcnt(0)
	global_load_dwordx4 v[114:117], v186, s[58:59]
	ds_write_b128 v200, v[110:113]
	ds_write_b128 v200, v[106:109] offset:64
	ds_read_b128 v[106:109], v201
	ds_read_b128 v[110:113], v201 offset:1152
	v_mov_b32_e32 v185, v155
	v_mov_b32_e32 v183, v155
	s_waitcnt lgkmcnt(1)
	v_pk_fma_f32 v[108:109], v[178:179], v[108:109], v[144:145]
	v_add_u32_e32 v144, 0x8000, v202
	v_pk_fma_f32 v[106:107], v[180:181], v[106:107], v[142:143]
	v_lshlrev_b32_e32 v142, 2, v144
	global_store_dwordx4 v142, v[106:109], s[56:57] nt
	v_pk_mul_f32 v[142:143], v[176:177], v[106:107]
	s_waitcnt lgkmcnt(0)
	v_pk_fma_f32 v[112:113], v[178:179], v[112:113], v[140:141]
	v_pk_fma_f32 v[110:111], v[180:181], v[110:111], v[138:139]
	v_lshl_add_u64 v[138:139], s[56:57], 0, v[154:155]
	v_pk_mul_f32 v[208:209], v[174:175], v[108:109]
	v_cvt_pk_bf16_f32 v142, v142, v143
	v_pk_mul_f32 v[140:141], v[174:175], v[112:113]
	v_cvt_pk_bf16_f32 v143, v208, v209
	global_store_dwordx4 v[138:139], v[110:113], off nt
	v_pk_mul_f32 v[138:139], v[176:177], v[110:111]
	s_nop 0
	v_cvt_pk_bf16_f32 v138, v138, v139
	v_cvt_pk_bf16_f32 v139, v140, v141
	ds_write_b128 v200, v[102:105]
	ds_write_b128 v200, v[98:101] offset:64
	ds_read_b128 v[98:101], v201
	ds_read_b128 v[102:105], v201 offset:1152
	s_waitcnt lgkmcnt(1)
	v_pk_fma_f32 v[98:99], v[168:169], v[98:99], v[134:135]
	v_pk_fma_f32 v[100:101], v[166:167], v[100:101], v[136:137]
	v_lshl_add_u64 v[134:135], s[56:57], 0, v[184:185]
	v_pk_mul_f32 v[136:137], v[172:173], v[98:99]
	s_waitcnt lgkmcnt(0)
	v_pk_fma_f32 v[104:105], v[166:167], v[104:105], v[132:133]
	v_pk_fma_f32 v[102:103], v[168:169], v[102:103], v[130:131]
	v_lshl_add_u64 v[130:131], s[56:57], 0, v[182:183]
	global_store_dwordx4 v[134:135], v[98:101], off nt
	v_pk_mul_f32 v[134:135], v[170:171], v[100:101]
	v_cvt_pk_bf16_f32 v136, v136, v137
	v_pk_mul_f32 v[132:133], v[172:173], v[102:103]
	v_cvt_pk_bf16_f32 v137, v134, v135
	global_store_dwordx4 v[130:131], v[102:105], off nt
	ds_bpermute_b32 v130, v203, v136
	ds_bpermute_b32 v131, v203, v137
	v_pk_mul_f32 v[134:135], v[170:171], v[104:105]
	v_cvt_pk_bf16_f32 v132, v132, v133
	s_nop 0
	v_cvt_pk_bf16_f32 v133, v134, v135
	v_lshlrev_b32_e32 v134, 1, v144
	s_waitcnt lgkmcnt(0)
	v_add_u32_e32 v250, 0xfffff040, v134
	v_cndmask_b32_e64 v250, v134, v250, s[40:41]
	v_cndmask_b32_e64 v248, v142, v130, s[40:41]
	v_cndmask_b32_e64 v249, v143, v131, s[40:41]
	global_store_dwordx2 v250, v[248:249], s[54:55]
	v_cndmask_b32_e64 v246, v130, v142, s[40:41]
	v_cndmask_b32_e64 v247, v131, v143, s[40:41]
	s_waitcnt lgkmcnt(1)
	v_add_u32_e32 v130, 0x1040, v134
	v_cndmask_b32_e64 v130, v134, v130, s[38:39]
	global_store_dwordx2 v130, v[246:247], s[54:55]
	ds_bpermute_b32 v130, v203, v132
	s_waitcnt lgkmcnt(1)
	ds_bpermute_b32 v131, v203, v133
	v_add_u32_e32 v133, 0xc000, v202
	v_lshlrev_b32_e32 v132, 1, v133
	s_waitcnt lgkmcnt(0)
	v_add_u32_e32 v250, 0xfffff040, v132
	v_cndmask_b32_e64 v250, v132, v250, s[40:41]
	v_cndmask_b32_e64 v248, v138, v130, s[40:41]
	v_cndmask_b32_e64 v249, v139, v131, s[40:41]
	global_store_dwordx2 v250, v[248:249], s[54:55]
	v_cndmask_b32_e64 v246, v130, v138, s[40:41]
	v_cndmask_b32_e64 v247, v131, v139, s[40:41]
	v_mul_f32_e32 v99, v99, v99
	v_fmac_f32_e32 v99, v98, v98
	v_mul_f32_e32 v98, v101, v101
	v_mul_f32_e32 v109, v109, v109
	v_fmac_f32_e32 v98, v100, v100
	v_mul_f32_e32 v107, v107, v107
	v_fmac_f32_e32 v109, v108, v108
	v_mul_f32_e32 v108, v111, v111
	v_mul_f32_e32 v111, v113, v113
	v_add_f32_e32 v98, v99, v98
	v_mul_f32_e32 v99, v103, v103
	v_mul_f32_e32 v100, v105, v105
	v_fmac_f32_e32 v111, v112, v112
	v_fmac_f32_e32 v99, v102, v102
	v_fmac_f32_e32 v100, v104, v104
	v_fmac_f32_e32 v107, v106, v106
	v_fmac_f32_e32 v108, v110, v110
	v_add_f32_e32 v99, v99, v100
	v_add_f32_e32 v100, v107, v109
	v_add_f32_e32 v101, v108, v111
	v_add_f32_e32 v98, v100, v98
	v_add_f32_e32 v99, v101, v99
	ds_bpermute_b32 v100, v204, v98
	ds_bpermute_b32 v101, v204, v99
	s_waitcnt lgkmcnt(1)
	v_add_f32_e32 v98, v98, v100
	s_waitcnt lgkmcnt(0)
	v_add_f32_e32 v101, v99, v101
	ds_bpermute_b32 v100, v205, v98
	ds_bpermute_b32 v102, v205, v101
	s_waitcnt lgkmcnt(1)
	v_add_f32_e32 v98, v98, v100
	s_waitcnt lgkmcnt(0)
	v_add_f32_e32 v100, v101, v102
	ds_bpermute_b32 v99, v206, v98
	ds_bpermute_b32 v101, v206, v100
	v_add_u32_e32 v102, 0x1040, v132
	v_cndmask_b32_e64 v102, v132, v102, s[38:39]
	global_store_dwordx2 v102, v[246:247], s[54:55]
	s_and_saveexec_b64 s[16:17], s[42:43]
	s_cbranch_execz .LBB0_340
; #define LAS __attribute__((address_space(3)))
; #define ERN_EOFF(q, m) (eb + (unsigned)((((q) & 1) * HALF + (m) * 16) * DM + ERN_COL((q) >> 1)))
;     __device__ __forceinline__ void operator()(const f32x4 (&acc)[2][2][4][2], const Unit& u, int wr, int wc, int fr, int fq) const {
;     ...
;         for (int g = 0; g < 8; ++g) { const int ai = g >> 2, m = g & 3;
;             if (g + 1 < 8) ERN_LOADX(g + 1);
;             float sq0 = 0.f, sq1 = 0.f; u32x2 hw[2][2];
; #pragma unroll
;             for (int bj = 0; bj < 2; ++bj) {
;                 *(LAS f32x4*)(st + wr_off) = acc[ai][bj][m][0]; *(LAS f32x4*)(st + wr_off + 64) = acc[ai][bj][m][1];
;                 const f32x4 a0 = *(const LAS f32x4*)(st + rd_off), a1 = *(const LAS f32x4*)(st + rd_off + 8 * 144);
;                 { const f32x4 xv = xb[g & 1][bj][0] + gv[bj] * a0; __builtin_nontemporal_store(xv, (f32x4*)((char*)xo + 4u * ERN_EOFF(g, bj, 0)));
;                   sq0 += (xv.x * xv.x + xv.y * xv.y) + (xv.z * xv.z + xv.w * xv.w);
;                   const f32x4 hv = xv * gsn[bj]; hw[bj][0].x = cvt_pk_bf16(hv.x, hv.y); hw[bj][0].y = cvt_pk_bf16(hv.z, hv.w); }
;                 { const f32x4 xv = xb[g & 1][bj][1] + gv[bj] * a1; __builtin_nontemporal_store(xv, (f32x4*)((char*)xo + 4u * ERN_EOFF(g, bj, 1)));
;                   sq1 += (xv.x * xv.x + xv.y * xv.y) + (xv.z * xv.z + xv.w * xv.w);
;                   const f32x4 hv = xv * gsn[bj]; hw[bj][1].x = cvt_pk_bf16(hv.x, hv.y); hw[bj][1].y = cvt_pk_bf16(hv.z, hv.w); }
;             }
;             if (!NOH && !PLAIN) {
; #pragma unroll
;                 for (int rh = 0; rh < 2; ++rh) { u32x2 rv; rv.x = __shfl_xor(hw[1][rh].x, 8); rv.y = __shfl_xor(hw[1][rh].y, 8);
;                     const unsigned e0 = ERN_EOFF(g, 0, rh);
;                     const unsigned ee = odd ? (e0 - DM + 32) : e0, eo2 = odd ? e0 : (e0 + DM + 32);
;                     *(u32x2*)((char*)ho + 2u * ee) = odd ? rv : hw[0][rh];
;                     *(u32x2*)((char*)ho + 2u * eo2) = odd ? hw[0][rh] : rv; }
;             }
;             if (!PLAIN) { sq0 += __shfl_xor(sq0, 1); sq0 += __shfl_xor(sq0, 2); sq0 += __shfl_xor(sq0, 4);
;             sq1 += __shfl_xor(sq1, 1); sq1 += __shfl_xor(sq1, 2); sq1 += __shfl_xor(sq1, 4); }
;             if (!PLAIN && pc == 0) { sst[g * 16 + rr] = sq0; sst[g * 16 + 8 + rr] = sq1; }
	s_waitcnt lgkmcnt(1)
	v_add_f32_e32 v98, v98, v99
	s_waitcnt lgkmcnt(0)
	v_add_f32_e32 v99, v100, v101
	ds_write2_b32 v194, v98, v99 offset0:16 offset1:24
.LBB0_340:
	s_or_b64 exec, exec, s[16:17]
	v_add_u32_e32 v98, 0x60000, v207
	v_add_u32_e32 v154, 0x70000, v207
	v_add_u32_e32 v132, 0x60080, v207
	global_load_dwordx4 v[106:109], v154, s[58:59]
	global_load_dwordx4 v[102:105], v132, s[58:59]
	v_add_u32_e32 v130, 0x70080, v207
	global_load_dwordx4 v[110:113], v98, s[58:59]
	s_waitcnt lgkmcnt(0)
	global_load_dwordx4 v[98:101], v130, s[58:59]
	ds_write_b128 v200, v[94:97]
	ds_write_b128 v200, v[90:93] offset:64
	ds_read_b128 v[90:93], v201
	ds_read_b128 v[94:97], v201 offset:1152
	v_mov_b32_e32 v191, v155
	v_mov_b32_e32 v189, v155
	v_mov_b32_e32 v187, v155
	s_waitcnt vmcnt(11) lgkmcnt(1)
	v_pk_fma_f32 v[92:93], v[178:179], v[92:93], v[128:129]
	v_add_u32_e32 v128, 0x10000, v202
	v_pk_fma_f32 v[90:91], v[180:181], v[90:91], v[126:127]
	v_lshlrev_b32_e32 v126, 2, v128
	global_store_dwordx4 v126, v[90:93], s[56:57] nt
	v_pk_mul_f32 v[126:127], v[176:177], v[90:91]
	s_waitcnt lgkmcnt(0)
	v_pk_fma_f32 v[96:97], v[178:179], v[96:97], v[124:125]
	v_pk_fma_f32 v[94:95], v[180:181], v[94:95], v[122:123]
	v_lshl_add_u64 v[122:123], s[56:57], 0, v[190:191]
	v_pk_mul_f32 v[134:135], v[174:175], v[92:93]
	v_cvt_pk_bf16_f32 v126, v126, v127
	v_pk_mul_f32 v[124:125], v[174:175], v[96:97]
	v_cvt_pk_bf16_f32 v127, v134, v135
	global_store_dwordx4 v[122:123], v[94:97], off nt
	v_pk_mul_f32 v[122:123], v[176:177], v[94:95]
	s_nop 0
	v_cvt_pk_bf16_f32 v122, v122, v123
	v_cvt_pk_bf16_f32 v123, v124, v125
	ds_write_b128 v200, v[86:89]
	ds_write_b128 v200, v[82:85] offset:64
	ds_read_b128 v[82:85], v201
	ds_read_b128 v[86:89], v201 offset:1152
	s_waitcnt lgkmcnt(1)
	v_pk_fma_f32 v[82:83], v[168:169], v[82:83], v[118:119]
	v_pk_fma_f32 v[84:85], v[166:167], v[84:85], v[120:121]
	v_lshl_add_u64 v[118:119], s[56:57], 0, v[188:189]
	v_pk_mul_f32 v[120:121], v[172:173], v[82:83]
	s_waitcnt vmcnt(12) lgkmcnt(0)
	v_pk_fma_f32 v[88:89], v[166:167], v[88:89], v[116:117]
	v_pk_fma_f32 v[86:87], v[168:169], v[86:87], v[114:115]
	v_lshl_add_u64 v[114:115], s[56:57], 0, v[186:187]
	global_store_dwordx4 v[118:119], v[82:85], off nt
	v_pk_mul_f32 v[118:119], v[170:171], v[84:85]
	v_cvt_pk_bf16_f32 v120, v120, v121
	v_pk_mul_f32 v[116:117], v[172:173], v[86:87]
	v_cvt_pk_bf16_f32 v121, v118, v119
	global_store_dwordx4 v[114:115], v[86:89], off nt
	ds_bpermute_b32 v114, v203, v120
	ds_bpermute_b32 v115, v203, v121
	v_pk_mul_f32 v[118:119], v[170:171], v[88:89]
	v_cvt_pk_bf16_f32 v116, v116, v117
	s_nop 0
	v_cvt_pk_bf16_f32 v117, v118, v119
	v_lshlrev_b32_e32 v118, 1, v128
	s_waitcnt lgkmcnt(0)
	v_add_u32_e32 v250, 0xfffff040, v118
	v_cndmask_b32_e64 v250, v118, v250, s[40:41]
	v_cndmask_b32_e64 v248, v126, v114, s[40:41]
	v_cndmask_b32_e64 v249, v127, v115, s[40:41]
	global_store_dwordx2 v250, v[248:249], s[54:55]
	v_cndmask_b32_e64 v246, v114, v126, s[40:41]
	v_cndmask_b32_e64 v247, v115, v127, s[40:41]
	s_waitcnt lgkmcnt(1)
	v_add_u32_e32 v114, 0x1040, v118
	v_cndmask_b32_e64 v114, v118, v114, s[38:39]
	global_store_dwordx2 v114, v[246:247], s[54:55]
	ds_bpermute_b32 v114, v203, v116
	s_waitcnt lgkmcnt(1)
	ds_bpermute_b32 v115, v203, v117
	v_add_u32_e32 v117, 0x14000, v202
	v_lshlrev_b32_e32 v116, 1, v117
	s_waitcnt lgkmcnt(0)
	v_add_u32_e32 v250, 0xfffff040, v116
	v_cndmask_b32_e64 v250, v116, v250, s[40:41]
	v_cndmask_b32_e64 v248, v122, v114, s[40:41]
	v_cndmask_b32_e64 v249, v123, v115, s[40:41]
	global_store_dwordx2 v250, v[248:249], s[54:55]
	v_cndmask_b32_e64 v246, v114, v122, s[40:41]
	v_cndmask_b32_e64 v247, v115, v123, s[40:41]
	v_mul_f32_e32 v83, v83, v83
	v_fmac_f32_e32 v83, v82, v82
	v_mul_f32_e32 v82, v85, v85
	v_mul_f32_e32 v93, v93, v93
	v_fmac_f32_e32 v82, v84, v84
	v_mul_f32_e32 v91, v91, v91
	v_fmac_f32_e32 v93, v92, v92
	v_mul_f32_e32 v92, v95, v95
	v_mul_f32_e32 v95, v97, v97
	v_add_f32_e32 v82, v83, v82
	v_mul_f32_e32 v83, v87, v87
	v_mul_f32_e32 v84, v89, v89
	v_fmac_f32_e32 v95, v96, v96
	v_fmac_f32_e32 v83, v86, v86
	v_fmac_f32_e32 v84, v88, v88
	v_fmac_f32_e32 v91, v90, v90
	v_fmac_f32_e32 v92, v94, v94
	v_add_f32_e32 v83, v83, v84
	v_add_f32_e32 v84, v91, v93
	v_add_f32_e32 v85, v92, v95
	v_add_f32_e32 v82, v84, v82
	v_add_f32_e32 v83, v85, v83
	ds_bpermute_b32 v84, v204, v82
	ds_bpermute_b32 v85, v204, v83
	s_waitcnt lgkmcnt(1)
	v_add_f32_e32 v82, v82, v84
	s_waitcnt lgkmcnt(0)
	v_add_f32_e32 v85, v83, v85
	ds_bpermute_b32 v84, v205, v82
	ds_bpermute_b32 v86, v205, v85
	s_waitcnt lgkmcnt(1)
	v_add_f32_e32 v82, v82, v84
	s_waitcnt lgkmcnt(0)
	v_add_f32_e32 v84, v85, v86
	ds_bpermute_b32 v83, v206, v82
	ds_bpermute_b32 v85, v206, v84
	v_add_u32_e32 v86, 0x1040, v116
	v_cndmask_b32_e64 v86, v116, v86, s[38:39]
	global_store_dwordx2 v86, v[246:247], s[54:55]
	s_and_saveexec_b64 s[16:17], s[42:43]
	s_cbranch_execz .LBB0_350
	s_waitcnt lgkmcnt(1)
	v_add_f32_e32 v82, v82, v83
	s_waitcnt lgkmcnt(0)
	v_add_f32_e32 v83, v84, v85
	ds_write2_b32 v194, v82, v83 offset0:32 offset1:40
; #define LAS __attribute__((address_space(3)))
; #define ERN_EOFF(q, m) (eb + (unsigned)((((q) & 1) * HALF + (m) * 16) * DM + ERN_COL((q) >> 1)))
;     __device__ __forceinline__ void operator()(const f32x4 (&acc)[2][2][4][2], const Unit& u, int wr, int wc, int fr, int fq) const {
;     ...
;         for (int g = 0; g < 8; ++g) { const int ai = g >> 2, m = g & 3;
;             if (g + 1 < 8) ERN_LOADX(g + 1);
;             float sq0 = 0.f, sq1 = 0.f; u32x2 hw[2][2];
; #pragma unroll
;             for (int bj = 0; bj < 2; ++bj) {
;                 *(LAS f32x4*)(st + wr_off) = acc[ai][bj][m][0]; *(LAS f32x4*)(st + wr_off + 64) = acc[ai][bj][m][1];
;                 const f32x4 a0 = *(const LAS f32x4*)(st + rd_off), a1 = *(const LAS f32x4*)(st + rd_off + 8 * 144);
;                 { const f32x4 xv = xb[g & 1][bj][0] + gv[bj] * a0; __builtin_nontemporal_store(xv, (f32x4*)((char*)xo + 4u * ERN_EOFF(g, bj, 0)));
;                   sq0 += (xv.x * xv.x + xv.y * xv.y) + (xv.z * xv.z + xv.w * xv.w);
;                   const f32x4 hv = xv * gsn[bj]; hw[bj][0].x = cvt_pk_bf16(hv.x, hv.y); hw[bj][0].y = cvt_pk_bf16(hv.z, hv.w); }
;                 { const f32x4 xv = xb[g & 1][bj][1] + gv[bj] * a1; __builtin_nontemporal_store(xv, (f32x4*)((char*)xo + 4u * ERN_EOFF(g, bj, 1)));
;                   sq1 += (xv.x * xv.x + xv.y * xv.y) + (xv.z * xv.z + xv.w * xv.w);
;                   const f32x4 hv = xv * gsn[bj]; hw[bj][1].x = cvt_pk_bf16(hv.x, hv.y); hw[bj][1].y = cvt_pk_bf16(hv.z, hv.w); }
;             }
;             if (!NOH && !PLAIN) {
; #pragma unroll
;                 for (int rh = 0; rh < 2; ++rh) { u32x2 rv; rv.x = __shfl_xor(hw[1][rh].x, 8); rv.y = __shfl_xor(hw[1][rh].y, 8);
;                     const unsigned e0 = ERN_EOFF(g, 0, rh);
;                     const unsigned ee = odd ? (e0 - DM + 32) : e0, eo2 = odd ? e0 : (e0 + DM + 32);
;                     *(u32x2*)((char*)ho + 2u * ee) = odd ? rv : hw[0][rh];
;                     *(u32x2*)((char*)ho + 2u * eo2) = odd ? hw[0][rh] : rv; }
;             }
;             if (!PLAIN) { sq0 += __shfl_xor(sq0, 1); sq0 += __shfl_xor(sq0, 2); sq0 += __shfl_xor(sq0, 4);
;             sq1 += __shfl_xor(sq1, 1); sq1 += __shfl_xor(sq1, 2); sq1 += __shfl_xor(sq1, 4); }
;             if (!PLAIN && pc == 0) { sst[g * 16 + rr] = sq0; sst[g * 16 + 8 + rr] = sq1; }
.LBB0_350:
	s_or_b64 exec, exec, s[16:17]
	v_add_u32_e32 v82, 0x100000, v207
	s_waitcnt lgkmcnt(1)
	v_add_u32_e32 v83, 0x110000, v207
	v_add_u32_e32 v116, 0x100080, v207
	global_load_dwordx4 v[94:97], v82, s[58:59]
	global_load_dwordx4 v[90:93], v83, s[58:59]
	v_add_u32_e32 v114, 0x110080, v207
	global_load_dwordx4 v[86:89], v116, s[58:59]
	s_waitcnt lgkmcnt(0)
	global_load_dwordx4 v[82:85], v114, s[58:59]
	ds_write_b128 v200, v[78:81]
	ds_write_b128 v200, v[74:77] offset:64
	ds_read_b128 v[74:77], v201
	ds_read_b128 v[78:81], v201 offset:1152
	v_mov_b32_e32 v133, v155
	v_mov_b32_e32 v131, v155
	s_waitcnt vmcnt(11) lgkmcnt(1)
	v_pk_fma_f32 v[76:77], v[178:179], v[76:77], v[112:113]
	v_add_u32_e32 v112, 0x18000, v202
	v_pk_fma_f32 v[74:75], v[180:181], v[74:75], v[110:111]
	v_lshlrev_b32_e32 v110, 2, v112
	global_store_dwordx4 v110, v[74:77], s[56:57] nt
	v_pk_mul_f32 v[110:111], v[176:177], v[74:75]
	s_waitcnt lgkmcnt(0)
	v_pk_fma_f32 v[80:81], v[178:179], v[80:81], v[108:109]
	v_pk_fma_f32 v[78:79], v[180:181], v[78:79], v[106:107]
	v_lshl_add_u64 v[106:107], s[56:57], 0, v[154:155]
	v_pk_mul_f32 v[118:119], v[174:175], v[76:77]
	v_cvt_pk_bf16_f32 v110, v110, v111
	v_pk_mul_f32 v[108:109], v[174:175], v[80:81]
	v_cvt_pk_bf16_f32 v111, v118, v119
	global_store_dwordx4 v[106:107], v[78:81], off nt
	v_pk_mul_f32 v[106:107], v[176:177], v[78:79]
	s_nop 0
	v_cvt_pk_bf16_f32 v106, v106, v107
	v_cvt_pk_bf16_f32 v107, v108, v109
	ds_write_b128 v200, v[70:73]
	ds_write_b128 v200, v[66:69] offset:64
	ds_read_b128 v[66:69], v201
	ds_read_b128 v[70:73], v201 offset:1152
	s_waitcnt lgkmcnt(1)
	v_pk_fma_f32 v[66:67], v[168:169], v[66:67], v[102:103]
	v_pk_fma_f32 v[68:69], v[166:167], v[68:69], v[104:105]
	v_lshl_add_u64 v[102:103], s[56:57], 0, v[132:133]
	v_pk_mul_f32 v[104:105], v[172:173], v[66:67]
	s_waitcnt vmcnt(12) lgkmcnt(0)
	v_pk_fma_f32 v[72:73], v[166:167], v[72:73], v[100:101]
	v_pk_fma_f32 v[70:71], v[168:169], v[70:71], v[98:99]
	v_lshl_add_u64 v[98:99], s[56:57], 0, v[130:131]
	global_store_dwordx4 v[102:103], v[66:69], off nt
	v_pk_mul_f32 v[102:103], v[170:171], v[68:69]
	v_cvt_pk_bf16_f32 v104, v104, v105
	v_pk_mul_f32 v[100:101], v[172:173], v[70:71]
	v_cvt_pk_bf16_f32 v105, v102, v103
	global_store_dwordx4 v[98:99], v[70:73], off nt
	ds_bpermute_b32 v98, v203, v104
	ds_bpermute_b32 v99, v203, v105
	v_pk_mul_f32 v[102:103], v[170:171], v[72:73]
	v_cvt_pk_bf16_f32 v100, v100, v101
	s_nop 0
	v_cvt_pk_bf16_f32 v101, v102, v103
	v_lshlrev_b32_e32 v102, 1, v112
	s_waitcnt lgkmcnt(0)
	v_add_u32_e32 v250, 0xfffff040, v102
	v_cndmask_b32_e64 v250, v102, v250, s[40:41]
	v_cndmask_b32_e64 v248, v110, v98, s[40:41]
	v_cndmask_b32_e64 v249, v111, v99, s[40:41]
	global_store_dwordx2 v250, v[248:249], s[54:55]
	v_cndmask_b32_e64 v246, v98, v110, s[40:41]
	v_cndmask_b32_e64 v247, v99, v111, s[40:41]
	s_waitcnt lgkmcnt(1)
	v_add_u32_e32 v98, 0x1040, v102
	v_cndmask_b32_e64 v98, v102, v98, s[38:39]
	global_store_dwordx2 v98, v[246:247], s[54:55]
	ds_bpermute_b32 v98, v203, v100
	s_waitcnt lgkmcnt(1)
	ds_bpermute_b32 v99, v203, v101
	v_add_u32_e32 v101, 0x1c000, v202
	v_lshlrev_b32_e32 v100, 1, v101
	s_waitcnt lgkmcnt(0)
	v_add_u32_e32 v250, 0xfffff040, v100
	v_cndmask_b32_e64 v250, v100, v250, s[40:41]
	v_cndmask_b32_e64 v248, v106, v98, s[40:41]
	v_cndmask_b32_e64 v249, v107, v99, s[40:41]
	global_store_dwordx2 v250, v[248:249], s[54:55]
	v_cndmask_b32_e64 v246, v98, v106, s[40:41]
	v_cndmask_b32_e64 v247, v99, v107, s[40:41]
	v_mul_f32_e32 v67, v67, v67
	v_fmac_f32_e32 v67, v66, v66
	v_mul_f32_e32 v66, v69, v69
	v_mul_f32_e32 v77, v77, v77
	v_fmac_f32_e32 v66, v68, v68
	v_mul_f32_e32 v75, v75, v75
	v_fmac_f32_e32 v77, v76, v76
	v_mul_f32_e32 v76, v79, v79
	v_mul_f32_e32 v79, v81, v81
	v_add_f32_e32 v66, v67, v66
	v_mul_f32_e32 v67, v71, v71
	v_mul_f32_e32 v68, v73, v73
	v_fmac_f32_e32 v79, v80, v80
	v_fmac_f32_e32 v67, v70, v70
	v_fmac_f32_e32 v68, v72, v72
	v_fmac_f32_e32 v75, v74, v74
	v_fmac_f32_e32 v76, v78, v78
	v_add_f32_e32 v67, v67, v68
	v_add_f32_e32 v68, v75, v77
	v_add_f32_e32 v69, v76, v79
	v_add_f32_e32 v66, v68, v66
	v_add_f32_e32 v67, v69, v67
	ds_bpermute_b32 v68, v204, v66
	ds_bpermute_b32 v69, v204, v67
	s_waitcnt lgkmcnt(1)
	v_add_f32_e32 v66, v66, v68
	s_waitcnt lgkmcnt(0)
	v_add_f32_e32 v69, v67, v69
	ds_bpermute_b32 v68, v205, v66
	ds_bpermute_b32 v70, v205, v69
	s_waitcnt lgkmcnt(1)
	v_add_f32_e32 v66, v66, v68
	s_waitcnt lgkmcnt(0)
	v_add_f32_e32 v68, v69, v70
	ds_bpermute_b32 v67, v206, v66
	ds_bpermute_b32 v69, v206, v68
	v_add_u32_e32 v70, 0x1040, v100
	v_cndmask_b32_e64 v70, v100, v70, s[38:39]
	global_store_dwordx2 v70, v[246:247], s[54:55]
	s_and_saveexec_b64 s[16:17], s[42:43]
	s_cbranch_execz .LBB0_360
	s_waitcnt lgkmcnt(1)
	v_add_f32_e32 v66, v66, v67
	s_waitcnt lgkmcnt(0)
	v_add_f32_e32 v67, v68, v69
	ds_write2_b32 v194, v66, v67 offset0:48 offset1:56
; #define LAS __attribute__((address_space(3)))
; #define ERN_EOFF(q, m) (eb + (unsigned)((((q) & 1) * HALF + (m) * 16) * DM + ERN_COL((q) >> 1)))
;     __device__ __forceinline__ void operator()(const f32x4 (&acc)[2][2][4][2], const Unit& u, int wr, int wc, int fr, int fq) const {
;     ...
;         ERN_LOADX(0);
; #pragma unroll
;         for (int g = 0; g < 8; ++g) { const int ai = g >> 2, m = g & 3;
;             if (g + 1 < 8) ERN_LOADX(g + 1);
;             float sq0 = 0.f, sq1 = 0.f; u32x2 hw[2][2];
; #pragma unroll
;             for (int bj = 0; bj < 2; ++bj) {
;                 *(LAS f32x4*)(st + wr_off) = acc[ai][bj][m][0]; *(LAS f32x4*)(st + wr_off + 64) = acc[ai][bj][m][1];
;                 const f32x4 a0 = *(const LAS f32x4*)(st + rd_off), a1 = *(const LAS f32x4*)(st + rd_off + 8 * 144);
;                 { const f32x4 xv = xb[g & 1][bj][0] + gv[bj] * a0; __builtin_nontemporal_store(xv, (f32x4*)((char*)xo + 4u * ERN_EOFF(g, bj, 0)));
;                   sq0 += (xv.x * xv.x + xv.y * xv.y) + (xv.z * xv.z + xv.w * xv.w);
;                   const f32x4 hv = xv * gsn[bj]; hw[bj][0].x = cvt_pk_bf16(hv.x, hv.y); hw[bj][0].y = cvt_pk_bf16(hv.z, hv.w); }
;                 { const f32x4 xv = xb[g & 1][bj][1] + gv[bj] * a1; __builtin_nontemporal_store(xv, (f32x4*)((char*)xo + 4u * ERN_EOFF(g, bj, 1)));
;                   sq1 += (xv.x * xv.x + xv.y * xv.y) + (xv.z * xv.z + xv.w * xv.w);
;                   const f32x4 hv = xv * gsn[bj]; hw[bj][1].x = cvt_pk_bf16(hv.x, hv.y); hw[bj][1].y = cvt_pk_bf16(hv.z, hv.w); }
;             }
;             if (!NOH && !PLAIN) {
; #pragma unroll
;                 for (int rh = 0; rh < 2; ++rh) { u32x2 rv; rv.x = __shfl_xor(hw[1][rh].x, 8); rv.y = __shfl_xor(hw[1][rh].y, 8);
;                     const unsigned e0 = ERN_EOFF(g, 0, rh);
;                     const unsigned ee = odd ? (e0 - DM + 32) : e0, eo2 = odd ? e0 : (e0 + DM + 32);
;                     *(u32x2*)((char*)ho + 2u * ee) = odd ? rv : hw[0][rh];
;                     *(u32x2*)((char*)ho + 2u * eo2) = odd ? hw[0][rh] : rv; }
;             }
;             if (!PLAIN) { sq0 += __shfl_xor(sq0, 1); sq0 += __shfl_xor(sq0, 2); sq0 += __shfl_xor(sq0, 4);
;             sq1 += __shfl_xor(sq1, 1); sq1 += __shfl_xor(sq1, 2); sq1 += __shfl_xor(sq1, 4); }
;             if (!PLAIN && pc == 0) { sst[g * 16 + rr] = sq0; sst[g * 16 + 8 + rr] = sq1; }
.LBB0_360:
	s_or_b64 exec, exec, s[16:17]
	v_add_u32_e32 v154, 0x120000, v207
	v_add_u32_e32 v100, 0x120080, v207
	v_add_u32_e32 v102, 0x130000, v207
	global_load_dwordx4 v[78:81], v154, s[58:59]
	global_load_dwordx4 v[74:77], v102, s[58:59]
	v_add_u32_e32 v98, 0x130080, v207
	global_load_dwordx4 v[70:73], v100, s[58:59]
	s_waitcnt lgkmcnt(0)
	global_load_dwordx4 v[66:69], v98, s[58:59]
	ds_write_b128 v200, v[62:65]
	ds_write_b128 v200, v[58:61] offset:64
	ds_read_b128 v[58:61], v201
	ds_read_b128 v[62:65], v201 offset:1152
	v_mov_b32_e32 v117, v155
	v_mov_b32_e32 v115, v155
	s_waitcnt vmcnt(13) lgkmcnt(1)
	v_pk_fma_f32 v[60:61], v[178:179], v[60:61], v[96:97]
	v_add_u32_e32 v96, 0x40000, v202
	v_pk_fma_f32 v[58:59], v[180:181], v[58:59], v[94:95]
	v_lshlrev_b32_e32 v94, 2, v96
	s_waitcnt vmcnt(12) lgkmcnt(0)
	v_pk_fma_f32 v[64:65], v[178:179], v[64:65], v[92:93]
	v_add_u32_e32 v92, 0x44000, v202
	global_store_dwordx4 v94, v[58:61], s[56:57] nt
	v_pk_mul_f32 v[94:95], v[176:177], v[58:59]
	v_pk_fma_f32 v[62:63], v[180:181], v[62:63], v[90:91]
	v_lshlrev_b32_e32 v90, 2, v92
	v_pk_mul_f32 v[104:105], v[174:175], v[60:61]
	v_cvt_pk_bf16_f32 v94, v94, v95
	s_nop 0
	v_cvt_pk_bf16_f32 v95, v104, v105
	global_store_dwordx4 v90, v[62:65], s[56:57] nt
	v_pk_mul_f32 v[90:91], v[176:177], v[62:63]
	v_pk_mul_f32 v[104:105], v[174:175], v[64:65]
	v_cvt_pk_bf16_f32 v90, v90, v91
	s_nop 0
	v_cvt_pk_bf16_f32 v91, v104, v105
	ds_write_b128 v200, v[54:57]
	ds_write_b128 v200, v[50:53] offset:64
	ds_read_b128 v[50:53], v201
	ds_read_b128 v[54:57], v201 offset:1152
	s_waitcnt vmcnt(13) lgkmcnt(1)
	v_pk_fma_f32 v[50:51], v[168:169], v[50:51], v[86:87]
	v_pk_fma_f32 v[52:53], v[166:167], v[52:53], v[88:89]
	v_lshl_add_u64 v[86:87], s[56:57], 0, v[116:117]
	v_pk_mul_f32 v[88:89], v[172:173], v[50:51]
	s_waitcnt vmcnt(12) lgkmcnt(0)
	v_pk_fma_f32 v[56:57], v[166:167], v[56:57], v[84:85]
	v_pk_fma_f32 v[54:55], v[168:169], v[54:55], v[82:83]
	v_lshl_add_u64 v[82:83], s[56:57], 0, v[114:115]
	global_store_dwordx4 v[86:87], v[50:53], off nt
	v_pk_mul_f32 v[86:87], v[170:171], v[52:53]
	v_cvt_pk_bf16_f32 v88, v88, v89
	v_pk_mul_f32 v[84:85], v[172:173], v[54:55]
	v_cvt_pk_bf16_f32 v89, v86, v87
	global_store_dwordx4 v[82:83], v[54:57], off nt
	ds_bpermute_b32 v82, v203, v88
	ds_bpermute_b32 v83, v203, v89
	v_pk_mul_f32 v[86:87], v[170:171], v[56:57]
	v_cvt_pk_bf16_f32 v84, v84, v85
	s_nop 0
	v_cvt_pk_bf16_f32 v85, v86, v87
	v_lshlrev_b32_e32 v86, 1, v96
	s_waitcnt lgkmcnt(0)
	v_add_u32_e32 v250, 0xfffff040, v86
	v_cndmask_b32_e64 v250, v86, v250, s[40:41]
	v_cndmask_b32_e64 v248, v94, v82, s[40:41]
	v_cndmask_b32_e64 v249, v95, v83, s[40:41]
	global_store_dwordx2 v250, v[248:249], s[54:55]
	v_cndmask_b32_e64 v246, v82, v94, s[40:41]
	v_cndmask_b32_e64 v247, v83, v95, s[40:41]
	s_waitcnt lgkmcnt(1)
	v_add_u32_e32 v82, 0x1040, v86
	v_cndmask_b32_e64 v82, v86, v82, s[38:39]
	global_store_dwordx2 v82, v[246:247], s[54:55]
	ds_bpermute_b32 v82, v203, v84
	s_waitcnt lgkmcnt(1)
	ds_bpermute_b32 v83, v203, v85
	v_lshlrev_b32_e32 v84, 1, v92
	s_waitcnt lgkmcnt(0)
	v_add_u32_e32 v250, 0xfffff040, v84
	v_cndmask_b32_e64 v250, v84, v250, s[40:41]
	v_cndmask_b32_e64 v248, v90, v82, s[40:41]
	v_cndmask_b32_e64 v249, v91, v83, s[40:41]
	global_store_dwordx2 v250, v[248:249], s[54:55]
	v_cndmask_b32_e64 v246, v82, v90, s[40:41]
	v_cndmask_b32_e64 v247, v83, v91, s[40:41]
	v_mul_f32_e32 v51, v51, v51
	v_fmac_f32_e32 v51, v50, v50
	v_mul_f32_e32 v50, v53, v53
	v_mul_f32_e32 v61, v61, v61
	v_fmac_f32_e32 v50, v52, v52
	v_mul_f32_e32 v59, v59, v59
	v_fmac_f32_e32 v61, v60, v60
	v_mul_f32_e32 v60, v63, v63
	v_mul_f32_e32 v63, v65, v65
	v_add_f32_e32 v50, v51, v50
	v_mul_f32_e32 v51, v55, v55
	v_mul_f32_e32 v52, v57, v57
	v_fmac_f32_e32 v63, v64, v64
	v_fmac_f32_e32 v51, v54, v54
	v_fmac_f32_e32 v52, v56, v56
	v_fmac_f32_e32 v59, v58, v58
	v_fmac_f32_e32 v60, v62, v62
	v_add_f32_e32 v51, v51, v52
	v_add_f32_e32 v52, v59, v61
	v_add_f32_e32 v53, v60, v63
	v_add_f32_e32 v50, v52, v50
	v_add_f32_e32 v51, v53, v51
	ds_bpermute_b32 v52, v204, v50
	ds_bpermute_b32 v53, v204, v51
	s_waitcnt lgkmcnt(1)
	v_add_f32_e32 v50, v50, v52
	s_waitcnt lgkmcnt(0)
	v_add_f32_e32 v53, v51, v53
	ds_bpermute_b32 v52, v205, v50
	ds_bpermute_b32 v54, v205, v53
	s_waitcnt lgkmcnt(1)
	v_add_f32_e32 v50, v50, v52
	s_waitcnt lgkmcnt(0)
	v_add_f32_e32 v52, v53, v54
	ds_bpermute_b32 v51, v206, v50
	ds_bpermute_b32 v53, v206, v52
	v_add_u32_e32 v54, 0x1040, v84
	v_cndmask_b32_e64 v54, v84, v54, s[38:39]
	global_store_dwordx2 v54, v[246:247], s[54:55]
	s_and_saveexec_b64 s[16:17], s[42:43]
	s_cbranch_execz .LBB0_370
	s_waitcnt lgkmcnt(1)
	v_add_f32_e32 v50, v50, v51
	s_waitcnt lgkmcnt(0)
	v_add_f32_e32 v51, v52, v53
	ds_write2_b32 v194, v50, v51 offset0:64 offset1:72
; #define LAS __attribute__((address_space(3)))
; #define ERN_EOFF(q, m) (eb + (unsigned)((((q) & 1) * HALF + (m) * 16) * DM + ERN_COL((q) >> 1)))
;     __device__ __forceinline__ void operator()(const f32x4 (&acc)[2][2][4][2], const Unit& u, int wr, int wc, int fr, int fq) const {
;     ...
;         ERN_LOADX(0);
; #pragma unroll
;         for (int g = 0; g < 8; ++g) { const int ai = g >> 2, m = g & 3;
;             if (g + 1 < 8) ERN_LOADX(g + 1);
;             float sq0 = 0.f, sq1 = 0.f; u32x2 hw[2][2];
; #pragma unroll
;             for (int bj = 0; bj < 2; ++bj) {
;                 *(LAS f32x4*)(st + wr_off) = acc[ai][bj][m][0]; *(LAS f32x4*)(st + wr_off + 64) = acc[ai][bj][m][1];
;                 const f32x4 a0 = *(const LAS f32x4*)(st + rd_off), a1 = *(const LAS f32x4*)(st + rd_off + 8 * 144);
;                 { const f32x4 xv = xb[g & 1][bj][0] + gv[bj] * a0; __builtin_nontemporal_store(xv, (f32x4*)((char*)xo + 4u * ERN_EOFF(g, bj, 0)));
;                   sq0 += (xv.x * xv.x + xv.y * xv.y) + (xv.z * xv.z + xv.w * xv.w);
;                   const f32x4 hv = xv * gsn[bj]; hw[bj][0].x = cvt_pk_bf16(hv.x, hv.y); hw[bj][0].y = cvt_pk_bf16(hv.z, hv.w); }
;                 { const f32x4 xv = xb[g & 1][bj][1] + gv[bj] * a1; __builtin_nontemporal_store(xv, (f32x4*)((char*)xo + 4u * ERN_EOFF(g, bj, 1)));
;                   sq1 += (xv.x * xv.x + xv.y * xv.y) + (xv.z * xv.z + xv.w * xv.w);
;                   const f32x4 hv = xv * gsn[bj]; hw[bj][1].x = cvt_pk_bf16(hv.x, hv.y); hw[bj][1].y = cvt_pk_bf16(hv.z, hv.w); }
;             }
;             if (!NOH && !PLAIN) {
; #pragma unroll
;                 for (int rh = 0; rh < 2; ++rh) { u32x2 rv; rv.x = __shfl_xor(hw[1][rh].x, 8); rv.y = __shfl_xor(hw[1][rh].y, 8);
;                     const unsigned e0 = ERN_EOFF(g, 0, rh);
;                     const unsigned ee = odd ? (e0 - DM + 32) : e0, eo2 = odd ? e0 : (e0 + DM + 32);
;                     *(u32x2*)((char*)ho + 2u * ee) = odd ? rv : hw[0][rh];
;                     *(u32x2*)((char*)ho + 2u * eo2) = odd ? hw[0][rh] : rv; }
;             }
;             if (!PLAIN) { sq0 += __shfl_xor(sq0, 1); sq0 += __shfl_xor(sq0, 2); sq0 += __shfl_xor(sq0, 4);
;             sq1 += __shfl_xor(sq1, 1); sq1 += __shfl_xor(sq1, 2); sq1 += __shfl_xor(sq1, 4); }
;             if (!PLAIN && pc == 0) { sst[g * 16 + rr] = sq0; sst[g * 16 + 8 + rr] = sq1; }
.LBB0_370:
	s_or_b64 exec, exec, s[16:17]
	v_add_u32_e32 v88, 0x140000, v207
	v_add_u32_e32 v84, 0x140080, v207
	v_add_u32_e32 v86, 0x150000, v207
	global_load_dwordx4 v[62:65], v88, s[58:59]
	global_load_dwordx4 v[58:61], v86, s[58:59]
	v_add_u32_e32 v82, 0x150080, v207
	global_load_dwordx4 v[54:57], v84, s[58:59]
	s_waitcnt lgkmcnt(0)
	global_load_dwordx4 v[50:53], v82, s[58:59]
	ds_write_b128 v200, v[46:49]
	ds_write_b128 v200, v[42:45] offset:64
	ds_read_b128 v[42:45], v201
	ds_read_b128 v[46:49], v201 offset:1152
	v_mov_b32_e32 v103, v155
	v_mov_b32_e32 v101, v155
	v_mov_b32_e32 v99, v155
	s_waitcnt vmcnt(13) lgkmcnt(1)
	v_pk_fma_f32 v[44:45], v[178:179], v[44:45], v[80:81]
	v_pk_fma_f32 v[42:43], v[180:181], v[42:43], v[78:79]
	v_lshl_add_u64 v[78:79], s[56:57], 0, v[154:155]
	global_store_dwordx4 v[78:79], v[42:45], off nt
	v_pk_mul_f32 v[78:79], v[176:177], v[42:43]
	s_waitcnt vmcnt(13) lgkmcnt(0)
	v_pk_fma_f32 v[48:49], v[178:179], v[48:49], v[76:77]
	v_pk_fma_f32 v[46:47], v[180:181], v[46:47], v[74:75]
	v_lshl_add_u64 v[74:75], s[56:57], 0, v[102:103]
	v_pk_mul_f32 v[80:81], v[174:175], v[44:45]
	v_cvt_pk_bf16_f32 v78, v78, v79
	v_pk_mul_f32 v[76:77], v[174:175], v[48:49]
	v_cvt_pk_bf16_f32 v79, v80, v81
	global_store_dwordx4 v[74:75], v[46:49], off nt
	v_pk_mul_f32 v[74:75], v[176:177], v[46:47]
	s_nop 0
	v_cvt_pk_bf16_f32 v74, v74, v75
	v_cvt_pk_bf16_f32 v75, v76, v77
	ds_write_b128 v200, v[38:41]
	ds_write_b128 v200, v[34:37] offset:64
	ds_read_b128 v[34:37], v201
	ds_read_b128 v[38:41], v201 offset:1152
	s_waitcnt vmcnt(13) lgkmcnt(1)
	v_pk_fma_f32 v[34:35], v[168:169], v[34:35], v[70:71]
	v_pk_fma_f32 v[36:37], v[166:167], v[36:37], v[72:73]
	v_lshl_add_u64 v[70:71], s[56:57], 0, v[100:101]
	v_pk_mul_f32 v[72:73], v[172:173], v[34:35]
	s_waitcnt vmcnt(12) lgkmcnt(0)
	v_pk_fma_f32 v[40:41], v[166:167], v[40:41], v[68:69]
	v_pk_fma_f32 v[38:39], v[168:169], v[38:39], v[66:67]
	v_lshl_add_u64 v[66:67], s[56:57], 0, v[98:99]
	global_store_dwordx4 v[70:71], v[34:37], off nt
	v_pk_mul_f32 v[70:71], v[170:171], v[36:37]
	v_cvt_pk_bf16_f32 v72, v72, v73
	v_pk_mul_f32 v[68:69], v[172:173], v[38:39]
	v_cvt_pk_bf16_f32 v73, v70, v71
	global_store_dwordx4 v[66:67], v[38:41], off nt
	ds_bpermute_b32 v66, v203, v72
	ds_bpermute_b32 v67, v203, v73
	v_pk_mul_f32 v[70:71], v[170:171], v[40:41]
	v_cvt_pk_bf16_f32 v68, v68, v69
	s_nop 0
	v_cvt_pk_bf16_f32 v69, v70, v71
	v_add_u32_e32 v71, 0x48000, v202
	v_lshlrev_b32_e32 v70, 1, v71
	s_waitcnt lgkmcnt(0)
	v_add_u32_e32 v250, 0xfffff040, v70
	v_cndmask_b32_e64 v250, v70, v250, s[40:41]
	v_cndmask_b32_e64 v248, v78, v66, s[40:41]
	v_cndmask_b32_e64 v249, v79, v67, s[40:41]
	global_store_dwordx2 v250, v[248:249], s[54:55]
	v_cndmask_b32_e64 v246, v66, v78, s[40:41]
	v_cndmask_b32_e64 v247, v67, v79, s[40:41]
	s_waitcnt lgkmcnt(1)
	v_add_u32_e32 v66, 0x1040, v70
	v_cndmask_b32_e64 v66, v70, v66, s[38:39]
	global_store_dwordx2 v66, v[246:247], s[54:55]
	ds_bpermute_b32 v66, v203, v68
	s_waitcnt lgkmcnt(1)
	ds_bpermute_b32 v67, v203, v69
	v_add_u32_e32 v69, 0x4c000, v202
	v_lshlrev_b32_e32 v68, 1, v69
	s_waitcnt lgkmcnt(0)
	v_add_u32_e32 v250, 0xfffff040, v68
	v_cndmask_b32_e64 v250, v68, v250, s[40:41]
	v_cndmask_b32_e64 v248, v74, v66, s[40:41]
	v_cndmask_b32_e64 v249, v75, v67, s[40:41]
	global_store_dwordx2 v250, v[248:249], s[54:55]
	v_cndmask_b32_e64 v246, v66, v74, s[40:41]
	v_cndmask_b32_e64 v247, v67, v75, s[40:41]
	v_mul_f32_e32 v35, v35, v35
	v_fmac_f32_e32 v35, v34, v34
	v_mul_f32_e32 v34, v37, v37
	v_mul_f32_e32 v45, v45, v45
	v_fmac_f32_e32 v34, v36, v36
	v_mul_f32_e32 v43, v43, v43
	v_fmac_f32_e32 v45, v44, v44
	v_mul_f32_e32 v44, v47, v47
	v_mul_f32_e32 v47, v49, v49
	v_add_f32_e32 v34, v35, v34
	v_mul_f32_e32 v35, v39, v39
	v_mul_f32_e32 v36, v41, v41
	v_fmac_f32_e32 v47, v48, v48
	v_fmac_f32_e32 v35, v38, v38
	v_fmac_f32_e32 v36, v40, v40
	v_fmac_f32_e32 v43, v42, v42
	v_fmac_f32_e32 v44, v46, v46
	v_add_f32_e32 v35, v35, v36
	v_add_f32_e32 v36, v43, v45
	v_add_f32_e32 v37, v44, v47
	v_add_f32_e32 v34, v36, v34
	v_add_f32_e32 v35, v37, v35
	ds_bpermute_b32 v36, v204, v34
	ds_bpermute_b32 v37, v204, v35
	s_waitcnt lgkmcnt(1)
	v_add_f32_e32 v34, v34, v36
	s_waitcnt lgkmcnt(0)
	v_add_f32_e32 v37, v35, v37
	ds_bpermute_b32 v36, v205, v34
	ds_bpermute_b32 v38, v205, v37
	s_waitcnt lgkmcnt(1)
	v_add_f32_e32 v34, v34, v36
	s_waitcnt lgkmcnt(0)
	v_add_f32_e32 v36, v37, v38
	ds_bpermute_b32 v35, v206, v34
	ds_bpermute_b32 v37, v206, v36
	v_add_u32_e32 v38, 0x1040, v68
	v_cndmask_b32_e64 v38, v68, v38, s[38:39]
	global_store_dwordx2 v38, v[246:247], s[54:55]
	s_and_saveexec_b64 s[16:17], s[42:43]
	s_cbranch_execz .LBB0_380
	s_waitcnt lgkmcnt(1)
	v_add_f32_e32 v34, v34, v35
	s_waitcnt lgkmcnt(0)
	v_add_f32_e32 v35, v36, v37
	ds_write2_b32 v194, v34, v35 offset0:80 offset1:88
; #define LAS __attribute__((address_space(3)))
; #define ERN_EOFF(q, m) (eb + (unsigned)((((q) & 1) * HALF + (m) * 16) * DM + ERN_COL((q) >> 1)))
;     __device__ __forceinline__ void operator()(const f32x4 (&acc)[2][2][4][2], const Unit& u, int wr, int wc, int fr, int fq) const {
;     ...
;         ERN_LOADX(0);
; #pragma unroll
;         for (int g = 0; g < 8; ++g) { const int ai = g >> 2, m = g & 3;
;             if (g + 1 < 8) ERN_LOADX(g + 1);
;             float sq0 = 0.f, sq1 = 0.f; u32x2 hw[2][2];
; #pragma unroll
;             for (int bj = 0; bj < 2; ++bj) {
;                 *(LAS f32x4*)(st + wr_off) = acc[ai][bj][m][0]; *(LAS f32x4*)(st + wr_off + 64) = acc[ai][bj][m][1];
;                 const f32x4 a0 = *(const LAS f32x4*)(st + rd_off), a1 = *(const LAS f32x4*)(st + rd_off + 8 * 144);
;                 { const f32x4 xv = xb[g & 1][bj][0] + gv[bj] * a0; __builtin_nontemporal_store(xv, (f32x4*)((char*)xo + 4u * ERN_EOFF(g, bj, 0)));
;                   sq0 += (xv.x * xv.x + xv.y * xv.y) + (xv.z * xv.z + xv.w * xv.w);
;                   const f32x4 hv = xv * gsn[bj]; hw[bj][0].x = cvt_pk_bf16(hv.x, hv.y); hw[bj][0].y = cvt_pk_bf16(hv.z, hv.w); }
;                 { const f32x4 xv = xb[g & 1][bj][1] + gv[bj] * a1; __builtin_nontemporal_store(xv, (f32x4*)((char*)xo + 4u * ERN_EOFF(g, bj, 1)));
;                   sq1 += (xv.x * xv.x + xv.y * xv.y) + (xv.z * xv.z + xv.w * xv.w);
;                   const f32x4 hv = xv * gsn[bj]; hw[bj][1].x = cvt_pk_bf16(hv.x, hv.y); hw[bj][1].y = cvt_pk_bf16(hv.z, hv.w); }
;             }
;             if (!NOH && !PLAIN) {
; #pragma unroll
;                 for (int rh = 0; rh < 2; ++rh) { u32x2 rv; rv.x = __shfl_xor(hw[1][rh].x, 8); rv.y = __shfl_xor(hw[1][rh].y, 8);
;                     const unsigned e0 = ERN_EOFF(g, 0, rh);
;                     const unsigned ee = odd ? (e0 - DM + 32) : e0, eo2 = odd ? e0 : (e0 + DM + 32);
;                     *(u32x2*)((char*)ho + 2u * ee) = odd ? rv : hw[0][rh];
;                     *(u32x2*)((char*)ho + 2u * eo2) = odd ? hw[0][rh] : rv; }
;             }
;             if (!PLAIN) { sq0 += __shfl_xor(sq0, 1); sq0 += __shfl_xor(sq0, 2); sq0 += __shfl_xor(sq0, 4);
;             sq1 += __shfl_xor(sq1, 1); sq1 += __shfl_xor(sq1, 2); sq1 += __shfl_xor(sq1, 4); }
;             if (!PLAIN && pc == 0) { sst[g * 16 + rr] = sq0; sst[g * 16 + 8 + rr] = sq1; }
.LBB0_380:
	s_or_b64 exec, exec, s[16:17]
	v_add_u32_e32 v154, 0x160000, v207
	v_add_u32_e32 v68, 0x160080, v207
	v_add_u32_e32 v70, 0x170000, v207
	global_load_dwordx4 v[46:49], v154, s[58:59]
	global_load_dwordx4 v[42:45], v70, s[58:59]
	v_add_u32_e32 v66, 0x170080, v207
	global_load_dwordx4 v[38:41], v68, s[58:59]
	s_waitcnt lgkmcnt(0)
	global_load_dwordx4 v[34:37], v66, s[58:59]
	ds_write_b128 v200, v[30:33]
	ds_write_b128 v200, v[26:29] offset:64
	ds_read_b128 v[26:29], v201
	ds_read_b128 v[30:33], v201 offset:1152
	v_mov_b32_e32 v89, v155
	v_mov_b32_e32 v87, v155
	v_mov_b32_e32 v85, v155
	s_waitcnt vmcnt(13) lgkmcnt(1)
	v_pk_fma_f32 v[28:29], v[178:179], v[28:29], v[64:65]
	v_pk_fma_f32 v[26:27], v[180:181], v[26:27], v[62:63]
	v_lshl_add_u64 v[62:63], s[56:57], 0, v[88:89]
	global_store_dwordx4 v[62:63], v[26:29], off nt
	v_pk_mul_f32 v[62:63], v[176:177], v[26:27]
	s_waitcnt vmcnt(13) lgkmcnt(0)
	v_pk_fma_f32 v[32:33], v[178:179], v[32:33], v[60:61]
	v_pk_fma_f32 v[30:31], v[180:181], v[30:31], v[58:59]
	v_lshl_add_u64 v[58:59], s[56:57], 0, v[86:87]
	v_pk_mul_f32 v[64:65], v[174:175], v[28:29]
	v_cvt_pk_bf16_f32 v62, v62, v63
	v_pk_mul_f32 v[60:61], v[174:175], v[32:33]
	v_cvt_pk_bf16_f32 v63, v64, v65
	global_store_dwordx4 v[58:59], v[30:33], off nt
	v_pk_mul_f32 v[58:59], v[176:177], v[30:31]
	v_mov_b32_e32 v83, v155
	v_cvt_pk_bf16_f32 v58, v58, v59
	v_cvt_pk_bf16_f32 v59, v60, v61
	ds_write_b128 v200, v[22:25]
	ds_write_b128 v200, v[18:21] offset:64
	ds_read_b128 v[18:21], v201
	ds_read_b128 v[22:25], v201 offset:1152
	s_waitcnt vmcnt(13) lgkmcnt(1)
	v_pk_fma_f32 v[18:19], v[168:169], v[18:19], v[54:55]
	v_pk_fma_f32 v[20:21], v[166:167], v[20:21], v[56:57]
	v_lshl_add_u64 v[54:55], s[56:57], 0, v[84:85]
	v_pk_mul_f32 v[56:57], v[172:173], v[18:19]
	s_waitcnt vmcnt(12) lgkmcnt(0)
	v_pk_fma_f32 v[24:25], v[166:167], v[24:25], v[52:53]
	v_pk_fma_f32 v[22:23], v[168:169], v[22:23], v[50:51]
	v_lshl_add_u64 v[50:51], s[56:57], 0, v[82:83]
	global_store_dwordx4 v[54:55], v[18:21], off nt
	v_pk_mul_f32 v[54:55], v[170:171], v[20:21]
	v_cvt_pk_bf16_f32 v56, v56, v57
	v_pk_mul_f32 v[52:53], v[172:173], v[22:23]
	v_cvt_pk_bf16_f32 v57, v54, v55
	global_store_dwordx4 v[50:51], v[22:25], off nt
	ds_bpermute_b32 v50, v203, v56
	ds_bpermute_b32 v51, v203, v57
	v_pk_mul_f32 v[54:55], v[170:171], v[24:25]
	v_cvt_pk_bf16_f32 v52, v52, v53
	s_nop 0
	v_cvt_pk_bf16_f32 v53, v54, v55
	v_add_u32_e32 v55, 0x50000, v202
	v_lshlrev_b32_e32 v54, 1, v55
	s_waitcnt lgkmcnt(0)
	v_add_u32_e32 v250, 0xfffff040, v54
	v_cndmask_b32_e64 v250, v54, v250, s[40:41]
	v_cndmask_b32_e64 v248, v62, v50, s[40:41]
	v_cndmask_b32_e64 v249, v63, v51, s[40:41]
	global_store_dwordx2 v250, v[248:249], s[54:55]
	v_cndmask_b32_e64 v246, v50, v62, s[40:41]
	v_cndmask_b32_e64 v247, v51, v63, s[40:41]
	s_waitcnt lgkmcnt(1)
	v_add_u32_e32 v50, 0x1040, v54
	v_cndmask_b32_e64 v50, v54, v50, s[38:39]
	global_store_dwordx2 v50, v[246:247], s[54:55]
	ds_bpermute_b32 v50, v203, v52
	s_waitcnt lgkmcnt(1)
	ds_bpermute_b32 v51, v203, v53
	v_add_u32_e32 v53, 0x54000, v202
	v_lshlrev_b32_e32 v52, 1, v53
	s_waitcnt lgkmcnt(0)
	v_add_u32_e32 v250, 0xfffff040, v52
	v_cndmask_b32_e64 v250, v52, v250, s[40:41]
	v_cndmask_b32_e64 v248, v58, v50, s[40:41]
	v_cndmask_b32_e64 v249, v59, v51, s[40:41]
	global_store_dwordx2 v250, v[248:249], s[54:55]
	v_cndmask_b32_e64 v246, v50, v58, s[40:41]
	v_cndmask_b32_e64 v247, v51, v59, s[40:41]
	v_mul_f32_e32 v19, v19, v19
	v_fmac_f32_e32 v19, v18, v18
	v_mul_f32_e32 v18, v21, v21
	v_mul_f32_e32 v29, v29, v29
	v_fmac_f32_e32 v18, v20, v20
	v_mul_f32_e32 v27, v27, v27
	v_fmac_f32_e32 v29, v28, v28
	v_mul_f32_e32 v28, v31, v31
	v_mul_f32_e32 v31, v33, v33
	v_add_f32_e32 v18, v19, v18
	v_mul_f32_e32 v19, v23, v23
	v_mul_f32_e32 v20, v25, v25
	v_fmac_f32_e32 v31, v32, v32
	v_fmac_f32_e32 v19, v22, v22
	v_fmac_f32_e32 v20, v24, v24
	v_fmac_f32_e32 v27, v26, v26
	v_fmac_f32_e32 v28, v30, v30
	v_add_f32_e32 v19, v19, v20
	v_add_f32_e32 v20, v27, v29
	v_add_f32_e32 v21, v28, v31
	v_add_f32_e32 v18, v20, v18
	v_add_f32_e32 v19, v21, v19
	ds_bpermute_b32 v20, v204, v18
	ds_bpermute_b32 v21, v204, v19
	s_waitcnt lgkmcnt(1)
	v_add_f32_e32 v18, v18, v20
	s_waitcnt lgkmcnt(0)
	v_add_f32_e32 v21, v19, v21
	ds_bpermute_b32 v20, v205, v18
	ds_bpermute_b32 v22, v205, v21
	s_waitcnt lgkmcnt(1)
	v_add_f32_e32 v18, v18, v20
	s_waitcnt lgkmcnt(0)
	v_add_f32_e32 v20, v21, v22
	ds_bpermute_b32 v19, v206, v18
	ds_bpermute_b32 v21, v206, v20
	v_add_u32_e32 v22, 0x1040, v52
	v_cndmask_b32_e64 v22, v52, v22, s[38:39]
	global_store_dwordx2 v22, v[246:247], s[54:55]
	s_and_saveexec_b64 s[16:17], s[42:43]
	s_cbranch_execz .LBB0_390
	s_waitcnt lgkmcnt(1)
	v_add_f32_e32 v18, v18, v19
	s_waitcnt lgkmcnt(0)
	v_add_f32_e32 v19, v20, v21
	ds_write2_b32 v194, v18, v19 offset0:96 offset1:104
; #define LAS __attribute__((address_space(3)))
; #define ERN_EOFF(q, m) (eb + (unsigned)((((q) & 1) * HALF + (m) * 16) * DM + ERN_COL((q) >> 1)))
;     __device__ __forceinline__ void operator()(const f32x4 (&acc)[2][2][4][2], const Unit& u, int wr, int wc, int fr, int fq) const {
;     ...
;         for (int g = 0; g < 8; ++g) { const int ai = g >> 2, m = g & 3;
;             if (g + 1 < 8) ERN_LOADX(g + 1);
;             float sq0 = 0.f, sq1 = 0.f; u32x2 hw[2][2];
; #pragma unroll
;             for (int bj = 0; bj < 2; ++bj) {
;                 *(LAS f32x4*)(st + wr_off) = acc[ai][bj][m][0]; *(LAS f32x4*)(st + wr_off + 64) = acc[ai][bj][m][1];
;                 const f32x4 a0 = *(const LAS f32x4*)(st + rd_off), a1 = *(const LAS f32x4*)(st + rd_off + 8 * 144);
;                 { const f32x4 xv = xb[g & 1][bj][0] + gv[bj] * a0; __builtin_nontemporal_store(xv, (f32x4*)((char*)xo + 4u * ERN_EOFF(g, bj, 0)));
;                   sq0 += (xv.x * xv.x + xv.y * xv.y) + (xv.z * xv.z + xv.w * xv.w);
;                   const f32x4 hv = xv * gsn[bj]; hw[bj][0].x = cvt_pk_bf16(hv.x, hv.y); hw[bj][0].y = cvt_pk_bf16(hv.z, hv.w); }
;                 { const f32x4 xv = xb[g & 1][bj][1] + gv[bj] * a1; __builtin_nontemporal_store(xv, (f32x4*)((char*)xo + 4u * ERN_EOFF(g, bj, 1)));
;                   sq1 += (xv.x * xv.x + xv.y * xv.y) + (xv.z * xv.z + xv.w * xv.w);
;                   const f32x4 hv = xv * gsn[bj]; hw[bj][1].x = cvt_pk_bf16(hv.x, hv.y); hw[bj][1].y = cvt_pk_bf16(hv.z, hv.w); }
;             }
;             if (!NOH && !PLAIN) {
; #pragma unroll
;                 for (int rh = 0; rh < 2; ++rh) { u32x2 rv; rv.x = __shfl_xor(hw[1][rh].x, 8); rv.y = __shfl_xor(hw[1][rh].y, 8);
;                     const unsigned e0 = ERN_EOFF(g, 0, rh);
;                     const unsigned ee = odd ? (e0 - DM + 32) : e0, eo2 = odd ? e0 : (e0 + DM + 32);
;                     *(u32x2*)((char*)ho + 2u * ee) = odd ? rv : hw[0][rh];
;                     *(u32x2*)((char*)ho + 2u * eo2) = odd ? hw[0][rh] : rv; }
;             }
;             if (!PLAIN) { sq0 += __shfl_xor(sq0, 1); sq0 += __shfl_xor(sq0, 2); sq0 += __shfl_xor(sq0, 4);
;             sq1 += __shfl_xor(sq1, 1); sq1 += __shfl_xor(sq1, 2); sq1 += __shfl_xor(sq1, 4); }
;             if (!PLAIN && pc == 0) { sst[g * 16 + rr] = sq0; sst[g * 16 + 8 + rr] = sq1; }
.LBB0_390:
	s_or_b64 exec, exec, s[16:17]
	ds_write_b128 v200, v[14:17]
	ds_write_b128 v200, v[10:13] offset:64
	ds_read_b128 v[10:13], v201
	ds_read_b128 v[14:17], v201 offset:1152
	s_waitcnt lgkmcnt(5)
	v_lshl_add_u64 v[18:19], s[56:57], 0, v[154:155]
	v_mov_b32_e32 v71, v155
	v_mov_b32_e32 v69, v155
	s_waitcnt vmcnt(9) lgkmcnt(1)
	v_pk_fma_f32 v[12:13], v[178:179], v[12:13], v[48:49]
	v_pk_fma_f32 v[10:11], v[180:181], v[10:11], v[46:47]
	global_store_dwordx4 v[18:19], v[10:13], off nt
	v_pk_mul_f32 v[18:19], v[174:175], v[12:13]
	v_pk_mul_f32 v[20:21], v[176:177], v[10:11]
	s_waitcnt vmcnt(9) lgkmcnt(0)
	v_pk_fma_f32 v[16:17], v[178:179], v[16:17], v[44:45]
	v_cvt_pk_bf16_f32 v20, v20, v21
	v_cvt_pk_bf16_f32 v21, v18, v19
	v_pk_fma_f32 v[14:15], v[180:181], v[14:15], v[42:43]
	v_lshl_add_u64 v[18:19], s[56:57], 0, v[70:71]
	global_store_dwordx4 v[18:19], v[14:17], off nt
	v_pk_mul_f32 v[18:19], v[176:177], v[14:15]
	v_pk_mul_f32 v[22:23], v[174:175], v[16:17]
	v_cvt_pk_bf16_f32 v18, v18, v19
	v_mov_b32_e32 v67, v155
	v_cvt_pk_bf16_f32 v19, v22, v23
	ds_write_b128 v200, v[6:9]
	ds_write_b128 v200, v[2:5] offset:64
	ds_read_b128 v[2:5], v201
	ds_read_b128 v[6:9], v201 offset:1152
	v_lshl_add_u64 v[22:23], s[56:57], 0, v[68:69]
	s_waitcnt vmcnt(9) lgkmcnt(1)
	v_pk_fma_f32 v[4:5], v[166:167], v[4:5], v[40:41]
	v_pk_fma_f32 v[2:3], v[168:169], v[2:3], v[38:39]
	global_store_dwordx4 v[22:23], v[2:5], off nt
	v_pk_mul_f32 v[22:23], v[170:171], v[4:5]
	v_pk_mul_f32 v[24:25], v[172:173], v[2:3]
	s_waitcnt vmcnt(9) lgkmcnt(0)
	v_pk_fma_f32 v[8:9], v[166:167], v[8:9], v[36:37]
	v_cvt_pk_bf16_f32 v28, v24, v25
	v_cvt_pk_bf16_f32 v29, v22, v23
	v_pk_fma_f32 v[6:7], v[168:169], v[6:7], v[34:35]
	v_lshl_add_u64 v[22:23], s[56:57], 0, v[66:67]
	global_store_dwordx4 v[22:23], v[6:9], off nt
	ds_bpermute_b32 v22, v203, v28
	ds_bpermute_b32 v23, v203, v29
	v_pk_mul_f32 v[26:27], v[170:171], v[8:9]
	v_pk_mul_f32 v[24:25], v[172:173], v[6:7]
	s_nop 0
	v_cvt_pk_bf16_f32 v24, v24, v25
	v_cvt_pk_bf16_f32 v25, v26, v27
	v_add_u32_e32 v27, 0x58000, v202
	v_lshlrev_b32_e32 v26, 1, v27
	s_waitcnt lgkmcnt(0)
	v_add_u32_e32 v250, 0xfffff040, v26
	v_cndmask_b32_e64 v250, v26, v250, s[40:41]
	v_cndmask_b32_e64 v248, v20, v22, s[40:41]
	v_cndmask_b32_e64 v249, v21, v23, s[40:41]
	global_store_dwordx2 v250, v[248:249], s[54:55]
	v_cndmask_b32_e64 v246, v22, v20, s[40:41]
	v_cndmask_b32_e64 v247, v23, v21, s[40:41]
	s_waitcnt lgkmcnt(1)
	v_add_u32_e32 v22, 0x1040, v26
	v_cndmask_b32_e64 v22, v26, v22, s[38:39]
	global_store_dwordx2 v22, v[246:247], s[54:55]
	ds_bpermute_b32 v20, v203, v24
	ds_bpermute_b32 v21, v203, v25
	s_waitcnt lgkmcnt(2)
	v_add_u32_e32 v23, 0x5c000, v202
	v_lshlrev_b32_e32 v22, 1, v23
	s_waitcnt lgkmcnt(0)
	v_add_u32_e32 v250, 0xfffff040, v22
	v_cndmask_b32_e64 v250, v22, v250, s[40:41]
	v_cndmask_b32_e64 v248, v18, v20, s[40:41]
	v_cndmask_b32_e64 v249, v19, v21, s[40:41]
	global_store_dwordx2 v250, v[248:249], s[54:55]
	v_cndmask_b32_e64 v246, v20, v18, s[40:41]
	v_cndmask_b32_e64 v247, v21, v19, s[40:41]
	v_mul_f32_e32 v3, v3, v3
	v_fmac_f32_e32 v3, v2, v2
	v_mul_f32_e32 v2, v5, v5
	v_mul_f32_e32 v13, v13, v13
	v_fmac_f32_e32 v2, v4, v4
	v_mul_f32_e32 v11, v11, v11
	v_fmac_f32_e32 v13, v12, v12
	v_mul_f32_e32 v12, v15, v15
	v_mul_f32_e32 v15, v17, v17
	v_add_f32_e32 v2, v3, v2
	v_mul_f32_e32 v3, v7, v7
	v_mul_f32_e32 v4, v9, v9
	v_fmac_f32_e32 v15, v16, v16
	v_fmac_f32_e32 v3, v6, v6
	v_fmac_f32_e32 v4, v8, v8
	v_fmac_f32_e32 v11, v10, v10
	v_fmac_f32_e32 v12, v14, v14
	v_add_f32_e32 v3, v3, v4
	v_add_f32_e32 v4, v11, v13
	v_add_f32_e32 v5, v12, v15
	v_add_f32_e32 v2, v4, v2
	v_add_f32_e32 v3, v5, v3
	ds_bpermute_b32 v4, v204, v2
	ds_bpermute_b32 v5, v204, v3
	s_waitcnt lgkmcnt(1)
	v_add_f32_e32 v2, v2, v4
	s_waitcnt lgkmcnt(0)
	v_add_f32_e32 v5, v3, v5
	ds_bpermute_b32 v4, v205, v2
	ds_bpermute_b32 v6, v205, v5
	s_waitcnt lgkmcnt(1)
	v_add_f32_e32 v2, v2, v4
	s_waitcnt lgkmcnt(0)
	v_add_f32_e32 v4, v5, v6
	ds_bpermute_b32 v3, v206, v2
	ds_bpermute_b32 v5, v206, v4
	v_add_u32_e32 v6, 0x1040, v22
	v_cndmask_b32_e64 v6, v22, v6, s[38:39]
	global_store_dwordx2 v6, v[246:247], s[54:55]
	s_and_saveexec_b64 s[16:17], s[42:43]
	s_cbranch_execz .LBB0_400
	s_waitcnt lgkmcnt(1)
	v_add_f32_e32 v2, v2, v3
	s_waitcnt lgkmcnt(0)
	v_add_f32_e32 v3, v4, v5
	ds_write2_b32 v194, v2, v3 offset0:112 offset1:120

; #define LAS __attribute__((address_space(3)))
;     __device__ __forceinline__ void operator()(const f32x4 (&acc)[2][2][4][2], const Unit& u, int wr, int wc, int fr, int fq) const {
;         const int s = u.pm >> 5, lane = fq * 16 + fr, rr = lane >> 3, pc = lane & 7;
;         const float* __restrict__ xi = xin + (size_t)u.pm * BM * DM; float* __restrict__ xo = xout + (size_t)u.pm * BM * DM; bf16_t* __restrict__ ho = Hn + (size_t)u.pm * BM * DM;
;         LAS unsigned char* st = lds_epi + (wr * 4 + wc) * 2304;
;         LAS float* sst = (LAS float*)(lds_epi + 18432 + (wr * 4 + wc) * 512);
;         const int colr = u.pn * BM + wc * 64 + 4 * pc;
;         const unsigned eb = (unsigned)((wr * 64 + rr) * DM + colr);
;         f32x4 gv[2], gsn[2];
; #pragma unroll
;         for (int bj = 0; bj < 2; ++bj) { gv[bj] = *(const f32x4*)(gate + (size_t)s * MODW + colr + bj * 32) * (0.5f * GS2);
;             if (!PLAIN) gsn[bj] = *(const f32x4*)(gnext + colr + bj * 32) * (*(const f32x4*)(scnext + (size_t)s * MODW + colr + bj * 32) + 1.0f); else gsn[bj] = gv[bj]; }
;         const unsigned wr_off = (unsigned)(fr * 144 + 16 * fq), rd_off = (unsigned)(rr * 144 + pc * 16);
;         const bool odd = (rr & 1) != 0;
;         f32x4 xb[2][2][2];
;     ...
;         ERN_LOADX(0);
; #pragma unroll
;         for (int g = 0; g < 8; ++g) { const int ai = g >> 2, m = g & 3;
;             if (g + 1 < 8) ERN_LOADX(g + 1);
;             float sq0 = 0.f, sq1 = 0.f; u32x2 hw[2][2];
; #pragma unroll
;             for (int bj = 0; bj < 2; ++bj) {
;                 *(LAS f32x4*)(st + wr_off) = acc[ai][bj][m][0]; *(LAS f32x4*)(st + wr_off + 64) = acc[ai][bj][m][1];
;                 const f32x4 a0 = *(const LAS f32x4*)(st + rd_off), a1 = *(const LAS f32x4*)(st + rd_off + 8 * 144);
;                 { const f32x4 xv = xb[g & 1][bj][0] + gv[bj] * a0; __builtin_nontemporal_store(xv, (f32x4*)((char*)xo + 4u * ERN_EOFF(g, bj, 0)));
;                   sq0 += (xv.x * xv.x + xv.y * xv.y) + (xv.z * xv.z + xv.w * xv.w);
;                   const f32x4 hv = xv * gsn[bj]; hw[bj][0].x = cvt_pk_bf16(hv.x, hv.y); hw[bj][0].y = cvt_pk_bf16(hv.z, hv.w); }
;                 { const f32x4 xv = xb[g & 1][bj][1] + gv[bj] * a1; __builtin_nontemporal_store(xv, (f32x4*)((char*)xo + 4u * ERN_EOFF(g, bj, 1)));
;                   sq1 += (xv.x * xv.x + xv.y * xv.y) + (xv.z * xv.z + xv.w * xv.w);
.LBB0_1253:
	s_ashr_i32 s0, s92, 5
	s_ashr_i32 s93, s92, 31
	v_lshl_or_b32 v50, s46, 8, v192
	s_mul_hi_i32 s15, s0, 0x12000
	s_mul_i32 s0, s0, 0x12000
	s_add_u32 s16, s35, s0
	v_ashrrev_i32_e32 v51, 31, v50
	s_addc_u32 s17, s36, s15
	v_lshlrev_b64 v[52:53], 2, v[50:51]
	v_lshl_add_u64 v[138:139], s[16:17], 0, v[52:53]
	s_add_u32 s16, s37, s0
	s_addc_u32 s17, s52, s15
	v_lshl_add_u64 v[140:141], s[8:9], 0, v[52:53]
	v_lshl_add_u64 v[52:53], s[16:17], 0, v[52:53]
	s_lshl_b64 s[16:17], s[92:93], 21
	s_add_u32 s48, s90, s16
	v_add_u32_e32 v202, v50, v193
	s_addc_u32 s49, s91, s17
	v_lshlrev_b32_e32 v205, 2, v202
	global_load_dwordx4 v[54:57], v[138:139], off
	global_load_dwordx4 v[174:177], v[140:141], off
	global_load_dwordx4 v[178:181], v[52:53], off
	global_load_dwordx4 v[206:209], v[52:53], off offset:128
	global_load_dwordx4 v[186:189], v205, s[48:49]
	v_add_u32_e32 v50, 0x10000, v205
	global_load_dwordx4 v[210:213], v50, s[48:49]
	global_load_dwordx4 v[214:217], v[140:141], off offset:128
	s_nop 0
	global_load_dwordx4 v[50:53], v[138:139], off offset:128
	global_load_dwordx4 v[218:221], v205, s[48:49] offset:128
	v_add_u32_e32 v204, 0x10080, v205
	global_load_dwordx4 v[222:225], v204, s[48:49]
	v_add_u32_e32 v138, 0x20000, v205
	v_add_u32_e32 v162, 0x30000, v205
	v_add_u32_e32 v184, 0x20080, v205
	v_add_u32_e32 v182, 0x30080, v205
	global_load_dwordx4 v[150:153], v138, s[48:49]
	global_load_dwordx4 v[146:149], v162, s[48:49]
	global_load_dwordx4 v[142:145], v184, s[48:49]
	s_nop 0
	global_load_dwordx4 v[138:141], v182, s[48:49]
	ds_write_b128 v200, v[134:137]
	ds_write_b128 v200, v[130:133] offset:64
	v_and_b32_e32 v135, 64, v199
	ds_read_b128 v[130:133], v201
	ds_read_b128 v[226:229], v201 offset:1152
	v_xor_b32_e32 v134, 8, v199
	v_add_u32_e32 v183, 64, v135
	v_cmp_lt_i32_e32 vcc, v134, v183
	v_add_u32_e32 v185, 0x4000, v202
	v_lshlrev_b32_e32 v230, 2, v185
	v_cndmask_b32_e32 v134, v199, v134, vcc
	v_lshlrev_b32_e32 v203, 2, v134
	s_lshl_b64 s[16:17], s[92:93], 20
	v_readlane_b32 s0, v252, 41
	s_add_u32 s46, s0, s16
	v_readlane_b32 s0, v252, 42
	s_addc_u32 s47, s0, s17
	s_waitcnt vmcnt(0)
	v_pk_add_f32 v[134:135], v[180:181], 1.0 op_sel_hi:[1,0]
	v_pk_add_f32 v[136:137], v[178:179], 1.0 op_sel_hi:[1,0]
	v_pk_mul_f32 v[178:179], v[176:177], v[134:135]
	v_pk_mul_f32 v[180:181], v[174:175], v[136:137]
	s_waitcnt lgkmcnt(1)
	v_pk_fma_f32 v[134:135], v[54:55], v[130:131], v[186:187]
	s_waitcnt lgkmcnt(0)
	v_pk_fma_f32 v[130:131], v[54:55], v[226:227], v[210:211]
	v_pk_fma_f32 v[136:137], v[56:57], v[132:133], v[188:189]
	v_pk_fma_f32 v[132:133], v[56:57], v[228:229], v[212:213]
	v_pk_mul_f32 v[186:187], v[180:181], v[130:131]
	v_pk_add_f32 v[190:191], v[208:209], 1.0 op_sel_hi:[1,0]
	global_store_dwordx4 v205, v[134:137], s[48:49] nt
	v_pk_mul_f32 v[174:175], v[178:179], v[136:137]
	v_pk_mul_f32 v[176:177], v[180:181], v[134:135]
	v_pk_mul_f32 v[208:209], v[178:179], v[132:133]
	v_cvt_pk_bf16_f32 v188, v176, v177
	v_cvt_pk_bf16_f32 v189, v174, v175
	global_store_dwordx4 v230, v[130:133], s[48:49] nt
	v_cvt_pk_bf16_f32 v186, v186, v187
	v_cvt_pk_bf16_f32 v187, v208, v209
	ds_write_b128 v200, v[126:129]
	ds_write_b128 v200, v[122:125] offset:64
	ds_read_b128 v[122:125], v201
	v_pk_add_f32 v[126:127], v[206:207], 1.0 op_sel_hi:[1,0]
	ds_read_b128 v[206:209], v201 offset:1152
	v_pk_mul_f32 v[174:175], v[216:217], v[190:191]
	v_pk_mul_f32 v[176:177], v[214:215], v[126:127]
	s_waitcnt lgkmcnt(1)
	v_pk_fma_f32 v[128:129], v[52:53], v[124:125], v[220:221]
	v_pk_fma_f32 v[126:127], v[50:51], v[122:123], v[218:219]
	s_waitcnt lgkmcnt(0)
	v_pk_fma_f32 v[122:123], v[50:51], v[206:207], v[222:223]
	v_pk_mul_f32 v[190:191], v[174:175], v[128:129]
	v_pk_mul_f32 v[206:207], v[176:177], v[126:127]
	global_store_dwordx4 v205, v[126:129], s[48:49] offset:128 nt
	v_cvt_pk_bf16_f32 v206, v206, v207
	v_cvt_pk_bf16_f32 v191, v190, v191
	ds_bpermute_b32 v190, v203, v206
	ds_bpermute_b32 v191, v203, v191
	v_pk_fma_f32 v[124:125], v[52:53], v[208:209], v[224:225]
	v_pk_mul_f32 v[206:207], v[176:177], v[122:123]
	global_store_dwordx4 v204, v[122:125], s[48:49] nt
	v_cvt_pk_bf16_f32 v204, v206, v207
	v_lshlrev_b32_e32 v207, 1, v202
	v_pk_mul_f32 v[208:209], v[174:175], v[124:125]
	s_nop 0
	v_cvt_pk_bf16_f32 v206, v208, v209
	s_waitcnt lgkmcnt(0)
	v_add_u32_e32 v250, 0xfffff040, v207
	v_cndmask_b32_e64 v250, v207, v250, s[40:41]
	v_cndmask_b32_e64 v248, v188, v190, s[40:41]
	v_cndmask_b32_e64 v249, v189, v191, s[40:41]
	global_store_dwordx2 v250, v[248:249], s[46:47]
	v_cndmask_b32_e64 v246, v190, v188, s[40:41]
	v_cndmask_b32_e64 v247, v191, v189, s[40:41]
	s_waitcnt lgkmcnt(1)
	v_add_u32_e32 v190, 0x1040, v207
	v_cndmask_b32_e64 v190, v207, v190, s[38:39]
	global_store_dwordx2 v190, v[246:247], s[46:47]
	ds_bpermute_b32 v188, v203, v204
	ds_bpermute_b32 v189, v203, v206
	v_lshlrev_b32_e32 v206, 1, v185
	s_and_saveexec_b64 s[16:17], s[40:41]
	v_readlane_b32 s60, v252, 4
	v_readlane_b32 s58, v252, 10
	s_xor_b64 s[16:17], exec, s[16:17]
	v_readlane_b32 s61, v252, 5
	v_readlane_b32 s59, v252, 11
	s_cbranch_execz .LBB0_1259
	v_lshlrev_b32_e32 v206, 1, v185
	v_add_u32_e32 v185, 0xfffff040, v206
	s_waitcnt lgkmcnt(0)
	global_store_dwordx2 v185, v[188:189], s[46:47]

; #define LAS __attribute__((address_space(3)))
; #define ERN_EOFF(q, m) (eb + (unsigned)((((q) & 1) * HALF + (m) * 16) * DM + ERN_COL((q) >> 1)))
;     __device__ __forceinline__ void operator()(const f32x4 (&acc)[2][2][4][2], const Unit& u, int wr, int wc, int fr, int fq) const {
;     ...
;         ERN_LOADX(0);
; #pragma unroll
;         for (int g = 0; g < 8; ++g) { const int ai = g >> 2, m = g & 3;
;             if (g + 1 < 8) ERN_LOADX(g + 1);
;             float sq0 = 0.f, sq1 = 0.f; u32x2 hw[2][2];
; #pragma unroll
;             for (int bj = 0; bj < 2; ++bj) {
;                 *(LAS f32x4*)(st + wr_off) = acc[ai][bj][m][0]; *(LAS f32x4*)(st + wr_off + 64) = acc[ai][bj][m][1];
;                 const f32x4 a0 = *(const LAS f32x4*)(st + rd_off), a1 = *(const LAS f32x4*)(st + rd_off + 8 * 144);
;                 { const f32x4 xv = xb[g & 1][bj][0] + gv[bj] * a0; __builtin_nontemporal_store(xv, (f32x4*)((char*)xo + 4u * ERN_EOFF(g, bj, 0)));
;                   sq0 += (xv.x * xv.x + xv.y * xv.y) + (xv.z * xv.z + xv.w * xv.w);
;                   const f32x4 hv = xv * gsn[bj]; hw[bj][0].x = cvt_pk_bf16(hv.x, hv.y); hw[bj][0].y = cvt_pk_bf16(hv.z, hv.w); }
;                 { const f32x4 xv = xb[g & 1][bj][1] + gv[bj] * a1; __builtin_nontemporal_store(xv, (f32x4*)((char*)xo + 4u * ERN_EOFF(g, bj, 1)));
;                   sq1 += (xv.x * xv.x + xv.y * xv.y) + (xv.z * xv.z + xv.w * xv.w);
;                   const f32x4 hv = xv * gsn[bj]; hw[bj][1].x = cvt_pk_bf16(hv.x, hv.y); hw[bj][1].y = cvt_pk_bf16(hv.z, hv.w); }
;             }
;             if (!NOH && !PLAIN) {
; #pragma unroll
;                 for (int rh = 0; rh < 2; ++rh) { u32x2 rv; rv.x = __shfl_xor(hw[1][rh].x, 8); rv.y = __shfl_xor(hw[1][rh].y, 8);
;                     const unsigned e0 = ERN_EOFF(g, 0, rh);
;                     const unsigned ee = odd ? (e0 - DM + 32) : e0, eo2 = odd ? e0 : (e0 + DM + 32);
;                     *(u32x2*)((char*)ho + 2u * ee) = odd ? rv : hw[0][rh];
;                     *(u32x2*)((char*)ho + 2u * eo2) = odd ? hw[0][rh] : rv; }
;             }
;             if (!PLAIN) { sq0 += __shfl_xor(sq0, 1); sq0 += __shfl_xor(sq0, 2); sq0 += __shfl_xor(sq0, 4);
;             sq1 += __shfl_xor(sq1, 1); sq1 += __shfl_xor(sq1, 2); sq1 += __shfl_xor(sq1, 4); }
;             if (!PLAIN && pc == 0) { sst[g * 16 + rr] = sq0; sst[g * 16 + 8 + rr] = sq1; }
.LBB0_1263:
	s_or_b64 exec, exec, s[16:17]
	v_lshl_add_u64 v[206:207], s[48:49], 0, v[162:163]
	v_add_u32_e32 v122, 0x40000, v205
	v_add_u32_e32 v162, 0x50000, v205
	v_add_u32_e32 v186, 0x40080, v205
	global_load_dwordx4 v[130:133], v162, s[48:49]
	global_load_dwordx4 v[126:129], v186, s[48:49]
	v_add_u32_e32 v188, 0x50080, v205
	global_load_dwordx4 v[134:137], v122, s[48:49]
	s_waitcnt lgkmcnt(0)
	global_load_dwordx4 v[122:125], v188, s[48:49]
	ds_write_b128 v200, v[118:121]
	ds_write_b128 v200, v[114:117] offset:64
	ds_read_b128 v[114:117], v201
	ds_read_b128 v[118:121], v201 offset:1152
	v_mov_b32_e32 v185, v163
	v_mov_b32_e32 v183, v163
	v_lshl_add_u64 v[182:183], s[48:49], 0, v[182:183]
	s_waitcnt lgkmcnt(1)
	v_pk_fma_f32 v[116:117], v[56:57], v[116:117], v[152:153]
	v_add_u32_e32 v152, 0x8000, v202
	v_pk_fma_f32 v[114:115], v[54:55], v[114:115], v[150:151]
	v_lshlrev_b32_e32 v150, 2, v152
	s_waitcnt lgkmcnt(0)
	v_pk_fma_f32 v[118:119], v[54:55], v[118:119], v[146:147]
	global_store_dwordx4 v150, v[114:117], s[48:49] nt
	v_pk_mul_f32 v[150:151], v[180:181], v[114:115]
	v_pk_fma_f32 v[120:121], v[56:57], v[120:121], v[148:149]
	v_pk_mul_f32 v[146:147], v[180:181], v[118:119]
	v_pk_mul_f32 v[208:209], v[178:179], v[116:117]
	v_cvt_pk_bf16_f32 v150, v150, v151
	v_pk_mul_f32 v[148:149], v[178:179], v[120:121]
	v_cvt_pk_bf16_f32 v151, v208, v209
	global_store_dwordx4 v[206:207], v[118:121], off nt
	v_cvt_pk_bf16_f32 v146, v146, v147
	v_cvt_pk_bf16_f32 v147, v148, v149
	ds_write_b128 v200, v[110:113]
	ds_write_b128 v200, v[106:109] offset:64
	ds_read_b128 v[106:109], v201
	ds_read_b128 v[110:113], v201 offset:1152
	v_lshl_add_u64 v[148:149], s[48:49], 0, v[184:185]
	s_waitcnt lgkmcnt(1)
	v_pk_fma_f32 v[106:107], v[50:51], v[106:107], v[142:143]
	v_pk_fma_f32 v[108:109], v[52:53], v[108:109], v[144:145]
	v_pk_mul_f32 v[144:145], v[176:177], v[106:107]
	global_store_dwordx4 v[148:149], v[106:109], off nt
	v_pk_mul_f32 v[142:143], v[174:175], v[108:109]
	v_cvt_pk_bf16_f32 v144, v144, v145
	s_waitcnt lgkmcnt(0)
	v_pk_fma_f32 v[110:111], v[50:51], v[110:111], v[138:139]
	v_cvt_pk_bf16_f32 v145, v142, v143
	ds_bpermute_b32 v138, v203, v144
	ds_bpermute_b32 v139, v203, v145
	v_pk_fma_f32 v[112:113], v[52:53], v[112:113], v[140:141]
	v_pk_mul_f32 v[140:141], v[176:177], v[110:111]
	v_pk_mul_f32 v[142:143], v[174:175], v[112:113]
	global_store_dwordx4 v[182:183], v[110:113], off nt
	v_cvt_pk_bf16_f32 v140, v140, v141
	v_cvt_pk_bf16_f32 v141, v142, v143
	v_lshlrev_b32_e32 v142, 1, v152
	s_waitcnt lgkmcnt(0)
	v_add_u32_e32 v250, 0xfffff040, v142
	v_cndmask_b32_e64 v250, v142, v250, s[40:41]
	v_cndmask_b32_e64 v248, v150, v138, s[40:41]
	v_cndmask_b32_e64 v249, v151, v139, s[40:41]
	global_store_dwordx2 v250, v[248:249], s[46:47]
	v_cndmask_b32_e64 v246, v138, v150, s[40:41]
	v_cndmask_b32_e64 v247, v139, v151, s[40:41]
	s_waitcnt lgkmcnt(1)
	v_add_u32_e32 v138, 0x1040, v142
	v_cndmask_b32_e64 v138, v142, v138, s[38:39]
	global_store_dwordx2 v138, v[246:247], s[46:47]
	ds_bpermute_b32 v138, v203, v140
	s_waitcnt lgkmcnt(1)
	ds_bpermute_b32 v139, v203, v141
	v_add_u32_e32 v141, 0xc000, v202
	v_lshlrev_b32_e32 v140, 1, v141
	s_waitcnt lgkmcnt(0)
	v_add_u32_e32 v250, 0xfffff040, v140
	v_cndmask_b32_e64 v250, v140, v250, s[40:41]
	v_cndmask_b32_e64 v248, v146, v138, s[40:41]
	v_cndmask_b32_e64 v249, v147, v139, s[40:41]
	global_store_dwordx2 v250, v[248:249], s[46:47]
	v_cndmask_b32_e64 v246, v138, v146, s[40:41]
	v_cndmask_b32_e64 v247, v139, v147, s[40:41]
	v_mul_f32_e32 v107, v107, v107
	v_fmac_f32_e32 v107, v106, v106
	v_mul_f32_e32 v106, v109, v109
	v_mul_f32_e32 v117, v117, v117
	v_fmac_f32_e32 v106, v108, v108
	v_mul_f32_e32 v115, v115, v115
	v_fmac_f32_e32 v117, v116, v116
	v_mul_f32_e32 v116, v119, v119
	v_mul_f32_e32 v119, v121, v121
	v_add_f32_e32 v106, v107, v106
	v_mul_f32_e32 v107, v111, v111
	v_mul_f32_e32 v108, v113, v113
	v_fmac_f32_e32 v119, v120, v120
	v_fmac_f32_e32 v107, v110, v110
	v_fmac_f32_e32 v108, v112, v112
	v_fmac_f32_e32 v115, v114, v114
	v_fmac_f32_e32 v116, v118, v118
	v_add_f32_e32 v107, v107, v108
	v_add_f32_e32 v108, v115, v117
	v_add_f32_e32 v109, v116, v119
	v_add_f32_e32 v106, v108, v106
	v_add_f32_e32 v107, v109, v107
	ds_bpermute_b32 v108, v190, v106
	ds_bpermute_b32 v109, v190, v107
	s_waitcnt lgkmcnt(1)
	v_add_f32_e32 v106, v106, v108
	s_waitcnt lgkmcnt(0)
	v_add_f32_e32 v109, v107, v109
	ds_bpermute_b32 v108, v191, v106
	ds_bpermute_b32 v110, v191, v109
	s_waitcnt lgkmcnt(1)
	v_add_f32_e32 v106, v106, v108
	s_waitcnt lgkmcnt(0)
	v_add_f32_e32 v108, v109, v110
	ds_bpermute_b32 v107, v204, v106
	ds_bpermute_b32 v109, v204, v108
	v_add_u32_e32 v110, 0x1040, v140
	v_cndmask_b32_e64 v110, v140, v110, s[38:39]
	global_store_dwordx2 v110, v[246:247], s[46:47]
	s_and_saveexec_b64 s[16:17], s[42:43]
	s_cbranch_execz .LBB0_1273
	s_waitcnt lgkmcnt(1)
	v_add_f32_e32 v106, v106, v107
	s_waitcnt lgkmcnt(0)
	v_add_f32_e32 v107, v108, v109
	ds_write2_b32 v194, v106, v107 offset0:16 offset1:24
; #define LAS __attribute__((address_space(3)))
; #define ERN_EOFF(q, m) (eb + (unsigned)((((q) & 1) * HALF + (m) * 16) * DM + ERN_COL((q) >> 1)))
;     __device__ __forceinline__ void operator()(const f32x4 (&acc)[2][2][4][2], const Unit& u, int wr, int wc, int fr, int fq) const {
;     ...
;         ERN_LOADX(0);
; #pragma unroll
;         for (int g = 0; g < 8; ++g) { const int ai = g >> 2, m = g & 3;
;             if (g + 1 < 8) ERN_LOADX(g + 1);
;             float sq0 = 0.f, sq1 = 0.f; u32x2 hw[2][2];
; #pragma unroll
;             for (int bj = 0; bj < 2; ++bj) {
;                 *(LAS f32x4*)(st + wr_off) = acc[ai][bj][m][0]; *(LAS f32x4*)(st + wr_off + 64) = acc[ai][bj][m][1];
;                 const f32x4 a0 = *(const LAS f32x4*)(st + rd_off), a1 = *(const LAS f32x4*)(st + rd_off + 8 * 144);
;                 { const f32x4 xv = xb[g & 1][bj][0] + gv[bj] * a0; __builtin_nontemporal_store(xv, (f32x4*)((char*)xo + 4u * ERN_EOFF(g, bj, 0)));
;                   sq0 += (xv.x * xv.x + xv.y * xv.y) + (xv.z * xv.z + xv.w * xv.w);
;                   const f32x4 hv = xv * gsn[bj]; hw[bj][0].x = cvt_pk_bf16(hv.x, hv.y); hw[bj][0].y = cvt_pk_bf16(hv.z, hv.w); }
;                 { const f32x4 xv = xb[g & 1][bj][1] + gv[bj] * a1; __builtin_nontemporal_store(xv, (f32x4*)((char*)xo + 4u * ERN_EOFF(g, bj, 1)));
;                   sq1 += (xv.x * xv.x + xv.y * xv.y) + (xv.z * xv.z + xv.w * xv.w);
;                   const f32x4 hv = xv * gsn[bj]; hw[bj][1].x = cvt_pk_bf16(hv.x, hv.y); hw[bj][1].y = cvt_pk_bf16(hv.z, hv.w); }
;             }
;             if (!NOH && !PLAIN) {
; #pragma unroll
;                 for (int rh = 0; rh < 2; ++rh) { u32x2 rv; rv.x = __shfl_xor(hw[1][rh].x, 8); rv.y = __shfl_xor(hw[1][rh].y, 8);
;                     const unsigned e0 = ERN_EOFF(g, 0, rh);
;                     const unsigned ee = odd ? (e0 - DM + 32) : e0, eo2 = odd ? e0 : (e0 + DM + 32);
;                     *(u32x2*)((char*)ho + 2u * ee) = odd ? rv : hw[0][rh];
;                     *(u32x2*)((char*)ho + 2u * eo2) = odd ? hw[0][rh] : rv; }
;             }
;             if (!PLAIN) { sq0 += __shfl_xor(sq0, 1); sq0 += __shfl_xor(sq0, 2); sq0 += __shfl_xor(sq0, 4);
;             sq1 += __shfl_xor(sq1, 1); sq1 += __shfl_xor(sq1, 2); sq1 += __shfl_xor(sq1, 4); }
;             if (!PLAIN && pc == 0) { sst[g * 16 + rr] = sq0; sst[g * 16 + 8 + rr] = sq1; }
.LBB0_1273:
	s_or_b64 exec, exec, s[16:17]
	v_lshl_add_u64 v[142:143], s[48:49], 0, v[162:163]
	v_add_u32_e32 v106, 0x60000, v205
	v_add_u32_e32 v162, 0x70000, v205
	v_add_u32_e32 v138, 0x60080, v205
	global_load_dwordx4 v[114:117], v162, s[48:49]
	global_load_dwordx4 v[110:113], v138, s[48:49]
	v_add_u32_e32 v140, 0x70080, v205
	global_load_dwordx4 v[118:121], v106, s[48:49]
	s_waitcnt lgkmcnt(0)
	global_load_dwordx4 v[106:109], v140, s[48:49]
	ds_write_b128 v200, v[102:105]
	ds_write_b128 v200, v[98:101] offset:64
	ds_read_b128 v[98:101], v201
	ds_read_b128 v[102:105], v201 offset:1152
	v_mov_b32_e32 v187, v163
	v_mov_b32_e32 v189, v163
	s_waitcnt vmcnt(11) lgkmcnt(1)
	v_pk_fma_f32 v[100:101], v[56:57], v[100:101], v[136:137]
	v_add_u32_e32 v136, 0x10000, v202
	v_pk_fma_f32 v[98:99], v[54:55], v[98:99], v[134:135]
	v_lshlrev_b32_e32 v134, 2, v136
	s_waitcnt lgkmcnt(0)
	v_pk_fma_f32 v[102:103], v[54:55], v[102:103], v[130:131]
	global_store_dwordx4 v134, v[98:101], s[48:49] nt
	v_pk_mul_f32 v[134:135], v[180:181], v[98:99]
	v_pk_fma_f32 v[104:105], v[56:57], v[104:105], v[132:133]
	v_pk_mul_f32 v[130:131], v[180:181], v[102:103]
	v_pk_mul_f32 v[144:145], v[178:179], v[100:101]
	v_cvt_pk_bf16_f32 v134, v134, v135
	v_pk_mul_f32 v[132:133], v[178:179], v[104:105]
	v_cvt_pk_bf16_f32 v135, v144, v145
	global_store_dwordx4 v[142:143], v[102:105], off nt
	v_cvt_pk_bf16_f32 v130, v130, v131
	v_cvt_pk_bf16_f32 v131, v132, v133
	ds_write_b128 v200, v[94:97]
	ds_write_b128 v200, v[90:93] offset:64
	ds_read_b128 v[90:93], v201
	ds_read_b128 v[94:97], v201 offset:1152
	v_lshl_add_u64 v[132:133], s[48:49], 0, v[186:187]
	v_lshl_add_u64 v[142:143], s[48:49], 0, v[188:189]
	s_waitcnt lgkmcnt(1)
	v_pk_fma_f32 v[90:91], v[50:51], v[90:91], v[126:127]
	v_pk_fma_f32 v[92:93], v[52:53], v[92:93], v[128:129]
	v_pk_mul_f32 v[128:129], v[176:177], v[90:91]
	global_store_dwordx4 v[132:133], v[90:93], off nt
	v_pk_mul_f32 v[126:127], v[174:175], v[92:93]
	v_cvt_pk_bf16_f32 v128, v128, v129
	s_waitcnt vmcnt(13) lgkmcnt(0)
	v_pk_fma_f32 v[94:95], v[50:51], v[94:95], v[122:123]
	v_cvt_pk_bf16_f32 v129, v126, v127
	ds_bpermute_b32 v122, v203, v128
	ds_bpermute_b32 v123, v203, v129
	v_pk_fma_f32 v[96:97], v[52:53], v[96:97], v[124:125]
	v_pk_mul_f32 v[124:125], v[176:177], v[94:95]
	v_pk_mul_f32 v[126:127], v[174:175], v[96:97]
	global_store_dwordx4 v[142:143], v[94:97], off nt
	v_cvt_pk_bf16_f32 v124, v124, v125
	v_cvt_pk_bf16_f32 v125, v126, v127
	v_lshlrev_b32_e32 v126, 1, v136
	s_waitcnt lgkmcnt(0)
	v_add_u32_e32 v250, 0xfffff040, v126
	v_cndmask_b32_e64 v250, v126, v250, s[40:41]
	v_cndmask_b32_e64 v248, v134, v122, s[40:41]
	v_cndmask_b32_e64 v249, v135, v123, s[40:41]
	global_store_dwordx2 v250, v[248:249], s[46:47]
	v_cndmask_b32_e64 v246, v122, v134, s[40:41]
	v_cndmask_b32_e64 v247, v123, v135, s[40:41]
	s_waitcnt lgkmcnt(1)
	v_add_u32_e32 v122, 0x1040, v126
	v_cndmask_b32_e64 v122, v126, v122, s[38:39]
	global_store_dwordx2 v122, v[246:247], s[46:47]
	ds_bpermute_b32 v122, v203, v124
	s_waitcnt lgkmcnt(1)
	ds_bpermute_b32 v123, v203, v125
	v_add_u32_e32 v125, 0x14000, v202
	v_lshlrev_b32_e32 v124, 1, v125
	s_waitcnt lgkmcnt(0)
	v_add_u32_e32 v250, 0xfffff040, v124
	v_cndmask_b32_e64 v250, v124, v250, s[40:41]
	v_cndmask_b32_e64 v248, v130, v122, s[40:41]
	v_cndmask_b32_e64 v249, v131, v123, s[40:41]
	global_store_dwordx2 v250, v[248:249], s[46:47]
	v_cndmask_b32_e64 v246, v122, v130, s[40:41]
	v_cndmask_b32_e64 v247, v123, v131, s[40:41]
	v_mul_f32_e32 v91, v91, v91
	v_fmac_f32_e32 v91, v90, v90
	v_mul_f32_e32 v90, v93, v93
	v_mul_f32_e32 v101, v101, v101
	v_fmac_f32_e32 v90, v92, v92
	v_mul_f32_e32 v99, v99, v99
	v_fmac_f32_e32 v101, v100, v100
	v_mul_f32_e32 v100, v103, v103
	v_mul_f32_e32 v103, v105, v105
	v_add_f32_e32 v90, v91, v90
	v_mul_f32_e32 v91, v95, v95
	v_mul_f32_e32 v92, v97, v97
	v_fmac_f32_e32 v103, v104, v104
	v_fmac_f32_e32 v91, v94, v94
	v_fmac_f32_e32 v92, v96, v96
	v_fmac_f32_e32 v99, v98, v98
	v_fmac_f32_e32 v100, v102, v102
	v_add_f32_e32 v91, v91, v92
	v_add_f32_e32 v92, v99, v101
	v_add_f32_e32 v93, v100, v103
	v_add_f32_e32 v90, v92, v90
	v_add_f32_e32 v91, v93, v91
	ds_bpermute_b32 v92, v190, v90
	ds_bpermute_b32 v93, v190, v91
	s_waitcnt lgkmcnt(1)
	v_add_f32_e32 v90, v90, v92
	s_waitcnt lgkmcnt(0)
	v_add_f32_e32 v93, v91, v93
	ds_bpermute_b32 v92, v191, v90
	ds_bpermute_b32 v94, v191, v93
	s_waitcnt lgkmcnt(1)
	v_add_f32_e32 v90, v90, v92
	s_waitcnt lgkmcnt(0)
	v_add_f32_e32 v92, v93, v94
	ds_bpermute_b32 v91, v204, v90
	ds_bpermute_b32 v93, v204, v92
	v_add_u32_e32 v94, 0x1040, v124
	v_cndmask_b32_e64 v94, v124, v94, s[38:39]
	global_store_dwordx2 v94, v[246:247], s[46:47]
	s_and_saveexec_b64 s[16:17], s[42:43]
	s_cbranch_execz .LBB0_1283
	s_waitcnt lgkmcnt(1)
	v_add_f32_e32 v90, v90, v91
	s_waitcnt lgkmcnt(0)
	v_add_f32_e32 v91, v92, v93
	ds_write2_b32 v194, v90, v91 offset0:32 offset1:40
; #define LAS __attribute__((address_space(3)))
; #define ERN_EOFF(q, m) (eb + (unsigned)((((q) & 1) * HALF + (m) * 16) * DM + ERN_COL((q) >> 1)))
;     __device__ __forceinline__ void operator()(const f32x4 (&acc)[2][2][4][2], const Unit& u, int wr, int wc, int fr, int fq) const {
;     ...
;         ERN_LOADX(0);
; #pragma unroll
;         for (int g = 0; g < 8; ++g) { const int ai = g >> 2, m = g & 3;
;             if (g + 1 < 8) ERN_LOADX(g + 1);
;             float sq0 = 0.f, sq1 = 0.f; u32x2 hw[2][2];
; #pragma unroll
;             for (int bj = 0; bj < 2; ++bj) {
;                 *(LAS f32x4*)(st + wr_off) = acc[ai][bj][m][0]; *(LAS f32x4*)(st + wr_off + 64) = acc[ai][bj][m][1];
;                 const f32x4 a0 = *(const LAS f32x4*)(st + rd_off), a1 = *(const LAS f32x4*)(st + rd_off + 8 * 144);
;                 { const f32x4 xv = xb[g & 1][bj][0] + gv[bj] * a0; __builtin_nontemporal_store(xv, (f32x4*)((char*)xo + 4u * ERN_EOFF(g, bj, 0)));
;                   sq0 += (xv.x * xv.x + xv.y * xv.y) + (xv.z * xv.z + xv.w * xv.w);
;                   const f32x4 hv = xv * gsn[bj]; hw[bj][0].x = cvt_pk_bf16(hv.x, hv.y); hw[bj][0].y = cvt_pk_bf16(hv.z, hv.w); }
;                 { const f32x4 xv = xb[g & 1][bj][1] + gv[bj] * a1; __builtin_nontemporal_store(xv, (f32x4*)((char*)xo + 4u * ERN_EOFF(g, bj, 1)));
;                   sq1 += (xv.x * xv.x + xv.y * xv.y) + (xv.z * xv.z + xv.w * xv.w);
;                   const f32x4 hv = xv * gsn[bj]; hw[bj][1].x = cvt_pk_bf16(hv.x, hv.y); hw[bj][1].y = cvt_pk_bf16(hv.z, hv.w); }
;             }
;             if (!NOH && !PLAIN) {
; #pragma unroll
;                 for (int rh = 0; rh < 2; ++rh) { u32x2 rv; rv.x = __shfl_xor(hw[1][rh].x, 8); rv.y = __shfl_xor(hw[1][rh].y, 8);
;                     const unsigned e0 = ERN_EOFF(g, 0, rh);
;                     const unsigned ee = odd ? (e0 - DM + 32) : e0, eo2 = odd ? e0 : (e0 + DM + 32);
;                     *(u32x2*)((char*)ho + 2u * ee) = odd ? rv : hw[0][rh];
;                     *(u32x2*)((char*)ho + 2u * eo2) = odd ? hw[0][rh] : rv; }
;             }
;             if (!PLAIN) { sq0 += __shfl_xor(sq0, 1); sq0 += __shfl_xor(sq0, 2); sq0 += __shfl_xor(sq0, 4);
;             sq1 += __shfl_xor(sq1, 1); sq1 += __shfl_xor(sq1, 2); sq1 += __shfl_xor(sq1, 4); }
;             if (!PLAIN && pc == 0) { sst[g * 16 + rr] = sq0; sst[g * 16 + 8 + rr] = sq1; }
.LBB0_1283:
	s_or_b64 exec, exec, s[16:17]
	v_lshl_add_u64 v[124:125], s[48:49], 0, v[162:163]
	v_add_u32_e32 v90, 0x100000, v205
	s_waitcnt lgkmcnt(1)
	v_add_u32_e32 v91, 0x110000, v205
	v_add_u32_e32 v162, 0x100080, v205
	global_load_dwordx4 v[102:105], v90, s[48:49]
	global_load_dwordx4 v[98:101], v91, s[48:49]
	v_add_u32_e32 v122, 0x110080, v205
	global_load_dwordx4 v[94:97], v162, s[48:49]
	s_waitcnt lgkmcnt(0)
	global_load_dwordx4 v[90:93], v122, s[48:49]
	ds_write_b128 v200, v[86:89]
	ds_write_b128 v200, v[82:85] offset:64
	ds_read_b128 v[82:85], v201
	ds_read_b128 v[86:89], v201 offset:1152
	v_mov_b32_e32 v139, v163
	v_mov_b32_e32 v141, v163
	s_waitcnt vmcnt(11) lgkmcnt(1)
	v_pk_fma_f32 v[84:85], v[56:57], v[84:85], v[120:121]
	v_add_u32_e32 v120, 0x18000, v202
	v_pk_fma_f32 v[82:83], v[54:55], v[82:83], v[118:119]
	v_lshlrev_b32_e32 v118, 2, v120
	s_waitcnt lgkmcnt(0)
	v_pk_fma_f32 v[86:87], v[54:55], v[86:87], v[114:115]
	global_store_dwordx4 v118, v[82:85], s[48:49] nt
	v_pk_mul_f32 v[118:119], v[180:181], v[82:83]
	v_pk_fma_f32 v[88:89], v[56:57], v[88:89], v[116:117]
	v_pk_mul_f32 v[114:115], v[180:181], v[86:87]
	v_pk_mul_f32 v[126:127], v[178:179], v[84:85]
	v_cvt_pk_bf16_f32 v118, v118, v119
	v_pk_mul_f32 v[116:117], v[178:179], v[88:89]
	v_cvt_pk_bf16_f32 v119, v126, v127
	global_store_dwordx4 v[124:125], v[86:89], off nt
	v_cvt_pk_bf16_f32 v114, v114, v115
	v_cvt_pk_bf16_f32 v115, v116, v117
	ds_write_b128 v200, v[78:81]
	ds_write_b128 v200, v[74:77] offset:64
	ds_read_b128 v[74:77], v201
	ds_read_b128 v[78:81], v201 offset:1152
	v_lshl_add_u64 v[116:117], s[48:49], 0, v[138:139]
	v_lshl_add_u64 v[124:125], s[48:49], 0, v[140:141]
	s_waitcnt lgkmcnt(1)
	v_pk_fma_f32 v[74:75], v[50:51], v[74:75], v[110:111]
	v_pk_fma_f32 v[76:77], v[52:53], v[76:77], v[112:113]
	v_pk_mul_f32 v[112:113], v[176:177], v[74:75]
	global_store_dwordx4 v[116:117], v[74:77], off nt
	v_pk_mul_f32 v[110:111], v[174:175], v[76:77]
	v_cvt_pk_bf16_f32 v112, v112, v113
	s_waitcnt vmcnt(13) lgkmcnt(0)
	v_pk_fma_f32 v[78:79], v[50:51], v[78:79], v[106:107]
	v_cvt_pk_bf16_f32 v113, v110, v111
	ds_bpermute_b32 v106, v203, v112
	ds_bpermute_b32 v107, v203, v113
	v_pk_fma_f32 v[80:81], v[52:53], v[80:81], v[108:109]
	v_pk_mul_f32 v[108:109], v[176:177], v[78:79]
	v_pk_mul_f32 v[110:111], v[174:175], v[80:81]
	global_store_dwordx4 v[124:125], v[78:81], off nt
	v_cvt_pk_bf16_f32 v108, v108, v109
	v_cvt_pk_bf16_f32 v109, v110, v111
	v_lshlrev_b32_e32 v110, 1, v120
	s_waitcnt lgkmcnt(0)
	v_add_u32_e32 v250, 0xfffff040, v110
	v_cndmask_b32_e64 v250, v110, v250, s[40:41]
	v_cndmask_b32_e64 v248, v118, v106, s[40:41]
	v_cndmask_b32_e64 v249, v119, v107, s[40:41]
	global_store_dwordx2 v250, v[248:249], s[46:47]
	v_cndmask_b32_e64 v246, v106, v118, s[40:41]
	v_cndmask_b32_e64 v247, v107, v119, s[40:41]
	s_waitcnt lgkmcnt(1)
	v_add_u32_e32 v106, 0x1040, v110
	v_cndmask_b32_e64 v106, v110, v106, s[38:39]
	global_store_dwordx2 v106, v[246:247], s[46:47]
	ds_bpermute_b32 v106, v203, v108
	s_waitcnt lgkmcnt(1)
	ds_bpermute_b32 v107, v203, v109
	v_add_u32_e32 v109, 0x1c000, v202
	v_lshlrev_b32_e32 v108, 1, v109
	s_waitcnt lgkmcnt(0)
	v_add_u32_e32 v250, 0xfffff040, v108
	v_cndmask_b32_e64 v250, v108, v250, s[40:41]
	v_cndmask_b32_e64 v248, v114, v106, s[40:41]
	v_cndmask_b32_e64 v249, v115, v107, s[40:41]
	global_store_dwordx2 v250, v[248:249], s[46:47]
	v_cndmask_b32_e64 v246, v106, v114, s[40:41]
	v_cndmask_b32_e64 v247, v107, v115, s[40:41]
	v_mul_f32_e32 v75, v75, v75
	v_fmac_f32_e32 v75, v74, v74
	v_mul_f32_e32 v74, v77, v77
	v_mul_f32_e32 v85, v85, v85
	v_fmac_f32_e32 v74, v76, v76
	v_mul_f32_e32 v83, v83, v83
	v_fmac_f32_e32 v85, v84, v84
	v_mul_f32_e32 v84, v87, v87
	v_mul_f32_e32 v87, v89, v89
	v_add_f32_e32 v74, v75, v74
	v_mul_f32_e32 v75, v79, v79
	v_mul_f32_e32 v76, v81, v81
	v_fmac_f32_e32 v87, v88, v88
	v_fmac_f32_e32 v75, v78, v78
	v_fmac_f32_e32 v76, v80, v80
	v_fmac_f32_e32 v83, v82, v82
	v_fmac_f32_e32 v84, v86, v86
	v_add_f32_e32 v75, v75, v76
	v_add_f32_e32 v76, v83, v85
	v_add_f32_e32 v77, v84, v87
	v_add_f32_e32 v74, v76, v74
	v_add_f32_e32 v75, v77, v75
	ds_bpermute_b32 v76, v190, v74
	ds_bpermute_b32 v77, v190, v75
	s_waitcnt lgkmcnt(1)
	v_add_f32_e32 v74, v74, v76
	s_waitcnt lgkmcnt(0)
	v_add_f32_e32 v77, v75, v77
	ds_bpermute_b32 v76, v191, v74
	ds_bpermute_b32 v78, v191, v77
	s_waitcnt lgkmcnt(1)
	v_add_f32_e32 v74, v74, v76
	s_waitcnt lgkmcnt(0)
	v_add_f32_e32 v76, v77, v78
	ds_bpermute_b32 v75, v204, v74
	ds_bpermute_b32 v77, v204, v76
	v_add_u32_e32 v78, 0x1040, v108
	v_cndmask_b32_e64 v78, v108, v78, s[38:39]
	global_store_dwordx2 v78, v[246:247], s[46:47]
	s_and_saveexec_b64 s[16:17], s[42:43]
	s_cbranch_execz .LBB0_1293
	s_waitcnt lgkmcnt(1)
	v_add_f32_e32 v74, v74, v75
	s_waitcnt lgkmcnt(0)
	v_add_f32_e32 v75, v76, v77
	ds_write2_b32 v194, v74, v75 offset0:48 offset1:56
; #define LAS __attribute__((address_space(3)))
; #define ERN_EOFF(q, m) (eb + (unsigned)((((q) & 1) * HALF + (m) * 16) * DM + ERN_COL((q) >> 1)))
;     __device__ __forceinline__ void operator()(const f32x4 (&acc)[2][2][4][2], const Unit& u, int wr, int wc, int fr, int fq) const {
;     ...
;         ERN_LOADX(0);
; #pragma unroll
;         for (int g = 0; g < 8; ++g) { const int ai = g >> 2, m = g & 3;
;             if (g + 1 < 8) ERN_LOADX(g + 1);
;             float sq0 = 0.f, sq1 = 0.f; u32x2 hw[2][2];
; #pragma unroll
;             for (int bj = 0; bj < 2; ++bj) {
;                 *(LAS f32x4*)(st + wr_off) = acc[ai][bj][m][0]; *(LAS f32x4*)(st + wr_off + 64) = acc[ai][bj][m][1];
;                 const f32x4 a0 = *(const LAS f32x4*)(st + rd_off), a1 = *(const LAS f32x4*)(st + rd_off + 8 * 144);
;                 { const f32x4 xv = xb[g & 1][bj][0] + gv[bj] * a0; __builtin_nontemporal_store(xv, (f32x4*)((char*)xo + 4u * ERN_EOFF(g, bj, 0)));
;                   sq0 += (xv.x * xv.x + xv.y * xv.y) + (xv.z * xv.z + xv.w * xv.w);
;                   const f32x4 hv = xv * gsn[bj]; hw[bj][0].x = cvt_pk_bf16(hv.x, hv.y); hw[bj][0].y = cvt_pk_bf16(hv.z, hv.w); }
;                 { const f32x4 xv = xb[g & 1][bj][1] + gv[bj] * a1; __builtin_nontemporal_store(xv, (f32x4*)((char*)xo + 4u * ERN_EOFF(g, bj, 1)));
;                   sq1 += (xv.x * xv.x + xv.y * xv.y) + (xv.z * xv.z + xv.w * xv.w);
;                   const f32x4 hv = xv * gsn[bj]; hw[bj][1].x = cvt_pk_bf16(hv.x, hv.y); hw[bj][1].y = cvt_pk_bf16(hv.z, hv.w); }
;             }
;             if (!NOH && !PLAIN) {
; #pragma unroll
;                 for (int rh = 0; rh < 2; ++rh) { u32x2 rv; rv.x = __shfl_xor(hw[1][rh].x, 8); rv.y = __shfl_xor(hw[1][rh].y, 8);
;                     const unsigned e0 = ERN_EOFF(g, 0, rh);
;                     const unsigned ee = odd ? (e0 - DM + 32) : e0, eo2 = odd ? e0 : (e0 + DM + 32);
;                     *(u32x2*)((char*)ho + 2u * ee) = odd ? rv : hw[0][rh];
;                     *(u32x2*)((char*)ho + 2u * eo2) = odd ? hw[0][rh] : rv; }
;             }
;             if (!PLAIN) { sq0 += __shfl_xor(sq0, 1); sq0 += __shfl_xor(sq0, 2); sq0 += __shfl_xor(sq0, 4);
;             sq1 += __shfl_xor(sq1, 1); sq1 += __shfl_xor(sq1, 2); sq1 += __shfl_xor(sq1, 4); }
;             if (!PLAIN && pc == 0) { sst[g * 16 + rr] = sq0; sst[g * 16 + 8 + rr] = sq1; }
.LBB0_1293:
	s_or_b64 exec, exec, s[16:17]
	v_lshl_add_u64 v[112:113], s[48:49], 0, v[162:163]
	v_add_u32_e32 v162, 0x120000, v205
	v_add_u32_e32 v108, 0x120080, v205
	v_add_u32_e32 v110, 0x130000, v205
	global_load_dwordx4 v[86:89], v162, s[48:49]
	global_load_dwordx4 v[82:85], v110, s[48:49]
	v_add_u32_e32 v106, 0x130080, v205
	global_load_dwordx4 v[78:81], v108, s[48:49]
	s_waitcnt lgkmcnt(0)
	global_load_dwordx4 v[74:77], v106, s[48:49]
	ds_write_b128 v200, v[70:73]
	ds_write_b128 v200, v[66:69] offset:64
	ds_read_b128 v[66:69], v201
	ds_read_b128 v[70:73], v201 offset:1152
	v_mov_b32_e32 v123, v163
	s_waitcnt vmcnt(13) lgkmcnt(1)
	v_pk_fma_f32 v[68:69], v[56:57], v[68:69], v[104:105]
	v_add_u32_e32 v104, 0x40000, v202
	v_pk_fma_f32 v[66:67], v[54:55], v[66:67], v[102:103]
	v_lshlrev_b32_e32 v102, 2, v104
	s_waitcnt vmcnt(12) lgkmcnt(0)
	v_pk_fma_f32 v[72:73], v[56:57], v[72:73], v[100:101]
	v_add_u32_e32 v100, 0x44000, v202
	global_store_dwordx4 v102, v[66:69], s[48:49] nt
	v_pk_mul_f32 v[102:103], v[180:181], v[66:67]
	v_pk_fma_f32 v[70:71], v[54:55], v[70:71], v[98:99]
	v_lshlrev_b32_e32 v98, 2, v100
	v_pk_mul_f32 v[114:115], v[178:179], v[68:69]
	v_cvt_pk_bf16_f32 v102, v102, v103
	s_nop 0
	v_cvt_pk_bf16_f32 v103, v114, v115
	global_store_dwordx4 v98, v[70:73], s[48:49] nt
	v_pk_mul_f32 v[98:99], v[180:181], v[70:71]
	v_pk_mul_f32 v[114:115], v[178:179], v[72:73]
	v_cvt_pk_bf16_f32 v98, v98, v99
	s_nop 0
	v_cvt_pk_bf16_f32 v99, v114, v115
	ds_write_b128 v200, v[62:65]
	ds_write_b128 v200, v[58:61] offset:64
	ds_read_b128 v[58:61], v201
	ds_read_b128 v[62:65], v201 offset:1152
	v_lshl_add_u64 v[114:115], s[48:49], 0, v[122:123]
	s_waitcnt vmcnt(13) lgkmcnt(1)
	v_pk_fma_f32 v[58:59], v[50:51], v[58:59], v[94:95]
	v_pk_fma_f32 v[60:61], v[52:53], v[60:61], v[96:97]
	v_pk_mul_f32 v[96:97], v[176:177], v[58:59]
	global_store_dwordx4 v[112:113], v[58:61], off nt
	v_pk_mul_f32 v[94:95], v[174:175], v[60:61]
	v_cvt_pk_bf16_f32 v96, v96, v97
	s_waitcnt vmcnt(13) lgkmcnt(0)
	v_pk_fma_f32 v[62:63], v[50:51], v[62:63], v[90:91]
	v_cvt_pk_bf16_f32 v97, v94, v95
	ds_bpermute_b32 v90, v203, v96
	ds_bpermute_b32 v91, v203, v97
	v_pk_fma_f32 v[64:65], v[52:53], v[64:65], v[92:93]
	v_pk_mul_f32 v[92:93], v[176:177], v[62:63]
	v_pk_mul_f32 v[94:95], v[174:175], v[64:65]
	global_store_dwordx4 v[114:115], v[62:65], off nt
	v_cvt_pk_bf16_f32 v92, v92, v93
	v_cvt_pk_bf16_f32 v93, v94, v95
	v_lshlrev_b32_e32 v94, 1, v104
	s_waitcnt lgkmcnt(0)
	v_add_u32_e32 v250, 0xfffff040, v94
	v_cndmask_b32_e64 v250, v94, v250, s[40:41]
	v_cndmask_b32_e64 v248, v102, v90, s[40:41]
	v_cndmask_b32_e64 v249, v103, v91, s[40:41]
	global_store_dwordx2 v250, v[248:249], s[46:47]
	v_cndmask_b32_e64 v246, v90, v102, s[40:41]
	v_cndmask_b32_e64 v247, v91, v103, s[40:41]
	s_waitcnt lgkmcnt(1)
	v_add_u32_e32 v90, 0x1040, v94
	v_cndmask_b32_e64 v90, v94, v90, s[38:39]
	global_store_dwordx2 v90, v[246:247], s[46:47]
	ds_bpermute_b32 v90, v203, v92
	s_waitcnt lgkmcnt(1)
	ds_bpermute_b32 v91, v203, v93
	v_lshlrev_b32_e32 v92, 1, v100
	s_waitcnt lgkmcnt(0)
	v_add_u32_e32 v250, 0xfffff040, v92
	v_cndmask_b32_e64 v250, v92, v250, s[40:41]
	v_cndmask_b32_e64 v248, v98, v90, s[40:41]
	v_cndmask_b32_e64 v249, v99, v91, s[40:41]
	global_store_dwordx2 v250, v[248:249], s[46:47]
	v_cndmask_b32_e64 v246, v90, v98, s[40:41]
	v_cndmask_b32_e64 v247, v91, v99, s[40:41]
	v_mul_f32_e32 v59, v59, v59
	v_fmac_f32_e32 v59, v58, v58
	v_mul_f32_e32 v58, v61, v61
	v_mul_f32_e32 v69, v69, v69
	v_fmac_f32_e32 v58, v60, v60
	v_mul_f32_e32 v67, v67, v67
	v_fmac_f32_e32 v69, v68, v68
	v_mul_f32_e32 v68, v71, v71
	v_mul_f32_e32 v71, v73, v73
	v_add_f32_e32 v58, v59, v58
	v_mul_f32_e32 v59, v63, v63
	v_mul_f32_e32 v60, v65, v65
	v_fmac_f32_e32 v71, v72, v72
	v_fmac_f32_e32 v59, v62, v62
	v_fmac_f32_e32 v60, v64, v64
	v_fmac_f32_e32 v67, v66, v66
	v_fmac_f32_e32 v68, v70, v70
	v_add_f32_e32 v59, v59, v60
	v_add_f32_e32 v60, v67, v69
	v_add_f32_e32 v61, v68, v71
	v_add_f32_e32 v58, v60, v58
	v_add_f32_e32 v59, v61, v59
	ds_bpermute_b32 v60, v190, v58
	ds_bpermute_b32 v61, v190, v59
	s_waitcnt lgkmcnt(1)
	v_add_f32_e32 v58, v58, v60
	s_waitcnt lgkmcnt(0)
	v_add_f32_e32 v61, v59, v61
	ds_bpermute_b32 v60, v191, v58
	ds_bpermute_b32 v62, v191, v61
	s_waitcnt lgkmcnt(1)
	v_add_f32_e32 v58, v58, v60
	s_waitcnt lgkmcnt(0)
	v_add_f32_e32 v60, v61, v62
	ds_bpermute_b32 v59, v204, v58
	ds_bpermute_b32 v61, v204, v60
	v_add_u32_e32 v62, 0x1040, v92
	v_cndmask_b32_e64 v62, v92, v62, s[38:39]
	global_store_dwordx2 v62, v[246:247], s[46:47]
	s_and_saveexec_b64 s[16:17], s[42:43]
	s_cbranch_execz .LBB0_1303
	s_waitcnt lgkmcnt(1)
	v_add_f32_e32 v58, v58, v59
	s_waitcnt lgkmcnt(0)
	v_add_f32_e32 v59, v60, v61
	ds_write2_b32 v194, v58, v59 offset0:64 offset1:72
; #define LAS __attribute__((address_space(3)))
; #define ERN_EOFF(q, m) (eb + (unsigned)((((q) & 1) * HALF + (m) * 16) * DM + ERN_COL((q) >> 1)))
;     __device__ __forceinline__ void operator()(const f32x4 (&acc)[2][2][4][2], const Unit& u, int wr, int wc, int fr, int fq) const {
;     ...
;         ERN_LOADX(0);
; #pragma unroll
;         for (int g = 0; g < 8; ++g) { const int ai = g >> 2, m = g & 3;
;             if (g + 1 < 8) ERN_LOADX(g + 1);
;             float sq0 = 0.f, sq1 = 0.f; u32x2 hw[2][2];
; #pragma unroll
;             for (int bj = 0; bj < 2; ++bj) {
;                 *(LAS f32x4*)(st + wr_off) = acc[ai][bj][m][0]; *(LAS f32x4*)(st + wr_off + 64) = acc[ai][bj][m][1];
;                 const f32x4 a0 = *(const LAS f32x4*)(st + rd_off), a1 = *(const LAS f32x4*)(st + rd_off + 8 * 144);
;                 { const f32x4 xv = xb[g & 1][bj][0] + gv[bj] * a0; __builtin_nontemporal_store(xv, (f32x4*)((char*)xo + 4u * ERN_EOFF(g, bj, 0)));
;                   sq0 += (xv.x * xv.x + xv.y * xv.y) + (xv.z * xv.z + xv.w * xv.w);
;                   const f32x4 hv = xv * gsn[bj]; hw[bj][0].x = cvt_pk_bf16(hv.x, hv.y); hw[bj][0].y = cvt_pk_bf16(hv.z, hv.w); }
;                 { const f32x4 xv = xb[g & 1][bj][1] + gv[bj] * a1; __builtin_nontemporal_store(xv, (f32x4*)((char*)xo + 4u * ERN_EOFF(g, bj, 1)));
;                   sq1 += (xv.x * xv.x + xv.y * xv.y) + (xv.z * xv.z + xv.w * xv.w);
;                   const f32x4 hv = xv * gsn[bj]; hw[bj][1].x = cvt_pk_bf16(hv.x, hv.y); hw[bj][1].y = cvt_pk_bf16(hv.z, hv.w); }
;             }
;             if (!NOH && !PLAIN) {
; #pragma unroll
;                 for (int rh = 0; rh < 2; ++rh) { u32x2 rv; rv.x = __shfl_xor(hw[1][rh].x, 8); rv.y = __shfl_xor(hw[1][rh].y, 8);
;                     const unsigned e0 = ERN_EOFF(g, 0, rh);
;                     const unsigned ee = odd ? (e0 - DM + 32) : e0, eo2 = odd ? e0 : (e0 + DM + 32);
;                     *(u32x2*)((char*)ho + 2u * ee) = odd ? rv : hw[0][rh];
;                     *(u32x2*)((char*)ho + 2u * eo2) = odd ? hw[0][rh] : rv; }
;             }
;             if (!PLAIN) { sq0 += __shfl_xor(sq0, 1); sq0 += __shfl_xor(sq0, 2); sq0 += __shfl_xor(sq0, 4);
;             sq1 += __shfl_xor(sq1, 1); sq1 += __shfl_xor(sq1, 2); sq1 += __shfl_xor(sq1, 4); }
;             if (!PLAIN && pc == 0) { sst[g * 16 + rr] = sq0; sst[g * 16 + 8 + rr] = sq1; }
.LBB0_1303:
	s_or_b64 exec, exec, s[16:17]
	v_lshl_add_u64 v[96:97], s[48:49], 0, v[162:163]
	v_add_u32_e32 v162, 0x140000, v205
	v_add_u32_e32 v92, 0x140080, v205
	v_add_u32_e32 v94, 0x150000, v205
	global_load_dwordx4 v[70:73], v162, s[48:49]
	global_load_dwordx4 v[66:69], v94, s[48:49]
	v_add_u32_e32 v90, 0x150080, v205
	global_load_dwordx4 v[62:65], v92, s[48:49]
	s_waitcnt lgkmcnt(0)
	global_load_dwordx4 v[58:61], v90, s[48:49]
	ds_write_b128 v200, v[46:49]
	ds_write_b128 v200, v[42:45] offset:64
	ds_read_b128 v[42:45], v201
	ds_read_b128 v[46:49], v201 offset:1152
	v_mov_b32_e32 v111, v163
	v_lshl_add_u64 v[98:99], s[48:49], 0, v[110:111]
	v_mov_b32_e32 v109, v163
	s_waitcnt vmcnt(13) lgkmcnt(1)
	v_pk_fma_f32 v[42:43], v[54:55], v[42:43], v[86:87]
	s_waitcnt vmcnt(12) lgkmcnt(0)
	v_pk_fma_f32 v[46:47], v[54:55], v[46:47], v[82:83]
	v_pk_fma_f32 v[44:45], v[56:57], v[44:45], v[88:89]
	v_pk_mul_f32 v[86:87], v[180:181], v[42:43]
	v_pk_fma_f32 v[48:49], v[56:57], v[48:49], v[84:85]
	v_pk_mul_f32 v[82:83], v[180:181], v[46:47]
	global_store_dwordx4 v[96:97], v[42:45], off nt
	v_pk_mul_f32 v[88:89], v[178:179], v[44:45]
	v_cvt_pk_bf16_f32 v86, v86, v87
	v_pk_mul_f32 v[84:85], v[178:179], v[48:49]
	v_cvt_pk_bf16_f32 v87, v88, v89
	global_store_dwordx4 v[98:99], v[46:49], off nt
	v_cvt_pk_bf16_f32 v82, v82, v83
	v_cvt_pk_bf16_f32 v83, v84, v85
	ds_write_b128 v200, v[38:41]
	ds_write_b128 v200, v[34:37] offset:64
	ds_read_b128 v[34:37], v201
	ds_read_b128 v[38:41], v201 offset:1152
	v_lshl_add_u64 v[84:85], s[48:49], 0, v[108:109]
	v_mov_b32_e32 v107, v163
	v_lshl_add_u64 v[88:89], s[48:49], 0, v[106:107]
	s_waitcnt vmcnt(13) lgkmcnt(1)
	v_pk_fma_f32 v[34:35], v[50:51], v[34:35], v[78:79]
	v_pk_fma_f32 v[36:37], v[52:53], v[36:37], v[80:81]
	v_pk_mul_f32 v[80:81], v[176:177], v[34:35]
	global_store_dwordx4 v[84:85], v[34:37], off nt
	v_pk_mul_f32 v[78:79], v[174:175], v[36:37]
	v_cvt_pk_bf16_f32 v80, v80, v81
	s_waitcnt vmcnt(13) lgkmcnt(0)
	v_pk_fma_f32 v[38:39], v[50:51], v[38:39], v[74:75]
	v_cvt_pk_bf16_f32 v81, v78, v79
	ds_bpermute_b32 v74, v203, v80
	ds_bpermute_b32 v75, v203, v81
	v_pk_fma_f32 v[40:41], v[52:53], v[40:41], v[76:77]
	v_pk_mul_f32 v[76:77], v[176:177], v[38:39]
	v_pk_mul_f32 v[78:79], v[174:175], v[40:41]
	global_store_dwordx4 v[88:89], v[38:41], off nt
	v_cvt_pk_bf16_f32 v76, v76, v77
	v_cvt_pk_bf16_f32 v77, v78, v79
	v_add_u32_e32 v79, 0x48000, v202
	v_lshlrev_b32_e32 v78, 1, v79
	s_waitcnt lgkmcnt(0)
	v_add_u32_e32 v250, 0xfffff040, v78
	v_cndmask_b32_e64 v250, v78, v250, s[40:41]
	v_cndmask_b32_e64 v248, v86, v74, s[40:41]
	v_cndmask_b32_e64 v249, v87, v75, s[40:41]
	global_store_dwordx2 v250, v[248:249], s[46:47]
	v_cndmask_b32_e64 v246, v74, v86, s[40:41]
	v_cndmask_b32_e64 v247, v75, v87, s[40:41]
	s_waitcnt lgkmcnt(1)
	v_add_u32_e32 v74, 0x1040, v78
	v_cndmask_b32_e64 v74, v78, v74, s[38:39]
	global_store_dwordx2 v74, v[246:247], s[46:47]
	ds_bpermute_b32 v74, v203, v76
	s_waitcnt lgkmcnt(1)
	ds_bpermute_b32 v75, v203, v77
	v_add_u32_e32 v77, 0x4c000, v202
	v_lshlrev_b32_e32 v76, 1, v77
	s_waitcnt lgkmcnt(0)
	v_add_u32_e32 v250, 0xfffff040, v76
	v_cndmask_b32_e64 v250, v76, v250, s[40:41]
	v_cndmask_b32_e64 v248, v82, v74, s[40:41]
	v_cndmask_b32_e64 v249, v83, v75, s[40:41]
	global_store_dwordx2 v250, v[248:249], s[46:47]
	v_cndmask_b32_e64 v246, v74, v82, s[40:41]
	v_cndmask_b32_e64 v247, v75, v83, s[40:41]
	v_mul_f32_e32 v35, v35, v35
	v_fmac_f32_e32 v35, v34, v34
	v_mul_f32_e32 v34, v37, v37
	v_mul_f32_e32 v45, v45, v45
	v_fmac_f32_e32 v34, v36, v36
	v_mul_f32_e32 v43, v43, v43
	v_fmac_f32_e32 v45, v44, v44
	v_mul_f32_e32 v44, v47, v47
	v_mul_f32_e32 v47, v49, v49
	v_add_f32_e32 v34, v35, v34
	v_mul_f32_e32 v35, v39, v39
	v_mul_f32_e32 v36, v41, v41
	v_fmac_f32_e32 v47, v48, v48
	v_fmac_f32_e32 v35, v38, v38
	v_fmac_f32_e32 v36, v40, v40
	v_fmac_f32_e32 v43, v42, v42
	v_fmac_f32_e32 v44, v46, v46
	v_add_f32_e32 v35, v35, v36
	v_add_f32_e32 v36, v43, v45
	v_add_f32_e32 v37, v44, v47
	v_add_f32_e32 v34, v36, v34
	v_add_f32_e32 v35, v37, v35
	ds_bpermute_b32 v36, v190, v34
	ds_bpermute_b32 v37, v190, v35
	s_waitcnt lgkmcnt(1)
	v_add_f32_e32 v34, v34, v36
	s_waitcnt lgkmcnt(0)
	v_add_f32_e32 v37, v35, v37
	ds_bpermute_b32 v36, v191, v34
	ds_bpermute_b32 v38, v191, v37
	s_waitcnt lgkmcnt(1)
	v_add_f32_e32 v34, v34, v36
	s_waitcnt lgkmcnt(0)
	v_add_f32_e32 v36, v37, v38
	ds_bpermute_b32 v35, v204, v34
	ds_bpermute_b32 v37, v204, v36
	v_add_u32_e32 v38, 0x1040, v76
	v_cndmask_b32_e64 v38, v76, v38, s[38:39]
	global_store_dwordx2 v38, v[246:247], s[46:47]
	s_and_saveexec_b64 s[16:17], s[42:43]
	s_cbranch_execz .LBB0_1313
	s_waitcnt lgkmcnt(1)
	v_add_f32_e32 v34, v34, v35
	s_waitcnt lgkmcnt(0)
	v_add_f32_e32 v35, v36, v37
	ds_write2_b32 v194, v34, v35 offset0:80 offset1:88
; #define LAS __attribute__((address_space(3)))
; #define ERN_EOFF(q, m) (eb + (unsigned)((((q) & 1) * HALF + (m) * 16) * DM + ERN_COL((q) >> 1)))
;     __device__ __forceinline__ void operator()(const f32x4 (&acc)[2][2][4][2], const Unit& u, int wr, int wc, int fr, int fq) const {
;     ...
;         ERN_LOADX(0);
; #pragma unroll
;         for (int g = 0; g < 8; ++g) { const int ai = g >> 2, m = g & 3;
;             if (g + 1 < 8) ERN_LOADX(g + 1);
;             float sq0 = 0.f, sq1 = 0.f; u32x2 hw[2][2];
; #pragma unroll
;             for (int bj = 0; bj < 2; ++bj) {
;                 *(LAS f32x4*)(st + wr_off) = acc[ai][bj][m][0]; *(LAS f32x4*)(st + wr_off + 64) = acc[ai][bj][m][1];
;                 const f32x4 a0 = *(const LAS f32x4*)(st + rd_off), a1 = *(const LAS f32x4*)(st + rd_off + 8 * 144);
;                 { const f32x4 xv = xb[g & 1][bj][0] + gv[bj] * a0; __builtin_nontemporal_store(xv, (f32x4*)((char*)xo + 4u * ERN_EOFF(g, bj, 0)));
;                   sq0 += (xv.x * xv.x + xv.y * xv.y) + (xv.z * xv.z + xv.w * xv.w);
;                   const f32x4 hv = xv * gsn[bj]; hw[bj][0].x = cvt_pk_bf16(hv.x, hv.y); hw[bj][0].y = cvt_pk_bf16(hv.z, hv.w); }
;                 { const f32x4 xv = xb[g & 1][bj][1] + gv[bj] * a1; __builtin_nontemporal_store(xv, (f32x4*)((char*)xo + 4u * ERN_EOFF(g, bj, 1)));
;                   sq1 += (xv.x * xv.x + xv.y * xv.y) + (xv.z * xv.z + xv.w * xv.w);
;                   const f32x4 hv = xv * gsn[bj]; hw[bj][1].x = cvt_pk_bf16(hv.x, hv.y); hw[bj][1].y = cvt_pk_bf16(hv.z, hv.w); }
;             }
;             if (!NOH && !PLAIN) {
; #pragma unroll
;                 for (int rh = 0; rh < 2; ++rh) { u32x2 rv; rv.x = __shfl_xor(hw[1][rh].x, 8); rv.y = __shfl_xor(hw[1][rh].y, 8);
;                     const unsigned e0 = ERN_EOFF(g, 0, rh);
;                     const unsigned ee = odd ? (e0 - DM + 32) : e0, eo2 = odd ? e0 : (e0 + DM + 32);
;                     *(u32x2*)((char*)ho + 2u * ee) = odd ? rv : hw[0][rh];
;                     *(u32x2*)((char*)ho + 2u * eo2) = odd ? hw[0][rh] : rv; }
;             }
;             if (!PLAIN) { sq0 += __shfl_xor(sq0, 1); sq0 += __shfl_xor(sq0, 2); sq0 += __shfl_xor(sq0, 4);
;             sq1 += __shfl_xor(sq1, 1); sq1 += __shfl_xor(sq1, 2); sq1 += __shfl_xor(sq1, 4); }
;             if (!PLAIN && pc == 0) { sst[g * 16 + rr] = sq0; sst[g * 16 + 8 + rr] = sq1; }
.LBB0_1313:
	s_or_b64 exec, exec, s[16:17]
	v_lshl_add_u64 v[80:81], s[48:49], 0, v[162:163]
	v_add_u32_e32 v162, 0x160000, v205
	v_add_u32_e32 v76, 0x160080, v205
	v_add_u32_e32 v78, 0x170000, v205
	global_load_dwordx4 v[46:49], v162, s[48:49]
	global_load_dwordx4 v[42:45], v78, s[48:49]
	v_add_u32_e32 v74, 0x170080, v205
	global_load_dwordx4 v[38:41], v76, s[48:49]
	s_waitcnt lgkmcnt(0)
	global_load_dwordx4 v[34:37], v74, s[48:49]
	ds_write_b128 v200, v[30:33]
	ds_write_b128 v200, v[26:29] offset:64
	ds_read_b128 v[26:29], v201
	ds_read_b128 v[30:33], v201 offset:1152
	v_mov_b32_e32 v95, v163
	v_lshl_add_u64 v[82:83], s[48:49], 0, v[94:95]
	v_mov_b32_e32 v93, v163
	s_waitcnt vmcnt(13) lgkmcnt(1)
	v_pk_fma_f32 v[26:27], v[54:55], v[26:27], v[70:71]
	s_waitcnt vmcnt(12) lgkmcnt(0)
	v_pk_fma_f32 v[30:31], v[54:55], v[30:31], v[66:67]
	v_pk_fma_f32 v[28:29], v[56:57], v[28:29], v[72:73]
	v_pk_mul_f32 v[70:71], v[180:181], v[26:27]
	v_pk_fma_f32 v[32:33], v[56:57], v[32:33], v[68:69]
	v_pk_mul_f32 v[66:67], v[180:181], v[30:31]
	global_store_dwordx4 v[80:81], v[26:29], off nt
	v_pk_mul_f32 v[72:73], v[178:179], v[28:29]
	v_cvt_pk_bf16_f32 v70, v70, v71
	v_pk_mul_f32 v[68:69], v[178:179], v[32:33]
	v_cvt_pk_bf16_f32 v71, v72, v73
	global_store_dwordx4 v[82:83], v[30:33], off nt
	v_cvt_pk_bf16_f32 v66, v66, v67
	v_cvt_pk_bf16_f32 v67, v68, v69
	ds_write_b128 v200, v[22:25]
	ds_write_b128 v200, v[18:21] offset:64
	ds_read_b128 v[18:21], v201
	ds_read_b128 v[22:25], v201 offset:1152
	v_lshl_add_u64 v[68:69], s[48:49], 0, v[92:93]
	v_mov_b32_e32 v91, v163
	v_lshl_add_u64 v[72:73], s[48:49], 0, v[90:91]
	s_waitcnt vmcnt(13) lgkmcnt(1)
	v_pk_fma_f32 v[18:19], v[50:51], v[18:19], v[62:63]
	v_pk_fma_f32 v[20:21], v[52:53], v[20:21], v[64:65]
	v_pk_mul_f32 v[64:65], v[176:177], v[18:19]
	global_store_dwordx4 v[68:69], v[18:21], off nt
	v_pk_mul_f32 v[62:63], v[174:175], v[20:21]
	v_cvt_pk_bf16_f32 v64, v64, v65
	s_waitcnt vmcnt(13) lgkmcnt(0)
	v_pk_fma_f32 v[22:23], v[50:51], v[22:23], v[58:59]
	v_cvt_pk_bf16_f32 v65, v62, v63
	ds_bpermute_b32 v58, v203, v64
	ds_bpermute_b32 v59, v203, v65
	v_pk_fma_f32 v[24:25], v[52:53], v[24:25], v[60:61]
	v_pk_mul_f32 v[60:61], v[176:177], v[22:23]
	v_pk_mul_f32 v[62:63], v[174:175], v[24:25]
	global_store_dwordx4 v[72:73], v[22:25], off nt
	v_cvt_pk_bf16_f32 v60, v60, v61
	v_cvt_pk_bf16_f32 v61, v62, v63
	v_add_u32_e32 v63, 0x50000, v202
	v_lshlrev_b32_e32 v62, 1, v63
	s_waitcnt lgkmcnt(0)
	v_add_u32_e32 v250, 0xfffff040, v62
	v_cndmask_b32_e64 v250, v62, v250, s[40:41]
	v_cndmask_b32_e64 v248, v70, v58, s[40:41]
	v_cndmask_b32_e64 v249, v71, v59, s[40:41]
	global_store_dwordx2 v250, v[248:249], s[46:47]
	v_cndmask_b32_e64 v246, v58, v70, s[40:41]
	v_cndmask_b32_e64 v247, v59, v71, s[40:41]
	s_waitcnt lgkmcnt(1)
	v_add_u32_e32 v58, 0x1040, v62
	v_cndmask_b32_e64 v58, v62, v58, s[38:39]
	global_store_dwordx2 v58, v[246:247], s[46:47]
	ds_bpermute_b32 v58, v203, v60
	s_waitcnt lgkmcnt(1)
	ds_bpermute_b32 v59, v203, v61
	v_add_u32_e32 v61, 0x54000, v202
	v_lshlrev_b32_e32 v60, 1, v61
	s_waitcnt lgkmcnt(0)
	v_add_u32_e32 v250, 0xfffff040, v60
	v_cndmask_b32_e64 v250, v60, v250, s[40:41]
	v_cndmask_b32_e64 v248, v66, v58, s[40:41]
	v_cndmask_b32_e64 v249, v67, v59, s[40:41]
	global_store_dwordx2 v250, v[248:249], s[46:47]
	v_cndmask_b32_e64 v246, v58, v66, s[40:41]
	v_cndmask_b32_e64 v247, v59, v67, s[40:41]
	v_mul_f32_e32 v19, v19, v19
	v_fmac_f32_e32 v19, v18, v18
	v_mul_f32_e32 v18, v21, v21
	v_mul_f32_e32 v29, v29, v29
	v_fmac_f32_e32 v18, v20, v20
	v_mul_f32_e32 v27, v27, v27
	v_fmac_f32_e32 v29, v28, v28
	v_mul_f32_e32 v28, v31, v31
	v_mul_f32_e32 v31, v33, v33
	v_add_f32_e32 v18, v19, v18
	v_mul_f32_e32 v19, v23, v23
	v_mul_f32_e32 v20, v25, v25
	v_fmac_f32_e32 v31, v32, v32
	v_fmac_f32_e32 v19, v22, v22
	v_fmac_f32_e32 v20, v24, v24
	v_fmac_f32_e32 v27, v26, v26
	v_fmac_f32_e32 v28, v30, v30
	v_add_f32_e32 v19, v19, v20
	v_add_f32_e32 v20, v27, v29
	v_add_f32_e32 v21, v28, v31
	v_add_f32_e32 v18, v20, v18
	v_add_f32_e32 v19, v21, v19
	ds_bpermute_b32 v20, v190, v18
	ds_bpermute_b32 v21, v190, v19
	s_waitcnt lgkmcnt(1)
	v_add_f32_e32 v18, v18, v20
	s_waitcnt lgkmcnt(0)
	v_add_f32_e32 v21, v19, v21
	ds_bpermute_b32 v20, v191, v18
	ds_bpermute_b32 v22, v191, v21
	s_waitcnt lgkmcnt(1)
	v_add_f32_e32 v18, v18, v20
	s_waitcnt lgkmcnt(0)
	v_add_f32_e32 v20, v21, v22
	ds_bpermute_b32 v19, v204, v18
	ds_bpermute_b32 v21, v204, v20
	v_add_u32_e32 v22, 0x1040, v60
	v_cndmask_b32_e64 v22, v60, v22, s[38:39]
	global_store_dwordx2 v22, v[246:247], s[46:47]
	s_and_saveexec_b64 s[16:17], s[42:43]
	s_cbranch_execz .LBB0_1323
	s_waitcnt lgkmcnt(1)
	v_add_f32_e32 v18, v18, v19
	s_waitcnt lgkmcnt(0)
	v_add_f32_e32 v19, v20, v21
	ds_write2_b32 v194, v18, v19 offset0:96 offset1:104
; #define LAS __attribute__((address_space(3)))
; #define ERN_EOFF(q, m) (eb + (unsigned)((((q) & 1) * HALF + (m) * 16) * DM + ERN_COL((q) >> 1)))
;     __device__ __forceinline__ void operator()(const f32x4 (&acc)[2][2][4][2], const Unit& u, int wr, int wc, int fr, int fq) const {
;     ...
;         for (int g = 0; g < 8; ++g) { const int ai = g >> 2, m = g & 3;
;             if (g + 1 < 8) ERN_LOADX(g + 1);
;             float sq0 = 0.f, sq1 = 0.f; u32x2 hw[2][2];
; #pragma unroll
;             for (int bj = 0; bj < 2; ++bj) {
;                 *(LAS f32x4*)(st + wr_off) = acc[ai][bj][m][0]; *(LAS f32x4*)(st + wr_off + 64) = acc[ai][bj][m][1];
;                 const f32x4 a0 = *(const LAS f32x4*)(st + rd_off), a1 = *(const LAS f32x4*)(st + rd_off + 8 * 144);
;                 { const f32x4 xv = xb[g & 1][bj][0] + gv[bj] * a0; __builtin_nontemporal_store(xv, (f32x4*)((char*)xo + 4u * ERN_EOFF(g, bj, 0)));
;                   sq0 += (xv.x * xv.x + xv.y * xv.y) + (xv.z * xv.z + xv.w * xv.w);
;                   const f32x4 hv = xv * gsn[bj]; hw[bj][0].x = cvt_pk_bf16(hv.x, hv.y); hw[bj][0].y = cvt_pk_bf16(hv.z, hv.w); }
;                 { const f32x4 xv = xb[g & 1][bj][1] + gv[bj] * a1; __builtin_nontemporal_store(xv, (f32x4*)((char*)xo + 4u * ERN_EOFF(g, bj, 1)));
;                   sq1 += (xv.x * xv.x + xv.y * xv.y) + (xv.z * xv.z + xv.w * xv.w);
;                   const f32x4 hv = xv * gsn[bj]; hw[bj][1].x = cvt_pk_bf16(hv.x, hv.y); hw[bj][1].y = cvt_pk_bf16(hv.z, hv.w); }
;             }
;             if (!NOH && !PLAIN) {
; #pragma unroll
;                 for (int rh = 0; rh < 2; ++rh) { u32x2 rv; rv.x = __shfl_xor(hw[1][rh].x, 8); rv.y = __shfl_xor(hw[1][rh].y, 8);
;                     const unsigned e0 = ERN_EOFF(g, 0, rh);
;                     const unsigned ee = odd ? (e0 - DM + 32) : e0, eo2 = odd ? e0 : (e0 + DM + 32);
;                     *(u32x2*)((char*)ho + 2u * ee) = odd ? rv : hw[0][rh];
;                     *(u32x2*)((char*)ho + 2u * eo2) = odd ? hw[0][rh] : rv; }
;             }
;             if (!PLAIN) { sq0 += __shfl_xor(sq0, 1); sq0 += __shfl_xor(sq0, 2); sq0 += __shfl_xor(sq0, 4);
;             sq1 += __shfl_xor(sq1, 1); sq1 += __shfl_xor(sq1, 2); sq1 += __shfl_xor(sq1, 4); }
;             if (!PLAIN && pc == 0) { sst[g * 16 + rr] = sq0; sst[g * 16 + 8 + rr] = sq1; }
.LBB0_1323:
	s_or_b64 exec, exec, s[16:17]
	ds_write_b128 v200, v[14:17]
	ds_write_b128 v200, v[10:13] offset:64
	ds_read_b128 v[10:13], v201
	ds_read_b128 v[14:17], v201 offset:1152
	s_waitcnt lgkmcnt(5)
	v_lshl_add_u64 v[18:19], s[48:49], 0, v[162:163]
	v_mov_b32_e32 v79, v163
	v_lshl_add_u64 v[22:23], s[48:49], 0, v[78:79]
	s_waitcnt vmcnt(9) lgkmcnt(1)
	v_pk_fma_f32 v[12:13], v[56:57], v[12:13], v[48:49]
	v_pk_fma_f32 v[10:11], v[54:55], v[10:11], v[46:47]
	global_store_dwordx4 v[18:19], v[10:13], off nt
	v_pk_mul_f32 v[18:19], v[178:179], v[12:13]
	v_pk_mul_f32 v[20:21], v[180:181], v[10:11]
	s_waitcnt vmcnt(9) lgkmcnt(0)
	v_pk_fma_f32 v[14:15], v[54:55], v[14:15], v[42:43]
	v_cvt_pk_bf16_f32 v20, v20, v21
	v_cvt_pk_bf16_f32 v21, v18, v19
	v_pk_fma_f32 v[16:17], v[56:57], v[16:17], v[44:45]
	v_pk_mul_f32 v[18:19], v[180:181], v[14:15]
	global_store_dwordx4 v[22:23], v[14:17], off nt
	v_pk_mul_f32 v[22:23], v[178:179], v[16:17]
	v_cvt_pk_bf16_f32 v18, v18, v19
	v_mov_b32_e32 v77, v163
	v_cvt_pk_bf16_f32 v19, v22, v23
	ds_write_b128 v200, v[6:9]
	ds_write_b128 v200, v[2:5] offset:64
	ds_read_b128 v[2:5], v201
	ds_read_b128 v[6:9], v201 offset:1152
	v_lshl_add_u64 v[22:23], s[48:49], 0, v[76:77]
	v_mov_b32_e32 v75, v163
	v_lshl_add_u64 v[24:25], s[48:49], 0, v[74:75]
	s_waitcnt vmcnt(9) lgkmcnt(1)
	v_pk_fma_f32 v[4:5], v[52:53], v[4:5], v[40:41]
	v_pk_fma_f32 v[2:3], v[50:51], v[2:3], v[38:39]
	global_store_dwordx4 v[22:23], v[2:5], off nt
	v_pk_mul_f32 v[22:23], v[174:175], v[4:5]
	v_pk_mul_f32 v[26:27], v[176:177], v[2:3]
	s_waitcnt vmcnt(9) lgkmcnt(0)
	v_pk_fma_f32 v[8:9], v[52:53], v[8:9], v[36:37]
	v_cvt_pk_bf16_f32 v28, v26, v27
	v_cvt_pk_bf16_f32 v23, v22, v23
	ds_bpermute_b32 v22, v203, v28
	ds_bpermute_b32 v23, v203, v23
	v_pk_fma_f32 v[6:7], v[50:51], v[6:7], v[34:35]
	global_store_dwordx4 v[24:25], v[6:9], off nt
	v_pk_mul_f32 v[26:27], v[174:175], v[8:9]
	v_pk_mul_f32 v[24:25], v[176:177], v[6:7]
	s_nop 0
	v_cvt_pk_bf16_f32 v24, v24, v25
	v_cvt_pk_bf16_f32 v25, v26, v27
	v_add_u32_e32 v27, 0x58000, v202
	v_lshlrev_b32_e32 v26, 1, v27
	s_waitcnt lgkmcnt(0)
	v_add_u32_e32 v250, 0xfffff040, v26
	v_cndmask_b32_e64 v250, v26, v250, s[40:41]
	v_cndmask_b32_e64 v248, v20, v22, s[40:41]
	v_cndmask_b32_e64 v249, v21, v23, s[40:41]
	global_store_dwordx2 v250, v[248:249], s[46:47]
	v_cndmask_b32_e64 v246, v22, v20, s[40:41]
	v_cndmask_b32_e64 v247, v23, v21, s[40:41]
	s_waitcnt lgkmcnt(1)
	v_add_u32_e32 v22, 0x1040, v26
	v_cndmask_b32_e64 v22, v26, v22, s[38:39]
	global_store_dwordx2 v22, v[246:247], s[46:47]
	ds_bpermute_b32 v20, v203, v24
	ds_bpermute_b32 v21, v203, v25
	s_waitcnt lgkmcnt(2)
	v_add_u32_e32 v23, 0x5c000, v202
	v_lshlrev_b32_e32 v22, 1, v23
	s_waitcnt lgkmcnt(0)
	v_add_u32_e32 v250, 0xfffff040, v22
	v_cndmask_b32_e64 v250, v22, v250, s[40:41]
	v_cndmask_b32_e64 v248, v18, v20, s[40:41]
	v_cndmask_b32_e64 v249, v19, v21, s[40:41]
	global_store_dwordx2 v250, v[248:249], s[46:47]
	v_cndmask_b32_e64 v246, v20, v18, s[40:41]
	v_cndmask_b32_e64 v247, v21, v19, s[40:41]
	v_mul_f32_e32 v3, v3, v3
	v_fmac_f32_e32 v3, v2, v2
	v_mul_f32_e32 v2, v5, v5
	v_mul_f32_e32 v13, v13, v13
	v_fmac_f32_e32 v2, v4, v4
	v_mul_f32_e32 v11, v11, v11
	v_fmac_f32_e32 v13, v12, v12
	v_mul_f32_e32 v12, v15, v15
	v_mul_f32_e32 v15, v17, v17
	v_add_f32_e32 v2, v3, v2
	v_mul_f32_e32 v3, v7, v7
	v_mul_f32_e32 v4, v9, v9
	v_fmac_f32_e32 v15, v16, v16
	v_fmac_f32_e32 v3, v6, v6
	v_fmac_f32_e32 v4, v8, v8
	v_fmac_f32_e32 v11, v10, v10
	v_fmac_f32_e32 v12, v14, v14
	v_add_f32_e32 v3, v3, v4
	v_add_f32_e32 v4, v11, v13
	v_add_f32_e32 v5, v12, v15
	v_add_f32_e32 v2, v4, v2
	v_add_f32_e32 v3, v5, v3
	ds_bpermute_b32 v4, v190, v2
	ds_bpermute_b32 v5, v190, v3
	s_waitcnt lgkmcnt(1)
	v_add_f32_e32 v2, v2, v4
	s_waitcnt lgkmcnt(0)
	v_add_f32_e32 v5, v3, v5
	ds_bpermute_b32 v4, v191, v2
	ds_bpermute_b32 v6, v191, v5
	s_waitcnt lgkmcnt(1)
	v_add_f32_e32 v2, v2, v4
	s_waitcnt lgkmcnt(0)
	v_add_f32_e32 v4, v5, v6
	ds_bpermute_b32 v3, v204, v2
	ds_bpermute_b32 v5, v204, v4
	v_add_u32_e32 v6, 0x1040, v22
	v_cndmask_b32_e64 v6, v22, v6, s[38:39]
	global_store_dwordx2 v6, v[246:247], s[46:47]
	s_and_saveexec_b64 s[16:17], s[42:43]
	s_cbranch_execz .LBB0_1333
	s_waitcnt lgkmcnt(1)
	v_add_f32_e32 v2, v2, v3
	s_waitcnt lgkmcnt(0)
	v_add_f32_e32 v3, v4, v5
	ds_write2_b32 v194, v2, v3 offset0:112 offset1:120

; #define LAS __attribute__((address_space(3)))
;     __device__ __forceinline__ void operator()(const f32x4 (&acc)[2][2][4][2], const Unit& u, int wr, int wc, int fr, int fq) const {
;         const int s = u.pm >> 5, lane = fq * 16 + fr, rr = lane >> 3, pc = lane & 7;
;         const float* __restrict__ xi = xin + (size_t)u.pm * BM * DM; float* __restrict__ xo = xout + (size_t)u.pm * BM * DM; bf16_t* __restrict__ ho = Hn + (size_t)u.pm * BM * DM;
;         LAS unsigned char* st = lds_epi + (wr * 4 + wc) * 2304;
;         LAS float* sst = (LAS float*)(lds_epi + 18432 + (wr * 4 + wc) * 512);
;         const int colr = u.pn * BM + wc * 64 + 4 * pc;
;         const unsigned eb = (unsigned)((wr * 64 + rr) * DM + colr);
;         f32x4 gv[2], gsn[2];
; #pragma unroll
;         for (int bj = 0; bj < 2; ++bj) { gv[bj] = *(const f32x4*)(gate + (size_t)s * MODW + colr + bj * 32) * (0.5f * GS2);
;             if (!PLAIN) gsn[bj] = *(const f32x4*)(gnext + colr + bj * 32) * (*(const f32x4*)(scnext + (size_t)s * MODW + colr + bj * 32) + 1.0f); else gsn[bj] = gv[bj]; }
;         const unsigned wr_off = (unsigned)(fr * 144 + 16 * fq), rd_off = (unsigned)(rr * 144 + pc * 16);
;         const bool odd = (rr & 1) != 0;
;         f32x4 xb[2][2][2];
;     ...
;         ERN_LOADX(0);
; #pragma unroll
;         for (int g = 0; g < 8; ++g) { const int ai = g >> 2, m = g & 3;
;             if (g + 1 < 8) ERN_LOADX(g + 1);
;             float sq0 = 0.f, sq1 = 0.f; u32x2 hw[2][2];
; #pragma unroll
;             for (int bj = 0; bj < 2; ++bj) {
;                 *(LAS f32x4*)(st + wr_off) = acc[ai][bj][m][0]; *(LAS f32x4*)(st + wr_off + 64) = acc[ai][bj][m][1];
;                 const f32x4 a0 = *(const LAS f32x4*)(st + rd_off), a1 = *(const LAS f32x4*)(st + rd_off + 8 * 144);
;                 { const f32x4 xv = xb[g & 1][bj][0] + gv[bj] * a0; __builtin_nontemporal_store(xv, (f32x4*)((char*)xo + 4u * ERN_EOFF(g, bj, 0)));
;                   sq0 += (xv.x * xv.x + xv.y * xv.y) + (xv.z * xv.z + xv.w * xv.w);
;                   const f32x4 hv = xv * gsn[bj]; hw[bj][0].x = cvt_pk_bf16(hv.x, hv.y); hw[bj][0].y = cvt_pk_bf16(hv.z, hv.w); }
;                 { const f32x4 xv = xb[g & 1][bj][1] + gv[bj] * a1; __builtin_nontemporal_store(xv, (f32x4*)((char*)xo + 4u * ERN_EOFF(g, bj, 1)));
;                   sq1 += (xv.x * xv.x + xv.y * xv.y) + (xv.z * xv.z + xv.w * xv.w);
.LBB0_1598:
	s_ashr_i32 s16, s8, 5
	s_ashr_i32 s9, s8, 31
	v_lshl_or_b32 v130, s0, 8, v192
	s_mul_i32 s20, s16, 0x12000
	s_mul_hi_i32 s0, s16, 0x12000
	s_add_u32 s16, s37, s20
	v_ashrrev_i32_e32 v131, 31, v130
	s_addc_u32 s17, s48, s0
	v_lshlrev_b64 v[132:133], 2, v[130:131]
	v_lshl_add_u64 v[134:135], s[16:17], 0, v[132:133]
	s_add_u32 s16, s26, s20
	s_addc_u32 s17, s27, s0
	v_lshl_add_u64 v[136:137], s[4:5], 0, v[132:133]
	v_lshl_add_u64 v[132:133], s[16:17], 0, v[132:133]
	s_lshl_b64 s[16:17], s[8:9], 21
	s_add_u32 s22, s90, s16
	v_add_u32_e32 v202, v130, v193
	s_addc_u32 s23, s91, s17
	v_lshlrev_b32_e32 v205, 2, v202
	global_load_dwordx4 v[170:173], v[136:137], off
	global_load_dwordx4 v[166:169], v[134:135], off
	global_load_dwordx4 v[186:189], v[134:135], off offset:128
	global_load_dwordx4 v[206:209], v[132:133], off
	global_load_dwordx4 v[210:213], v[132:133], off offset:128
	global_load_dwordx4 v[214:217], v205, s[22:23]
	v_add_u32_e32 v130, 0x10000, v205
	global_load_dwordx4 v[218:221], v130, s[22:23]
	global_load_dwordx4 v[222:225], v[136:137], off offset:128
	global_load_dwordx4 v[226:229], v205, s[22:23] offset:128
	v_add_u32_e32 v204, 0x10080, v205
	global_load_dwordx4 v[230:233], v204, s[22:23]
	v_add_u32_e32 v130, 0x20000, v205
	v_add_u32_e32 v154, 0x30000, v205
	v_add_u32_e32 v184, 0x20080, v205
	v_add_u32_e32 v182, 0x30080, v205
	global_load_dwordx4 v[142:145], v130, s[22:23]
	global_load_dwordx4 v[138:141], v154, s[22:23]
	global_load_dwordx4 v[134:137], v184, s[22:23]
	s_nop 0
	global_load_dwordx4 v[130:133], v182, s[22:23]
	ds_write_b128 v200, v[126:129]
	ds_write_b128 v200, v[122:125] offset:64
	v_and_b32_e32 v127, 64, v199
	ds_read_b128 v[122:125], v201
	ds_read_b128 v[234:237], v201 offset:1152
	v_xor_b32_e32 v126, 8, v199
	v_add_u32_e32 v183, 64, v127
	v_cmp_lt_i32_e32 vcc, v126, v183
	v_add_u32_e32 v185, 0x4000, v202
	v_lshlrev_b32_e32 v238, 2, v185
	v_cndmask_b32_e32 v126, v199, v126, vcc
	v_lshlrev_b32_e32 v203, 2, v126
	s_lshl_b64 s[16:17], s[8:9], 20
	s_add_u32 s20, s93, s16
	s_addc_u32 s21, s92, s17
	s_waitcnt vmcnt(0)
	v_pk_mul_f32 v[180:181], v[166:167], 0.5 op_sel_hi:[1,0]
	v_pk_mul_f32 v[176:177], v[168:169], 0.5 op_sel_hi:[1,0]
	v_pk_add_f32 v[126:127], v[208:209], 1.0 op_sel_hi:[1,0]
	v_pk_add_f32 v[128:129], v[206:207], 1.0 op_sel_hi:[1,0]
	v_pk_mul_f32 v[174:175], v[172:173], v[126:127]
	v_pk_mul_f32 v[178:179], v[170:171], v[128:129]
	s_waitcnt lgkmcnt(1)
	v_pk_fma_f32 v[126:127], v[180:181], v[122:123], v[214:215]
	s_waitcnt lgkmcnt(0)
	v_pk_fma_f32 v[122:123], v[180:181], v[234:235], v[218:219]
	v_pk_mul_f32 v[168:169], v[186:187], 0.5 op_sel_hi:[1,0]
	v_pk_fma_f32 v[128:129], v[176:177], v[124:125], v[216:217]
	v_pk_fma_f32 v[124:125], v[176:177], v[236:237], v[220:221]
	v_pk_mul_f32 v[186:187], v[178:179], v[122:123]
	v_pk_mul_f32 v[166:167], v[188:189], 0.5 op_sel_hi:[1,0]
	global_store_dwordx4 v205, v[126:129], s[22:23] nt
	v_pk_mul_f32 v[170:171], v[174:175], v[128:129]
	v_pk_mul_f32 v[172:173], v[178:179], v[126:127]
	v_pk_mul_f32 v[206:207], v[174:175], v[124:125]
	v_cvt_pk_bf16_f32 v188, v172, v173
	v_cvt_pk_bf16_f32 v189, v170, v171
	global_store_dwordx4 v238, v[122:125], s[22:23] nt
	v_cvt_pk_bf16_f32 v186, v186, v187
	v_cvt_pk_bf16_f32 v187, v206, v207
	ds_write_b128 v200, v[118:121]
	ds_write_b128 v200, v[114:117] offset:64
	ds_read_b128 v[114:117], v201
	ds_read_b128 v[206:209], v201 offset:1152
	v_pk_add_f32 v[190:191], v[212:213], 1.0 op_sel_hi:[1,0]
	v_pk_add_f32 v[118:119], v[210:211], 1.0 op_sel_hi:[1,0]
	v_pk_mul_f32 v[170:171], v[224:225], v[190:191]
	v_pk_mul_f32 v[172:173], v[222:223], v[118:119]
	s_waitcnt lgkmcnt(1)
	v_pk_fma_f32 v[120:121], v[166:167], v[116:117], v[228:229]
	v_pk_fma_f32 v[118:119], v[168:169], v[114:115], v[226:227]
	s_waitcnt lgkmcnt(0)
	v_pk_fma_f32 v[114:115], v[168:169], v[206:207], v[230:231]
	v_pk_mul_f32 v[190:191], v[170:171], v[120:121]
	v_pk_mul_f32 v[206:207], v[172:173], v[118:119]
	global_store_dwordx4 v205, v[118:121], s[22:23] offset:128 nt
	v_cvt_pk_bf16_f32 v206, v206, v207
	v_cvt_pk_bf16_f32 v191, v190, v191
	ds_bpermute_b32 v190, v203, v206
	ds_bpermute_b32 v191, v203, v191
	v_pk_fma_f32 v[116:117], v[166:167], v[208:209], v[232:233]
	v_pk_mul_f32 v[206:207], v[172:173], v[114:115]
	global_store_dwordx4 v204, v[114:117], s[22:23] nt
	v_cvt_pk_bf16_f32 v204, v206, v207
	v_lshlrev_b32_e32 v207, 1, v202
	v_pk_mul_f32 v[208:209], v[170:171], v[116:117]
	s_nop 0
	v_cvt_pk_bf16_f32 v206, v208, v209
	s_waitcnt lgkmcnt(0)
	v_add_u32_e32 v250, 0xfffff040, v207
	v_cndmask_b32_e64 v250, v207, v250, s[40:41]
	v_cndmask_b32_e64 v248, v188, v190, s[40:41]
	v_cndmask_b32_e64 v249, v189, v191, s[40:41]
	global_store_dwordx2 v250, v[248:249], s[20:21]
	v_cndmask_b32_e64 v246, v190, v188, s[40:41]
	v_cndmask_b32_e64 v247, v191, v189, s[40:41]
	s_waitcnt lgkmcnt(1)
	v_add_u32_e32 v190, 0x1040, v207
	v_cndmask_b32_e64 v190, v207, v190, s[38:39]
	global_store_dwordx2 v190, v[246:247], s[20:21]
	ds_bpermute_b32 v188, v203, v204
	ds_bpermute_b32 v189, v203, v206
	v_lshlrev_b32_e32 v206, 1, v185
	s_waitcnt lgkmcnt(0)
; #define LAS __attribute__((address_space(3)))
; #define ERN_EOFF(q, m) (eb + (unsigned)((((q) & 1) * HALF + (m) * 16) * DM + ERN_COL((q) >> 1)))
;     __device__ __forceinline__ void operator()(const f32x4 (&acc)[2][2][4][2], const Unit& u, int wr, int wc, int fr, int fq) const {
;     ...
;         ERN_LOADX(0);
; #pragma unroll
;         for (int g = 0; g < 8; ++g) { const int ai = g >> 2, m = g & 3;
;             if (g + 1 < 8) ERN_LOADX(g + 1);
;             float sq0 = 0.f, sq1 = 0.f; u32x2 hw[2][2];
; #pragma unroll
;             for (int bj = 0; bj < 2; ++bj) {
;                 *(LAS f32x4*)(st + wr_off) = acc[ai][bj][m][0]; *(LAS f32x4*)(st + wr_off + 64) = acc[ai][bj][m][1];
;                 const f32x4 a0 = *(const LAS f32x4*)(st + rd_off), a1 = *(const LAS f32x4*)(st + rd_off + 8 * 144);
;                 { const f32x4 xv = xb[g & 1][bj][0] + gv[bj] * a0; __builtin_nontemporal_store(xv, (f32x4*)((char*)xo + 4u * ERN_EOFF(g, bj, 0)));
;                   sq0 += (xv.x * xv.x + xv.y * xv.y) + (xv.z * xv.z + xv.w * xv.w);
;                   const f32x4 hv = xv * gsn[bj]; hw[bj][0].x = cvt_pk_bf16(hv.x, hv.y); hw[bj][0].y = cvt_pk_bf16(hv.z, hv.w); }
;                 { const f32x4 xv = xb[g & 1][bj][1] + gv[bj] * a1; __builtin_nontemporal_store(xv, (f32x4*)((char*)xo + 4u * ERN_EOFF(g, bj, 1)));
;                   sq1 += (xv.x * xv.x + xv.y * xv.y) + (xv.z * xv.z + xv.w * xv.w);
;                   const f32x4 hv = xv * gsn[bj]; hw[bj][1].x = cvt_pk_bf16(hv.x, hv.y); hw[bj][1].y = cvt_pk_bf16(hv.z, hv.w); }
;             }
;             if (!NOH && !PLAIN) {
; #pragma unroll
;                 for (int rh = 0; rh < 2; ++rh) { u32x2 rv; rv.x = __shfl_xor(hw[1][rh].x, 8); rv.y = __shfl_xor(hw[1][rh].y, 8);
;                     const unsigned e0 = ERN_EOFF(g, 0, rh);
;                     const unsigned ee = odd ? (e0 - DM + 32) : e0, eo2 = odd ? e0 : (e0 + DM + 32);
;                     *(u32x2*)((char*)ho + 2u * ee) = odd ? rv : hw[0][rh];
;                     *(u32x2*)((char*)ho + 2u * eo2) = odd ? hw[0][rh] : rv; }
;             }
;             if (!PLAIN) { sq0 += __shfl_xor(sq0, 1); sq0 += __shfl_xor(sq0, 2); sq0 += __shfl_xor(sq0, 4);
;             sq1 += __shfl_xor(sq1, 1); sq1 += __shfl_xor(sq1, 2); sq1 += __shfl_xor(sq1, 4); }
;             if (!PLAIN && pc == 0) { sst[g * 16 + rr] = sq0; sst[g * 16 + 8 + rr] = sq1; }
	v_add_u32_e32 v250, 0xfffff040, v206
	v_cndmask_b32_e64 v250, v206, v250, s[40:41]
	v_cndmask_b32_e64 v248, v186, v188, s[40:41]
	v_cndmask_b32_e64 v249, v187, v189, s[40:41]
	global_store_dwordx2 v250, v[248:249], s[20:21]
	v_cndmask_b32_e64 v246, v188, v186, s[40:41]
	v_cndmask_b32_e64 v247, v189, v187, s[40:41]
	v_mul_f32_e32 v119, v119, v119
	v_mul_f32_e32 v127, v127, v127
	v_mul_f32_e32 v129, v129, v129
	v_fmac_f32_e32 v119, v118, v118
	v_mul_f32_e32 v118, v121, v121
	v_fmac_f32_e32 v129, v128, v128
	v_fmac_f32_e32 v118, v120, v120
	v_mul_f32_e32 v115, v115, v115
	v_fmac_f32_e32 v127, v126, v126
	v_add_f32_e32 v118, v119, v118
	v_fmac_f32_e32 v115, v114, v114
	v_mul_f32_e32 v114, v117, v117
	v_add_f32_e32 v117, v127, v129
	v_add_f32_e32 v117, v117, v118
	v_xor_b32_e32 v118, 1, v199
	v_cmp_lt_i32_e32 vcc, v118, v183
	v_mul_f32_e32 v123, v123, v123
	v_mul_f32_e32 v125, v125, v125
	v_cndmask_b32_e32 v118, v199, v118, vcc
	v_lshlrev_b32_e32 v190, 2, v118
	ds_bpermute_b32 v118, v190, v117
	v_fmac_f32_e32 v114, v116, v116
	v_fmac_f32_e32 v125, v124, v124
	v_fmac_f32_e32 v123, v122, v122
	v_add_f32_e32 v114, v115, v114
	s_waitcnt lgkmcnt(0)
	v_add_f32_e32 v116, v117, v118
	v_xor_b32_e32 v117, 2, v199
	v_cmp_lt_i32_e32 vcc, v117, v183
	v_add_f32_e32 v115, v123, v125
	v_add_f32_e32 v115, v115, v114
	v_cndmask_b32_e32 v117, v199, v117, vcc
	v_lshlrev_b32_e32 v191, 2, v117
	ds_bpermute_b32 v117, v191, v116
	ds_bpermute_b32 v118, v190, v115
	s_waitcnt lgkmcnt(1)
	v_add_f32_e32 v114, v116, v117
	s_waitcnt lgkmcnt(0)
	v_add_f32_e32 v117, v115, v118
	ds_bpermute_b32 v118, v191, v117
	v_xor_b32_e32 v116, 4, v199
	v_cmp_lt_i32_e32 vcc, v116, v183
	s_nop 1
	v_cndmask_b32_e32 v115, v199, v116, vcc
	v_lshlrev_b32_e32 v204, 2, v115
	s_waitcnt lgkmcnt(0)
	v_add_f32_e32 v116, v117, v118
	ds_bpermute_b32 v115, v204, v114
	ds_bpermute_b32 v117, v204, v116
	v_add_u32_e32 v118, 0x1040, v206
	v_cndmask_b32_e64 v118, v206, v118, s[38:39]
	global_store_dwordx2 v118, v[246:247], s[20:21]
	s_and_saveexec_b64 s[16:17], s[42:43]
	s_cbranch_execz .LBB0_1608
	s_waitcnt lgkmcnt(1)
	v_add_f32_e32 v114, v114, v115
	s_waitcnt lgkmcnt(0)
	v_add_f32_e32 v115, v116, v117
	ds_write2_b32 v194, v114, v115 offset1:8
.LBB0_1608:
	s_or_b64 exec, exec, s[16:17]
	v_lshl_add_u64 v[206:207], s[22:23], 0, v[154:155]
	v_add_u32_e32 v114, 0x40000, v205
	v_add_u32_e32 v154, 0x50000, v205
	v_add_u32_e32 v186, 0x40080, v205
	global_load_dwordx4 v[122:125], v154, s[22:23]
	global_load_dwordx4 v[118:121], v186, s[22:23]
	v_add_u32_e32 v188, 0x50080, v205
	global_load_dwordx4 v[126:129], v114, s[22:23]
	s_waitcnt lgkmcnt(0)
	global_load_dwordx4 v[114:117], v188, s[22:23]
	ds_write_b128 v200, v[110:113]
	ds_write_b128 v200, v[106:109] offset:64
	ds_read_b128 v[106:109], v201
	ds_read_b128 v[110:113], v201 offset:1152
	v_mov_b32_e32 v185, v155
	v_mov_b32_e32 v183, v155
	v_lshl_add_u64 v[182:183], s[22:23], 0, v[182:183]
	s_waitcnt lgkmcnt(1)
	v_pk_fma_f32 v[108:109], v[176:177], v[108:109], v[144:145]
	v_add_u32_e32 v144, 0x8000, v202
	v_pk_fma_f32 v[106:107], v[180:181], v[106:107], v[142:143]
	v_lshlrev_b32_e32 v142, 2, v144
	s_waitcnt lgkmcnt(0)
	v_pk_fma_f32 v[110:111], v[180:181], v[110:111], v[138:139]
	global_store_dwordx4 v142, v[106:109], s[22:23] nt
	v_pk_mul_f32 v[142:143], v[178:179], v[106:107]
	v_pk_fma_f32 v[112:113], v[176:177], v[112:113], v[140:141]
	v_pk_mul_f32 v[138:139], v[178:179], v[110:111]
	v_pk_mul_f32 v[208:209], v[174:175], v[108:109]
	v_cvt_pk_bf16_f32 v142, v142, v143
	v_pk_mul_f32 v[140:141], v[174:175], v[112:113]
	v_cvt_pk_bf16_f32 v143, v208, v209
	global_store_dwordx4 v[206:207], v[110:113], off nt
	v_cvt_pk_bf16_f32 v138, v138, v139
	v_cvt_pk_bf16_f32 v139, v140, v141
	ds_write_b128 v200, v[102:105]
	ds_write_b128 v200, v[98:101] offset:64
	ds_read_b128 v[98:101], v201
	ds_read_b128 v[102:105], v201 offset:1152
	v_lshl_add_u64 v[140:141], s[22:23], 0, v[184:185]
	s_waitcnt lgkmcnt(1)
	v_pk_fma_f32 v[98:99], v[168:169], v[98:99], v[134:135]
	v_pk_fma_f32 v[100:101], v[166:167], v[100:101], v[136:137]
	v_pk_mul_f32 v[136:137], v[172:173], v[98:99]
	global_store_dwordx4 v[140:141], v[98:101], off nt
	v_pk_mul_f32 v[134:135], v[170:171], v[100:101]
	v_cvt_pk_bf16_f32 v136, v136, v137
	s_waitcnt lgkmcnt(0)
	v_pk_fma_f32 v[102:103], v[168:169], v[102:103], v[130:131]
	v_cvt_pk_bf16_f32 v137, v134, v135
	ds_bpermute_b32 v130, v203, v136
	ds_bpermute_b32 v131, v203, v137
	v_pk_fma_f32 v[104:105], v[166:167], v[104:105], v[132:133]
	v_pk_mul_f32 v[132:133], v[172:173], v[102:103]
	v_pk_mul_f32 v[134:135], v[170:171], v[104:105]
	global_store_dwordx4 v[182:183], v[102:105], off nt
	v_cvt_pk_bf16_f32 v132, v132, v133
	v_cvt_pk_bf16_f32 v133, v134, v135
	v_lshlrev_b32_e32 v134, 1, v144
	s_waitcnt lgkmcnt(0)
	v_add_u32_e32 v250, 0xfffff040, v134
	v_cndmask_b32_e64 v250, v134, v250, s[40:41]
	v_cndmask_b32_e64 v248, v142, v130, s[40:41]
	v_cndmask_b32_e64 v249, v143, v131, s[40:41]
	global_store_dwordx2 v250, v[248:249], s[20:21]
	v_cndmask_b32_e64 v246, v130, v142, s[40:41]
	v_cndmask_b32_e64 v247, v131, v143, s[40:41]
	s_waitcnt lgkmcnt(1)
	v_add_u32_e32 v130, 0x1040, v134
	v_cndmask_b32_e64 v130, v134, v130, s[38:39]
	global_store_dwordx2 v130, v[246:247], s[20:21]
	ds_bpermute_b32 v130, v203, v132
	s_waitcnt lgkmcnt(1)
	ds_bpermute_b32 v131, v203, v133
	v_add_u32_e32 v133, 0xc000, v202
	v_lshlrev_b32_e32 v132, 1, v133
	s_waitcnt lgkmcnt(0)
	v_add_u32_e32 v250, 0xfffff040, v132
	v_cndmask_b32_e64 v250, v132, v250, s[40:41]
	v_cndmask_b32_e64 v248, v138, v130, s[40:41]
	v_cndmask_b32_e64 v249, v139, v131, s[40:41]
	global_store_dwordx2 v250, v[248:249], s[20:21]
	v_cndmask_b32_e64 v246, v130, v138, s[40:41]
	v_cndmask_b32_e64 v247, v131, v139, s[40:41]
	v_mul_f32_e32 v99, v99, v99
	v_fmac_f32_e32 v99, v98, v98
	v_mul_f32_e32 v98, v101, v101
	v_mul_f32_e32 v109, v109, v109
	v_fmac_f32_e32 v98, v100, v100
	v_mul_f32_e32 v107, v107, v107
	v_fmac_f32_e32 v109, v108, v108
	v_mul_f32_e32 v108, v111, v111
	v_mul_f32_e32 v111, v113, v113
	v_add_f32_e32 v98, v99, v98
	v_mul_f32_e32 v99, v103, v103
	v_mul_f32_e32 v100, v105, v105
	v_fmac_f32_e32 v111, v112, v112
	v_fmac_f32_e32 v99, v102, v102
	v_fmac_f32_e32 v100, v104, v104
	v_fmac_f32_e32 v107, v106, v106
	v_fmac_f32_e32 v108, v110, v110
	v_add_f32_e32 v99, v99, v100
	v_add_f32_e32 v100, v107, v109
	v_add_f32_e32 v101, v108, v111
	v_add_f32_e32 v98, v100, v98
	v_add_f32_e32 v99, v101, v99
	ds_bpermute_b32 v100, v190, v98
	ds_bpermute_b32 v101, v190, v99
	s_waitcnt lgkmcnt(1)
	v_add_f32_e32 v98, v98, v100
	s_waitcnt lgkmcnt(0)
	v_add_f32_e32 v101, v99, v101
	ds_bpermute_b32 v100, v191, v98
	ds_bpermute_b32 v102, v191, v101
	s_waitcnt lgkmcnt(1)
	v_add_f32_e32 v98, v98, v100
	s_waitcnt lgkmcnt(0)
	v_add_f32_e32 v100, v101, v102
	ds_bpermute_b32 v99, v204, v98
	ds_bpermute_b32 v101, v204, v100
	v_add_u32_e32 v102, 0x1040, v132
	v_cndmask_b32_e64 v102, v132, v102, s[38:39]
	global_store_dwordx2 v102, v[246:247], s[20:21]
	s_and_saveexec_b64 s[16:17], s[42:43]
	s_cbranch_execz .LBB0_1618
; #define LAS __attribute__((address_space(3)))
; #define ERN_EOFF(q, m) (eb + (unsigned)((((q) & 1) * HALF + (m) * 16) * DM + ERN_COL((q) >> 1)))
;     __device__ __forceinline__ void operator()(const f32x4 (&acc)[2][2][4][2], const Unit& u, int wr, int wc, int fr, int fq) const {
;     ...
;         ERN_LOADX(0);
; #pragma unroll
;         for (int g = 0; g < 8; ++g) { const int ai = g >> 2, m = g & 3;
;             if (g + 1 < 8) ERN_LOADX(g + 1);
;             float sq0 = 0.f, sq1 = 0.f; u32x2 hw[2][2];
; #pragma unroll
;             for (int bj = 0; bj < 2; ++bj) {
;                 *(LAS f32x4*)(st + wr_off) = acc[ai][bj][m][0]; *(LAS f32x4*)(st + wr_off + 64) = acc[ai][bj][m][1];
;                 const f32x4 a0 = *(const LAS f32x4*)(st + rd_off), a1 = *(const LAS f32x4*)(st + rd_off + 8 * 144);
;                 { const f32x4 xv = xb[g & 1][bj][0] + gv[bj] * a0; __builtin_nontemporal_store(xv, (f32x4*)((char*)xo + 4u * ERN_EOFF(g, bj, 0)));
;                   sq0 += (xv.x * xv.x + xv.y * xv.y) + (xv.z * xv.z + xv.w * xv.w);
;                   const f32x4 hv = xv * gsn[bj]; hw[bj][0].x = cvt_pk_bf16(hv.x, hv.y); hw[bj][0].y = cvt_pk_bf16(hv.z, hv.w); }
;                 { const f32x4 xv = xb[g & 1][bj][1] + gv[bj] * a1; __builtin_nontemporal_store(xv, (f32x4*)((char*)xo + 4u * ERN_EOFF(g, bj, 1)));
;                   sq1 += (xv.x * xv.x + xv.y * xv.y) + (xv.z * xv.z + xv.w * xv.w);
;                   const f32x4 hv = xv * gsn[bj]; hw[bj][1].x = cvt_pk_bf16(hv.x, hv.y); hw[bj][1].y = cvt_pk_bf16(hv.z, hv.w); }
;             }
;             if (!NOH && !PLAIN) {
; #pragma unroll
;                 for (int rh = 0; rh < 2; ++rh) { u32x2 rv; rv.x = __shfl_xor(hw[1][rh].x, 8); rv.y = __shfl_xor(hw[1][rh].y, 8);
;                     const unsigned e0 = ERN_EOFF(g, 0, rh);
;                     const unsigned ee = odd ? (e0 - DM + 32) : e0, eo2 = odd ? e0 : (e0 + DM + 32);
;                     *(u32x2*)((char*)ho + 2u * ee) = odd ? rv : hw[0][rh];
;                     *(u32x2*)((char*)ho + 2u * eo2) = odd ? hw[0][rh] : rv; }
;             }
;             if (!PLAIN) { sq0 += __shfl_xor(sq0, 1); sq0 += __shfl_xor(sq0, 2); sq0 += __shfl_xor(sq0, 4);
;             sq1 += __shfl_xor(sq1, 1); sq1 += __shfl_xor(sq1, 2); sq1 += __shfl_xor(sq1, 4); }
;             if (!PLAIN && pc == 0) { sst[g * 16 + rr] = sq0; sst[g * 16 + 8 + rr] = sq1; }
	s_waitcnt lgkmcnt(1)
	v_add_f32_e32 v98, v98, v99
	s_waitcnt lgkmcnt(0)
	v_add_f32_e32 v99, v100, v101
	ds_write2_b32 v194, v98, v99 offset0:16 offset1:24
.LBB0_1618:
	s_or_b64 exec, exec, s[16:17]
	v_lshl_add_u64 v[134:135], s[22:23], 0, v[154:155]
	v_add_u32_e32 v98, 0x60000, v205
	v_add_u32_e32 v154, 0x70000, v205
	v_add_u32_e32 v130, 0x60080, v205
	global_load_dwordx4 v[106:109], v154, s[22:23]
	global_load_dwordx4 v[102:105], v130, s[22:23]
	v_add_u32_e32 v132, 0x70080, v205
	global_load_dwordx4 v[110:113], v98, s[22:23]
	s_waitcnt lgkmcnt(0)
	global_load_dwordx4 v[98:101], v132, s[22:23]
	ds_write_b128 v200, v[94:97]
	ds_write_b128 v200, v[90:93] offset:64
	ds_read_b128 v[90:93], v201
	ds_read_b128 v[94:97], v201 offset:1152
	v_mov_b32_e32 v187, v155
	v_mov_b32_e32 v189, v155
	s_waitcnt vmcnt(11) lgkmcnt(1)
	v_pk_fma_f32 v[92:93], v[176:177], v[92:93], v[128:129]
	v_add_u32_e32 v128, 0x10000, v202
	v_pk_fma_f32 v[90:91], v[180:181], v[90:91], v[126:127]
	v_lshlrev_b32_e32 v126, 2, v128
	s_waitcnt lgkmcnt(0)
	v_pk_fma_f32 v[94:95], v[180:181], v[94:95], v[122:123]
	global_store_dwordx4 v126, v[90:93], s[22:23] nt
	v_pk_mul_f32 v[126:127], v[178:179], v[90:91]
	v_pk_fma_f32 v[96:97], v[176:177], v[96:97], v[124:125]
	v_pk_mul_f32 v[122:123], v[178:179], v[94:95]
	v_pk_mul_f32 v[136:137], v[174:175], v[92:93]
	v_cvt_pk_bf16_f32 v126, v126, v127
	v_pk_mul_f32 v[124:125], v[174:175], v[96:97]
	v_cvt_pk_bf16_f32 v127, v136, v137
	global_store_dwordx4 v[134:135], v[94:97], off nt
	v_cvt_pk_bf16_f32 v122, v122, v123
	v_cvt_pk_bf16_f32 v123, v124, v125
	ds_write_b128 v200, v[86:89]
	ds_write_b128 v200, v[82:85] offset:64
	ds_read_b128 v[82:85], v201
	ds_read_b128 v[86:89], v201 offset:1152
	v_lshl_add_u64 v[124:125], s[22:23], 0, v[186:187]
	v_lshl_add_u64 v[134:135], s[22:23], 0, v[188:189]
	s_waitcnt lgkmcnt(1)
	v_pk_fma_f32 v[82:83], v[168:169], v[82:83], v[118:119]
	v_pk_fma_f32 v[84:85], v[166:167], v[84:85], v[120:121]
	v_pk_mul_f32 v[120:121], v[172:173], v[82:83]
	global_store_dwordx4 v[124:125], v[82:85], off nt
	v_pk_mul_f32 v[118:119], v[170:171], v[84:85]
	v_cvt_pk_bf16_f32 v120, v120, v121
	s_waitcnt vmcnt(13) lgkmcnt(0)
	v_pk_fma_f32 v[86:87], v[168:169], v[86:87], v[114:115]
	v_cvt_pk_bf16_f32 v121, v118, v119
	ds_bpermute_b32 v114, v203, v120
	ds_bpermute_b32 v115, v203, v121
	v_pk_fma_f32 v[88:89], v[166:167], v[88:89], v[116:117]
	v_pk_mul_f32 v[116:117], v[172:173], v[86:87]
	v_pk_mul_f32 v[118:119], v[170:171], v[88:89]
	global_store_dwordx4 v[134:135], v[86:89], off nt
	v_cvt_pk_bf16_f32 v116, v116, v117
	v_cvt_pk_bf16_f32 v117, v118, v119
	v_lshlrev_b32_e32 v118, 1, v128
	s_waitcnt lgkmcnt(0)
	v_add_u32_e32 v250, 0xfffff040, v118
	v_cndmask_b32_e64 v250, v118, v250, s[40:41]
	v_cndmask_b32_e64 v248, v126, v114, s[40:41]
	v_cndmask_b32_e64 v249, v127, v115, s[40:41]
	global_store_dwordx2 v250, v[248:249], s[20:21]
	v_cndmask_b32_e64 v246, v114, v126, s[40:41]
	v_cndmask_b32_e64 v247, v115, v127, s[40:41]
	s_waitcnt lgkmcnt(1)
	v_add_u32_e32 v114, 0x1040, v118
	v_cndmask_b32_e64 v114, v118, v114, s[38:39]
	global_store_dwordx2 v114, v[246:247], s[20:21]
	ds_bpermute_b32 v114, v203, v116
	s_waitcnt lgkmcnt(1)
	ds_bpermute_b32 v115, v203, v117
	v_add_u32_e32 v117, 0x14000, v202
	v_lshlrev_b32_e32 v116, 1, v117
	s_waitcnt lgkmcnt(0)
	v_add_u32_e32 v250, 0xfffff040, v116
	v_cndmask_b32_e64 v250, v116, v250, s[40:41]
	v_cndmask_b32_e64 v248, v122, v114, s[40:41]
	v_cndmask_b32_e64 v249, v123, v115, s[40:41]
	global_store_dwordx2 v250, v[248:249], s[20:21]
	v_cndmask_b32_e64 v246, v114, v122, s[40:41]
	v_cndmask_b32_e64 v247, v115, v123, s[40:41]
	v_mul_f32_e32 v83, v83, v83
	v_fmac_f32_e32 v83, v82, v82
	v_mul_f32_e32 v82, v85, v85
	v_mul_f32_e32 v93, v93, v93
	v_fmac_f32_e32 v82, v84, v84
	v_mul_f32_e32 v91, v91, v91
	v_fmac_f32_e32 v93, v92, v92
	v_mul_f32_e32 v92, v95, v95
	v_mul_f32_e32 v95, v97, v97
	v_add_f32_e32 v82, v83, v82
	v_mul_f32_e32 v83, v87, v87
	v_mul_f32_e32 v84, v89, v89
	v_fmac_f32_e32 v95, v96, v96
	v_fmac_f32_e32 v83, v86, v86
	v_fmac_f32_e32 v84, v88, v88
	v_fmac_f32_e32 v91, v90, v90
	v_fmac_f32_e32 v92, v94, v94
	v_add_f32_e32 v83, v83, v84
	v_add_f32_e32 v84, v91, v93
	v_add_f32_e32 v85, v92, v95
	v_add_f32_e32 v82, v84, v82
	v_add_f32_e32 v83, v85, v83
	ds_bpermute_b32 v84, v190, v82
	ds_bpermute_b32 v85, v190, v83
	s_waitcnt lgkmcnt(1)
	v_add_f32_e32 v82, v82, v84
	s_waitcnt lgkmcnt(0)
	v_add_f32_e32 v85, v83, v85
	ds_bpermute_b32 v84, v191, v82
	ds_bpermute_b32 v86, v191, v85
	s_waitcnt lgkmcnt(1)
	v_add_f32_e32 v82, v82, v84
	s_waitcnt lgkmcnt(0)
	v_add_f32_e32 v84, v85, v86
	ds_bpermute_b32 v83, v204, v82
	ds_bpermute_b32 v85, v204, v84
	v_add_u32_e32 v86, 0x1040, v116
	v_cndmask_b32_e64 v86, v116, v86, s[38:39]
	global_store_dwordx2 v86, v[246:247], s[20:21]
	s_and_saveexec_b64 s[16:17], s[42:43]
	s_cbranch_execz .LBB0_1628
	s_waitcnt lgkmcnt(1)
	v_add_f32_e32 v82, v82, v83
	s_waitcnt lgkmcnt(0)
	v_add_f32_e32 v83, v84, v85
	ds_write2_b32 v194, v82, v83 offset0:32 offset1:40
; #define LAS __attribute__((address_space(3)))
; #define ERN_EOFF(q, m) (eb + (unsigned)((((q) & 1) * HALF + (m) * 16) * DM + ERN_COL((q) >> 1)))
;     __device__ __forceinline__ void operator()(const f32x4 (&acc)[2][2][4][2], const Unit& u, int wr, int wc, int fr, int fq) const {
;     ...
;         ERN_LOADX(0);
; #pragma unroll
;         for (int g = 0; g < 8; ++g) { const int ai = g >> 2, m = g & 3;
;             if (g + 1 < 8) ERN_LOADX(g + 1);
;             float sq0 = 0.f, sq1 = 0.f; u32x2 hw[2][2];
; #pragma unroll
;             for (int bj = 0; bj < 2; ++bj) {
;                 *(LAS f32x4*)(st + wr_off) = acc[ai][bj][m][0]; *(LAS f32x4*)(st + wr_off + 64) = acc[ai][bj][m][1];
;                 const f32x4 a0 = *(const LAS f32x4*)(st + rd_off), a1 = *(const LAS f32x4*)(st + rd_off + 8 * 144);
;                 { const f32x4 xv = xb[g & 1][bj][0] + gv[bj] * a0; __builtin_nontemporal_store(xv, (f32x4*)((char*)xo + 4u * ERN_EOFF(g, bj, 0)));
;                   sq0 += (xv.x * xv.x + xv.y * xv.y) + (xv.z * xv.z + xv.w * xv.w);
;                   const f32x4 hv = xv * gsn[bj]; hw[bj][0].x = cvt_pk_bf16(hv.x, hv.y); hw[bj][0].y = cvt_pk_bf16(hv.z, hv.w); }
;                 { const f32x4 xv = xb[g & 1][bj][1] + gv[bj] * a1; __builtin_nontemporal_store(xv, (f32x4*)((char*)xo + 4u * ERN_EOFF(g, bj, 1)));
;                   sq1 += (xv.x * xv.x + xv.y * xv.y) + (xv.z * xv.z + xv.w * xv.w);
;                   const f32x4 hv = xv * gsn[bj]; hw[bj][1].x = cvt_pk_bf16(hv.x, hv.y); hw[bj][1].y = cvt_pk_bf16(hv.z, hv.w); }
;             }
;             if (!NOH && !PLAIN) {
; #pragma unroll
;                 for (int rh = 0; rh < 2; ++rh) { u32x2 rv; rv.x = __shfl_xor(hw[1][rh].x, 8); rv.y = __shfl_xor(hw[1][rh].y, 8);
;                     const unsigned e0 = ERN_EOFF(g, 0, rh);
;                     const unsigned ee = odd ? (e0 - DM + 32) : e0, eo2 = odd ? e0 : (e0 + DM + 32);
;                     *(u32x2*)((char*)ho + 2u * ee) = odd ? rv : hw[0][rh];
;                     *(u32x2*)((char*)ho + 2u * eo2) = odd ? hw[0][rh] : rv; }
;             }
;             if (!PLAIN) { sq0 += __shfl_xor(sq0, 1); sq0 += __shfl_xor(sq0, 2); sq0 += __shfl_xor(sq0, 4);
;             sq1 += __shfl_xor(sq1, 1); sq1 += __shfl_xor(sq1, 2); sq1 += __shfl_xor(sq1, 4); }
;             if (!PLAIN && pc == 0) { sst[g * 16 + rr] = sq0; sst[g * 16 + 8 + rr] = sq1; }
.LBB0_1628:
	s_or_b64 exec, exec, s[16:17]
	v_lshl_add_u64 v[116:117], s[22:23], 0, v[154:155]
	v_add_u32_e32 v82, 0x100000, v205
	s_waitcnt lgkmcnt(1)
	v_add_u32_e32 v83, 0x110000, v205
	v_add_u32_e32 v154, 0x100080, v205
	global_load_dwordx4 v[94:97], v82, s[22:23]
	global_load_dwordx4 v[90:93], v83, s[22:23]
	v_add_u32_e32 v114, 0x110080, v205
	global_load_dwordx4 v[86:89], v154, s[22:23]
	s_waitcnt lgkmcnt(0)
	global_load_dwordx4 v[82:85], v114, s[22:23]
	ds_write_b128 v200, v[78:81]
	ds_write_b128 v200, v[74:77] offset:64
	ds_read_b128 v[74:77], v201
	ds_read_b128 v[78:81], v201 offset:1152
	v_mov_b32_e32 v131, v155
	v_mov_b32_e32 v133, v155
	s_waitcnt vmcnt(11) lgkmcnt(1)
	v_pk_fma_f32 v[76:77], v[176:177], v[76:77], v[112:113]
	v_add_u32_e32 v112, 0x18000, v202
	v_pk_fma_f32 v[74:75], v[180:181], v[74:75], v[110:111]
	v_lshlrev_b32_e32 v110, 2, v112
	s_waitcnt lgkmcnt(0)
	v_pk_fma_f32 v[78:79], v[180:181], v[78:79], v[106:107]
	global_store_dwordx4 v110, v[74:77], s[22:23] nt
	v_pk_mul_f32 v[110:111], v[178:179], v[74:75]
	v_pk_fma_f32 v[80:81], v[176:177], v[80:81], v[108:109]
	v_pk_mul_f32 v[106:107], v[178:179], v[78:79]
	v_pk_mul_f32 v[118:119], v[174:175], v[76:77]
	v_cvt_pk_bf16_f32 v110, v110, v111
	v_pk_mul_f32 v[108:109], v[174:175], v[80:81]
	v_cvt_pk_bf16_f32 v111, v118, v119
	global_store_dwordx4 v[116:117], v[78:81], off nt
	v_cvt_pk_bf16_f32 v106, v106, v107
	v_cvt_pk_bf16_f32 v107, v108, v109
	ds_write_b128 v200, v[70:73]
	ds_write_b128 v200, v[66:69] offset:64
	ds_read_b128 v[66:69], v201
	ds_read_b128 v[70:73], v201 offset:1152
	v_lshl_add_u64 v[108:109], s[22:23], 0, v[130:131]
	v_lshl_add_u64 v[116:117], s[22:23], 0, v[132:133]
	s_waitcnt lgkmcnt(1)
	v_pk_fma_f32 v[66:67], v[168:169], v[66:67], v[102:103]
	v_pk_fma_f32 v[68:69], v[166:167], v[68:69], v[104:105]
	v_pk_mul_f32 v[104:105], v[172:173], v[66:67]
	global_store_dwordx4 v[108:109], v[66:69], off nt
	v_pk_mul_f32 v[102:103], v[170:171], v[68:69]
	v_cvt_pk_bf16_f32 v104, v104, v105
	s_waitcnt vmcnt(13) lgkmcnt(0)
	v_pk_fma_f32 v[70:71], v[168:169], v[70:71], v[98:99]
	v_cvt_pk_bf16_f32 v105, v102, v103
	ds_bpermute_b32 v98, v203, v104
	ds_bpermute_b32 v99, v203, v105
	v_pk_fma_f32 v[72:73], v[166:167], v[72:73], v[100:101]
	v_pk_mul_f32 v[100:101], v[172:173], v[70:71]
	v_pk_mul_f32 v[102:103], v[170:171], v[72:73]
	global_store_dwordx4 v[116:117], v[70:73], off nt
	v_cvt_pk_bf16_f32 v100, v100, v101
	v_cvt_pk_bf16_f32 v101, v102, v103
	v_lshlrev_b32_e32 v102, 1, v112
	s_waitcnt lgkmcnt(0)
	v_add_u32_e32 v250, 0xfffff040, v102
	v_cndmask_b32_e64 v250, v102, v250, s[40:41]
	v_cndmask_b32_e64 v248, v110, v98, s[40:41]
	v_cndmask_b32_e64 v249, v111, v99, s[40:41]
	global_store_dwordx2 v250, v[248:249], s[20:21]
	v_cndmask_b32_e64 v246, v98, v110, s[40:41]
	v_cndmask_b32_e64 v247, v99, v111, s[40:41]
	s_waitcnt lgkmcnt(1)
	v_add_u32_e32 v98, 0x1040, v102
	v_cndmask_b32_e64 v98, v102, v98, s[38:39]
	global_store_dwordx2 v98, v[246:247], s[20:21]
	ds_bpermute_b32 v98, v203, v100
	s_waitcnt lgkmcnt(1)
	ds_bpermute_b32 v99, v203, v101
	v_add_u32_e32 v101, 0x1c000, v202
	v_lshlrev_b32_e32 v100, 1, v101
	s_waitcnt lgkmcnt(0)
	v_add_u32_e32 v250, 0xfffff040, v100
	v_cndmask_b32_e64 v250, v100, v250, s[40:41]
	v_cndmask_b32_e64 v248, v106, v98, s[40:41]
	v_cndmask_b32_e64 v249, v107, v99, s[40:41]
	global_store_dwordx2 v250, v[248:249], s[20:21]
	v_cndmask_b32_e64 v246, v98, v106, s[40:41]
	v_cndmask_b32_e64 v247, v99, v107, s[40:41]
	v_mul_f32_e32 v67, v67, v67
	v_fmac_f32_e32 v67, v66, v66
	v_mul_f32_e32 v66, v69, v69
	v_mul_f32_e32 v77, v77, v77
	v_fmac_f32_e32 v66, v68, v68
	v_mul_f32_e32 v75, v75, v75
	v_fmac_f32_e32 v77, v76, v76
	v_mul_f32_e32 v76, v79, v79
	v_mul_f32_e32 v79, v81, v81
	v_add_f32_e32 v66, v67, v66
	v_mul_f32_e32 v67, v71, v71
	v_mul_f32_e32 v68, v73, v73
	v_fmac_f32_e32 v79, v80, v80
	v_fmac_f32_e32 v67, v70, v70
	v_fmac_f32_e32 v68, v72, v72
	v_fmac_f32_e32 v75, v74, v74
	v_fmac_f32_e32 v76, v78, v78
	v_add_f32_e32 v67, v67, v68
	v_add_f32_e32 v68, v75, v77
	v_add_f32_e32 v69, v76, v79
	v_add_f32_e32 v66, v68, v66
	v_add_f32_e32 v67, v69, v67
	ds_bpermute_b32 v68, v190, v66
	ds_bpermute_b32 v69, v190, v67
	s_waitcnt lgkmcnt(1)
	v_add_f32_e32 v66, v66, v68
	s_waitcnt lgkmcnt(0)
	v_add_f32_e32 v69, v67, v69
	ds_bpermute_b32 v68, v191, v66
	ds_bpermute_b32 v70, v191, v69
	s_waitcnt lgkmcnt(1)
	v_add_f32_e32 v66, v66, v68
	s_waitcnt lgkmcnt(0)
	v_add_f32_e32 v68, v69, v70
	ds_bpermute_b32 v67, v204, v66
	ds_bpermute_b32 v69, v204, v68
	v_add_u32_e32 v70, 0x1040, v100
	v_cndmask_b32_e64 v70, v100, v70, s[38:39]
	global_store_dwordx2 v70, v[246:247], s[20:21]
	s_and_saveexec_b64 s[16:17], s[42:43]
	s_cbranch_execz .LBB0_1638
	s_waitcnt lgkmcnt(1)
	v_add_f32_e32 v66, v66, v67
	s_waitcnt lgkmcnt(0)
	v_add_f32_e32 v67, v68, v69
	ds_write2_b32 v194, v66, v67 offset0:48 offset1:56
; #define LAS __attribute__((address_space(3)))
; #define ERN_EOFF(q, m) (eb + (unsigned)((((q) & 1) * HALF + (m) * 16) * DM + ERN_COL((q) >> 1)))
;     __device__ __forceinline__ void operator()(const f32x4 (&acc)[2][2][4][2], const Unit& u, int wr, int wc, int fr, int fq) const {
;     ...
;         ERN_LOADX(0);
; #pragma unroll
;         for (int g = 0; g < 8; ++g) { const int ai = g >> 2, m = g & 3;
;             if (g + 1 < 8) ERN_LOADX(g + 1);
;             float sq0 = 0.f, sq1 = 0.f; u32x2 hw[2][2];
; #pragma unroll
;             for (int bj = 0; bj < 2; ++bj) {
;                 *(LAS f32x4*)(st + wr_off) = acc[ai][bj][m][0]; *(LAS f32x4*)(st + wr_off + 64) = acc[ai][bj][m][1];
;                 const f32x4 a0 = *(const LAS f32x4*)(st + rd_off), a1 = *(const LAS f32x4*)(st + rd_off + 8 * 144);
;                 { const f32x4 xv = xb[g & 1][bj][0] + gv[bj] * a0; __builtin_nontemporal_store(xv, (f32x4*)((char*)xo + 4u * ERN_EOFF(g, bj, 0)));
;                   sq0 += (xv.x * xv.x + xv.y * xv.y) + (xv.z * xv.z + xv.w * xv.w);
;                   const f32x4 hv = xv * gsn[bj]; hw[bj][0].x = cvt_pk_bf16(hv.x, hv.y); hw[bj][0].y = cvt_pk_bf16(hv.z, hv.w); }
;                 { const f32x4 xv = xb[g & 1][bj][1] + gv[bj] * a1; __builtin_nontemporal_store(xv, (f32x4*)((char*)xo + 4u * ERN_EOFF(g, bj, 1)));
;                   sq1 += (xv.x * xv.x + xv.y * xv.y) + (xv.z * xv.z + xv.w * xv.w);
;                   const f32x4 hv = xv * gsn[bj]; hw[bj][1].x = cvt_pk_bf16(hv.x, hv.y); hw[bj][1].y = cvt_pk_bf16(hv.z, hv.w); }
;             }
;             if (!NOH && !PLAIN) {
; #pragma unroll
;                 for (int rh = 0; rh < 2; ++rh) { u32x2 rv; rv.x = __shfl_xor(hw[1][rh].x, 8); rv.y = __shfl_xor(hw[1][rh].y, 8);
;                     const unsigned e0 = ERN_EOFF(g, 0, rh);
;                     const unsigned ee = odd ? (e0 - DM + 32) : e0, eo2 = odd ? e0 : (e0 + DM + 32);
;                     *(u32x2*)((char*)ho + 2u * ee) = odd ? rv : hw[0][rh];
;                     *(u32x2*)((char*)ho + 2u * eo2) = odd ? hw[0][rh] : rv; }
;             }
;             if (!PLAIN) { sq0 += __shfl_xor(sq0, 1); sq0 += __shfl_xor(sq0, 2); sq0 += __shfl_xor(sq0, 4);
;             sq1 += __shfl_xor(sq1, 1); sq1 += __shfl_xor(sq1, 2); sq1 += __shfl_xor(sq1, 4); }
;             if (!PLAIN && pc == 0) { sst[g * 16 + rr] = sq0; sst[g * 16 + 8 + rr] = sq1; }
.LBB0_1638:
	s_or_b64 exec, exec, s[16:17]
	v_lshl_add_u64 v[104:105], s[22:23], 0, v[154:155]
	v_add_u32_e32 v154, 0x120000, v205
	v_add_u32_e32 v100, 0x120080, v205
	v_add_u32_e32 v102, 0x130000, v205
	global_load_dwordx4 v[78:81], v154, s[22:23]
	global_load_dwordx4 v[74:77], v102, s[22:23]
	v_add_u32_e32 v98, 0x130080, v205
	global_load_dwordx4 v[70:73], v100, s[22:23]
	s_waitcnt lgkmcnt(0)
	global_load_dwordx4 v[66:69], v98, s[22:23]
	ds_write_b128 v200, v[62:65]
	ds_write_b128 v200, v[58:61] offset:64
	ds_read_b128 v[58:61], v201
	ds_read_b128 v[62:65], v201 offset:1152
	v_mov_b32_e32 v115, v155
	s_waitcnt vmcnt(13) lgkmcnt(1)
	v_pk_fma_f32 v[60:61], v[176:177], v[60:61], v[96:97]
	v_add_u32_e32 v96, 0x40000, v202
	v_pk_fma_f32 v[58:59], v[180:181], v[58:59], v[94:95]
	v_lshlrev_b32_e32 v94, 2, v96
	s_waitcnt vmcnt(12) lgkmcnt(0)
	v_pk_fma_f32 v[64:65], v[176:177], v[64:65], v[92:93]
	v_add_u32_e32 v92, 0x44000, v202
	global_store_dwordx4 v94, v[58:61], s[22:23] nt
	v_pk_mul_f32 v[94:95], v[178:179], v[58:59]
	v_pk_fma_f32 v[62:63], v[180:181], v[62:63], v[90:91]
	v_lshlrev_b32_e32 v90, 2, v92
	v_pk_mul_f32 v[106:107], v[174:175], v[60:61]
	v_cvt_pk_bf16_f32 v94, v94, v95
	s_nop 0
	v_cvt_pk_bf16_f32 v95, v106, v107
	global_store_dwordx4 v90, v[62:65], s[22:23] nt
	v_pk_mul_f32 v[90:91], v[178:179], v[62:63]
	v_pk_mul_f32 v[106:107], v[174:175], v[64:65]
	v_cvt_pk_bf16_f32 v90, v90, v91
	s_nop 0
	v_cvt_pk_bf16_f32 v91, v106, v107
	ds_write_b128 v200, v[54:57]
	ds_write_b128 v200, v[50:53] offset:64
	ds_read_b128 v[50:53], v201
	ds_read_b128 v[54:57], v201 offset:1152
	v_lshl_add_u64 v[106:107], s[22:23], 0, v[114:115]
	s_waitcnt vmcnt(13) lgkmcnt(1)
	v_pk_fma_f32 v[50:51], v[168:169], v[50:51], v[86:87]
	v_pk_fma_f32 v[52:53], v[166:167], v[52:53], v[88:89]
	v_pk_mul_f32 v[88:89], v[172:173], v[50:51]
	global_store_dwordx4 v[104:105], v[50:53], off nt
	v_pk_mul_f32 v[86:87], v[170:171], v[52:53]
	v_cvt_pk_bf16_f32 v88, v88, v89
	s_waitcnt vmcnt(13) lgkmcnt(0)
	v_pk_fma_f32 v[54:55], v[168:169], v[54:55], v[82:83]
	v_cvt_pk_bf16_f32 v89, v86, v87
	ds_bpermute_b32 v82, v203, v88
	ds_bpermute_b32 v83, v203, v89
	v_pk_fma_f32 v[56:57], v[166:167], v[56:57], v[84:85]
	v_pk_mul_f32 v[84:85], v[172:173], v[54:55]
	v_pk_mul_f32 v[86:87], v[170:171], v[56:57]
	global_store_dwordx4 v[106:107], v[54:57], off nt
	v_cvt_pk_bf16_f32 v84, v84, v85
	v_cvt_pk_bf16_f32 v85, v86, v87
	v_lshlrev_b32_e32 v86, 1, v96
	s_waitcnt lgkmcnt(0)
	v_add_u32_e32 v250, 0xfffff040, v86
	v_cndmask_b32_e64 v250, v86, v250, s[40:41]
	v_cndmask_b32_e64 v248, v94, v82, s[40:41]
	v_cndmask_b32_e64 v249, v95, v83, s[40:41]
	global_store_dwordx2 v250, v[248:249], s[20:21]
	v_cndmask_b32_e64 v246, v82, v94, s[40:41]
	v_cndmask_b32_e64 v247, v83, v95, s[40:41]
	s_waitcnt lgkmcnt(1)
	v_add_u32_e32 v82, 0x1040, v86
	v_cndmask_b32_e64 v82, v86, v82, s[38:39]
	global_store_dwordx2 v82, v[246:247], s[20:21]
	ds_bpermute_b32 v82, v203, v84
	s_waitcnt lgkmcnt(1)
	ds_bpermute_b32 v83, v203, v85
	v_lshlrev_b32_e32 v84, 1, v92
	s_waitcnt lgkmcnt(0)
	v_add_u32_e32 v250, 0xfffff040, v84
	v_cndmask_b32_e64 v250, v84, v250, s[40:41]
	v_cndmask_b32_e64 v248, v90, v82, s[40:41]
	v_cndmask_b32_e64 v249, v91, v83, s[40:41]
	global_store_dwordx2 v250, v[248:249], s[20:21]
	v_cndmask_b32_e64 v246, v82, v90, s[40:41]
	v_cndmask_b32_e64 v247, v83, v91, s[40:41]
	v_mul_f32_e32 v51, v51, v51
	v_fmac_f32_e32 v51, v50, v50
	v_mul_f32_e32 v50, v53, v53
	v_mul_f32_e32 v61, v61, v61
	v_fmac_f32_e32 v50, v52, v52
	v_mul_f32_e32 v59, v59, v59
	v_fmac_f32_e32 v61, v60, v60
	v_mul_f32_e32 v60, v63, v63
	v_mul_f32_e32 v63, v65, v65
	v_add_f32_e32 v50, v51, v50
	v_mul_f32_e32 v51, v55, v55
	v_mul_f32_e32 v52, v57, v57
	v_fmac_f32_e32 v63, v64, v64
	v_fmac_f32_e32 v51, v54, v54
	v_fmac_f32_e32 v52, v56, v56
	v_fmac_f32_e32 v59, v58, v58
	v_fmac_f32_e32 v60, v62, v62
	v_add_f32_e32 v51, v51, v52
	v_add_f32_e32 v52, v59, v61
	v_add_f32_e32 v53, v60, v63
	v_add_f32_e32 v50, v52, v50
	v_add_f32_e32 v51, v53, v51
	ds_bpermute_b32 v52, v190, v50
	ds_bpermute_b32 v53, v190, v51
	s_waitcnt lgkmcnt(1)
	v_add_f32_e32 v50, v50, v52
	s_waitcnt lgkmcnt(0)
	v_add_f32_e32 v53, v51, v53
	ds_bpermute_b32 v52, v191, v50
	ds_bpermute_b32 v54, v191, v53
	s_waitcnt lgkmcnt(1)
	v_add_f32_e32 v50, v50, v52
	s_waitcnt lgkmcnt(0)
	v_add_f32_e32 v52, v53, v54
	ds_bpermute_b32 v51, v204, v50
	ds_bpermute_b32 v53, v204, v52
	v_add_u32_e32 v54, 0x1040, v84
	v_cndmask_b32_e64 v54, v84, v54, s[38:39]
	global_store_dwordx2 v54, v[246:247], s[20:21]
	s_and_saveexec_b64 s[16:17], s[42:43]
	s_cbranch_execz .LBB0_1648
	s_waitcnt lgkmcnt(1)
	v_add_f32_e32 v50, v50, v51
	s_waitcnt lgkmcnt(0)
	v_add_f32_e32 v51, v52, v53
	ds_write2_b32 v194, v50, v51 offset0:64 offset1:72
; #define LAS __attribute__((address_space(3)))
; #define ERN_EOFF(q, m) (eb + (unsigned)((((q) & 1) * HALF + (m) * 16) * DM + ERN_COL((q) >> 1)))
;     __device__ __forceinline__ void operator()(const f32x4 (&acc)[2][2][4][2], const Unit& u, int wr, int wc, int fr, int fq) const {
;     ...
;         ERN_LOADX(0);
; #pragma unroll
;         for (int g = 0; g < 8; ++g) { const int ai = g >> 2, m = g & 3;
;             if (g + 1 < 8) ERN_LOADX(g + 1);
;             float sq0 = 0.f, sq1 = 0.f; u32x2 hw[2][2];
; #pragma unroll
;             for (int bj = 0; bj < 2; ++bj) {
;                 *(LAS f32x4*)(st + wr_off) = acc[ai][bj][m][0]; *(LAS f32x4*)(st + wr_off + 64) = acc[ai][bj][m][1];
;                 const f32x4 a0 = *(const LAS f32x4*)(st + rd_off), a1 = *(const LAS f32x4*)(st + rd_off + 8 * 144);
;                 { const f32x4 xv = xb[g & 1][bj][0] + gv[bj] * a0; __builtin_nontemporal_store(xv, (f32x4*)((char*)xo + 4u * ERN_EOFF(g, bj, 0)));
;                   sq0 += (xv.x * xv.x + xv.y * xv.y) + (xv.z * xv.z + xv.w * xv.w);
;                   const f32x4 hv = xv * gsn[bj]; hw[bj][0].x = cvt_pk_bf16(hv.x, hv.y); hw[bj][0].y = cvt_pk_bf16(hv.z, hv.w); }
;                 { const f32x4 xv = xb[g & 1][bj][1] + gv[bj] * a1; __builtin_nontemporal_store(xv, (f32x4*)((char*)xo + 4u * ERN_EOFF(g, bj, 1)));
;                   sq1 += (xv.x * xv.x + xv.y * xv.y) + (xv.z * xv.z + xv.w * xv.w);
;                   const f32x4 hv = xv * gsn[bj]; hw[bj][1].x = cvt_pk_bf16(hv.x, hv.y); hw[bj][1].y = cvt_pk_bf16(hv.z, hv.w); }
;             }
;             if (!NOH && !PLAIN) {
; #pragma unroll
;                 for (int rh = 0; rh < 2; ++rh) { u32x2 rv; rv.x = __shfl_xor(hw[1][rh].x, 8); rv.y = __shfl_xor(hw[1][rh].y, 8);
;                     const unsigned e0 = ERN_EOFF(g, 0, rh);
;                     const unsigned ee = odd ? (e0 - DM + 32) : e0, eo2 = odd ? e0 : (e0 + DM + 32);
;                     *(u32x2*)((char*)ho + 2u * ee) = odd ? rv : hw[0][rh];
;                     *(u32x2*)((char*)ho + 2u * eo2) = odd ? hw[0][rh] : rv; }
;             }
;             if (!PLAIN) { sq0 += __shfl_xor(sq0, 1); sq0 += __shfl_xor(sq0, 2); sq0 += __shfl_xor(sq0, 4);
;             sq1 += __shfl_xor(sq1, 1); sq1 += __shfl_xor(sq1, 2); sq1 += __shfl_xor(sq1, 4); }
;             if (!PLAIN && pc == 0) { sst[g * 16 + rr] = sq0; sst[g * 16 + 8 + rr] = sq1; }
.LBB0_1648:
	s_or_b64 exec, exec, s[16:17]
	v_lshl_add_u64 v[88:89], s[22:23], 0, v[154:155]
	v_add_u32_e32 v154, 0x140000, v205
	v_add_u32_e32 v84, 0x140080, v205
	v_add_u32_e32 v86, 0x150000, v205
	global_load_dwordx4 v[62:65], v154, s[22:23]
	global_load_dwordx4 v[58:61], v86, s[22:23]
	v_add_u32_e32 v82, 0x150080, v205
	global_load_dwordx4 v[54:57], v84, s[22:23]
	s_waitcnt lgkmcnt(0)
	global_load_dwordx4 v[50:53], v82, s[22:23]
	ds_write_b128 v200, v[46:49]
	ds_write_b128 v200, v[42:45] offset:64
	ds_read_b128 v[42:45], v201
	ds_read_b128 v[46:49], v201 offset:1152
	v_mov_b32_e32 v103, v155
	v_lshl_add_u64 v[90:91], s[22:23], 0, v[102:103]
	v_mov_b32_e32 v101, v155
	s_waitcnt vmcnt(13) lgkmcnt(1)
	v_pk_fma_f32 v[42:43], v[180:181], v[42:43], v[78:79]
	s_waitcnt vmcnt(12) lgkmcnt(0)
	v_pk_fma_f32 v[46:47], v[180:181], v[46:47], v[74:75]
	v_pk_fma_f32 v[44:45], v[176:177], v[44:45], v[80:81]
	v_pk_mul_f32 v[78:79], v[178:179], v[42:43]
	v_pk_fma_f32 v[48:49], v[176:177], v[48:49], v[76:77]
	v_pk_mul_f32 v[74:75], v[178:179], v[46:47]
	global_store_dwordx4 v[88:89], v[42:45], off nt
	v_pk_mul_f32 v[80:81], v[174:175], v[44:45]
	v_cvt_pk_bf16_f32 v78, v78, v79
	v_pk_mul_f32 v[76:77], v[174:175], v[48:49]
	v_cvt_pk_bf16_f32 v79, v80, v81
	global_store_dwordx4 v[90:91], v[46:49], off nt
	v_cvt_pk_bf16_f32 v74, v74, v75
	v_cvt_pk_bf16_f32 v75, v76, v77
	ds_write_b128 v200, v[38:41]
	ds_write_b128 v200, v[34:37] offset:64
	ds_read_b128 v[34:37], v201
	ds_read_b128 v[38:41], v201 offset:1152
	v_lshl_add_u64 v[76:77], s[22:23], 0, v[100:101]
	v_mov_b32_e32 v99, v155
	v_lshl_add_u64 v[80:81], s[22:23], 0, v[98:99]
	s_waitcnt vmcnt(13) lgkmcnt(1)
	v_pk_fma_f32 v[34:35], v[168:169], v[34:35], v[70:71]
	v_pk_fma_f32 v[36:37], v[166:167], v[36:37], v[72:73]
	v_pk_mul_f32 v[72:73], v[172:173], v[34:35]
	global_store_dwordx4 v[76:77], v[34:37], off nt
	v_pk_mul_f32 v[70:71], v[170:171], v[36:37]
	v_cvt_pk_bf16_f32 v72, v72, v73
	s_waitcnt vmcnt(13) lgkmcnt(0)
	v_pk_fma_f32 v[38:39], v[168:169], v[38:39], v[66:67]
	v_cvt_pk_bf16_f32 v73, v70, v71
	ds_bpermute_b32 v66, v203, v72
	ds_bpermute_b32 v67, v203, v73
	v_pk_fma_f32 v[40:41], v[166:167], v[40:41], v[68:69]
	v_pk_mul_f32 v[68:69], v[172:173], v[38:39]
	v_pk_mul_f32 v[70:71], v[170:171], v[40:41]
	global_store_dwordx4 v[80:81], v[38:41], off nt
	v_cvt_pk_bf16_f32 v68, v68, v69
	v_cvt_pk_bf16_f32 v69, v70, v71
	v_add_u32_e32 v71, 0x48000, v202
	v_lshlrev_b32_e32 v70, 1, v71
	s_waitcnt lgkmcnt(0)
	v_add_u32_e32 v250, 0xfffff040, v70
	v_cndmask_b32_e64 v250, v70, v250, s[40:41]
	v_cndmask_b32_e64 v248, v78, v66, s[40:41]
	v_cndmask_b32_e64 v249, v79, v67, s[40:41]
	global_store_dwordx2 v250, v[248:249], s[20:21]
	v_cndmask_b32_e64 v246, v66, v78, s[40:41]
	v_cndmask_b32_e64 v247, v67, v79, s[40:41]
	s_waitcnt lgkmcnt(1)
	v_add_u32_e32 v66, 0x1040, v70
	v_cndmask_b32_e64 v66, v70, v66, s[38:39]
	global_store_dwordx2 v66, v[246:247], s[20:21]
	ds_bpermute_b32 v66, v203, v68
	s_waitcnt lgkmcnt(1)
	ds_bpermute_b32 v67, v203, v69
	v_add_u32_e32 v69, 0x4c000, v202
	v_lshlrev_b32_e32 v68, 1, v69
	s_waitcnt lgkmcnt(0)
	v_add_u32_e32 v250, 0xfffff040, v68
	v_cndmask_b32_e64 v250, v68, v250, s[40:41]
	v_cndmask_b32_e64 v248, v74, v66, s[40:41]
	v_cndmask_b32_e64 v249, v75, v67, s[40:41]
	global_store_dwordx2 v250, v[248:249], s[20:21]
	v_cndmask_b32_e64 v246, v66, v74, s[40:41]
	v_cndmask_b32_e64 v247, v67, v75, s[40:41]
	v_mul_f32_e32 v35, v35, v35
	v_fmac_f32_e32 v35, v34, v34
	v_mul_f32_e32 v34, v37, v37
	v_mul_f32_e32 v45, v45, v45
	v_fmac_f32_e32 v34, v36, v36
	v_mul_f32_e32 v43, v43, v43
	v_fmac_f32_e32 v45, v44, v44
	v_mul_f32_e32 v44, v47, v47
	v_mul_f32_e32 v47, v49, v49
	v_add_f32_e32 v34, v35, v34
	v_mul_f32_e32 v35, v39, v39
	v_mul_f32_e32 v36, v41, v41
	v_fmac_f32_e32 v47, v48, v48
	v_fmac_f32_e32 v35, v38, v38
	v_fmac_f32_e32 v36, v40, v40
	v_fmac_f32_e32 v43, v42, v42
	v_fmac_f32_e32 v44, v46, v46
	v_add_f32_e32 v35, v35, v36
	v_add_f32_e32 v36, v43, v45
	v_add_f32_e32 v37, v44, v47
	v_add_f32_e32 v34, v36, v34
	v_add_f32_e32 v35, v37, v35
	ds_bpermute_b32 v36, v190, v34
	ds_bpermute_b32 v37, v190, v35
	s_waitcnt lgkmcnt(1)
	v_add_f32_e32 v34, v34, v36
	s_waitcnt lgkmcnt(0)
	v_add_f32_e32 v37, v35, v37
	ds_bpermute_b32 v36, v191, v34
	ds_bpermute_b32 v38, v191, v37
	s_waitcnt lgkmcnt(1)
	v_add_f32_e32 v34, v34, v36
	s_waitcnt lgkmcnt(0)
	v_add_f32_e32 v36, v37, v38
	ds_bpermute_b32 v35, v204, v34
	ds_bpermute_b32 v37, v204, v36
	v_add_u32_e32 v38, 0x1040, v68
	v_cndmask_b32_e64 v38, v68, v38, s[38:39]
	global_store_dwordx2 v38, v[246:247], s[20:21]
	s_and_saveexec_b64 s[16:17], s[42:43]
	s_cbranch_execz .LBB0_1658
	s_waitcnt lgkmcnt(1)
	v_add_f32_e32 v34, v34, v35
	s_waitcnt lgkmcnt(0)
	v_add_f32_e32 v35, v36, v37
	ds_write2_b32 v194, v34, v35 offset0:80 offset1:88
; #define LAS __attribute__((address_space(3)))
; #define ERN_EOFF(q, m) (eb + (unsigned)((((q) & 1) * HALF + (m) * 16) * DM + ERN_COL((q) >> 1)))
;     __device__ __forceinline__ void operator()(const f32x4 (&acc)[2][2][4][2], const Unit& u, int wr, int wc, int fr, int fq) const {
;     ...
;         ERN_LOADX(0);
; #pragma unroll
;         for (int g = 0; g < 8; ++g) { const int ai = g >> 2, m = g & 3;
;             if (g + 1 < 8) ERN_LOADX(g + 1);
;             float sq0 = 0.f, sq1 = 0.f; u32x2 hw[2][2];
; #pragma unroll
;             for (int bj = 0; bj < 2; ++bj) {
;                 *(LAS f32x4*)(st + wr_off) = acc[ai][bj][m][0]; *(LAS f32x4*)(st + wr_off + 64) = acc[ai][bj][m][1];
;                 const f32x4 a0 = *(const LAS f32x4*)(st + rd_off), a1 = *(const LAS f32x4*)(st + rd_off + 8 * 144);
;                 { const f32x4 xv = xb[g & 1][bj][0] + gv[bj] * a0; __builtin_nontemporal_store(xv, (f32x4*)((char*)xo + 4u * ERN_EOFF(g, bj, 0)));
;                   sq0 += (xv.x * xv.x + xv.y * xv.y) + (xv.z * xv.z + xv.w * xv.w);
;                   const f32x4 hv = xv * gsn[bj]; hw[bj][0].x = cvt_pk_bf16(hv.x, hv.y); hw[bj][0].y = cvt_pk_bf16(hv.z, hv.w); }
;                 { const f32x4 xv = xb[g & 1][bj][1] + gv[bj] * a1; __builtin_nontemporal_store(xv, (f32x4*)((char*)xo + 4u * ERN_EOFF(g, bj, 1)));
;                   sq1 += (xv.x * xv.x + xv.y * xv.y) + (xv.z * xv.z + xv.w * xv.w);
;                   const f32x4 hv = xv * gsn[bj]; hw[bj][1].x = cvt_pk_bf16(hv.x, hv.y); hw[bj][1].y = cvt_pk_bf16(hv.z, hv.w); }
;             }
;             if (!NOH && !PLAIN) {
; #pragma unroll
;                 for (int rh = 0; rh < 2; ++rh) { u32x2 rv; rv.x = __shfl_xor(hw[1][rh].x, 8); rv.y = __shfl_xor(hw[1][rh].y, 8);
;                     const unsigned e0 = ERN_EOFF(g, 0, rh);
;                     const unsigned ee = odd ? (e0 - DM + 32) : e0, eo2 = odd ? e0 : (e0 + DM + 32);
;                     *(u32x2*)((char*)ho + 2u * ee) = odd ? rv : hw[0][rh];
;                     *(u32x2*)((char*)ho + 2u * eo2) = odd ? hw[0][rh] : rv; }
;             }
;             if (!PLAIN) { sq0 += __shfl_xor(sq0, 1); sq0 += __shfl_xor(sq0, 2); sq0 += __shfl_xor(sq0, 4);
;             sq1 += __shfl_xor(sq1, 1); sq1 += __shfl_xor(sq1, 2); sq1 += __shfl_xor(sq1, 4); }
;             if (!PLAIN && pc == 0) { sst[g * 16 + rr] = sq0; sst[g * 16 + 8 + rr] = sq1; }
.LBB0_1658:
	s_or_b64 exec, exec, s[16:17]
	v_lshl_add_u64 v[72:73], s[22:23], 0, v[154:155]
	v_add_u32_e32 v154, 0x160000, v205
	v_add_u32_e32 v68, 0x160080, v205
	v_add_u32_e32 v70, 0x170000, v205
	global_load_dwordx4 v[46:49], v154, s[22:23]
	global_load_dwordx4 v[42:45], v70, s[22:23]
	v_add_u32_e32 v66, 0x170080, v205
	global_load_dwordx4 v[38:41], v68, s[22:23]
	s_waitcnt lgkmcnt(0)
	global_load_dwordx4 v[34:37], v66, s[22:23]
	ds_write_b128 v200, v[30:33]
	ds_write_b128 v200, v[26:29] offset:64
	ds_read_b128 v[26:29], v201
	ds_read_b128 v[30:33], v201 offset:1152
	v_mov_b32_e32 v87, v155
	v_lshl_add_u64 v[74:75], s[22:23], 0, v[86:87]
	v_mov_b32_e32 v85, v155
	s_waitcnt vmcnt(13) lgkmcnt(1)
	v_pk_fma_f32 v[26:27], v[180:181], v[26:27], v[62:63]
	s_waitcnt vmcnt(12) lgkmcnt(0)
	v_pk_fma_f32 v[30:31], v[180:181], v[30:31], v[58:59]
	v_pk_fma_f32 v[28:29], v[176:177], v[28:29], v[64:65]
	v_pk_mul_f32 v[62:63], v[178:179], v[26:27]
	v_pk_fma_f32 v[32:33], v[176:177], v[32:33], v[60:61]
	v_pk_mul_f32 v[58:59], v[178:179], v[30:31]
	global_store_dwordx4 v[72:73], v[26:29], off nt
	v_pk_mul_f32 v[64:65], v[174:175], v[28:29]
	v_cvt_pk_bf16_f32 v62, v62, v63
	v_pk_mul_f32 v[60:61], v[174:175], v[32:33]
	v_cvt_pk_bf16_f32 v63, v64, v65
	global_store_dwordx4 v[74:75], v[30:33], off nt
	v_cvt_pk_bf16_f32 v58, v58, v59
	v_cvt_pk_bf16_f32 v59, v60, v61
	ds_write_b128 v200, v[22:25]
	ds_write_b128 v200, v[18:21] offset:64
	ds_read_b128 v[18:21], v201
	ds_read_b128 v[22:25], v201 offset:1152
	v_lshl_add_u64 v[60:61], s[22:23], 0, v[84:85]
	v_mov_b32_e32 v83, v155
	v_lshl_add_u64 v[64:65], s[22:23], 0, v[82:83]
	s_waitcnt vmcnt(13) lgkmcnt(1)
	v_pk_fma_f32 v[18:19], v[168:169], v[18:19], v[54:55]
	v_pk_fma_f32 v[20:21], v[166:167], v[20:21], v[56:57]
	v_pk_mul_f32 v[56:57], v[172:173], v[18:19]
	global_store_dwordx4 v[60:61], v[18:21], off nt
	v_pk_mul_f32 v[54:55], v[170:171], v[20:21]
	v_cvt_pk_bf16_f32 v56, v56, v57
	s_waitcnt vmcnt(13) lgkmcnt(0)
	v_pk_fma_f32 v[22:23], v[168:169], v[22:23], v[50:51]
	v_cvt_pk_bf16_f32 v57, v54, v55
	ds_bpermute_b32 v50, v203, v56
	ds_bpermute_b32 v51, v203, v57
	v_pk_fma_f32 v[24:25], v[166:167], v[24:25], v[52:53]
	v_pk_mul_f32 v[52:53], v[172:173], v[22:23]
	v_pk_mul_f32 v[54:55], v[170:171], v[24:25]
	global_store_dwordx4 v[64:65], v[22:25], off nt
	v_cvt_pk_bf16_f32 v52, v52, v53
	v_cvt_pk_bf16_f32 v53, v54, v55
	v_add_u32_e32 v55, 0x50000, v202
	v_lshlrev_b32_e32 v54, 1, v55
	s_waitcnt lgkmcnt(0)
	v_add_u32_e32 v250, 0xfffff040, v54
	v_cndmask_b32_e64 v250, v54, v250, s[40:41]
	v_cndmask_b32_e64 v248, v62, v50, s[40:41]
	v_cndmask_b32_e64 v249, v63, v51, s[40:41]
	global_store_dwordx2 v250, v[248:249], s[20:21]
	v_cndmask_b32_e64 v246, v50, v62, s[40:41]
	v_cndmask_b32_e64 v247, v51, v63, s[40:41]
	s_waitcnt lgkmcnt(1)
	v_add_u32_e32 v50, 0x1040, v54
	v_cndmask_b32_e64 v50, v54, v50, s[38:39]
	global_store_dwordx2 v50, v[246:247], s[20:21]
	ds_bpermute_b32 v50, v203, v52
	s_waitcnt lgkmcnt(1)
	ds_bpermute_b32 v51, v203, v53
	v_add_u32_e32 v53, 0x54000, v202
	v_lshlrev_b32_e32 v52, 1, v53
	s_waitcnt lgkmcnt(0)
	v_add_u32_e32 v250, 0xfffff040, v52
	v_cndmask_b32_e64 v250, v52, v250, s[40:41]
	v_cndmask_b32_e64 v248, v58, v50, s[40:41]
	v_cndmask_b32_e64 v249, v59, v51, s[40:41]
	global_store_dwordx2 v250, v[248:249], s[20:21]
	v_cndmask_b32_e64 v246, v50, v58, s[40:41]
	v_cndmask_b32_e64 v247, v51, v59, s[40:41]
	v_mul_f32_e32 v19, v19, v19
	v_fmac_f32_e32 v19, v18, v18
	v_mul_f32_e32 v18, v21, v21
	v_mul_f32_e32 v29, v29, v29
	v_fmac_f32_e32 v18, v20, v20
	v_mul_f32_e32 v27, v27, v27
	v_fmac_f32_e32 v29, v28, v28
	v_mul_f32_e32 v28, v31, v31
	v_mul_f32_e32 v31, v33, v33
	v_add_f32_e32 v18, v19, v18
	v_mul_f32_e32 v19, v23, v23
	v_mul_f32_e32 v20, v25, v25
	v_fmac_f32_e32 v31, v32, v32
	v_fmac_f32_e32 v19, v22, v22
	v_fmac_f32_e32 v20, v24, v24
	v_fmac_f32_e32 v27, v26, v26
	v_fmac_f32_e32 v28, v30, v30
	v_add_f32_e32 v19, v19, v20
	v_add_f32_e32 v20, v27, v29
	v_add_f32_e32 v21, v28, v31
	v_add_f32_e32 v18, v20, v18
	v_add_f32_e32 v19, v21, v19
	ds_bpermute_b32 v20, v190, v18
	ds_bpermute_b32 v21, v190, v19
	s_waitcnt lgkmcnt(1)
	v_add_f32_e32 v18, v18, v20
	s_waitcnt lgkmcnt(0)
	v_add_f32_e32 v21, v19, v21
	ds_bpermute_b32 v20, v191, v18
	ds_bpermute_b32 v22, v191, v21
	s_waitcnt lgkmcnt(1)
	v_add_f32_e32 v18, v18, v20
	s_waitcnt lgkmcnt(0)
	v_add_f32_e32 v20, v21, v22
	ds_bpermute_b32 v19, v204, v18
	ds_bpermute_b32 v21, v204, v20
	v_add_u32_e32 v22, 0x1040, v52
	v_cndmask_b32_e64 v22, v52, v22, s[38:39]
	global_store_dwordx2 v22, v[246:247], s[20:21]
	s_and_saveexec_b64 s[16:17], s[42:43]
	s_cbranch_execz .LBB0_1668
	s_waitcnt lgkmcnt(1)
	v_add_f32_e32 v18, v18, v19
	s_waitcnt lgkmcnt(0)
	v_add_f32_e32 v19, v20, v21
	ds_write2_b32 v194, v18, v19 offset0:96 offset1:104
; #define LAS __attribute__((address_space(3)))
; #define ERN_EOFF(q, m) (eb + (unsigned)((((q) & 1) * HALF + (m) * 16) * DM + ERN_COL((q) >> 1)))
;     __device__ __forceinline__ void operator()(const f32x4 (&acc)[2][2][4][2], const Unit& u, int wr, int wc, int fr, int fq) const {
;     ...
;         for (int g = 0; g < 8; ++g) { const int ai = g >> 2, m = g & 3;
;             if (g + 1 < 8) ERN_LOADX(g + 1);
;             float sq0 = 0.f, sq1 = 0.f; u32x2 hw[2][2];
; #pragma unroll
;             for (int bj = 0; bj < 2; ++bj) {
;                 *(LAS f32x4*)(st + wr_off) = acc[ai][bj][m][0]; *(LAS f32x4*)(st + wr_off + 64) = acc[ai][bj][m][1];
;                 const f32x4 a0 = *(const LAS f32x4*)(st + rd_off), a1 = *(const LAS f32x4*)(st + rd_off + 8 * 144);
;                 { const f32x4 xv = xb[g & 1][bj][0] + gv[bj] * a0; __builtin_nontemporal_store(xv, (f32x4*)((char*)xo + 4u * ERN_EOFF(g, bj, 0)));
;                   sq0 += (xv.x * xv.x + xv.y * xv.y) + (xv.z * xv.z + xv.w * xv.w);
;                   const f32x4 hv = xv * gsn[bj]; hw[bj][0].x = cvt_pk_bf16(hv.x, hv.y); hw[bj][0].y = cvt_pk_bf16(hv.z, hv.w); }
;                 { const f32x4 xv = xb[g & 1][bj][1] + gv[bj] * a1; __builtin_nontemporal_store(xv, (f32x4*)((char*)xo + 4u * ERN_EOFF(g, bj, 1)));
;                   sq1 += (xv.x * xv.x + xv.y * xv.y) + (xv.z * xv.z + xv.w * xv.w);
;                   const f32x4 hv = xv * gsn[bj]; hw[bj][1].x = cvt_pk_bf16(hv.x, hv.y); hw[bj][1].y = cvt_pk_bf16(hv.z, hv.w); }
;             }
;             if (!NOH && !PLAIN) {
; #pragma unroll
;                 for (int rh = 0; rh < 2; ++rh) { u32x2 rv; rv.x = __shfl_xor(hw[1][rh].x, 8); rv.y = __shfl_xor(hw[1][rh].y, 8);
;                     const unsigned e0 = ERN_EOFF(g, 0, rh);
;                     const unsigned ee = odd ? (e0 - DM + 32) : e0, eo2 = odd ? e0 : (e0 + DM + 32);
;                     *(u32x2*)((char*)ho + 2u * ee) = odd ? rv : hw[0][rh];
;                     *(u32x2*)((char*)ho + 2u * eo2) = odd ? hw[0][rh] : rv; }
;             }
;             if (!PLAIN) { sq0 += __shfl_xor(sq0, 1); sq0 += __shfl_xor(sq0, 2); sq0 += __shfl_xor(sq0, 4);
;             sq1 += __shfl_xor(sq1, 1); sq1 += __shfl_xor(sq1, 2); sq1 += __shfl_xor(sq1, 4); }
;             if (!PLAIN && pc == 0) { sst[g * 16 + rr] = sq0; sst[g * 16 + 8 + rr] = sq1; }
.LBB0_1668:
	s_or_b64 exec, exec, s[16:17]
	ds_write_b128 v200, v[14:17]
	ds_write_b128 v200, v[10:13] offset:64
	ds_read_b128 v[10:13], v201
	ds_read_b128 v[14:17], v201 offset:1152
	s_waitcnt lgkmcnt(5)
	v_lshl_add_u64 v[18:19], s[22:23], 0, v[154:155]
	v_mov_b32_e32 v71, v155
	v_lshl_add_u64 v[22:23], s[22:23], 0, v[70:71]
	s_waitcnt vmcnt(9) lgkmcnt(1)
	v_pk_fma_f32 v[12:13], v[176:177], v[12:13], v[48:49]
	v_pk_fma_f32 v[10:11], v[180:181], v[10:11], v[46:47]
	global_store_dwordx4 v[18:19], v[10:13], off nt
	v_pk_mul_f32 v[18:19], v[174:175], v[12:13]
	v_pk_mul_f32 v[20:21], v[178:179], v[10:11]
	s_waitcnt vmcnt(9) lgkmcnt(0)
	v_pk_fma_f32 v[14:15], v[180:181], v[14:15], v[42:43]
	v_cvt_pk_bf16_f32 v20, v20, v21
	v_cvt_pk_bf16_f32 v21, v18, v19
	v_pk_fma_f32 v[16:17], v[176:177], v[16:17], v[44:45]
	v_pk_mul_f32 v[18:19], v[178:179], v[14:15]
	global_store_dwordx4 v[22:23], v[14:17], off nt
	v_pk_mul_f32 v[22:23], v[174:175], v[16:17]
	v_cvt_pk_bf16_f32 v18, v18, v19
	v_mov_b32_e32 v69, v155
	v_cvt_pk_bf16_f32 v19, v22, v23
	ds_write_b128 v200, v[6:9]
	ds_write_b128 v200, v[2:5] offset:64
	ds_read_b128 v[2:5], v201
	ds_read_b128 v[6:9], v201 offset:1152
	v_lshl_add_u64 v[22:23], s[22:23], 0, v[68:69]
	v_mov_b32_e32 v67, v155
	v_lshl_add_u64 v[24:25], s[22:23], 0, v[66:67]
	s_waitcnt vmcnt(9) lgkmcnt(1)
	v_pk_fma_f32 v[4:5], v[166:167], v[4:5], v[40:41]
	v_pk_fma_f32 v[2:3], v[168:169], v[2:3], v[38:39]
	global_store_dwordx4 v[22:23], v[2:5], off nt
	v_pk_mul_f32 v[22:23], v[170:171], v[4:5]
	v_pk_mul_f32 v[26:27], v[172:173], v[2:3]
	s_waitcnt vmcnt(9) lgkmcnt(0)
	v_pk_fma_f32 v[8:9], v[166:167], v[8:9], v[36:37]
	v_cvt_pk_bf16_f32 v28, v26, v27
	v_cvt_pk_bf16_f32 v23, v22, v23
	ds_bpermute_b32 v22, v203, v28
	ds_bpermute_b32 v23, v203, v23
	v_pk_fma_f32 v[6:7], v[168:169], v[6:7], v[34:35]
	global_store_dwordx4 v[24:25], v[6:9], off nt
	v_pk_mul_f32 v[26:27], v[170:171], v[8:9]
	v_pk_mul_f32 v[24:25], v[172:173], v[6:7]
	s_nop 0
	v_cvt_pk_bf16_f32 v24, v24, v25
	v_cvt_pk_bf16_f32 v25, v26, v27
	v_add_u32_e32 v27, 0x58000, v202
	v_lshlrev_b32_e32 v26, 1, v27
	s_waitcnt lgkmcnt(0)
	v_add_u32_e32 v250, 0xfffff040, v26
	v_cndmask_b32_e64 v250, v26, v250, s[40:41]
	v_cndmask_b32_e64 v248, v20, v22, s[40:41]
	v_cndmask_b32_e64 v249, v21, v23, s[40:41]
	global_store_dwordx2 v250, v[248:249], s[20:21]
	v_cndmask_b32_e64 v246, v22, v20, s[40:41]
	v_cndmask_b32_e64 v247, v23, v21, s[40:41]
	s_waitcnt lgkmcnt(1)
	v_add_u32_e32 v22, 0x1040, v26
	v_cndmask_b32_e64 v22, v26, v22, s[38:39]
	global_store_dwordx2 v22, v[246:247], s[20:21]
	ds_bpermute_b32 v20, v203, v24
	ds_bpermute_b32 v21, v203, v25
	s_waitcnt lgkmcnt(2)
	v_add_u32_e32 v23, 0x5c000, v202
	v_lshlrev_b32_e32 v22, 1, v23
	s_waitcnt lgkmcnt(0)
	v_add_u32_e32 v250, 0xfffff040, v22
	v_cndmask_b32_e64 v250, v22, v250, s[40:41]
	v_cndmask_b32_e64 v248, v18, v20, s[40:41]
	v_cndmask_b32_e64 v249, v19, v21, s[40:41]
	global_store_dwordx2 v250, v[248:249], s[20:21]
	v_cndmask_b32_e64 v246, v20, v18, s[40:41]
	v_cndmask_b32_e64 v247, v21, v19, s[40:41]
	v_mul_f32_e32 v3, v3, v3
	v_fmac_f32_e32 v3, v2, v2
	v_mul_f32_e32 v2, v5, v5
	v_mul_f32_e32 v13, v13, v13
	v_fmac_f32_e32 v2, v4, v4
	v_mul_f32_e32 v11, v11, v11
	v_fmac_f32_e32 v13, v12, v12
	v_mul_f32_e32 v12, v15, v15
	v_mul_f32_e32 v15, v17, v17
	v_add_f32_e32 v2, v3, v2
	v_mul_f32_e32 v3, v7, v7
	v_mul_f32_e32 v4, v9, v9
	v_fmac_f32_e32 v15, v16, v16
	v_fmac_f32_e32 v3, v6, v6
	v_fmac_f32_e32 v4, v8, v8
	v_fmac_f32_e32 v11, v10, v10
	v_fmac_f32_e32 v12, v14, v14
	v_add_f32_e32 v3, v3, v4
	v_add_f32_e32 v4, v11, v13
	v_add_f32_e32 v5, v12, v15
	v_add_f32_e32 v2, v4, v2
	v_add_f32_e32 v3, v5, v3
	ds_bpermute_b32 v4, v190, v2
	ds_bpermute_b32 v5, v190, v3
	s_waitcnt lgkmcnt(1)
	v_add_f32_e32 v2, v2, v4
	s_waitcnt lgkmcnt(0)
	v_add_f32_e32 v5, v3, v5
	ds_bpermute_b32 v4, v191, v2
	ds_bpermute_b32 v6, v191, v5
	s_waitcnt lgkmcnt(1)
	v_add_f32_e32 v2, v2, v4
	s_waitcnt lgkmcnt(0)
	v_add_f32_e32 v4, v5, v6
	ds_bpermute_b32 v3, v204, v2
	ds_bpermute_b32 v5, v204, v4
	v_add_u32_e32 v6, 0x1040, v22
	v_cndmask_b32_e64 v6, v22, v6, s[38:39]
	global_store_dwordx2 v6, v[246:247], s[20:21]
	s_and_saveexec_b64 s[16:17], s[42:43]
	s_cbranch_execz .LBB0_1678
	s_waitcnt lgkmcnt(1)
	v_add_f32_e32 v2, v2, v3
	s_waitcnt lgkmcnt(0)
	v_add_f32_e32 v3, v4, v5
	ds_write2_b32 v194, v2, v3 offset0:112 offset1:120

; #define LAS __attribute__((address_space(3)))
;     __device__ __forceinline__ void operator()(const f32x4 (&acc)[2][2][4][2], const Unit& u, int wr, int wc, int fr, int fq) const {
;         const int s = u.pm >> 5, lane = fq * 16 + fr, rr = lane >> 3, pc = lane & 7;
;         const float* __restrict__ xi = xin + (size_t)u.pm * BM * DM; float* __restrict__ xo = xout + (size_t)u.pm * BM * DM; bf16_t* __restrict__ ho = Hn + (size_t)u.pm * BM * DM;
;         LAS unsigned char* st = lds_epi + (wr * 4 + wc) * 2304;
;         LAS float* sst = (LAS float*)(lds_epi + 18432 + (wr * 4 + wc) * 512);
;         const int colr = u.pn * BM + wc * 64 + 4 * pc;
;         const unsigned eb = (unsigned)((wr * 64 + rr) * DM + colr);
;         f32x4 gv[2], gsn[2];
; #pragma unroll
;         for (int bj = 0; bj < 2; ++bj) { gv[bj] = *(const f32x4*)(gate + (size_t)s * MODW + colr + bj * 32) * (0.5f * GS2);
;             if (!PLAIN) gsn[bj] = *(const f32x4*)(gnext + colr + bj * 32) * (*(const f32x4*)(scnext + (size_t)s * MODW + colr + bj * 32) + 1.0f); else gsn[bj] = gv[bj]; }
;         const unsigned wr_off = (unsigned)(fr * 144 + 16 * fq), rd_off = (unsigned)(rr * 144 + pc * 16);
;         const bool odd = (rr & 1) != 0;
;         f32x4 xb[2][2][2];
;     ...
;         ERN_LOADX(0);
; #pragma unroll
;         for (int g = 0; g < 8; ++g) { const int ai = g >> 2, m = g & 3;
;             if (g + 1 < 8) ERN_LOADX(g + 1);
;             float sq0 = 0.f, sq1 = 0.f; u32x2 hw[2][2];
; #pragma unroll
;             for (int bj = 0; bj < 2; ++bj) {
;                 *(LAS f32x4*)(st + wr_off) = acc[ai][bj][m][0]; *(LAS f32x4*)(st + wr_off + 64) = acc[ai][bj][m][1];
;                 const f32x4 a0 = *(const LAS f32x4*)(st + rd_off), a1 = *(const LAS f32x4*)(st + rd_off + 8 * 144);
;                 { const f32x4 xv = xb[g & 1][bj][0] + gv[bj] * a0; __builtin_nontemporal_store(xv, (f32x4*)((char*)xo + 4u * ERN_EOFF(g, bj, 0)));
;                   sq0 += (xv.x * xv.x + xv.y * xv.y) + (xv.z * xv.z + xv.w * xv.w);
;                   const f32x4 hv = xv * gsn[bj]; hw[bj][0].x = cvt_pk_bf16(hv.x, hv.y); hw[bj][0].y = cvt_pk_bf16(hv.z, hv.w); }
;                 { const f32x4 xv = xb[g & 1][bj][1] + gv[bj] * a1; __builtin_nontemporal_store(xv, (f32x4*)((char*)xo + 4u * ERN_EOFF(g, bj, 1)));
;                   sq1 += (xv.x * xv.x + xv.y * xv.y) + (xv.z * xv.z + xv.w * xv.w);
.LBB0_1929:
	s_ashr_i32 s18, s4, 5
	s_ashr_i32 s5, s4, 31
	v_lshl_or_b32 v130, s0, 8, v192
	s_mul_i32 s20, s18, 0x12000
	s_mul_hi_i32 s0, s18, 0x12000
	s_add_u32 s18, s33, s20
	v_ashrrev_i32_e32 v131, 31, v130
	s_addc_u32 s19, s34, s0
	v_lshlrev_b64 v[132:133], 2, v[130:131]
	v_lshl_add_u64 v[134:135], s[18:19], 0, v[132:133]
	s_add_u32 s18, s35, s20
	s_addc_u32 s19, s36, s0
	v_lshl_add_u64 v[136:137], s[10:11], 0, v[132:133]
	v_lshl_add_u64 v[132:133], s[18:19], 0, v[132:133]
	s_lshl_b64 s[18:19], s[4:5], 21
	s_add_u32 s20, s90, s18
	v_add_u32_e32 v202, v130, v193
	s_addc_u32 s21, s91, s19
	v_lshlrev_b32_e32 v205, 2, v202
	global_load_dwordx4 v[170:173], v[136:137], off
	global_load_dwordx4 v[166:169], v[134:135], off
	global_load_dwordx4 v[186:189], v[134:135], off offset:128
	global_load_dwordx4 v[206:209], v[132:133], off
	global_load_dwordx4 v[210:213], v[132:133], off offset:128
	global_load_dwordx4 v[214:217], v205, s[20:21]
	v_add_u32_e32 v130, 0x10000, v205
	global_load_dwordx4 v[218:221], v130, s[20:21]
	global_load_dwordx4 v[222:225], v[136:137], off offset:128
	global_load_dwordx4 v[226:229], v205, s[20:21] offset:128
	v_add_u32_e32 v204, 0x10080, v205
	global_load_dwordx4 v[230:233], v204, s[20:21]
	v_add_u32_e32 v130, 0x20000, v205
	v_add_u32_e32 v154, 0x30000, v205
	v_add_u32_e32 v184, 0x20080, v205
	v_add_u32_e32 v182, 0x30080, v205
	global_load_dwordx4 v[142:145], v130, s[20:21]
	global_load_dwordx4 v[138:141], v154, s[20:21]
	global_load_dwordx4 v[134:137], v184, s[20:21]
	s_nop 0
	global_load_dwordx4 v[130:133], v182, s[20:21]
	ds_write_b128 v200, v[126:129]
	ds_write_b128 v200, v[122:125] offset:64
	v_and_b32_e32 v127, 64, v199
	ds_read_b128 v[122:125], v201
	ds_read_b128 v[234:237], v201 offset:1152
	v_xor_b32_e32 v126, 8, v199
	v_add_u32_e32 v183, 64, v127
	v_cmp_lt_i32_e32 vcc, v126, v183
	v_add_u32_e32 v185, 0x4000, v202
	v_lshlrev_b32_e32 v238, 2, v185
	v_cndmask_b32_e32 v126, v199, v126, vcc
	v_lshlrev_b32_e32 v203, 2, v126
	s_lshl_b64 s[18:19], s[4:5], 20
	s_add_u32 s18, s93, s18
	s_addc_u32 s19, s92, s19
	s_waitcnt vmcnt(0)
	v_pk_mul_f32 v[180:181], v[166:167], 0.5 op_sel_hi:[1,0]
	v_pk_mul_f32 v[176:177], v[168:169], 0.5 op_sel_hi:[1,0]
	v_pk_add_f32 v[126:127], v[208:209], 1.0 op_sel_hi:[1,0]
	v_pk_add_f32 v[128:129], v[206:207], 1.0 op_sel_hi:[1,0]
	v_pk_mul_f32 v[174:175], v[172:173], v[126:127]
	v_pk_mul_f32 v[178:179], v[170:171], v[128:129]
	s_waitcnt lgkmcnt(1)
	v_pk_fma_f32 v[126:127], v[180:181], v[122:123], v[214:215]
	s_waitcnt lgkmcnt(0)
	v_pk_fma_f32 v[122:123], v[180:181], v[234:235], v[218:219]
	v_pk_mul_f32 v[168:169], v[186:187], 0.5 op_sel_hi:[1,0]
	v_pk_fma_f32 v[128:129], v[176:177], v[124:125], v[216:217]
	v_pk_fma_f32 v[124:125], v[176:177], v[236:237], v[220:221]
	v_pk_mul_f32 v[186:187], v[178:179], v[122:123]
	v_pk_mul_f32 v[166:167], v[188:189], 0.5 op_sel_hi:[1,0]
	global_store_dwordx4 v205, v[126:129], s[20:21] nt
	v_pk_mul_f32 v[170:171], v[174:175], v[128:129]
	v_pk_mul_f32 v[172:173], v[178:179], v[126:127]
	v_pk_mul_f32 v[206:207], v[174:175], v[124:125]
	v_cvt_pk_bf16_f32 v188, v172, v173
	v_cvt_pk_bf16_f32 v189, v170, v171
	global_store_dwordx4 v238, v[122:125], s[20:21] nt
	v_cvt_pk_bf16_f32 v186, v186, v187
	v_cvt_pk_bf16_f32 v187, v206, v207
	ds_write_b128 v200, v[118:121]
	ds_write_b128 v200, v[114:117] offset:64
	ds_read_b128 v[114:117], v201
	ds_read_b128 v[206:209], v201 offset:1152
	v_pk_add_f32 v[190:191], v[212:213], 1.0 op_sel_hi:[1,0]
	v_pk_add_f32 v[118:119], v[210:211], 1.0 op_sel_hi:[1,0]
	v_pk_mul_f32 v[170:171], v[224:225], v[190:191]
	v_pk_mul_f32 v[172:173], v[222:223], v[118:119]
	s_waitcnt lgkmcnt(1)
	v_pk_fma_f32 v[120:121], v[166:167], v[116:117], v[228:229]
	v_pk_fma_f32 v[118:119], v[168:169], v[114:115], v[226:227]
	s_waitcnt lgkmcnt(0)
	v_pk_fma_f32 v[114:115], v[168:169], v[206:207], v[230:231]
	v_pk_mul_f32 v[190:191], v[170:171], v[120:121]
	v_pk_mul_f32 v[206:207], v[172:173], v[118:119]
	global_store_dwordx4 v205, v[118:121], s[20:21] offset:128 nt
	v_cvt_pk_bf16_f32 v206, v206, v207
	v_cvt_pk_bf16_f32 v191, v190, v191
	ds_bpermute_b32 v190, v203, v206
	ds_bpermute_b32 v191, v203, v191
	v_pk_fma_f32 v[116:117], v[166:167], v[208:209], v[232:233]
	v_pk_mul_f32 v[206:207], v[172:173], v[114:115]
	global_store_dwordx4 v204, v[114:117], s[20:21] nt
	v_cvt_pk_bf16_f32 v204, v206, v207
	v_lshlrev_b32_e32 v207, 1, v202
	v_pk_mul_f32 v[208:209], v[170:171], v[116:117]
	s_nop 0
	v_cvt_pk_bf16_f32 v206, v208, v209
	s_waitcnt lgkmcnt(0)
	v_add_u32_e32 v250, 0xfffff040, v207
	v_cndmask_b32_e64 v250, v207, v250, s[40:41]
	v_cndmask_b32_e64 v248, v188, v190, s[40:41]
	v_cndmask_b32_e64 v249, v189, v191, s[40:41]
	global_store_dwordx2 v250, v[248:249], s[18:19]
	v_cndmask_b32_e64 v246, v190, v188, s[40:41]
	v_cndmask_b32_e64 v247, v191, v189, s[40:41]
	s_waitcnt lgkmcnt(1)
	v_add_u32_e32 v190, 0x1040, v207
	v_cndmask_b32_e64 v190, v207, v190, s[38:39]
	global_store_dwordx2 v190, v[246:247], s[18:19]
	ds_bpermute_b32 v188, v203, v204
	ds_bpermute_b32 v189, v203, v206
	v_lshlrev_b32_e32 v206, 1, v185
	s_waitcnt lgkmcnt(0)
; #define LAS __attribute__((address_space(3)))
; __device__ __forceinline__ unsigned cvt_pk_bf16(float lo, float hi) { unsigned r; asm volatile("v_cvt_pk_bf16_f32 %0, %1, %2" : "=v"(r) : "v"(lo), "v"(hi)); return r; }
;     __device__ __forceinline__ void operator()(const f32x4 (&acc)[2][2][4][2], const Unit& u, int wr, int wc, int fr, int fq) const {
;     ...
;             if (g + 1 < 8) ERN_LOADX(g + 1);
;             float sq0 = 0.f, sq1 = 0.f; u32x2 hw[2][2];
; #pragma unroll
;             for (int bj = 0; bj < 2; ++bj) {
;                 *(LAS f32x4*)(st + wr_off) = acc[ai][bj][m][0]; *(LAS f32x4*)(st + wr_off + 64) = acc[ai][bj][m][1];
;                 const f32x4 a0 = *(const LAS f32x4*)(st + rd_off), a1 = *(const LAS f32x4*)(st + rd_off + 8 * 144);
;                 { const f32x4 xv = xb[g & 1][bj][0] + gv[bj] * a0; __builtin_nontemporal_store(xv, (f32x4*)((char*)xo + 4u * ERN_EOFF(g, bj, 0)));
;                   sq0 += (xv.x * xv.x + xv.y * xv.y) + (xv.z * xv.z + xv.w * xv.w);
;                   const f32x4 hv = xv * gsn[bj]; hw[bj][0].x = cvt_pk_bf16(hv.x, hv.y); hw[bj][0].y = cvt_pk_bf16(hv.z, hv.w); }
;                 { const f32x4 xv = xb[g & 1][bj][1] + gv[bj] * a1; __builtin_nontemporal_store(xv, (f32x4*)((char*)xo + 4u * ERN_EOFF(g, bj, 1)));
;                   sq1 += (xv.x * xv.x + xv.y * xv.y) + (xv.z * xv.z + xv.w * xv.w);
;                   const f32x4 hv = xv * gsn[bj]; hw[bj][1].x = cvt_pk_bf16(hv.x, hv.y); hw[bj][1].y = cvt_pk_bf16(hv.z, hv.w); }
;             }
;             if (!NOH && !PLAIN) {
; #pragma unroll
;                 for (int rh = 0; rh < 2; ++rh) { u32x2 rv; rv.x = __shfl_xor(hw[1][rh].x, 8); rv.y = __shfl_xor(hw[1][rh].y, 8);
;                     const unsigned e0 = ERN_EOFF(g, 0, rh);
;                     const unsigned ee = odd ? (e0 - DM + 32) : e0, eo2 = odd ? e0 : (e0 + DM + 32);
;                     *(u32x2*)((char*)ho + 2u * ee) = odd ? rv : hw[0][rh];
;                     *(u32x2*)((char*)ho + 2u * eo2) = odd ? hw[0][rh] : rv; }
;             }
;             if (!PLAIN) { sq0 += __shfl_xor(sq0, 1); sq0 += __shfl_xor(sq0, 2); sq0 += __shfl_xor(sq0, 4);
;             sq1 += __shfl_xor(sq1, 1); sq1 += __shfl_xor(sq1, 2); sq1 += __shfl_xor(sq1, 4); }
;             if (!PLAIN && pc == 0) { sst[g * 16 + rr] = sq0; sst[g * 16 + 8 + rr] = sq1; }
	v_add_u32_e32 v250, 0xfffff040, v206
	v_cndmask_b32_e64 v250, v206, v250, s[40:41]
	v_cndmask_b32_e64 v248, v186, v188, s[40:41]
	v_cndmask_b32_e64 v249, v187, v189, s[40:41]
	global_store_dwordx2 v250, v[248:249], s[18:19]
	v_cndmask_b32_e64 v246, v188, v186, s[40:41]
	v_cndmask_b32_e64 v247, v189, v187, s[40:41]
	v_mul_f32_e32 v119, v119, v119
	v_mul_f32_e32 v127, v127, v127
	v_mul_f32_e32 v129, v129, v129
	v_fmac_f32_e32 v119, v118, v118
	v_mul_f32_e32 v118, v121, v121
	v_fmac_f32_e32 v129, v128, v128
	v_fmac_f32_e32 v118, v120, v120
	v_mul_f32_e32 v115, v115, v115
	v_fmac_f32_e32 v127, v126, v126
	v_add_f32_e32 v118, v119, v118
	v_fmac_f32_e32 v115, v114, v114
	v_mul_f32_e32 v114, v117, v117
	v_add_f32_e32 v117, v127, v129
	v_add_f32_e32 v117, v117, v118
	v_xor_b32_e32 v118, 1, v199
	v_cmp_lt_i32_e32 vcc, v118, v183
	v_mul_f32_e32 v123, v123, v123
	v_mul_f32_e32 v125, v125, v125
	v_cndmask_b32_e32 v118, v199, v118, vcc
	v_lshlrev_b32_e32 v190, 2, v118
	ds_bpermute_b32 v118, v190, v117
	v_fmac_f32_e32 v114, v116, v116
	v_fmac_f32_e32 v125, v124, v124
	v_fmac_f32_e32 v123, v122, v122
	v_add_f32_e32 v114, v115, v114
	s_waitcnt lgkmcnt(0)
	v_add_f32_e32 v116, v117, v118
	v_xor_b32_e32 v117, 2, v199
	v_cmp_lt_i32_e32 vcc, v117, v183
	v_add_f32_e32 v115, v123, v125
	v_add_f32_e32 v115, v115, v114
	v_cndmask_b32_e32 v117, v199, v117, vcc
	v_lshlrev_b32_e32 v191, 2, v117
	ds_bpermute_b32 v117, v191, v116
	ds_bpermute_b32 v118, v190, v115
	s_waitcnt lgkmcnt(1)
	v_add_f32_e32 v114, v116, v117
	s_waitcnt lgkmcnt(0)
	v_add_f32_e32 v117, v115, v118
	ds_bpermute_b32 v118, v191, v117
	v_xor_b32_e32 v116, 4, v199
	v_cmp_lt_i32_e32 vcc, v116, v183
	s_nop 1
	v_cndmask_b32_e32 v115, v199, v116, vcc
	v_lshlrev_b32_e32 v204, 2, v115
	s_waitcnt lgkmcnt(0)
	v_add_f32_e32 v116, v117, v118
	ds_bpermute_b32 v115, v204, v114
	ds_bpermute_b32 v117, v204, v116
	v_add_u32_e32 v118, 0x1040, v206
	v_cndmask_b32_e64 v118, v206, v118, s[38:39]
	global_store_dwordx2 v118, v[246:247], s[18:19]
	s_and_saveexec_b64 s[22:23], s[42:43]
	s_cbranch_execz .LBB0_1939
	s_waitcnt lgkmcnt(1)
	v_add_f32_e32 v114, v114, v115
	s_waitcnt lgkmcnt(0)
	v_add_f32_e32 v115, v116, v117
	ds_write2_b32 v194, v114, v115 offset1:8
.LBB0_1939:
	s_or_b64 exec, exec, s[22:23]
	v_lshl_add_u64 v[206:207], s[20:21], 0, v[154:155]
	v_add_u32_e32 v114, 0x40000, v205
	v_add_u32_e32 v154, 0x50000, v205
	v_add_u32_e32 v186, 0x40080, v205
	global_load_dwordx4 v[122:125], v154, s[20:21]
	global_load_dwordx4 v[118:121], v186, s[20:21]
	v_add_u32_e32 v188, 0x50080, v205
	global_load_dwordx4 v[126:129], v114, s[20:21]
	s_waitcnt lgkmcnt(0)
	global_load_dwordx4 v[114:117], v188, s[20:21]
	ds_write_b128 v200, v[110:113]
	ds_write_b128 v200, v[106:109] offset:64
	ds_read_b128 v[106:109], v201
	ds_read_b128 v[110:113], v201 offset:1152
	v_mov_b32_e32 v185, v155
	v_mov_b32_e32 v183, v155
	v_lshl_add_u64 v[182:183], s[20:21], 0, v[182:183]
	s_waitcnt lgkmcnt(1)
	v_pk_fma_f32 v[108:109], v[176:177], v[108:109], v[144:145]
	v_add_u32_e32 v144, 0x8000, v202
	v_pk_fma_f32 v[106:107], v[180:181], v[106:107], v[142:143]
	v_lshlrev_b32_e32 v142, 2, v144
	s_waitcnt lgkmcnt(0)
	v_pk_fma_f32 v[110:111], v[180:181], v[110:111], v[138:139]
	global_store_dwordx4 v142, v[106:109], s[20:21] nt
	v_pk_mul_f32 v[142:143], v[178:179], v[106:107]
	v_pk_fma_f32 v[112:113], v[176:177], v[112:113], v[140:141]
	v_pk_mul_f32 v[138:139], v[178:179], v[110:111]
	v_pk_mul_f32 v[208:209], v[174:175], v[108:109]
	v_cvt_pk_bf16_f32 v142, v142, v143
	v_pk_mul_f32 v[140:141], v[174:175], v[112:113]
	v_cvt_pk_bf16_f32 v143, v208, v209
	global_store_dwordx4 v[206:207], v[110:113], off nt
	v_cvt_pk_bf16_f32 v138, v138, v139
	v_cvt_pk_bf16_f32 v139, v140, v141
	ds_write_b128 v200, v[102:105]
	ds_write_b128 v200, v[98:101] offset:64
	ds_read_b128 v[98:101], v201
	ds_read_b128 v[102:105], v201 offset:1152
	v_lshl_add_u64 v[140:141], s[20:21], 0, v[184:185]
	s_waitcnt lgkmcnt(1)
	v_pk_fma_f32 v[98:99], v[168:169], v[98:99], v[134:135]
	v_pk_fma_f32 v[100:101], v[166:167], v[100:101], v[136:137]
	v_pk_mul_f32 v[136:137], v[172:173], v[98:99]
	global_store_dwordx4 v[140:141], v[98:101], off nt
	v_pk_mul_f32 v[134:135], v[170:171], v[100:101]
	v_cvt_pk_bf16_f32 v136, v136, v137
	s_waitcnt lgkmcnt(0)
	v_pk_fma_f32 v[102:103], v[168:169], v[102:103], v[130:131]
	v_cvt_pk_bf16_f32 v137, v134, v135
	ds_bpermute_b32 v130, v203, v136
	ds_bpermute_b32 v131, v203, v137
	v_pk_fma_f32 v[104:105], v[166:167], v[104:105], v[132:133]
	v_pk_mul_f32 v[132:133], v[172:173], v[102:103]
	v_pk_mul_f32 v[134:135], v[170:171], v[104:105]
	global_store_dwordx4 v[182:183], v[102:105], off nt
	v_cvt_pk_bf16_f32 v132, v132, v133
	v_cvt_pk_bf16_f32 v133, v134, v135
	v_lshlrev_b32_e32 v134, 1, v144
	s_waitcnt lgkmcnt(0)
	v_add_u32_e32 v250, 0xfffff040, v134
	v_cndmask_b32_e64 v250, v134, v250, s[40:41]
	v_cndmask_b32_e64 v248, v142, v130, s[40:41]
	v_cndmask_b32_e64 v249, v143, v131, s[40:41]
	global_store_dwordx2 v250, v[248:249], s[18:19]
	v_cndmask_b32_e64 v246, v130, v142, s[40:41]
	v_cndmask_b32_e64 v247, v131, v143, s[40:41]
	s_waitcnt lgkmcnt(1)
	v_add_u32_e32 v130, 0x1040, v134
	v_cndmask_b32_e64 v130, v134, v130, s[38:39]
	global_store_dwordx2 v130, v[246:247], s[18:19]
	ds_bpermute_b32 v130, v203, v132
	s_waitcnt lgkmcnt(1)
	ds_bpermute_b32 v131, v203, v133
	v_add_u32_e32 v133, 0xc000, v202
	v_lshlrev_b32_e32 v132, 1, v133
	s_waitcnt lgkmcnt(0)
	v_add_u32_e32 v250, 0xfffff040, v132
	v_cndmask_b32_e64 v250, v132, v250, s[40:41]
	v_cndmask_b32_e64 v248, v138, v130, s[40:41]
	v_cndmask_b32_e64 v249, v139, v131, s[40:41]
	global_store_dwordx2 v250, v[248:249], s[18:19]
	v_cndmask_b32_e64 v246, v130, v138, s[40:41]
	v_cndmask_b32_e64 v247, v131, v139, s[40:41]
	v_mul_f32_e32 v99, v99, v99
	v_fmac_f32_e32 v99, v98, v98
	v_mul_f32_e32 v98, v101, v101
	v_mul_f32_e32 v109, v109, v109
	v_fmac_f32_e32 v98, v100, v100
	v_mul_f32_e32 v107, v107, v107
	v_fmac_f32_e32 v109, v108, v108
	v_mul_f32_e32 v108, v111, v111
	v_mul_f32_e32 v111, v113, v113
	v_add_f32_e32 v98, v99, v98
	v_mul_f32_e32 v99, v103, v103
	v_mul_f32_e32 v100, v105, v105
	v_fmac_f32_e32 v111, v112, v112
	v_fmac_f32_e32 v99, v102, v102
	v_fmac_f32_e32 v100, v104, v104
	v_fmac_f32_e32 v107, v106, v106
	v_fmac_f32_e32 v108, v110, v110
	v_add_f32_e32 v99, v99, v100
	v_add_f32_e32 v100, v107, v109
	v_add_f32_e32 v101, v108, v111
	v_add_f32_e32 v98, v100, v98
	v_add_f32_e32 v99, v101, v99
	ds_bpermute_b32 v100, v190, v98
	ds_bpermute_b32 v101, v190, v99
	s_waitcnt lgkmcnt(1)
	v_add_f32_e32 v98, v98, v100
	s_waitcnt lgkmcnt(0)
	v_add_f32_e32 v101, v99, v101
	ds_bpermute_b32 v100, v191, v98
	ds_bpermute_b32 v102, v191, v101
	s_waitcnt lgkmcnt(1)
	v_add_f32_e32 v98, v98, v100
	s_waitcnt lgkmcnt(0)
	v_add_f32_e32 v100, v101, v102
	ds_bpermute_b32 v99, v204, v98
	ds_bpermute_b32 v101, v204, v100
	v_add_u32_e32 v102, 0x1040, v132
	v_cndmask_b32_e64 v102, v132, v102, s[38:39]
	global_store_dwordx2 v102, v[246:247], s[18:19]
	s_and_saveexec_b64 s[22:23], s[42:43]
	s_cbranch_execz .LBB0_1949
; #define LAS __attribute__((address_space(3)))
; __device__ __forceinline__ unsigned cvt_pk_bf16(float lo, float hi) { unsigned r; asm volatile("v_cvt_pk_bf16_f32 %0, %1, %2" : "=v"(r) : "v"(lo), "v"(hi)); return r; }
;     __device__ __forceinline__ void operator()(const f32x4 (&acc)[2][2][4][2], const Unit& u, int wr, int wc, int fr, int fq) const {
;     ...
;             if (g + 1 < 8) ERN_LOADX(g + 1);
;             float sq0 = 0.f, sq1 = 0.f; u32x2 hw[2][2];
; #pragma unroll
;             for (int bj = 0; bj < 2; ++bj) {
;                 *(LAS f32x4*)(st + wr_off) = acc[ai][bj][m][0]; *(LAS f32x4*)(st + wr_off + 64) = acc[ai][bj][m][1];
;                 const f32x4 a0 = *(const LAS f32x4*)(st + rd_off), a1 = *(const LAS f32x4*)(st + rd_off + 8 * 144);
;                 { const f32x4 xv = xb[g & 1][bj][0] + gv[bj] * a0; __builtin_nontemporal_store(xv, (f32x4*)((char*)xo + 4u * ERN_EOFF(g, bj, 0)));
;                   sq0 += (xv.x * xv.x + xv.y * xv.y) + (xv.z * xv.z + xv.w * xv.w);
;                   const f32x4 hv = xv * gsn[bj]; hw[bj][0].x = cvt_pk_bf16(hv.x, hv.y); hw[bj][0].y = cvt_pk_bf16(hv.z, hv.w); }
;                 { const f32x4 xv = xb[g & 1][bj][1] + gv[bj] * a1; __builtin_nontemporal_store(xv, (f32x4*)((char*)xo + 4u * ERN_EOFF(g, bj, 1)));
;                   sq1 += (xv.x * xv.x + xv.y * xv.y) + (xv.z * xv.z + xv.w * xv.w);
;                   const f32x4 hv = xv * gsn[bj]; hw[bj][1].x = cvt_pk_bf16(hv.x, hv.y); hw[bj][1].y = cvt_pk_bf16(hv.z, hv.w); }
;             }
;             if (!NOH && !PLAIN) {
; #pragma unroll
;                 for (int rh = 0; rh < 2; ++rh) { u32x2 rv; rv.x = __shfl_xor(hw[1][rh].x, 8); rv.y = __shfl_xor(hw[1][rh].y, 8);
;                     const unsigned e0 = ERN_EOFF(g, 0, rh);
;                     const unsigned ee = odd ? (e0 - DM + 32) : e0, eo2 = odd ? e0 : (e0 + DM + 32);
;                     *(u32x2*)((char*)ho + 2u * ee) = odd ? rv : hw[0][rh];
;                     *(u32x2*)((char*)ho + 2u * eo2) = odd ? hw[0][rh] : rv; }
;             }
;             if (!PLAIN) { sq0 += __shfl_xor(sq0, 1); sq0 += __shfl_xor(sq0, 2); sq0 += __shfl_xor(sq0, 4);
;             sq1 += __shfl_xor(sq1, 1); sq1 += __shfl_xor(sq1, 2); sq1 += __shfl_xor(sq1, 4); }
;             if (!PLAIN && pc == 0) { sst[g * 16 + rr] = sq0; sst[g * 16 + 8 + rr] = sq1; }
	s_waitcnt lgkmcnt(1)
	v_add_f32_e32 v98, v98, v99
	s_waitcnt lgkmcnt(0)
	v_add_f32_e32 v99, v100, v101
	ds_write2_b32 v194, v98, v99 offset0:16 offset1:24
.LBB0_1949:
	s_or_b64 exec, exec, s[22:23]
	v_lshl_add_u64 v[134:135], s[20:21], 0, v[154:155]
	v_add_u32_e32 v98, 0x60000, v205
	v_add_u32_e32 v154, 0x70000, v205
	v_add_u32_e32 v130, 0x60080, v205
	global_load_dwordx4 v[106:109], v154, s[20:21]
	global_load_dwordx4 v[102:105], v130, s[20:21]
	v_add_u32_e32 v132, 0x70080, v205
	global_load_dwordx4 v[110:113], v98, s[20:21]
	s_waitcnt lgkmcnt(0)
	global_load_dwordx4 v[98:101], v132, s[20:21]
	ds_write_b128 v200, v[94:97]
	ds_write_b128 v200, v[90:93] offset:64
	ds_read_b128 v[90:93], v201
	ds_read_b128 v[94:97], v201 offset:1152
	v_mov_b32_e32 v187, v155
	v_mov_b32_e32 v189, v155
	s_waitcnt vmcnt(11) lgkmcnt(1)
	v_pk_fma_f32 v[92:93], v[176:177], v[92:93], v[128:129]
	v_add_u32_e32 v128, 0x10000, v202
	v_pk_fma_f32 v[90:91], v[180:181], v[90:91], v[126:127]
	v_lshlrev_b32_e32 v126, 2, v128
	s_waitcnt lgkmcnt(0)
	v_pk_fma_f32 v[94:95], v[180:181], v[94:95], v[122:123]
	global_store_dwordx4 v126, v[90:93], s[20:21] nt
	v_pk_mul_f32 v[126:127], v[178:179], v[90:91]
	v_pk_fma_f32 v[96:97], v[176:177], v[96:97], v[124:125]
	v_pk_mul_f32 v[122:123], v[178:179], v[94:95]
	v_pk_mul_f32 v[136:137], v[174:175], v[92:93]
	v_cvt_pk_bf16_f32 v126, v126, v127
	v_pk_mul_f32 v[124:125], v[174:175], v[96:97]
	v_cvt_pk_bf16_f32 v127, v136, v137
	global_store_dwordx4 v[134:135], v[94:97], off nt
	v_cvt_pk_bf16_f32 v122, v122, v123
	v_cvt_pk_bf16_f32 v123, v124, v125
	ds_write_b128 v200, v[86:89]
	ds_write_b128 v200, v[82:85] offset:64
	ds_read_b128 v[82:85], v201
	ds_read_b128 v[86:89], v201 offset:1152
	v_lshl_add_u64 v[124:125], s[20:21], 0, v[186:187]
	v_lshl_add_u64 v[134:135], s[20:21], 0, v[188:189]
	s_waitcnt lgkmcnt(1)
	v_pk_fma_f32 v[82:83], v[168:169], v[82:83], v[118:119]
	v_pk_fma_f32 v[84:85], v[166:167], v[84:85], v[120:121]
	v_pk_mul_f32 v[120:121], v[172:173], v[82:83]
	global_store_dwordx4 v[124:125], v[82:85], off nt
	v_pk_mul_f32 v[118:119], v[170:171], v[84:85]
	v_cvt_pk_bf16_f32 v120, v120, v121
	s_waitcnt vmcnt(13) lgkmcnt(0)
	v_pk_fma_f32 v[86:87], v[168:169], v[86:87], v[114:115]
	v_cvt_pk_bf16_f32 v121, v118, v119
	ds_bpermute_b32 v114, v203, v120
	ds_bpermute_b32 v115, v203, v121
	v_pk_fma_f32 v[88:89], v[166:167], v[88:89], v[116:117]
	v_pk_mul_f32 v[116:117], v[172:173], v[86:87]
	v_pk_mul_f32 v[118:119], v[170:171], v[88:89]
	global_store_dwordx4 v[134:135], v[86:89], off nt
	v_cvt_pk_bf16_f32 v116, v116, v117
	v_cvt_pk_bf16_f32 v117, v118, v119
	v_lshlrev_b32_e32 v118, 1, v128
	s_waitcnt lgkmcnt(0)
	v_add_u32_e32 v250, 0xfffff040, v118
	v_cndmask_b32_e64 v250, v118, v250, s[40:41]
	v_cndmask_b32_e64 v248, v126, v114, s[40:41]
	v_cndmask_b32_e64 v249, v127, v115, s[40:41]
	global_store_dwordx2 v250, v[248:249], s[18:19]
	v_cndmask_b32_e64 v246, v114, v126, s[40:41]
	v_cndmask_b32_e64 v247, v115, v127, s[40:41]
	s_waitcnt lgkmcnt(1)
	v_add_u32_e32 v114, 0x1040, v118
	v_cndmask_b32_e64 v114, v118, v114, s[38:39]
	global_store_dwordx2 v114, v[246:247], s[18:19]
	ds_bpermute_b32 v114, v203, v116
	s_waitcnt lgkmcnt(1)
	ds_bpermute_b32 v115, v203, v117
	v_add_u32_e32 v117, 0x14000, v202
	v_lshlrev_b32_e32 v116, 1, v117
	s_waitcnt lgkmcnt(0)
	v_add_u32_e32 v250, 0xfffff040, v116
	v_cndmask_b32_e64 v250, v116, v250, s[40:41]
	v_cndmask_b32_e64 v248, v122, v114, s[40:41]
	v_cndmask_b32_e64 v249, v123, v115, s[40:41]
	global_store_dwordx2 v250, v[248:249], s[18:19]
	v_cndmask_b32_e64 v246, v114, v122, s[40:41]
	v_cndmask_b32_e64 v247, v115, v123, s[40:41]
	v_mul_f32_e32 v83, v83, v83
	v_fmac_f32_e32 v83, v82, v82
	v_mul_f32_e32 v82, v85, v85
	v_mul_f32_e32 v93, v93, v93
	v_fmac_f32_e32 v82, v84, v84
	v_mul_f32_e32 v91, v91, v91
	v_fmac_f32_e32 v93, v92, v92
	v_mul_f32_e32 v92, v95, v95
	v_mul_f32_e32 v95, v97, v97
	v_add_f32_e32 v82, v83, v82
	v_mul_f32_e32 v83, v87, v87
	v_mul_f32_e32 v84, v89, v89
	v_fmac_f32_e32 v95, v96, v96
	v_fmac_f32_e32 v83, v86, v86
	v_fmac_f32_e32 v84, v88, v88
	v_fmac_f32_e32 v91, v90, v90
	v_fmac_f32_e32 v92, v94, v94
	v_add_f32_e32 v83, v83, v84
	v_add_f32_e32 v84, v91, v93
	v_add_f32_e32 v85, v92, v95
	v_add_f32_e32 v82, v84, v82
	v_add_f32_e32 v83, v85, v83
	ds_bpermute_b32 v84, v190, v82
	ds_bpermute_b32 v85, v190, v83
	s_waitcnt lgkmcnt(1)
	v_add_f32_e32 v82, v82, v84
	s_waitcnt lgkmcnt(0)
	v_add_f32_e32 v85, v83, v85
	ds_bpermute_b32 v84, v191, v82
	ds_bpermute_b32 v86, v191, v85
	s_waitcnt lgkmcnt(1)
	v_add_f32_e32 v82, v82, v84
	s_waitcnt lgkmcnt(0)
	v_add_f32_e32 v84, v85, v86
	ds_bpermute_b32 v83, v204, v82
	ds_bpermute_b32 v85, v204, v84
	v_add_u32_e32 v86, 0x1040, v116
	v_cndmask_b32_e64 v86, v116, v86, s[38:39]
	global_store_dwordx2 v86, v[246:247], s[18:19]
	s_and_saveexec_b64 s[22:23], s[42:43]
	s_cbranch_execz .LBB0_1959
	s_waitcnt lgkmcnt(1)
	v_add_f32_e32 v82, v82, v83
	s_waitcnt lgkmcnt(0)
	v_add_f32_e32 v83, v84, v85
	ds_write2_b32 v194, v82, v83 offset0:32 offset1:40
; #define LAS __attribute__((address_space(3)))
; __device__ __forceinline__ unsigned cvt_pk_bf16(float lo, float hi) { unsigned r; asm volatile("v_cvt_pk_bf16_f32 %0, %1, %2" : "=v"(r) : "v"(lo), "v"(hi)); return r; }
;     __device__ __forceinline__ void operator()(const f32x4 (&acc)[2][2][4][2], const Unit& u, int wr, int wc, int fr, int fq) const {
;     ...
;             if (g + 1 < 8) ERN_LOADX(g + 1);
;             float sq0 = 0.f, sq1 = 0.f; u32x2 hw[2][2];
; #pragma unroll
;             for (int bj = 0; bj < 2; ++bj) {
;                 *(LAS f32x4*)(st + wr_off) = acc[ai][bj][m][0]; *(LAS f32x4*)(st + wr_off + 64) = acc[ai][bj][m][1];
;                 const f32x4 a0 = *(const LAS f32x4*)(st + rd_off), a1 = *(const LAS f32x4*)(st + rd_off + 8 * 144);
;                 { const f32x4 xv = xb[g & 1][bj][0] + gv[bj] * a0; __builtin_nontemporal_store(xv, (f32x4*)((char*)xo + 4u * ERN_EOFF(g, bj, 0)));
;                   sq0 += (xv.x * xv.x + xv.y * xv.y) + (xv.z * xv.z + xv.w * xv.w);
;                   const f32x4 hv = xv * gsn[bj]; hw[bj][0].x = cvt_pk_bf16(hv.x, hv.y); hw[bj][0].y = cvt_pk_bf16(hv.z, hv.w); }
;                 { const f32x4 xv = xb[g & 1][bj][1] + gv[bj] * a1; __builtin_nontemporal_store(xv, (f32x4*)((char*)xo + 4u * ERN_EOFF(g, bj, 1)));
;                   sq1 += (xv.x * xv.x + xv.y * xv.y) + (xv.z * xv.z + xv.w * xv.w);
;                   const f32x4 hv = xv * gsn[bj]; hw[bj][1].x = cvt_pk_bf16(hv.x, hv.y); hw[bj][1].y = cvt_pk_bf16(hv.z, hv.w); }
;             }
;             if (!NOH && !PLAIN) {
; #pragma unroll
;                 for (int rh = 0; rh < 2; ++rh) { u32x2 rv; rv.x = __shfl_xor(hw[1][rh].x, 8); rv.y = __shfl_xor(hw[1][rh].y, 8);
;                     const unsigned e0 = ERN_EOFF(g, 0, rh);
;                     const unsigned ee = odd ? (e0 - DM + 32) : e0, eo2 = odd ? e0 : (e0 + DM + 32);
;                     *(u32x2*)((char*)ho + 2u * ee) = odd ? rv : hw[0][rh];
;                     *(u32x2*)((char*)ho + 2u * eo2) = odd ? hw[0][rh] : rv; }
;             }
;             if (!PLAIN) { sq0 += __shfl_xor(sq0, 1); sq0 += __shfl_xor(sq0, 2); sq0 += __shfl_xor(sq0, 4);
;             sq1 += __shfl_xor(sq1, 1); sq1 += __shfl_xor(sq1, 2); sq1 += __shfl_xor(sq1, 4); }
;             if (!PLAIN && pc == 0) { sst[g * 16 + rr] = sq0; sst[g * 16 + 8 + rr] = sq1; }
.LBB0_1959:
	s_or_b64 exec, exec, s[22:23]
	v_lshl_add_u64 v[116:117], s[20:21], 0, v[154:155]
	v_add_u32_e32 v82, 0x100000, v205
	s_waitcnt lgkmcnt(1)
	v_add_u32_e32 v83, 0x110000, v205
	v_add_u32_e32 v154, 0x100080, v205
	global_load_dwordx4 v[94:97], v82, s[20:21]
	global_load_dwordx4 v[90:93], v83, s[20:21]
	v_add_u32_e32 v114, 0x110080, v205
	global_load_dwordx4 v[86:89], v154, s[20:21]
	s_waitcnt lgkmcnt(0)
	global_load_dwordx4 v[82:85], v114, s[20:21]
	ds_write_b128 v200, v[78:81]
	ds_write_b128 v200, v[74:77] offset:64
	ds_read_b128 v[74:77], v201
	ds_read_b128 v[78:81], v201 offset:1152
	v_mov_b32_e32 v131, v155
	v_mov_b32_e32 v133, v155
	s_waitcnt vmcnt(11) lgkmcnt(1)
	v_pk_fma_f32 v[76:77], v[176:177], v[76:77], v[112:113]
	v_add_u32_e32 v112, 0x18000, v202
	v_pk_fma_f32 v[74:75], v[180:181], v[74:75], v[110:111]
	v_lshlrev_b32_e32 v110, 2, v112
	s_waitcnt lgkmcnt(0)
	v_pk_fma_f32 v[78:79], v[180:181], v[78:79], v[106:107]
	global_store_dwordx4 v110, v[74:77], s[20:21] nt
	v_pk_mul_f32 v[110:111], v[178:179], v[74:75]
	v_pk_fma_f32 v[80:81], v[176:177], v[80:81], v[108:109]
	v_pk_mul_f32 v[106:107], v[178:179], v[78:79]
	v_pk_mul_f32 v[118:119], v[174:175], v[76:77]
	v_cvt_pk_bf16_f32 v110, v110, v111
	v_pk_mul_f32 v[108:109], v[174:175], v[80:81]
	v_cvt_pk_bf16_f32 v111, v118, v119
	global_store_dwordx4 v[116:117], v[78:81], off nt
	v_cvt_pk_bf16_f32 v106, v106, v107
	v_cvt_pk_bf16_f32 v107, v108, v109
	ds_write_b128 v200, v[70:73]
	ds_write_b128 v200, v[66:69] offset:64
	ds_read_b128 v[66:69], v201
	ds_read_b128 v[70:73], v201 offset:1152
	v_lshl_add_u64 v[108:109], s[20:21], 0, v[130:131]
	v_lshl_add_u64 v[116:117], s[20:21], 0, v[132:133]
	s_waitcnt lgkmcnt(1)
	v_pk_fma_f32 v[66:67], v[168:169], v[66:67], v[102:103]
	v_pk_fma_f32 v[68:69], v[166:167], v[68:69], v[104:105]
	v_pk_mul_f32 v[104:105], v[172:173], v[66:67]
	global_store_dwordx4 v[108:109], v[66:69], off nt
	v_pk_mul_f32 v[102:103], v[170:171], v[68:69]
	v_cvt_pk_bf16_f32 v104, v104, v105
	s_waitcnt vmcnt(13) lgkmcnt(0)
	v_pk_fma_f32 v[70:71], v[168:169], v[70:71], v[98:99]
	v_cvt_pk_bf16_f32 v105, v102, v103
	ds_bpermute_b32 v98, v203, v104
	ds_bpermute_b32 v99, v203, v105
	v_pk_fma_f32 v[72:73], v[166:167], v[72:73], v[100:101]
	v_pk_mul_f32 v[100:101], v[172:173], v[70:71]
	v_pk_mul_f32 v[102:103], v[170:171], v[72:73]
	global_store_dwordx4 v[116:117], v[70:73], off nt
	v_cvt_pk_bf16_f32 v100, v100, v101
	v_cvt_pk_bf16_f32 v101, v102, v103
	v_lshlrev_b32_e32 v102, 1, v112
	s_waitcnt lgkmcnt(0)
	v_add_u32_e32 v250, 0xfffff040, v102
	v_cndmask_b32_e64 v250, v102, v250, s[40:41]
	v_cndmask_b32_e64 v248, v110, v98, s[40:41]
	v_cndmask_b32_e64 v249, v111, v99, s[40:41]
	global_store_dwordx2 v250, v[248:249], s[18:19]
	v_cndmask_b32_e64 v246, v98, v110, s[40:41]
	v_cndmask_b32_e64 v247, v99, v111, s[40:41]
	s_waitcnt lgkmcnt(1)
	v_add_u32_e32 v98, 0x1040, v102
	v_cndmask_b32_e64 v98, v102, v98, s[38:39]
	global_store_dwordx2 v98, v[246:247], s[18:19]
	ds_bpermute_b32 v98, v203, v100
	s_waitcnt lgkmcnt(1)
	ds_bpermute_b32 v99, v203, v101
	v_add_u32_e32 v101, 0x1c000, v202
	v_lshlrev_b32_e32 v100, 1, v101
	s_waitcnt lgkmcnt(0)
	v_add_u32_e32 v250, 0xfffff040, v100
	v_cndmask_b32_e64 v250, v100, v250, s[40:41]
	v_cndmask_b32_e64 v248, v106, v98, s[40:41]
	v_cndmask_b32_e64 v249, v107, v99, s[40:41]
	global_store_dwordx2 v250, v[248:249], s[18:19]
	v_cndmask_b32_e64 v246, v98, v106, s[40:41]
	v_cndmask_b32_e64 v247, v99, v107, s[40:41]
	v_mul_f32_e32 v67, v67, v67
	v_fmac_f32_e32 v67, v66, v66
	v_mul_f32_e32 v66, v69, v69
	v_mul_f32_e32 v77, v77, v77
	v_fmac_f32_e32 v66, v68, v68
	v_mul_f32_e32 v75, v75, v75
	v_fmac_f32_e32 v77, v76, v76
	v_mul_f32_e32 v76, v79, v79
	v_mul_f32_e32 v79, v81, v81
	v_add_f32_e32 v66, v67, v66
	v_mul_f32_e32 v67, v71, v71
	v_mul_f32_e32 v68, v73, v73
	v_fmac_f32_e32 v79, v80, v80
	v_fmac_f32_e32 v67, v70, v70
	v_fmac_f32_e32 v68, v72, v72
	v_fmac_f32_e32 v75, v74, v74
	v_fmac_f32_e32 v76, v78, v78
	v_add_f32_e32 v67, v67, v68
	v_add_f32_e32 v68, v75, v77
	v_add_f32_e32 v69, v76, v79
	v_add_f32_e32 v66, v68, v66
	v_add_f32_e32 v67, v69, v67
	ds_bpermute_b32 v68, v190, v66
	ds_bpermute_b32 v69, v190, v67
	s_waitcnt lgkmcnt(1)
	v_add_f32_e32 v66, v66, v68
	s_waitcnt lgkmcnt(0)
	v_add_f32_e32 v69, v67, v69
	ds_bpermute_b32 v68, v191, v66
	ds_bpermute_b32 v70, v191, v69
	s_waitcnt lgkmcnt(1)
	v_add_f32_e32 v66, v66, v68
	s_waitcnt lgkmcnt(0)
	v_add_f32_e32 v68, v69, v70
	ds_bpermute_b32 v67, v204, v66
	ds_bpermute_b32 v69, v204, v68
	v_add_u32_e32 v70, 0x1040, v100
	v_cndmask_b32_e64 v70, v100, v70, s[38:39]
	global_store_dwordx2 v70, v[246:247], s[18:19]
	s_and_saveexec_b64 s[22:23], s[42:43]
	s_cbranch_execz .LBB0_1969
	s_waitcnt lgkmcnt(1)
	v_add_f32_e32 v66, v66, v67
	s_waitcnt lgkmcnt(0)
	v_add_f32_e32 v67, v68, v69
	ds_write2_b32 v194, v66, v67 offset0:48 offset1:56
; #define LAS __attribute__((address_space(3)))
; __device__ __forceinline__ unsigned cvt_pk_bf16(float lo, float hi) { unsigned r; asm volatile("v_cvt_pk_bf16_f32 %0, %1, %2" : "=v"(r) : "v"(lo), "v"(hi)); return r; }
;     __device__ __forceinline__ void operator()(const f32x4 (&acc)[2][2][4][2], const Unit& u, int wr, int wc, int fr, int fq) const {
;     ...
;             if (g + 1 < 8) ERN_LOADX(g + 1);
;             float sq0 = 0.f, sq1 = 0.f; u32x2 hw[2][2];
; #pragma unroll
;             for (int bj = 0; bj < 2; ++bj) {
;                 *(LAS f32x4*)(st + wr_off) = acc[ai][bj][m][0]; *(LAS f32x4*)(st + wr_off + 64) = acc[ai][bj][m][1];
;                 const f32x4 a0 = *(const LAS f32x4*)(st + rd_off), a1 = *(const LAS f32x4*)(st + rd_off + 8 * 144);
;                 { const f32x4 xv = xb[g & 1][bj][0] + gv[bj] * a0; __builtin_nontemporal_store(xv, (f32x4*)((char*)xo + 4u * ERN_EOFF(g, bj, 0)));
;                   sq0 += (xv.x * xv.x + xv.y * xv.y) + (xv.z * xv.z + xv.w * xv.w);
;                   const f32x4 hv = xv * gsn[bj]; hw[bj][0].x = cvt_pk_bf16(hv.x, hv.y); hw[bj][0].y = cvt_pk_bf16(hv.z, hv.w); }
;                 { const f32x4 xv = xb[g & 1][bj][1] + gv[bj] * a1; __builtin_nontemporal_store(xv, (f32x4*)((char*)xo + 4u * ERN_EOFF(g, bj, 1)));
;                   sq1 += (xv.x * xv.x + xv.y * xv.y) + (xv.z * xv.z + xv.w * xv.w);
;                   const f32x4 hv = xv * gsn[bj]; hw[bj][1].x = cvt_pk_bf16(hv.x, hv.y); hw[bj][1].y = cvt_pk_bf16(hv.z, hv.w); }
;             }
;             if (!NOH && !PLAIN) {
; #pragma unroll
;                 for (int rh = 0; rh < 2; ++rh) { u32x2 rv; rv.x = __shfl_xor(hw[1][rh].x, 8); rv.y = __shfl_xor(hw[1][rh].y, 8);
;                     const unsigned e0 = ERN_EOFF(g, 0, rh);
;                     const unsigned ee = odd ? (e0 - DM + 32) : e0, eo2 = odd ? e0 : (e0 + DM + 32);
;                     *(u32x2*)((char*)ho + 2u * ee) = odd ? rv : hw[0][rh];
;                     *(u32x2*)((char*)ho + 2u * eo2) = odd ? hw[0][rh] : rv; }
;             }
;             if (!PLAIN) { sq0 += __shfl_xor(sq0, 1); sq0 += __shfl_xor(sq0, 2); sq0 += __shfl_xor(sq0, 4);
;             sq1 += __shfl_xor(sq1, 1); sq1 += __shfl_xor(sq1, 2); sq1 += __shfl_xor(sq1, 4); }
;             if (!PLAIN && pc == 0) { sst[g * 16 + rr] = sq0; sst[g * 16 + 8 + rr] = sq1; }
.LBB0_1969:
	s_or_b64 exec, exec, s[22:23]
	v_lshl_add_u64 v[104:105], s[20:21], 0, v[154:155]
	v_add_u32_e32 v154, 0x120000, v205
	v_add_u32_e32 v100, 0x120080, v205
	v_add_u32_e32 v102, 0x130000, v205
	global_load_dwordx4 v[78:81], v154, s[20:21]
	global_load_dwordx4 v[74:77], v102, s[20:21]
	v_add_u32_e32 v98, 0x130080, v205
	global_load_dwordx4 v[70:73], v100, s[20:21]
	s_waitcnt lgkmcnt(0)
	global_load_dwordx4 v[66:69], v98, s[20:21]
	ds_write_b128 v200, v[62:65]
	ds_write_b128 v200, v[58:61] offset:64
	ds_read_b128 v[58:61], v201
	ds_read_b128 v[62:65], v201 offset:1152
	v_mov_b32_e32 v115, v155
	s_waitcnt vmcnt(13) lgkmcnt(1)
	v_pk_fma_f32 v[60:61], v[176:177], v[60:61], v[96:97]
	v_add_u32_e32 v96, 0x40000, v202
	v_pk_fma_f32 v[58:59], v[180:181], v[58:59], v[94:95]
	v_lshlrev_b32_e32 v94, 2, v96
	s_waitcnt vmcnt(12) lgkmcnt(0)
	v_pk_fma_f32 v[64:65], v[176:177], v[64:65], v[92:93]
	v_add_u32_e32 v92, 0x44000, v202
	global_store_dwordx4 v94, v[58:61], s[20:21] nt
	v_pk_mul_f32 v[94:95], v[178:179], v[58:59]
	v_pk_fma_f32 v[62:63], v[180:181], v[62:63], v[90:91]
	v_lshlrev_b32_e32 v90, 2, v92
	v_pk_mul_f32 v[106:107], v[174:175], v[60:61]
	v_cvt_pk_bf16_f32 v94, v94, v95
	s_nop 0
	v_cvt_pk_bf16_f32 v95, v106, v107
	global_store_dwordx4 v90, v[62:65], s[20:21] nt
	v_pk_mul_f32 v[90:91], v[178:179], v[62:63]
	v_pk_mul_f32 v[106:107], v[174:175], v[64:65]
	v_cvt_pk_bf16_f32 v90, v90, v91
	s_nop 0
	v_cvt_pk_bf16_f32 v91, v106, v107
	ds_write_b128 v200, v[54:57]
	ds_write_b128 v200, v[50:53] offset:64
	ds_read_b128 v[50:53], v201
	ds_read_b128 v[54:57], v201 offset:1152
	v_lshl_add_u64 v[106:107], s[20:21], 0, v[114:115]
	s_waitcnt vmcnt(13) lgkmcnt(1)
	v_pk_fma_f32 v[50:51], v[168:169], v[50:51], v[86:87]
	v_pk_fma_f32 v[52:53], v[166:167], v[52:53], v[88:89]
	v_pk_mul_f32 v[88:89], v[172:173], v[50:51]
	global_store_dwordx4 v[104:105], v[50:53], off nt
	v_pk_mul_f32 v[86:87], v[170:171], v[52:53]
	v_cvt_pk_bf16_f32 v88, v88, v89
	s_waitcnt vmcnt(13) lgkmcnt(0)
	v_pk_fma_f32 v[54:55], v[168:169], v[54:55], v[82:83]
	v_cvt_pk_bf16_f32 v89, v86, v87
	ds_bpermute_b32 v82, v203, v88
	ds_bpermute_b32 v83, v203, v89
	v_pk_fma_f32 v[56:57], v[166:167], v[56:57], v[84:85]
	v_pk_mul_f32 v[84:85], v[172:173], v[54:55]
	v_pk_mul_f32 v[86:87], v[170:171], v[56:57]
	global_store_dwordx4 v[106:107], v[54:57], off nt
	v_cvt_pk_bf16_f32 v84, v84, v85
	v_cvt_pk_bf16_f32 v85, v86, v87
	v_lshlrev_b32_e32 v86, 1, v96
	s_waitcnt lgkmcnt(0)
	v_add_u32_e32 v250, 0xfffff040, v86
	v_cndmask_b32_e64 v250, v86, v250, s[40:41]
	v_cndmask_b32_e64 v248, v94, v82, s[40:41]
	v_cndmask_b32_e64 v249, v95, v83, s[40:41]
	global_store_dwordx2 v250, v[248:249], s[18:19]
	v_cndmask_b32_e64 v246, v82, v94, s[40:41]
	v_cndmask_b32_e64 v247, v83, v95, s[40:41]
	s_waitcnt lgkmcnt(1)
	v_add_u32_e32 v82, 0x1040, v86
	v_cndmask_b32_e64 v82, v86, v82, s[38:39]
	global_store_dwordx2 v82, v[246:247], s[18:19]
	ds_bpermute_b32 v82, v203, v84
	s_waitcnt lgkmcnt(1)
	ds_bpermute_b32 v83, v203, v85
	v_lshlrev_b32_e32 v84, 1, v92
	s_waitcnt lgkmcnt(0)
	v_add_u32_e32 v250, 0xfffff040, v84
	v_cndmask_b32_e64 v250, v84, v250, s[40:41]
	v_cndmask_b32_e64 v248, v90, v82, s[40:41]
	v_cndmask_b32_e64 v249, v91, v83, s[40:41]
	global_store_dwordx2 v250, v[248:249], s[18:19]
	v_cndmask_b32_e64 v246, v82, v90, s[40:41]
	v_cndmask_b32_e64 v247, v83, v91, s[40:41]
	v_mul_f32_e32 v51, v51, v51
	v_fmac_f32_e32 v51, v50, v50
	v_mul_f32_e32 v50, v53, v53
	v_mul_f32_e32 v61, v61, v61
	v_fmac_f32_e32 v50, v52, v52
	v_mul_f32_e32 v59, v59, v59
	v_fmac_f32_e32 v61, v60, v60
	v_mul_f32_e32 v60, v63, v63
	v_mul_f32_e32 v63, v65, v65
	v_add_f32_e32 v50, v51, v50
	v_mul_f32_e32 v51, v55, v55
	v_mul_f32_e32 v52, v57, v57
	v_fmac_f32_e32 v63, v64, v64
	v_fmac_f32_e32 v51, v54, v54
	v_fmac_f32_e32 v52, v56, v56
	v_fmac_f32_e32 v59, v58, v58
	v_fmac_f32_e32 v60, v62, v62
	v_add_f32_e32 v51, v51, v52
	v_add_f32_e32 v52, v59, v61
	v_add_f32_e32 v53, v60, v63
	v_add_f32_e32 v50, v52, v50
	v_add_f32_e32 v51, v53, v51
	ds_bpermute_b32 v52, v190, v50
	ds_bpermute_b32 v53, v190, v51
	s_waitcnt lgkmcnt(1)
	v_add_f32_e32 v50, v50, v52
	s_waitcnt lgkmcnt(0)
	v_add_f32_e32 v53, v51, v53
	ds_bpermute_b32 v52, v191, v50
	ds_bpermute_b32 v54, v191, v53
	s_waitcnt lgkmcnt(1)
	v_add_f32_e32 v50, v50, v52
	s_waitcnt lgkmcnt(0)
	v_add_f32_e32 v52, v53, v54
	ds_bpermute_b32 v51, v204, v50
	ds_bpermute_b32 v53, v204, v52
	v_add_u32_e32 v54, 0x1040, v84
	v_cndmask_b32_e64 v54, v84, v54, s[38:39]
	global_store_dwordx2 v54, v[246:247], s[18:19]
	s_and_saveexec_b64 s[22:23], s[42:43]
	s_cbranch_execz .LBB0_1979
	s_waitcnt lgkmcnt(1)
	v_add_f32_e32 v50, v50, v51
	s_waitcnt lgkmcnt(0)
	v_add_f32_e32 v51, v52, v53
	ds_write2_b32 v194, v50, v51 offset0:64 offset1:72
; #define LAS __attribute__((address_space(3)))
; __device__ __forceinline__ unsigned cvt_pk_bf16(float lo, float hi) { unsigned r; asm volatile("v_cvt_pk_bf16_f32 %0, %1, %2" : "=v"(r) : "v"(lo), "v"(hi)); return r; }
;     __device__ __forceinline__ void operator()(const f32x4 (&acc)[2][2][4][2], const Unit& u, int wr, int wc, int fr, int fq) const {
;     ...
;             if (g + 1 < 8) ERN_LOADX(g + 1);
;             float sq0 = 0.f, sq1 = 0.f; u32x2 hw[2][2];
; #pragma unroll
;             for (int bj = 0; bj < 2; ++bj) {
;                 *(LAS f32x4*)(st + wr_off) = acc[ai][bj][m][0]; *(LAS f32x4*)(st + wr_off + 64) = acc[ai][bj][m][1];
;                 const f32x4 a0 = *(const LAS f32x4*)(st + rd_off), a1 = *(const LAS f32x4*)(st + rd_off + 8 * 144);
;                 { const f32x4 xv = xb[g & 1][bj][0] + gv[bj] * a0; __builtin_nontemporal_store(xv, (f32x4*)((char*)xo + 4u * ERN_EOFF(g, bj, 0)));
;                   sq0 += (xv.x * xv.x + xv.y * xv.y) + (xv.z * xv.z + xv.w * xv.w);
;                   const f32x4 hv = xv * gsn[bj]; hw[bj][0].x = cvt_pk_bf16(hv.x, hv.y); hw[bj][0].y = cvt_pk_bf16(hv.z, hv.w); }
;                 { const f32x4 xv = xb[g & 1][bj][1] + gv[bj] * a1; __builtin_nontemporal_store(xv, (f32x4*)((char*)xo + 4u * ERN_EOFF(g, bj, 1)));
;                   sq1 += (xv.x * xv.x + xv.y * xv.y) + (xv.z * xv.z + xv.w * xv.w);
;                   const f32x4 hv = xv * gsn[bj]; hw[bj][1].x = cvt_pk_bf16(hv.x, hv.y); hw[bj][1].y = cvt_pk_bf16(hv.z, hv.w); }
;             }
;             if (!NOH && !PLAIN) {
; #pragma unroll
;                 for (int rh = 0; rh < 2; ++rh) { u32x2 rv; rv.x = __shfl_xor(hw[1][rh].x, 8); rv.y = __shfl_xor(hw[1][rh].y, 8);
;                     const unsigned e0 = ERN_EOFF(g, 0, rh);
;                     const unsigned ee = odd ? (e0 - DM + 32) : e0, eo2 = odd ? e0 : (e0 + DM + 32);
;                     *(u32x2*)((char*)ho + 2u * ee) = odd ? rv : hw[0][rh];
;                     *(u32x2*)((char*)ho + 2u * eo2) = odd ? hw[0][rh] : rv; }
;             }
;             if (!PLAIN) { sq0 += __shfl_xor(sq0, 1); sq0 += __shfl_xor(sq0, 2); sq0 += __shfl_xor(sq0, 4);
;             sq1 += __shfl_xor(sq1, 1); sq1 += __shfl_xor(sq1, 2); sq1 += __shfl_xor(sq1, 4); }
;             if (!PLAIN && pc == 0) { sst[g * 16 + rr] = sq0; sst[g * 16 + 8 + rr] = sq1; }
.LBB0_1979:
	s_or_b64 exec, exec, s[22:23]
	v_lshl_add_u64 v[88:89], s[20:21], 0, v[154:155]
	v_add_u32_e32 v154, 0x140000, v205
	v_add_u32_e32 v84, 0x140080, v205
	v_add_u32_e32 v86, 0x150000, v205
	global_load_dwordx4 v[62:65], v154, s[20:21]
	global_load_dwordx4 v[58:61], v86, s[20:21]
	v_add_u32_e32 v82, 0x150080, v205
	global_load_dwordx4 v[54:57], v84, s[20:21]
	s_waitcnt lgkmcnt(0)
	global_load_dwordx4 v[50:53], v82, s[20:21]
	ds_write_b128 v200, v[46:49]
	ds_write_b128 v200, v[42:45] offset:64
	ds_read_b128 v[42:45], v201
	ds_read_b128 v[46:49], v201 offset:1152
	v_mov_b32_e32 v103, v155
	v_lshl_add_u64 v[90:91], s[20:21], 0, v[102:103]
	v_mov_b32_e32 v101, v155
	s_waitcnt vmcnt(13) lgkmcnt(1)
	v_pk_fma_f32 v[42:43], v[180:181], v[42:43], v[78:79]
	s_waitcnt vmcnt(12) lgkmcnt(0)
	v_pk_fma_f32 v[46:47], v[180:181], v[46:47], v[74:75]
	v_pk_fma_f32 v[44:45], v[176:177], v[44:45], v[80:81]
	v_pk_mul_f32 v[78:79], v[178:179], v[42:43]
	v_pk_fma_f32 v[48:49], v[176:177], v[48:49], v[76:77]
	v_pk_mul_f32 v[74:75], v[178:179], v[46:47]
	global_store_dwordx4 v[88:89], v[42:45], off nt
	v_pk_mul_f32 v[80:81], v[174:175], v[44:45]
	v_cvt_pk_bf16_f32 v78, v78, v79
	v_pk_mul_f32 v[76:77], v[174:175], v[48:49]
	v_cvt_pk_bf16_f32 v79, v80, v81
	global_store_dwordx4 v[90:91], v[46:49], off nt
	v_cvt_pk_bf16_f32 v74, v74, v75
	v_cvt_pk_bf16_f32 v75, v76, v77
	ds_write_b128 v200, v[38:41]
	ds_write_b128 v200, v[34:37] offset:64
	ds_read_b128 v[34:37], v201
	ds_read_b128 v[38:41], v201 offset:1152
	v_lshl_add_u64 v[76:77], s[20:21], 0, v[100:101]
	v_mov_b32_e32 v99, v155
	v_lshl_add_u64 v[80:81], s[20:21], 0, v[98:99]
	s_waitcnt vmcnt(13) lgkmcnt(1)
	v_pk_fma_f32 v[34:35], v[168:169], v[34:35], v[70:71]
	v_pk_fma_f32 v[36:37], v[166:167], v[36:37], v[72:73]
	v_pk_mul_f32 v[72:73], v[172:173], v[34:35]
	global_store_dwordx4 v[76:77], v[34:37], off nt
	v_pk_mul_f32 v[70:71], v[170:171], v[36:37]
	v_cvt_pk_bf16_f32 v72, v72, v73
	s_waitcnt vmcnt(13) lgkmcnt(0)
	v_pk_fma_f32 v[38:39], v[168:169], v[38:39], v[66:67]
	v_cvt_pk_bf16_f32 v73, v70, v71
	ds_bpermute_b32 v66, v203, v72
	ds_bpermute_b32 v67, v203, v73
	v_pk_fma_f32 v[40:41], v[166:167], v[40:41], v[68:69]
	v_pk_mul_f32 v[68:69], v[172:173], v[38:39]
	v_pk_mul_f32 v[70:71], v[170:171], v[40:41]
	global_store_dwordx4 v[80:81], v[38:41], off nt
	v_cvt_pk_bf16_f32 v68, v68, v69
	v_cvt_pk_bf16_f32 v69, v70, v71
	v_add_u32_e32 v71, 0x48000, v202
	v_lshlrev_b32_e32 v70, 1, v71
	s_waitcnt lgkmcnt(0)
	v_add_u32_e32 v250, 0xfffff040, v70
	v_cndmask_b32_e64 v250, v70, v250, s[40:41]
	v_cndmask_b32_e64 v248, v78, v66, s[40:41]
	v_cndmask_b32_e64 v249, v79, v67, s[40:41]
	global_store_dwordx2 v250, v[248:249], s[18:19]
	v_cndmask_b32_e64 v246, v66, v78, s[40:41]
	v_cndmask_b32_e64 v247, v67, v79, s[40:41]
	s_waitcnt lgkmcnt(1)
	v_add_u32_e32 v66, 0x1040, v70
	v_cndmask_b32_e64 v66, v70, v66, s[38:39]
	global_store_dwordx2 v66, v[246:247], s[18:19]
	ds_bpermute_b32 v66, v203, v68
	s_waitcnt lgkmcnt(1)
	ds_bpermute_b32 v67, v203, v69
	v_add_u32_e32 v69, 0x4c000, v202
	v_lshlrev_b32_e32 v68, 1, v69
	s_waitcnt lgkmcnt(0)
	v_add_u32_e32 v250, 0xfffff040, v68
	v_cndmask_b32_e64 v250, v68, v250, s[40:41]
	v_cndmask_b32_e64 v248, v74, v66, s[40:41]
	v_cndmask_b32_e64 v249, v75, v67, s[40:41]
	global_store_dwordx2 v250, v[248:249], s[18:19]
	v_cndmask_b32_e64 v246, v66, v74, s[40:41]
	v_cndmask_b32_e64 v247, v67, v75, s[40:41]
	v_mul_f32_e32 v35, v35, v35
	v_fmac_f32_e32 v35, v34, v34
	v_mul_f32_e32 v34, v37, v37
	v_mul_f32_e32 v45, v45, v45
	v_fmac_f32_e32 v34, v36, v36
	v_mul_f32_e32 v43, v43, v43
	v_fmac_f32_e32 v45, v44, v44
	v_mul_f32_e32 v44, v47, v47
	v_mul_f32_e32 v47, v49, v49
	v_add_f32_e32 v34, v35, v34
	v_mul_f32_e32 v35, v39, v39
	v_mul_f32_e32 v36, v41, v41
	v_fmac_f32_e32 v47, v48, v48
	v_fmac_f32_e32 v35, v38, v38
	v_fmac_f32_e32 v36, v40, v40
	v_fmac_f32_e32 v43, v42, v42
	v_fmac_f32_e32 v44, v46, v46
	v_add_f32_e32 v35, v35, v36
	v_add_f32_e32 v36, v43, v45
	v_add_f32_e32 v37, v44, v47
	v_add_f32_e32 v34, v36, v34
	v_add_f32_e32 v35, v37, v35
	ds_bpermute_b32 v36, v190, v34
	ds_bpermute_b32 v37, v190, v35
	s_waitcnt lgkmcnt(1)
	v_add_f32_e32 v34, v34, v36
	s_waitcnt lgkmcnt(0)
	v_add_f32_e32 v37, v35, v37
	ds_bpermute_b32 v36, v191, v34
	ds_bpermute_b32 v38, v191, v37
	s_waitcnt lgkmcnt(1)
	v_add_f32_e32 v34, v34, v36
	s_waitcnt lgkmcnt(0)
	v_add_f32_e32 v36, v37, v38
	ds_bpermute_b32 v35, v204, v34
	ds_bpermute_b32 v37, v204, v36
	v_add_u32_e32 v38, 0x1040, v68
	v_cndmask_b32_e64 v38, v68, v38, s[38:39]
	global_store_dwordx2 v38, v[246:247], s[18:19]
	s_and_saveexec_b64 s[22:23], s[42:43]
	s_cbranch_execz .LBB0_1989
	s_waitcnt lgkmcnt(1)
	v_add_f32_e32 v34, v34, v35
	s_waitcnt lgkmcnt(0)
	v_add_f32_e32 v35, v36, v37
	ds_write2_b32 v194, v34, v35 offset0:80 offset1:88
; #define LAS __attribute__((address_space(3)))
; __device__ __forceinline__ unsigned cvt_pk_bf16(float lo, float hi) { unsigned r; asm volatile("v_cvt_pk_bf16_f32 %0, %1, %2" : "=v"(r) : "v"(lo), "v"(hi)); return r; }
;     __device__ __forceinline__ void operator()(const f32x4 (&acc)[2][2][4][2], const Unit& u, int wr, int wc, int fr, int fq) const {
;     ...
;             if (g + 1 < 8) ERN_LOADX(g + 1);
;             float sq0 = 0.f, sq1 = 0.f; u32x2 hw[2][2];
; #pragma unroll
;             for (int bj = 0; bj < 2; ++bj) {
;                 *(LAS f32x4*)(st + wr_off) = acc[ai][bj][m][0]; *(LAS f32x4*)(st + wr_off + 64) = acc[ai][bj][m][1];
;                 const f32x4 a0 = *(const LAS f32x4*)(st + rd_off), a1 = *(const LAS f32x4*)(st + rd_off + 8 * 144);
;                 { const f32x4 xv = xb[g & 1][bj][0] + gv[bj] * a0; __builtin_nontemporal_store(xv, (f32x4*)((char*)xo + 4u * ERN_EOFF(g, bj, 0)));
;                   sq0 += (xv.x * xv.x + xv.y * xv.y) + (xv.z * xv.z + xv.w * xv.w);
;                   const f32x4 hv = xv * gsn[bj]; hw[bj][0].x = cvt_pk_bf16(hv.x, hv.y); hw[bj][0].y = cvt_pk_bf16(hv.z, hv.w); }
;                 { const f32x4 xv = xb[g & 1][bj][1] + gv[bj] * a1; __builtin_nontemporal_store(xv, (f32x4*)((char*)xo + 4u * ERN_EOFF(g, bj, 1)));
;                   sq1 += (xv.x * xv.x + xv.y * xv.y) + (xv.z * xv.z + xv.w * xv.w);
;                   const f32x4 hv = xv * gsn[bj]; hw[bj][1].x = cvt_pk_bf16(hv.x, hv.y); hw[bj][1].y = cvt_pk_bf16(hv.z, hv.w); }
;             }
;             if (!NOH && !PLAIN) {
; #pragma unroll
;                 for (int rh = 0; rh < 2; ++rh) { u32x2 rv; rv.x = __shfl_xor(hw[1][rh].x, 8); rv.y = __shfl_xor(hw[1][rh].y, 8);
;                     const unsigned e0 = ERN_EOFF(g, 0, rh);
;                     const unsigned ee = odd ? (e0 - DM + 32) : e0, eo2 = odd ? e0 : (e0 + DM + 32);
;                     *(u32x2*)((char*)ho + 2u * ee) = odd ? rv : hw[0][rh];
;                     *(u32x2*)((char*)ho + 2u * eo2) = odd ? hw[0][rh] : rv; }
;             }
;             if (!PLAIN) { sq0 += __shfl_xor(sq0, 1); sq0 += __shfl_xor(sq0, 2); sq0 += __shfl_xor(sq0, 4);
;             sq1 += __shfl_xor(sq1, 1); sq1 += __shfl_xor(sq1, 2); sq1 += __shfl_xor(sq1, 4); }
;             if (!PLAIN && pc == 0) { sst[g * 16 + rr] = sq0; sst[g * 16 + 8 + rr] = sq1; }
.LBB0_1989:
	s_or_b64 exec, exec, s[22:23]
	v_lshl_add_u64 v[72:73], s[20:21], 0, v[154:155]
	v_add_u32_e32 v154, 0x160000, v205
	v_add_u32_e32 v68, 0x160080, v205
	v_add_u32_e32 v70, 0x170000, v205
	global_load_dwordx4 v[46:49], v154, s[20:21]
	global_load_dwordx4 v[42:45], v70, s[20:21]
	v_add_u32_e32 v66, 0x170080, v205
	global_load_dwordx4 v[38:41], v68, s[20:21]
	s_waitcnt lgkmcnt(0)
	global_load_dwordx4 v[34:37], v66, s[20:21]
	ds_write_b128 v200, v[30:33]
	ds_write_b128 v200, v[26:29] offset:64
	ds_read_b128 v[26:29], v201
	ds_read_b128 v[30:33], v201 offset:1152
	v_mov_b32_e32 v87, v155
	v_lshl_add_u64 v[74:75], s[20:21], 0, v[86:87]
	v_mov_b32_e32 v85, v155
	s_waitcnt vmcnt(13) lgkmcnt(1)
	v_pk_fma_f32 v[26:27], v[180:181], v[26:27], v[62:63]
	s_waitcnt vmcnt(12) lgkmcnt(0)
	v_pk_fma_f32 v[30:31], v[180:181], v[30:31], v[58:59]
	v_pk_fma_f32 v[28:29], v[176:177], v[28:29], v[64:65]
	v_pk_mul_f32 v[62:63], v[178:179], v[26:27]
	v_pk_fma_f32 v[32:33], v[176:177], v[32:33], v[60:61]
	v_pk_mul_f32 v[58:59], v[178:179], v[30:31]
	global_store_dwordx4 v[72:73], v[26:29], off nt
	v_pk_mul_f32 v[64:65], v[174:175], v[28:29]
	v_cvt_pk_bf16_f32 v62, v62, v63
	v_pk_mul_f32 v[60:61], v[174:175], v[32:33]
	v_cvt_pk_bf16_f32 v63, v64, v65
	global_store_dwordx4 v[74:75], v[30:33], off nt
	v_cvt_pk_bf16_f32 v58, v58, v59
	v_cvt_pk_bf16_f32 v59, v60, v61
	ds_write_b128 v200, v[22:25]
	ds_write_b128 v200, v[18:21] offset:64
	ds_read_b128 v[18:21], v201
	ds_read_b128 v[22:25], v201 offset:1152
	v_lshl_add_u64 v[60:61], s[20:21], 0, v[84:85]
	v_mov_b32_e32 v83, v155
	v_lshl_add_u64 v[64:65], s[20:21], 0, v[82:83]
	s_waitcnt vmcnt(13) lgkmcnt(1)
	v_pk_fma_f32 v[18:19], v[168:169], v[18:19], v[54:55]
	v_pk_fma_f32 v[20:21], v[166:167], v[20:21], v[56:57]
	v_pk_mul_f32 v[56:57], v[172:173], v[18:19]
	global_store_dwordx4 v[60:61], v[18:21], off nt
	v_pk_mul_f32 v[54:55], v[170:171], v[20:21]
	v_cvt_pk_bf16_f32 v56, v56, v57
	s_waitcnt vmcnt(13) lgkmcnt(0)
	v_pk_fma_f32 v[22:23], v[168:169], v[22:23], v[50:51]
	v_cvt_pk_bf16_f32 v57, v54, v55
	ds_bpermute_b32 v50, v203, v56
	ds_bpermute_b32 v51, v203, v57
	v_pk_fma_f32 v[24:25], v[166:167], v[24:25], v[52:53]
	v_pk_mul_f32 v[52:53], v[172:173], v[22:23]
	v_pk_mul_f32 v[54:55], v[170:171], v[24:25]
	global_store_dwordx4 v[64:65], v[22:25], off nt
	v_cvt_pk_bf16_f32 v52, v52, v53
	v_cvt_pk_bf16_f32 v53, v54, v55
	v_add_u32_e32 v55, 0x50000, v202
	v_lshlrev_b32_e32 v54, 1, v55
	s_waitcnt lgkmcnt(0)
	v_add_u32_e32 v250, 0xfffff040, v54
	v_cndmask_b32_e64 v250, v54, v250, s[40:41]
	v_cndmask_b32_e64 v248, v62, v50, s[40:41]
	v_cndmask_b32_e64 v249, v63, v51, s[40:41]
	global_store_dwordx2 v250, v[248:249], s[18:19]
	v_cndmask_b32_e64 v246, v50, v62, s[40:41]
	v_cndmask_b32_e64 v247, v51, v63, s[40:41]
	s_waitcnt lgkmcnt(1)
	v_add_u32_e32 v50, 0x1040, v54
	v_cndmask_b32_e64 v50, v54, v50, s[38:39]
	global_store_dwordx2 v50, v[246:247], s[18:19]
	ds_bpermute_b32 v50, v203, v52
	s_waitcnt lgkmcnt(1)
	ds_bpermute_b32 v51, v203, v53
	v_add_u32_e32 v53, 0x54000, v202
	v_lshlrev_b32_e32 v52, 1, v53
	s_waitcnt lgkmcnt(0)
	v_add_u32_e32 v250, 0xfffff040, v52
	v_cndmask_b32_e64 v250, v52, v250, s[40:41]
	v_cndmask_b32_e64 v248, v58, v50, s[40:41]
	v_cndmask_b32_e64 v249, v59, v51, s[40:41]
	global_store_dwordx2 v250, v[248:249], s[18:19]
	v_cndmask_b32_e64 v246, v50, v58, s[40:41]
	v_cndmask_b32_e64 v247, v51, v59, s[40:41]
	v_mul_f32_e32 v19, v19, v19
	v_fmac_f32_e32 v19, v18, v18
	v_mul_f32_e32 v18, v21, v21
	v_mul_f32_e32 v29, v29, v29
	v_fmac_f32_e32 v18, v20, v20
	v_mul_f32_e32 v27, v27, v27
	v_fmac_f32_e32 v29, v28, v28
	v_mul_f32_e32 v28, v31, v31
	v_mul_f32_e32 v31, v33, v33
	v_add_f32_e32 v18, v19, v18
	v_mul_f32_e32 v19, v23, v23
	v_mul_f32_e32 v20, v25, v25
	v_fmac_f32_e32 v31, v32, v32
	v_fmac_f32_e32 v19, v22, v22
	v_fmac_f32_e32 v20, v24, v24
	v_fmac_f32_e32 v27, v26, v26
	v_fmac_f32_e32 v28, v30, v30
	v_add_f32_e32 v19, v19, v20
	v_add_f32_e32 v20, v27, v29
	v_add_f32_e32 v21, v28, v31
	v_add_f32_e32 v18, v20, v18
	v_add_f32_e32 v19, v21, v19
	ds_bpermute_b32 v20, v190, v18
	ds_bpermute_b32 v21, v190, v19
	s_waitcnt lgkmcnt(1)
	v_add_f32_e32 v18, v18, v20
	s_waitcnt lgkmcnt(0)
	v_add_f32_e32 v21, v19, v21
	ds_bpermute_b32 v20, v191, v18
	ds_bpermute_b32 v22, v191, v21
	s_waitcnt lgkmcnt(1)
	v_add_f32_e32 v18, v18, v20
	s_waitcnt lgkmcnt(0)
	v_add_f32_e32 v20, v21, v22
	ds_bpermute_b32 v19, v204, v18
	ds_bpermute_b32 v21, v204, v20
	v_add_u32_e32 v22, 0x1040, v52
	v_cndmask_b32_e64 v22, v52, v22, s[38:39]
	global_store_dwordx2 v22, v[246:247], s[18:19]
	s_and_saveexec_b64 s[22:23], s[42:43]
	s_cbranch_execz .LBB0_1999
	s_waitcnt lgkmcnt(1)
	v_add_f32_e32 v18, v18, v19
	s_waitcnt lgkmcnt(0)
	v_add_f32_e32 v19, v20, v21
	ds_write2_b32 v194, v18, v19 offset0:96 offset1:104
; #define LAS __attribute__((address_space(3)))
; __device__ __forceinline__ unsigned cvt_pk_bf16(float lo, float hi) { unsigned r; asm volatile("v_cvt_pk_bf16_f32 %0, %1, %2" : "=v"(r) : "v"(lo), "v"(hi)); return r; }
; #define ERN_EOFF(q, m) (eb + (unsigned)((((q) & 1) * HALF + (m) * 16) * DM + ERN_COL((q) >> 1)))
;     __device__ __forceinline__ void operator()(const f32x4 (&acc)[2][2][4][2], const Unit& u, int wr, int wc, int fr, int fq) const {
;     ...
;             float sq0 = 0.f, sq1 = 0.f; u32x2 hw[2][2];
; #pragma unroll
;             for (int bj = 0; bj < 2; ++bj) {
;                 *(LAS f32x4*)(st + wr_off) = acc[ai][bj][m][0]; *(LAS f32x4*)(st + wr_off + 64) = acc[ai][bj][m][1];
;                 const f32x4 a0 = *(const LAS f32x4*)(st + rd_off), a1 = *(const LAS f32x4*)(st + rd_off + 8 * 144);
;                 { const f32x4 xv = xb[g & 1][bj][0] + gv[bj] * a0; __builtin_nontemporal_store(xv, (f32x4*)((char*)xo + 4u * ERN_EOFF(g, bj, 0)));
;                   sq0 += (xv.x * xv.x + xv.y * xv.y) + (xv.z * xv.z + xv.w * xv.w);
;                   const f32x4 hv = xv * gsn[bj]; hw[bj][0].x = cvt_pk_bf16(hv.x, hv.y); hw[bj][0].y = cvt_pk_bf16(hv.z, hv.w); }
;                 { const f32x4 xv = xb[g & 1][bj][1] + gv[bj] * a1; __builtin_nontemporal_store(xv, (f32x4*)((char*)xo + 4u * ERN_EOFF(g, bj, 1)));
;                   sq1 += (xv.x * xv.x + xv.y * xv.y) + (xv.z * xv.z + xv.w * xv.w);
;                   const f32x4 hv = xv * gsn[bj]; hw[bj][1].x = cvt_pk_bf16(hv.x, hv.y); hw[bj][1].y = cvt_pk_bf16(hv.z, hv.w); }
;             }
;             if (!NOH && !PLAIN) {
; #pragma unroll
;                 for (int rh = 0; rh < 2; ++rh) { u32x2 rv; rv.x = __shfl_xor(hw[1][rh].x, 8); rv.y = __shfl_xor(hw[1][rh].y, 8);
;                     const unsigned e0 = ERN_EOFF(g, 0, rh);
;                     const unsigned ee = odd ? (e0 - DM + 32) : e0, eo2 = odd ? e0 : (e0 + DM + 32);
;                     *(u32x2*)((char*)ho + 2u * ee) = odd ? rv : hw[0][rh];
;                     *(u32x2*)((char*)ho + 2u * eo2) = odd ? hw[0][rh] : rv; }
;             }
;             if (!PLAIN) { sq0 += __shfl_xor(sq0, 1); sq0 += __shfl_xor(sq0, 2); sq0 += __shfl_xor(sq0, 4);
;             sq1 += __shfl_xor(sq1, 1); sq1 += __shfl_xor(sq1, 2); sq1 += __shfl_xor(sq1, 4); }
;             if (!PLAIN && pc == 0) { sst[g * 16 + rr] = sq0; sst[g * 16 + 8 + rr] = sq1; }
.LBB0_1999:
	s_or_b64 exec, exec, s[22:23]
	ds_write_b128 v200, v[14:17]
	ds_write_b128 v200, v[10:13] offset:64
	ds_read_b128 v[10:13], v201
	ds_read_b128 v[14:17], v201 offset:1152
	s_waitcnt lgkmcnt(5)
	v_lshl_add_u64 v[18:19], s[20:21], 0, v[154:155]
	v_mov_b32_e32 v71, v155
	v_lshl_add_u64 v[22:23], s[20:21], 0, v[70:71]
	s_waitcnt vmcnt(9) lgkmcnt(1)
	v_pk_fma_f32 v[12:13], v[176:177], v[12:13], v[48:49]
	v_pk_fma_f32 v[10:11], v[180:181], v[10:11], v[46:47]
	global_store_dwordx4 v[18:19], v[10:13], off nt
	v_pk_mul_f32 v[18:19], v[174:175], v[12:13]
	v_pk_mul_f32 v[20:21], v[178:179], v[10:11]
	s_waitcnt vmcnt(9) lgkmcnt(0)
	v_pk_fma_f32 v[14:15], v[180:181], v[14:15], v[42:43]
	v_cvt_pk_bf16_f32 v20, v20, v21
	v_cvt_pk_bf16_f32 v21, v18, v19
	v_pk_fma_f32 v[16:17], v[176:177], v[16:17], v[44:45]
	v_pk_mul_f32 v[18:19], v[178:179], v[14:15]
	global_store_dwordx4 v[22:23], v[14:17], off nt
	v_pk_mul_f32 v[22:23], v[174:175], v[16:17]
	v_cvt_pk_bf16_f32 v18, v18, v19
	v_mov_b32_e32 v69, v155
	v_cvt_pk_bf16_f32 v19, v22, v23
	ds_write_b128 v200, v[6:9]
	ds_write_b128 v200, v[2:5] offset:64
	ds_read_b128 v[2:5], v201
	ds_read_b128 v[6:9], v201 offset:1152
	v_lshl_add_u64 v[22:23], s[20:21], 0, v[68:69]
	v_mov_b32_e32 v67, v155
	v_lshl_add_u64 v[24:25], s[20:21], 0, v[66:67]
	s_waitcnt vmcnt(9) lgkmcnt(1)
	v_pk_fma_f32 v[4:5], v[166:167], v[4:5], v[40:41]
	v_pk_fma_f32 v[2:3], v[168:169], v[2:3], v[38:39]
	global_store_dwordx4 v[22:23], v[2:5], off nt
	v_pk_mul_f32 v[22:23], v[170:171], v[4:5]
	v_pk_mul_f32 v[26:27], v[172:173], v[2:3]
	s_waitcnt vmcnt(9) lgkmcnt(0)
	v_pk_fma_f32 v[8:9], v[166:167], v[8:9], v[36:37]
	v_cvt_pk_bf16_f32 v28, v26, v27
	v_cvt_pk_bf16_f32 v23, v22, v23
	ds_bpermute_b32 v22, v203, v28
	ds_bpermute_b32 v23, v203, v23
	v_pk_fma_f32 v[6:7], v[168:169], v[6:7], v[34:35]
	global_store_dwordx4 v[24:25], v[6:9], off nt
	v_pk_mul_f32 v[26:27], v[170:171], v[8:9]
	v_pk_mul_f32 v[24:25], v[172:173], v[6:7]
	s_nop 0
	v_cvt_pk_bf16_f32 v24, v24, v25
	v_cvt_pk_bf16_f32 v25, v26, v27
	v_add_u32_e32 v27, 0x58000, v202
	v_lshlrev_b32_e32 v26, 1, v27
	s_waitcnt lgkmcnt(0)
	v_add_u32_e32 v250, 0xfffff040, v26
	v_cndmask_b32_e64 v250, v26, v250, s[40:41]
	v_cndmask_b32_e64 v248, v20, v22, s[40:41]
	v_cndmask_b32_e64 v249, v21, v23, s[40:41]
	global_store_dwordx2 v250, v[248:249], s[18:19]
	v_cndmask_b32_e64 v246, v22, v20, s[40:41]
	v_cndmask_b32_e64 v247, v23, v21, s[40:41]
	s_waitcnt lgkmcnt(1)
	v_add_u32_e32 v22, 0x1040, v26
	v_cndmask_b32_e64 v22, v26, v22, s[38:39]
	global_store_dwordx2 v22, v[246:247], s[18:19]
	ds_bpermute_b32 v20, v203, v24
	ds_bpermute_b32 v21, v203, v25
	s_waitcnt lgkmcnt(2)
	v_add_u32_e32 v23, 0x5c000, v202
	v_lshlrev_b32_e32 v22, 1, v23
	s_waitcnt lgkmcnt(0)
	v_add_u32_e32 v250, 0xfffff040, v22
	v_cndmask_b32_e64 v250, v22, v250, s[40:41]
	v_cndmask_b32_e64 v248, v18, v20, s[40:41]
	v_cndmask_b32_e64 v249, v19, v21, s[40:41]
	global_store_dwordx2 v250, v[248:249], s[18:19]
	v_cndmask_b32_e64 v246, v20, v18, s[40:41]
	v_cndmask_b32_e64 v247, v21, v19, s[40:41]
	v_mul_f32_e32 v3, v3, v3
	v_fmac_f32_e32 v3, v2, v2
	v_mul_f32_e32 v2, v5, v5
	v_mul_f32_e32 v13, v13, v13
	v_fmac_f32_e32 v2, v4, v4
	v_mul_f32_e32 v11, v11, v11
	v_fmac_f32_e32 v13, v12, v12
	v_mul_f32_e32 v12, v15, v15
	v_mul_f32_e32 v15, v17, v17
	v_add_f32_e32 v2, v3, v2
	v_mul_f32_e32 v3, v7, v7
	v_mul_f32_e32 v4, v9, v9
	v_fmac_f32_e32 v15, v16, v16
	v_fmac_f32_e32 v3, v6, v6
	v_fmac_f32_e32 v4, v8, v8
	v_fmac_f32_e32 v11, v10, v10
	v_fmac_f32_e32 v12, v14, v14
	v_add_f32_e32 v3, v3, v4
	v_add_f32_e32 v4, v11, v13
	v_add_f32_e32 v5, v12, v15
	v_add_f32_e32 v2, v4, v2
	v_add_f32_e32 v3, v5, v3
	ds_bpermute_b32 v4, v190, v2
	ds_bpermute_b32 v5, v190, v3
	s_waitcnt lgkmcnt(1)
	v_add_f32_e32 v2, v2, v4
	s_waitcnt lgkmcnt(0)
	v_add_f32_e32 v5, v3, v5
	ds_bpermute_b32 v4, v191, v2
	ds_bpermute_b32 v6, v191, v5
	s_waitcnt lgkmcnt(1)
	v_add_f32_e32 v2, v2, v4
	s_waitcnt lgkmcnt(0)
	v_add_f32_e32 v4, v5, v6
	ds_bpermute_b32 v3, v204, v2
	ds_bpermute_b32 v5, v204, v4
	v_add_u32_e32 v6, 0x1040, v22
	v_cndmask_b32_e64 v6, v22, v6, s[38:39]
	global_store_dwordx2 v6, v[246:247], s[18:19]
	s_and_saveexec_b64 s[18:19], s[42:43]
	s_cbranch_execz .LBB0_2009
	s_waitcnt lgkmcnt(1)
	v_add_f32_e32 v2, v2, v3
	s_waitcnt lgkmcnt(0)
	v_add_f32_e32 v3, v4, v5
	ds_write2_b32 v194, v2, v3 offset0:112 offset1:120

; #define LAS __attribute__((address_space(3)))
;     __device__ __forceinline__ void operator()(const f32x4 (&acc)[2][2][4][2], const Unit& u, int wr, int wc, int fr, int fq) const {
;         const int s = u.pm >> 5, lane = fq * 16 + fr, rr = lane >> 3, pc = lane & 7;
;         const float* __restrict__ xi = xin + (size_t)u.pm * BM * DM; float* __restrict__ xo = xout + (size_t)u.pm * BM * DM; bf16_t* __restrict__ ho = Hn + (size_t)u.pm * BM * DM;
;         LAS unsigned char* st = lds_epi + (wr * 4 + wc) * 2304;
;         LAS float* sst = (LAS float*)(lds_epi + 18432 + (wr * 4 + wc) * 512);
;         const int colr = u.pn * BM + wc * 64 + 4 * pc;
;         const unsigned eb = (unsigned)((wr * 64 + rr) * DM + colr);
;         f32x4 gv[2], gsn[2];
; #pragma unroll
;         for (int bj = 0; bj < 2; ++bj) { gv[bj] = *(const f32x4*)(gate + (size_t)s * MODW + colr + bj * 32) * (0.5f * GS2);
;             if (!PLAIN) gsn[bj] = *(const f32x4*)(gnext + colr + bj * 32) * (*(const f32x4*)(scnext + (size_t)s * MODW + colr + bj * 32) + 1.0f); else gsn[bj] = gv[bj]; }
;         const unsigned wr_off = (unsigned)(fr * 144 + 16 * fq), rd_off = (unsigned)(rr * 144 + pc * 16);
;         const bool odd = (rr & 1) != 0;
;         f32x4 xb[2][2][2];
;     ...
;         ERN_LOADX(0);
; #pragma unroll
;         for (int g = 0; g < 8; ++g) { const int ai = g >> 2, m = g & 3;
;             if (g + 1 < 8) ERN_LOADX(g + 1);
;             float sq0 = 0.f, sq1 = 0.f; u32x2 hw[2][2];
; #pragma unroll
;             for (int bj = 0; bj < 2; ++bj) {
;                 *(LAS f32x4*)(st + wr_off) = acc[ai][bj][m][0]; *(LAS f32x4*)(st + wr_off + 64) = acc[ai][bj][m][1];
;                 const f32x4 a0 = *(const LAS f32x4*)(st + rd_off), a1 = *(const LAS f32x4*)(st + rd_off + 8 * 144);
;                 { const f32x4 xv = xb[g & 1][bj][0] + gv[bj] * a0; __builtin_nontemporal_store(xv, (f32x4*)((char*)xo + 4u * ERN_EOFF(g, bj, 0)));
;                   sq0 += (xv.x * xv.x + xv.y * xv.y) + (xv.z * xv.z + xv.w * xv.w);
;                   const f32x4 hv = xv * gsn[bj]; hw[bj][0].x = cvt_pk_bf16(hv.x, hv.y); hw[bj][0].y = cvt_pk_bf16(hv.z, hv.w); }
;                 { const f32x4 xv = xb[g & 1][bj][1] + gv[bj] * a1; __builtin_nontemporal_store(xv, (f32x4*)((char*)xo + 4u * ERN_EOFF(g, bj, 1)));
;                   sq1 += (xv.x * xv.x + xv.y * xv.y) + (xv.z * xv.z + xv.w * xv.w);
.LBB0_2769:
	s_ashr_i32 s13, s2, 5
	s_ashr_i32 s3, s2, 31
	v_lshl_or_b32 v50, s20, 8, v192
	s_mul_hi_i32 s15, s13, 0x12000
	s_mul_i32 s13, s13, 0x12000
	s_add_u32 s20, s44, s13
	v_ashrrev_i32_e32 v51, 31, v50
	s_addc_u32 s21, s45, s15
	v_lshlrev_b64 v[52:53], 2, v[50:51]
	v_lshl_add_u64 v[138:139], s[20:21], 0, v[52:53]
	s_add_u32 s20, s46, s13
	s_addc_u32 s21, s47, s15
	v_lshl_add_u64 v[140:141], s[6:7], 0, v[52:53]
	v_lshl_add_u64 v[52:53], s[20:21], 0, v[52:53]
	s_lshl_b64 s[20:21], s[2:3], 21
	s_add_u32 s22, s90, s20
	v_add_u32_e32 v202, v50, v193
	s_addc_u32 s23, s91, s21
	v_lshlrev_b32_e32 v205, 2, v202
	global_load_dwordx4 v[54:57], v[138:139], off
	global_load_dwordx4 v[174:177], v[140:141], off
	global_load_dwordx4 v[178:181], v[52:53], off
	global_load_dwordx4 v[206:209], v[52:53], off offset:128
	global_load_dwordx4 v[186:189], v205, s[22:23]
	v_add_u32_e32 v50, 0x10000, v205
	global_load_dwordx4 v[210:213], v50, s[22:23]
	global_load_dwordx4 v[214:217], v[140:141], off offset:128
	s_nop 0
	global_load_dwordx4 v[50:53], v[138:139], off offset:128
	global_load_dwordx4 v[218:221], v205, s[22:23] offset:128
	v_add_u32_e32 v204, 0x10080, v205
	global_load_dwordx4 v[222:225], v204, s[22:23]
	v_add_u32_e32 v138, 0x20000, v205
	v_add_u32_e32 v162, 0x30000, v205
	v_add_u32_e32 v184, 0x20080, v205
	v_add_u32_e32 v182, 0x30080, v205
	global_load_dwordx4 v[150:153], v138, s[22:23]
	global_load_dwordx4 v[146:149], v162, s[22:23]
	global_load_dwordx4 v[142:145], v184, s[22:23]
	s_nop 0
	global_load_dwordx4 v[138:141], v182, s[22:23]
	ds_write_b128 v200, v[134:137]
	ds_write_b128 v200, v[130:133] offset:64
	v_and_b32_e32 v135, 64, v199
	ds_read_b128 v[130:133], v201
	ds_read_b128 v[226:229], v201 offset:1152
	v_xor_b32_e32 v134, 8, v199
	v_add_u32_e32 v183, 64, v135
	v_cmp_lt_i32_e32 vcc, v134, v183
	v_add_u32_e32 v185, 0x4000, v202
	v_lshlrev_b32_e32 v230, 2, v185
	v_cndmask_b32_e32 v134, v199, v134, vcc
	v_lshlrev_b32_e32 v203, 2, v134
	s_lshl_b64 s[20:21], s[2:3], 20
	s_add_u32 s20, s93, s20
	s_addc_u32 s21, s92, s21
	s_waitcnt vmcnt(0)
	v_pk_add_f32 v[134:135], v[180:181], 1.0 op_sel_hi:[1,0]
	v_pk_add_f32 v[136:137], v[178:179], 1.0 op_sel_hi:[1,0]
	v_pk_mul_f32 v[178:179], v[176:177], v[134:135]
	v_pk_mul_f32 v[180:181], v[174:175], v[136:137]
	s_waitcnt lgkmcnt(1)
	v_pk_fma_f32 v[134:135], v[54:55], v[130:131], v[186:187]
	s_waitcnt lgkmcnt(0)
	v_pk_fma_f32 v[130:131], v[54:55], v[226:227], v[210:211]
	v_pk_fma_f32 v[136:137], v[56:57], v[132:133], v[188:189]
	v_pk_fma_f32 v[132:133], v[56:57], v[228:229], v[212:213]
	v_pk_mul_f32 v[186:187], v[180:181], v[130:131]
	v_pk_add_f32 v[190:191], v[208:209], 1.0 op_sel_hi:[1,0]
	global_store_dwordx4 v205, v[134:137], s[22:23] nt
	v_pk_mul_f32 v[174:175], v[178:179], v[136:137]
	v_pk_mul_f32 v[176:177], v[180:181], v[134:135]
	v_pk_mul_f32 v[208:209], v[178:179], v[132:133]
	v_cvt_pk_bf16_f32 v188, v176, v177
	v_cvt_pk_bf16_f32 v189, v174, v175
	global_store_dwordx4 v230, v[130:133], s[22:23] nt
	v_cvt_pk_bf16_f32 v186, v186, v187
	v_cvt_pk_bf16_f32 v187, v208, v209
	ds_write_b128 v200, v[126:129]
	ds_write_b128 v200, v[122:125] offset:64
	ds_read_b128 v[122:125], v201
	v_pk_add_f32 v[126:127], v[206:207], 1.0 op_sel_hi:[1,0]
	ds_read_b128 v[206:209], v201 offset:1152
	v_pk_mul_f32 v[174:175], v[216:217], v[190:191]
	v_pk_mul_f32 v[176:177], v[214:215], v[126:127]
	s_waitcnt lgkmcnt(1)
	v_pk_fma_f32 v[128:129], v[52:53], v[124:125], v[220:221]
	v_pk_fma_f32 v[126:127], v[50:51], v[122:123], v[218:219]
	s_waitcnt lgkmcnt(0)
	v_pk_fma_f32 v[122:123], v[50:51], v[206:207], v[222:223]
	v_pk_mul_f32 v[190:191], v[174:175], v[128:129]
	v_pk_mul_f32 v[206:207], v[176:177], v[126:127]
	global_store_dwordx4 v205, v[126:129], s[22:23] offset:128 nt
	v_cvt_pk_bf16_f32 v206, v206, v207
	v_cvt_pk_bf16_f32 v191, v190, v191
	ds_bpermute_b32 v190, v203, v206
	ds_bpermute_b32 v191, v203, v191
	v_pk_fma_f32 v[124:125], v[52:53], v[208:209], v[224:225]
	v_pk_mul_f32 v[206:207], v[176:177], v[122:123]
	global_store_dwordx4 v204, v[122:125], s[22:23] nt
	v_cvt_pk_bf16_f32 v204, v206, v207
	v_lshlrev_b32_e32 v207, 1, v202
	v_pk_mul_f32 v[208:209], v[174:175], v[124:125]
	s_nop 0
	v_cvt_pk_bf16_f32 v206, v208, v209
	s_waitcnt lgkmcnt(0)
	v_add_u32_e32 v250, 0xfffff040, v207
	v_cndmask_b32_e64 v250, v207, v250, s[38:39]
	v_cndmask_b32_e64 v248, v188, v190, s[38:39]
	v_cndmask_b32_e64 v249, v189, v191, s[38:39]
	global_store_dwordx2 v250, v[248:249], s[20:21]
	v_cndmask_b32_e64 v246, v190, v188, s[38:39]
	v_cndmask_b32_e64 v247, v191, v189, s[38:39]
	s_waitcnt lgkmcnt(1)
	v_add_u32_e32 v190, 0x1040, v207
	v_cndmask_b32_e64 v190, v207, v190, s[36:37]
	global_store_dwordx2 v190, v[246:247], s[20:21]
	ds_bpermute_b32 v188, v203, v204
	ds_bpermute_b32 v189, v203, v206
	v_lshlrev_b32_e32 v206, 1, v185
	s_and_saveexec_b64 s[24:25], s[38:39]
	s_xor_b64 s[24:25], exec, s[24:25]
	s_mov_b64 s[58:59], s[70:71]
	s_cbranch_execz .LBB0_2775
	v_lshlrev_b32_e32 v206, 1, v185
	v_add_u32_e32 v185, 0xfffff040, v206
	s_waitcnt lgkmcnt(0)
	global_store_dwordx2 v185, v[188:189], s[20:21]

; #define LAS __attribute__((address_space(3)))
; __device__ __forceinline__ unsigned cvt_pk_bf16(float lo, float hi) { unsigned r; asm volatile("v_cvt_pk_bf16_f32 %0, %1, %2" : "=v"(r) : "v"(lo), "v"(hi)); return r; }
;     __device__ __forceinline__ void operator()(const f32x4 (&acc)[2][2][4][2], const Unit& u, int wr, int wc, int fr, int fq) const {
;     ...
;             if (g + 1 < 8) ERN_LOADX(g + 1);
;             float sq0 = 0.f, sq1 = 0.f; u32x2 hw[2][2];
; #pragma unroll
;             for (int bj = 0; bj < 2; ++bj) {
;                 *(LAS f32x4*)(st + wr_off) = acc[ai][bj][m][0]; *(LAS f32x4*)(st + wr_off + 64) = acc[ai][bj][m][1];
;                 const f32x4 a0 = *(const LAS f32x4*)(st + rd_off), a1 = *(const LAS f32x4*)(st + rd_off + 8 * 144);
;                 { const f32x4 xv = xb[g & 1][bj][0] + gv[bj] * a0; __builtin_nontemporal_store(xv, (f32x4*)((char*)xo + 4u * ERN_EOFF(g, bj, 0)));
;                   sq0 += (xv.x * xv.x + xv.y * xv.y) + (xv.z * xv.z + xv.w * xv.w);
;                   const f32x4 hv = xv * gsn[bj]; hw[bj][0].x = cvt_pk_bf16(hv.x, hv.y); hw[bj][0].y = cvt_pk_bf16(hv.z, hv.w); }
;                 { const f32x4 xv = xb[g & 1][bj][1] + gv[bj] * a1; __builtin_nontemporal_store(xv, (f32x4*)((char*)xo + 4u * ERN_EOFF(g, bj, 1)));
;                   sq1 += (xv.x * xv.x + xv.y * xv.y) + (xv.z * xv.z + xv.w * xv.w);
;                   const f32x4 hv = xv * gsn[bj]; hw[bj][1].x = cvt_pk_bf16(hv.x, hv.y); hw[bj][1].y = cvt_pk_bf16(hv.z, hv.w); }
;             }
;             if (!NOH && !PLAIN) {
; #pragma unroll
;                 for (int rh = 0; rh < 2; ++rh) { u32x2 rv; rv.x = __shfl_xor(hw[1][rh].x, 8); rv.y = __shfl_xor(hw[1][rh].y, 8);
;                     const unsigned e0 = ERN_EOFF(g, 0, rh);
;                     const unsigned ee = odd ? (e0 - DM + 32) : e0, eo2 = odd ? e0 : (e0 + DM + 32);
;                     *(u32x2*)((char*)ho + 2u * ee) = odd ? rv : hw[0][rh];
;                     *(u32x2*)((char*)ho + 2u * eo2) = odd ? hw[0][rh] : rv; }
;             }
;             if (!PLAIN) { sq0 += __shfl_xor(sq0, 1); sq0 += __shfl_xor(sq0, 2); sq0 += __shfl_xor(sq0, 4);
;             sq1 += __shfl_xor(sq1, 1); sq1 += __shfl_xor(sq1, 2); sq1 += __shfl_xor(sq1, 4); }
;             if (!PLAIN && pc == 0) { sst[g * 16 + rr] = sq0; sst[g * 16 + 8 + rr] = sq1; }
.LBB0_2779:
	s_or_b64 exec, exec, s[24:25]
	v_lshl_add_u64 v[206:207], s[22:23], 0, v[162:163]
	v_add_u32_e32 v122, 0x40000, v205
	v_add_u32_e32 v162, 0x50000, v205
	v_add_u32_e32 v186, 0x40080, v205
	global_load_dwordx4 v[130:133], v162, s[22:23]
	global_load_dwordx4 v[126:129], v186, s[22:23]
	v_add_u32_e32 v188, 0x50080, v205
	global_load_dwordx4 v[134:137], v122, s[22:23]
	s_waitcnt lgkmcnt(0)
	global_load_dwordx4 v[122:125], v188, s[22:23]
	ds_write_b128 v200, v[118:121]
	ds_write_b128 v200, v[114:117] offset:64
	ds_read_b128 v[114:117], v201
	ds_read_b128 v[118:121], v201 offset:1152
	v_mov_b32_e32 v185, v163
	v_mov_b32_e32 v183, v163
	v_lshl_add_u64 v[182:183], s[22:23], 0, v[182:183]
	s_waitcnt lgkmcnt(1)
	v_pk_fma_f32 v[116:117], v[56:57], v[116:117], v[152:153]
	v_add_u32_e32 v152, 0x8000, v202
	v_pk_fma_f32 v[114:115], v[54:55], v[114:115], v[150:151]
	v_lshlrev_b32_e32 v150, 2, v152
	s_waitcnt lgkmcnt(0)
	v_pk_fma_f32 v[118:119], v[54:55], v[118:119], v[146:147]
	global_store_dwordx4 v150, v[114:117], s[22:23] nt
	v_pk_mul_f32 v[150:151], v[180:181], v[114:115]
	v_pk_fma_f32 v[120:121], v[56:57], v[120:121], v[148:149]
	v_pk_mul_f32 v[146:147], v[180:181], v[118:119]
	v_pk_mul_f32 v[208:209], v[178:179], v[116:117]
	v_cvt_pk_bf16_f32 v150, v150, v151
	v_pk_mul_f32 v[148:149], v[178:179], v[120:121]
	v_cvt_pk_bf16_f32 v151, v208, v209
	global_store_dwordx4 v[206:207], v[118:121], off nt
	v_cvt_pk_bf16_f32 v146, v146, v147
	v_cvt_pk_bf16_f32 v147, v148, v149
	ds_write_b128 v200, v[110:113]
	ds_write_b128 v200, v[106:109] offset:64
	ds_read_b128 v[106:109], v201
	ds_read_b128 v[110:113], v201 offset:1152
	v_lshl_add_u64 v[148:149], s[22:23], 0, v[184:185]
	s_waitcnt lgkmcnt(1)
	v_pk_fma_f32 v[106:107], v[50:51], v[106:107], v[142:143]
	v_pk_fma_f32 v[108:109], v[52:53], v[108:109], v[144:145]
	v_pk_mul_f32 v[144:145], v[176:177], v[106:107]
	global_store_dwordx4 v[148:149], v[106:109], off nt
	v_pk_mul_f32 v[142:143], v[174:175], v[108:109]
	v_cvt_pk_bf16_f32 v144, v144, v145
	s_waitcnt lgkmcnt(0)
	v_pk_fma_f32 v[110:111], v[50:51], v[110:111], v[138:139]
	v_cvt_pk_bf16_f32 v145, v142, v143
	ds_bpermute_b32 v138, v203, v144
	ds_bpermute_b32 v139, v203, v145
	v_pk_fma_f32 v[112:113], v[52:53], v[112:113], v[140:141]
	v_pk_mul_f32 v[140:141], v[176:177], v[110:111]
	v_pk_mul_f32 v[142:143], v[174:175], v[112:113]
	global_store_dwordx4 v[182:183], v[110:113], off nt
	v_cvt_pk_bf16_f32 v140, v140, v141
	v_cvt_pk_bf16_f32 v141, v142, v143
	v_lshlrev_b32_e32 v142, 1, v152
	s_waitcnt lgkmcnt(0)
	v_add_u32_e32 v250, 0xfffff040, v142
	v_cndmask_b32_e64 v250, v142, v250, s[38:39]
	v_cndmask_b32_e64 v248, v150, v138, s[38:39]
	v_cndmask_b32_e64 v249, v151, v139, s[38:39]
	global_store_dwordx2 v250, v[248:249], s[20:21]
	v_cndmask_b32_e64 v246, v138, v150, s[38:39]
	v_cndmask_b32_e64 v247, v139, v151, s[38:39]
	s_waitcnt lgkmcnt(1)
	v_add_u32_e32 v138, 0x1040, v142
	v_cndmask_b32_e64 v138, v142, v138, s[36:37]
	global_store_dwordx2 v138, v[246:247], s[20:21]
	ds_bpermute_b32 v138, v203, v140
	s_waitcnt lgkmcnt(1)
	ds_bpermute_b32 v139, v203, v141
	v_add_u32_e32 v141, 0xc000, v202
	v_lshlrev_b32_e32 v140, 1, v141
	s_waitcnt lgkmcnt(0)
	v_add_u32_e32 v250, 0xfffff040, v140
	v_cndmask_b32_e64 v250, v140, v250, s[38:39]
	v_cndmask_b32_e64 v248, v146, v138, s[38:39]
	v_cndmask_b32_e64 v249, v147, v139, s[38:39]
	global_store_dwordx2 v250, v[248:249], s[20:21]
	v_cndmask_b32_e64 v246, v138, v146, s[38:39]
	v_cndmask_b32_e64 v247, v139, v147, s[38:39]
	v_mul_f32_e32 v107, v107, v107
	v_fmac_f32_e32 v107, v106, v106
	v_mul_f32_e32 v106, v109, v109
	v_mul_f32_e32 v117, v117, v117
	v_fmac_f32_e32 v106, v108, v108
	v_mul_f32_e32 v115, v115, v115
	v_fmac_f32_e32 v117, v116, v116
	v_mul_f32_e32 v116, v119, v119
	v_mul_f32_e32 v119, v121, v121
	v_add_f32_e32 v106, v107, v106
	v_mul_f32_e32 v107, v111, v111
	v_mul_f32_e32 v108, v113, v113
	v_fmac_f32_e32 v119, v120, v120
	v_fmac_f32_e32 v107, v110, v110
	v_fmac_f32_e32 v108, v112, v112
	v_fmac_f32_e32 v115, v114, v114
	v_fmac_f32_e32 v116, v118, v118
	v_add_f32_e32 v107, v107, v108
	v_add_f32_e32 v108, v115, v117
	v_add_f32_e32 v109, v116, v119
	v_add_f32_e32 v106, v108, v106
	v_add_f32_e32 v107, v109, v107
	ds_bpermute_b32 v108, v190, v106
	ds_bpermute_b32 v109, v190, v107
	s_waitcnt lgkmcnt(1)
	v_add_f32_e32 v106, v106, v108
	s_waitcnt lgkmcnt(0)
	v_add_f32_e32 v109, v107, v109
	ds_bpermute_b32 v108, v191, v106
	ds_bpermute_b32 v110, v191, v109
	s_waitcnt lgkmcnt(1)
	v_add_f32_e32 v106, v106, v108
	s_waitcnt lgkmcnt(0)
	v_add_f32_e32 v108, v109, v110
	ds_bpermute_b32 v107, v204, v106
	ds_bpermute_b32 v109, v204, v108
	v_add_u32_e32 v110, 0x1040, v140
	v_cndmask_b32_e64 v110, v140, v110, s[36:37]
	global_store_dwordx2 v110, v[246:247], s[20:21]
	s_and_saveexec_b64 s[24:25], s[40:41]
	s_cbranch_execz .LBB0_2789
	s_waitcnt lgkmcnt(1)
	v_add_f32_e32 v106, v106, v107
	s_waitcnt lgkmcnt(0)
	v_add_f32_e32 v107, v108, v109
	ds_write2_b32 v194, v106, v107 offset0:16 offset1:24
; #define LAS __attribute__((address_space(3)))
; __device__ __forceinline__ unsigned cvt_pk_bf16(float lo, float hi) { unsigned r; asm volatile("v_cvt_pk_bf16_f32 %0, %1, %2" : "=v"(r) : "v"(lo), "v"(hi)); return r; }
;     __device__ __forceinline__ void operator()(const f32x4 (&acc)[2][2][4][2], const Unit& u, int wr, int wc, int fr, int fq) const {
;     ...
;             if (g + 1 < 8) ERN_LOADX(g + 1);
;             float sq0 = 0.f, sq1 = 0.f; u32x2 hw[2][2];
; #pragma unroll
;             for (int bj = 0; bj < 2; ++bj) {
;                 *(LAS f32x4*)(st + wr_off) = acc[ai][bj][m][0]; *(LAS f32x4*)(st + wr_off + 64) = acc[ai][bj][m][1];
;                 const f32x4 a0 = *(const LAS f32x4*)(st + rd_off), a1 = *(const LAS f32x4*)(st + rd_off + 8 * 144);
;                 { const f32x4 xv = xb[g & 1][bj][0] + gv[bj] * a0; __builtin_nontemporal_store(xv, (f32x4*)((char*)xo + 4u * ERN_EOFF(g, bj, 0)));
;                   sq0 += (xv.x * xv.x + xv.y * xv.y) + (xv.z * xv.z + xv.w * xv.w);
;                   const f32x4 hv = xv * gsn[bj]; hw[bj][0].x = cvt_pk_bf16(hv.x, hv.y); hw[bj][0].y = cvt_pk_bf16(hv.z, hv.w); }
;                 { const f32x4 xv = xb[g & 1][bj][1] + gv[bj] * a1; __builtin_nontemporal_store(xv, (f32x4*)((char*)xo + 4u * ERN_EOFF(g, bj, 1)));
;                   sq1 += (xv.x * xv.x + xv.y * xv.y) + (xv.z * xv.z + xv.w * xv.w);
;                   const f32x4 hv = xv * gsn[bj]; hw[bj][1].x = cvt_pk_bf16(hv.x, hv.y); hw[bj][1].y = cvt_pk_bf16(hv.z, hv.w); }
;             }
;             if (!NOH && !PLAIN) {
; #pragma unroll
;                 for (int rh = 0; rh < 2; ++rh) { u32x2 rv; rv.x = __shfl_xor(hw[1][rh].x, 8); rv.y = __shfl_xor(hw[1][rh].y, 8);
;                     const unsigned e0 = ERN_EOFF(g, 0, rh);
;                     const unsigned ee = odd ? (e0 - DM + 32) : e0, eo2 = odd ? e0 : (e0 + DM + 32);
;                     *(u32x2*)((char*)ho + 2u * ee) = odd ? rv : hw[0][rh];
;                     *(u32x2*)((char*)ho + 2u * eo2) = odd ? hw[0][rh] : rv; }
;             }
;             if (!PLAIN) { sq0 += __shfl_xor(sq0, 1); sq0 += __shfl_xor(sq0, 2); sq0 += __shfl_xor(sq0, 4);
;             sq1 += __shfl_xor(sq1, 1); sq1 += __shfl_xor(sq1, 2); sq1 += __shfl_xor(sq1, 4); }
;             if (!PLAIN && pc == 0) { sst[g * 16 + rr] = sq0; sst[g * 16 + 8 + rr] = sq1; }
.LBB0_2789:
	s_or_b64 exec, exec, s[24:25]
	v_lshl_add_u64 v[142:143], s[22:23], 0, v[162:163]
	v_add_u32_e32 v106, 0x60000, v205
	v_add_u32_e32 v162, 0x70000, v205
	v_add_u32_e32 v138, 0x60080, v205
	global_load_dwordx4 v[114:117], v162, s[22:23]
	global_load_dwordx4 v[110:113], v138, s[22:23]
	v_add_u32_e32 v140, 0x70080, v205
	global_load_dwordx4 v[118:121], v106, s[22:23]
	s_waitcnt lgkmcnt(0)
	global_load_dwordx4 v[106:109], v140, s[22:23]
	ds_write_b128 v200, v[102:105]
	ds_write_b128 v200, v[98:101] offset:64
	ds_read_b128 v[98:101], v201
	ds_read_b128 v[102:105], v201 offset:1152
	v_mov_b32_e32 v187, v163
	v_mov_b32_e32 v189, v163
	s_waitcnt vmcnt(11) lgkmcnt(1)
	v_pk_fma_f32 v[100:101], v[56:57], v[100:101], v[136:137]
	v_add_u32_e32 v136, 0x10000, v202
	v_pk_fma_f32 v[98:99], v[54:55], v[98:99], v[134:135]
	v_lshlrev_b32_e32 v134, 2, v136
	s_waitcnt lgkmcnt(0)
	v_pk_fma_f32 v[102:103], v[54:55], v[102:103], v[130:131]
	global_store_dwordx4 v134, v[98:101], s[22:23] nt
	v_pk_mul_f32 v[134:135], v[180:181], v[98:99]
	v_pk_fma_f32 v[104:105], v[56:57], v[104:105], v[132:133]
	v_pk_mul_f32 v[130:131], v[180:181], v[102:103]
	v_pk_mul_f32 v[144:145], v[178:179], v[100:101]
	v_cvt_pk_bf16_f32 v134, v134, v135
	v_pk_mul_f32 v[132:133], v[178:179], v[104:105]
	v_cvt_pk_bf16_f32 v135, v144, v145
	global_store_dwordx4 v[142:143], v[102:105], off nt
	v_cvt_pk_bf16_f32 v130, v130, v131
	v_cvt_pk_bf16_f32 v131, v132, v133
	ds_write_b128 v200, v[94:97]
	ds_write_b128 v200, v[90:93] offset:64
	ds_read_b128 v[90:93], v201
	ds_read_b128 v[94:97], v201 offset:1152
	v_lshl_add_u64 v[132:133], s[22:23], 0, v[186:187]
	v_lshl_add_u64 v[142:143], s[22:23], 0, v[188:189]
	s_waitcnt lgkmcnt(1)
	v_pk_fma_f32 v[90:91], v[50:51], v[90:91], v[126:127]
	v_pk_fma_f32 v[92:93], v[52:53], v[92:93], v[128:129]
	v_pk_mul_f32 v[128:129], v[176:177], v[90:91]
	global_store_dwordx4 v[132:133], v[90:93], off nt
	v_pk_mul_f32 v[126:127], v[174:175], v[92:93]
	v_cvt_pk_bf16_f32 v128, v128, v129
	s_waitcnt vmcnt(13) lgkmcnt(0)
	v_pk_fma_f32 v[94:95], v[50:51], v[94:95], v[122:123]
	v_cvt_pk_bf16_f32 v129, v126, v127
	ds_bpermute_b32 v122, v203, v128
	ds_bpermute_b32 v123, v203, v129
	v_pk_fma_f32 v[96:97], v[52:53], v[96:97], v[124:125]
	v_pk_mul_f32 v[124:125], v[176:177], v[94:95]
	v_pk_mul_f32 v[126:127], v[174:175], v[96:97]
	global_store_dwordx4 v[142:143], v[94:97], off nt
	v_cvt_pk_bf16_f32 v124, v124, v125
	v_cvt_pk_bf16_f32 v125, v126, v127
	v_lshlrev_b32_e32 v126, 1, v136
	s_waitcnt lgkmcnt(0)
	v_add_u32_e32 v250, 0xfffff040, v126
	v_cndmask_b32_e64 v250, v126, v250, s[38:39]
	v_cndmask_b32_e64 v248, v134, v122, s[38:39]
	v_cndmask_b32_e64 v249, v135, v123, s[38:39]
	global_store_dwordx2 v250, v[248:249], s[20:21]
	v_cndmask_b32_e64 v246, v122, v134, s[38:39]
	v_cndmask_b32_e64 v247, v123, v135, s[38:39]
	s_waitcnt lgkmcnt(1)
	v_add_u32_e32 v122, 0x1040, v126
	v_cndmask_b32_e64 v122, v126, v122, s[36:37]
	global_store_dwordx2 v122, v[246:247], s[20:21]
	ds_bpermute_b32 v122, v203, v124
	s_waitcnt lgkmcnt(1)
	ds_bpermute_b32 v123, v203, v125
	v_add_u32_e32 v125, 0x14000, v202
	v_lshlrev_b32_e32 v124, 1, v125
	s_waitcnt lgkmcnt(0)
	v_add_u32_e32 v250, 0xfffff040, v124
	v_cndmask_b32_e64 v250, v124, v250, s[38:39]
	v_cndmask_b32_e64 v248, v130, v122, s[38:39]
	v_cndmask_b32_e64 v249, v131, v123, s[38:39]
	global_store_dwordx2 v250, v[248:249], s[20:21]
	v_cndmask_b32_e64 v246, v122, v130, s[38:39]
	v_cndmask_b32_e64 v247, v123, v131, s[38:39]
	v_mul_f32_e32 v91, v91, v91
	v_fmac_f32_e32 v91, v90, v90
	v_mul_f32_e32 v90, v93, v93
	v_mul_f32_e32 v101, v101, v101
	v_fmac_f32_e32 v90, v92, v92
	v_mul_f32_e32 v99, v99, v99
	v_fmac_f32_e32 v101, v100, v100
	v_mul_f32_e32 v100, v103, v103
	v_mul_f32_e32 v103, v105, v105
	v_add_f32_e32 v90, v91, v90
	v_mul_f32_e32 v91, v95, v95
	v_mul_f32_e32 v92, v97, v97
	v_fmac_f32_e32 v103, v104, v104
	v_fmac_f32_e32 v91, v94, v94
	v_fmac_f32_e32 v92, v96, v96
	v_fmac_f32_e32 v99, v98, v98
	v_fmac_f32_e32 v100, v102, v102
	v_add_f32_e32 v91, v91, v92
	v_add_f32_e32 v92, v99, v101
	v_add_f32_e32 v93, v100, v103
	v_add_f32_e32 v90, v92, v90
	v_add_f32_e32 v91, v93, v91
	ds_bpermute_b32 v92, v190, v90
	ds_bpermute_b32 v93, v190, v91
	s_waitcnt lgkmcnt(1)
	v_add_f32_e32 v90, v90, v92
	s_waitcnt lgkmcnt(0)
	v_add_f32_e32 v93, v91, v93
	ds_bpermute_b32 v92, v191, v90
	ds_bpermute_b32 v94, v191, v93
	s_waitcnt lgkmcnt(1)
	v_add_f32_e32 v90, v90, v92
	s_waitcnt lgkmcnt(0)
	v_add_f32_e32 v92, v93, v94
	ds_bpermute_b32 v91, v204, v90
	ds_bpermute_b32 v93, v204, v92
	v_add_u32_e32 v94, 0x1040, v124
	v_cndmask_b32_e64 v94, v124, v94, s[36:37]
	global_store_dwordx2 v94, v[246:247], s[20:21]
	s_and_saveexec_b64 s[24:25], s[40:41]
	s_cbranch_execz .LBB0_2799
	s_waitcnt lgkmcnt(1)
	v_add_f32_e32 v90, v90, v91
	s_waitcnt lgkmcnt(0)
	v_add_f32_e32 v91, v92, v93
	ds_write2_b32 v194, v90, v91 offset0:32 offset1:40
; #define LAS __attribute__((address_space(3)))
; __device__ __forceinline__ unsigned cvt_pk_bf16(float lo, float hi) { unsigned r; asm volatile("v_cvt_pk_bf16_f32 %0, %1, %2" : "=v"(r) : "v"(lo), "v"(hi)); return r; }
;     __device__ __forceinline__ void operator()(const f32x4 (&acc)[2][2][4][2], const Unit& u, int wr, int wc, int fr, int fq) const {
;     ...
;             if (g + 1 < 8) ERN_LOADX(g + 1);
;             float sq0 = 0.f, sq1 = 0.f; u32x2 hw[2][2];
; #pragma unroll
;             for (int bj = 0; bj < 2; ++bj) {
;                 *(LAS f32x4*)(st + wr_off) = acc[ai][bj][m][0]; *(LAS f32x4*)(st + wr_off + 64) = acc[ai][bj][m][1];
;                 const f32x4 a0 = *(const LAS f32x4*)(st + rd_off), a1 = *(const LAS f32x4*)(st + rd_off + 8 * 144);
;                 { const f32x4 xv = xb[g & 1][bj][0] + gv[bj] * a0; __builtin_nontemporal_store(xv, (f32x4*)((char*)xo + 4u * ERN_EOFF(g, bj, 0)));
;                   sq0 += (xv.x * xv.x + xv.y * xv.y) + (xv.z * xv.z + xv.w * xv.w);
;                   const f32x4 hv = xv * gsn[bj]; hw[bj][0].x = cvt_pk_bf16(hv.x, hv.y); hw[bj][0].y = cvt_pk_bf16(hv.z, hv.w); }
;                 { const f32x4 xv = xb[g & 1][bj][1] + gv[bj] * a1; __builtin_nontemporal_store(xv, (f32x4*)((char*)xo + 4u * ERN_EOFF(g, bj, 1)));
;                   sq1 += (xv.x * xv.x + xv.y * xv.y) + (xv.z * xv.z + xv.w * xv.w);
;                   const f32x4 hv = xv * gsn[bj]; hw[bj][1].x = cvt_pk_bf16(hv.x, hv.y); hw[bj][1].y = cvt_pk_bf16(hv.z, hv.w); }
;             }
;             if (!NOH && !PLAIN) {
; #pragma unroll
;                 for (int rh = 0; rh < 2; ++rh) { u32x2 rv; rv.x = __shfl_xor(hw[1][rh].x, 8); rv.y = __shfl_xor(hw[1][rh].y, 8);
;                     const unsigned e0 = ERN_EOFF(g, 0, rh);
;                     const unsigned ee = odd ? (e0 - DM + 32) : e0, eo2 = odd ? e0 : (e0 + DM + 32);
;                     *(u32x2*)((char*)ho + 2u * ee) = odd ? rv : hw[0][rh];
;                     *(u32x2*)((char*)ho + 2u * eo2) = odd ? hw[0][rh] : rv; }
;             }
;             if (!PLAIN) { sq0 += __shfl_xor(sq0, 1); sq0 += __shfl_xor(sq0, 2); sq0 += __shfl_xor(sq0, 4);
;             sq1 += __shfl_xor(sq1, 1); sq1 += __shfl_xor(sq1, 2); sq1 += __shfl_xor(sq1, 4); }
;             if (!PLAIN && pc == 0) { sst[g * 16 + rr] = sq0; sst[g * 16 + 8 + rr] = sq1; }
.LBB0_2799:
	s_or_b64 exec, exec, s[24:25]
	v_lshl_add_u64 v[124:125], s[22:23], 0, v[162:163]
	v_add_u32_e32 v90, 0x100000, v205
	s_waitcnt lgkmcnt(1)
	v_add_u32_e32 v91, 0x110000, v205
	v_add_u32_e32 v162, 0x100080, v205
	global_load_dwordx4 v[102:105], v90, s[22:23]
	global_load_dwordx4 v[98:101], v91, s[22:23]
	v_add_u32_e32 v122, 0x110080, v205
	global_load_dwordx4 v[94:97], v162, s[22:23]
	s_waitcnt lgkmcnt(0)
	global_load_dwordx4 v[90:93], v122, s[22:23]
	ds_write_b128 v200, v[86:89]
	ds_write_b128 v200, v[82:85] offset:64
	ds_read_b128 v[82:85], v201
	ds_read_b128 v[86:89], v201 offset:1152
	v_mov_b32_e32 v139, v163
	v_mov_b32_e32 v141, v163
	s_waitcnt vmcnt(11) lgkmcnt(1)
	v_pk_fma_f32 v[84:85], v[56:57], v[84:85], v[120:121]
	v_add_u32_e32 v120, 0x18000, v202
	v_pk_fma_f32 v[82:83], v[54:55], v[82:83], v[118:119]
	v_lshlrev_b32_e32 v118, 2, v120
	s_waitcnt lgkmcnt(0)
	v_pk_fma_f32 v[86:87], v[54:55], v[86:87], v[114:115]
	global_store_dwordx4 v118, v[82:85], s[22:23] nt
	v_pk_mul_f32 v[118:119], v[180:181], v[82:83]
	v_pk_fma_f32 v[88:89], v[56:57], v[88:89], v[116:117]
	v_pk_mul_f32 v[114:115], v[180:181], v[86:87]
	v_pk_mul_f32 v[126:127], v[178:179], v[84:85]
	v_cvt_pk_bf16_f32 v118, v118, v119
	v_pk_mul_f32 v[116:117], v[178:179], v[88:89]
	v_cvt_pk_bf16_f32 v119, v126, v127
	global_store_dwordx4 v[124:125], v[86:89], off nt
	v_cvt_pk_bf16_f32 v114, v114, v115
	v_cvt_pk_bf16_f32 v115, v116, v117
	ds_write_b128 v200, v[78:81]
	ds_write_b128 v200, v[74:77] offset:64
	ds_read_b128 v[74:77], v201
	ds_read_b128 v[78:81], v201 offset:1152
	v_lshl_add_u64 v[116:117], s[22:23], 0, v[138:139]
	v_lshl_add_u64 v[124:125], s[22:23], 0, v[140:141]
	s_waitcnt lgkmcnt(1)
	v_pk_fma_f32 v[74:75], v[50:51], v[74:75], v[110:111]
	v_pk_fma_f32 v[76:77], v[52:53], v[76:77], v[112:113]
	v_pk_mul_f32 v[112:113], v[176:177], v[74:75]
	global_store_dwordx4 v[116:117], v[74:77], off nt
	v_pk_mul_f32 v[110:111], v[174:175], v[76:77]
	v_cvt_pk_bf16_f32 v112, v112, v113
	s_waitcnt vmcnt(13) lgkmcnt(0)
	v_pk_fma_f32 v[78:79], v[50:51], v[78:79], v[106:107]
	v_cvt_pk_bf16_f32 v113, v110, v111
	ds_bpermute_b32 v106, v203, v112
	ds_bpermute_b32 v107, v203, v113
	v_pk_fma_f32 v[80:81], v[52:53], v[80:81], v[108:109]
	v_pk_mul_f32 v[108:109], v[176:177], v[78:79]
	v_pk_mul_f32 v[110:111], v[174:175], v[80:81]
	global_store_dwordx4 v[124:125], v[78:81], off nt
	v_cvt_pk_bf16_f32 v108, v108, v109
	v_cvt_pk_bf16_f32 v109, v110, v111
	v_lshlrev_b32_e32 v110, 1, v120
	s_waitcnt lgkmcnt(0)
	v_add_u32_e32 v250, 0xfffff040, v110
	v_cndmask_b32_e64 v250, v110, v250, s[38:39]
	v_cndmask_b32_e64 v248, v118, v106, s[38:39]
	v_cndmask_b32_e64 v249, v119, v107, s[38:39]
	global_store_dwordx2 v250, v[248:249], s[20:21]
	v_cndmask_b32_e64 v246, v106, v118, s[38:39]
	v_cndmask_b32_e64 v247, v107, v119, s[38:39]
	s_waitcnt lgkmcnt(1)
	v_add_u32_e32 v106, 0x1040, v110
	v_cndmask_b32_e64 v106, v110, v106, s[36:37]
	global_store_dwordx2 v106, v[246:247], s[20:21]
	ds_bpermute_b32 v106, v203, v108
	s_waitcnt lgkmcnt(1)
	ds_bpermute_b32 v107, v203, v109
	v_add_u32_e32 v109, 0x1c000, v202
	v_lshlrev_b32_e32 v108, 1, v109
	s_waitcnt lgkmcnt(0)
	v_add_u32_e32 v250, 0xfffff040, v108
	v_cndmask_b32_e64 v250, v108, v250, s[38:39]
	v_cndmask_b32_e64 v248, v114, v106, s[38:39]
	v_cndmask_b32_e64 v249, v115, v107, s[38:39]
	global_store_dwordx2 v250, v[248:249], s[20:21]
	v_cndmask_b32_e64 v246, v106, v114, s[38:39]
	v_cndmask_b32_e64 v247, v107, v115, s[38:39]
	v_mul_f32_e32 v75, v75, v75
	v_fmac_f32_e32 v75, v74, v74
	v_mul_f32_e32 v74, v77, v77
	v_mul_f32_e32 v85, v85, v85
	v_fmac_f32_e32 v74, v76, v76
	v_mul_f32_e32 v83, v83, v83
	v_fmac_f32_e32 v85, v84, v84
	v_mul_f32_e32 v84, v87, v87
	v_mul_f32_e32 v87, v89, v89
	v_add_f32_e32 v74, v75, v74
	v_mul_f32_e32 v75, v79, v79
	v_mul_f32_e32 v76, v81, v81
	v_fmac_f32_e32 v87, v88, v88
	v_fmac_f32_e32 v75, v78, v78
	v_fmac_f32_e32 v76, v80, v80
	v_fmac_f32_e32 v83, v82, v82
	v_fmac_f32_e32 v84, v86, v86
	v_add_f32_e32 v75, v75, v76
	v_add_f32_e32 v76, v83, v85
	v_add_f32_e32 v77, v84, v87
	v_add_f32_e32 v74, v76, v74
	v_add_f32_e32 v75, v77, v75
	ds_bpermute_b32 v76, v190, v74
	ds_bpermute_b32 v77, v190, v75
	s_waitcnt lgkmcnt(1)
	v_add_f32_e32 v74, v74, v76
	s_waitcnt lgkmcnt(0)
	v_add_f32_e32 v77, v75, v77
	ds_bpermute_b32 v76, v191, v74
	ds_bpermute_b32 v78, v191, v77
	s_waitcnt lgkmcnt(1)
	v_add_f32_e32 v74, v74, v76
	s_waitcnt lgkmcnt(0)
	v_add_f32_e32 v76, v77, v78
	ds_bpermute_b32 v75, v204, v74
	ds_bpermute_b32 v77, v204, v76
	v_add_u32_e32 v78, 0x1040, v108
	v_cndmask_b32_e64 v78, v108, v78, s[36:37]
	global_store_dwordx2 v78, v[246:247], s[20:21]
	s_and_saveexec_b64 s[24:25], s[40:41]
	s_cbranch_execz .LBB0_2809
	s_waitcnt lgkmcnt(1)
	v_add_f32_e32 v74, v74, v75
	s_waitcnt lgkmcnt(0)
	v_add_f32_e32 v75, v76, v77
	ds_write2_b32 v194, v74, v75 offset0:48 offset1:56
; #define LAS __attribute__((address_space(3)))
; __device__ __forceinline__ unsigned cvt_pk_bf16(float lo, float hi) { unsigned r; asm volatile("v_cvt_pk_bf16_f32 %0, %1, %2" : "=v"(r) : "v"(lo), "v"(hi)); return r; }
;     __device__ __forceinline__ void operator()(const f32x4 (&acc)[2][2][4][2], const Unit& u, int wr, int wc, int fr, int fq) const {
;     ...
;             if (g + 1 < 8) ERN_LOADX(g + 1);
;             float sq0 = 0.f, sq1 = 0.f; u32x2 hw[2][2];
; #pragma unroll
;             for (int bj = 0; bj < 2; ++bj) {
;                 *(LAS f32x4*)(st + wr_off) = acc[ai][bj][m][0]; *(LAS f32x4*)(st + wr_off + 64) = acc[ai][bj][m][1];
;                 const f32x4 a0 = *(const LAS f32x4*)(st + rd_off), a1 = *(const LAS f32x4*)(st + rd_off + 8 * 144);
;                 { const f32x4 xv = xb[g & 1][bj][0] + gv[bj] * a0; __builtin_nontemporal_store(xv, (f32x4*)((char*)xo + 4u * ERN_EOFF(g, bj, 0)));
;                   sq0 += (xv.x * xv.x + xv.y * xv.y) + (xv.z * xv.z + xv.w * xv.w);
;                   const f32x4 hv = xv * gsn[bj]; hw[bj][0].x = cvt_pk_bf16(hv.x, hv.y); hw[bj][0].y = cvt_pk_bf16(hv.z, hv.w); }
;                 { const f32x4 xv = xb[g & 1][bj][1] + gv[bj] * a1; __builtin_nontemporal_store(xv, (f32x4*)((char*)xo + 4u * ERN_EOFF(g, bj, 1)));
;                   sq1 += (xv.x * xv.x + xv.y * xv.y) + (xv.z * xv.z + xv.w * xv.w);
;                   const f32x4 hv = xv * gsn[bj]; hw[bj][1].x = cvt_pk_bf16(hv.x, hv.y); hw[bj][1].y = cvt_pk_bf16(hv.z, hv.w); }
;             }
;             if (!NOH && !PLAIN) {
; #pragma unroll
;                 for (int rh = 0; rh < 2; ++rh) { u32x2 rv; rv.x = __shfl_xor(hw[1][rh].x, 8); rv.y = __shfl_xor(hw[1][rh].y, 8);
;                     const unsigned e0 = ERN_EOFF(g, 0, rh);
;                     const unsigned ee = odd ? (e0 - DM + 32) : e0, eo2 = odd ? e0 : (e0 + DM + 32);
;                     *(u32x2*)((char*)ho + 2u * ee) = odd ? rv : hw[0][rh];
;                     *(u32x2*)((char*)ho + 2u * eo2) = odd ? hw[0][rh] : rv; }
;             }
;             if (!PLAIN) { sq0 += __shfl_xor(sq0, 1); sq0 += __shfl_xor(sq0, 2); sq0 += __shfl_xor(sq0, 4);
;             sq1 += __shfl_xor(sq1, 1); sq1 += __shfl_xor(sq1, 2); sq1 += __shfl_xor(sq1, 4); }
;             if (!PLAIN && pc == 0) { sst[g * 16 + rr] = sq0; sst[g * 16 + 8 + rr] = sq1; }
.LBB0_2809:
	s_or_b64 exec, exec, s[24:25]
	v_lshl_add_u64 v[112:113], s[22:23], 0, v[162:163]
	v_add_u32_e32 v162, 0x120000, v205
	v_add_u32_e32 v108, 0x120080, v205
	v_add_u32_e32 v110, 0x130000, v205
	global_load_dwordx4 v[86:89], v162, s[22:23]
	global_load_dwordx4 v[82:85], v110, s[22:23]
	v_add_u32_e32 v106, 0x130080, v205
	global_load_dwordx4 v[78:81], v108, s[22:23]
	s_waitcnt lgkmcnt(0)
	global_load_dwordx4 v[74:77], v106, s[22:23]
	ds_write_b128 v200, v[70:73]
	ds_write_b128 v200, v[66:69] offset:64
	ds_read_b128 v[66:69], v201
	ds_read_b128 v[70:73], v201 offset:1152
	v_mov_b32_e32 v123, v163
	s_waitcnt vmcnt(13) lgkmcnt(1)
	v_pk_fma_f32 v[68:69], v[56:57], v[68:69], v[104:105]
	v_add_u32_e32 v104, 0x40000, v202
	v_pk_fma_f32 v[66:67], v[54:55], v[66:67], v[102:103]
	v_lshlrev_b32_e32 v102, 2, v104
	s_waitcnt vmcnt(12) lgkmcnt(0)
	v_pk_fma_f32 v[72:73], v[56:57], v[72:73], v[100:101]
	v_add_u32_e32 v100, 0x44000, v202
	global_store_dwordx4 v102, v[66:69], s[22:23] nt
	v_pk_mul_f32 v[102:103], v[180:181], v[66:67]
	v_pk_fma_f32 v[70:71], v[54:55], v[70:71], v[98:99]
	v_lshlrev_b32_e32 v98, 2, v100
	v_pk_mul_f32 v[114:115], v[178:179], v[68:69]
	v_cvt_pk_bf16_f32 v102, v102, v103
	s_nop 0
	v_cvt_pk_bf16_f32 v103, v114, v115
	global_store_dwordx4 v98, v[70:73], s[22:23] nt
	v_pk_mul_f32 v[98:99], v[180:181], v[70:71]
	v_pk_mul_f32 v[114:115], v[178:179], v[72:73]
	v_cvt_pk_bf16_f32 v98, v98, v99
	s_nop 0
	v_cvt_pk_bf16_f32 v99, v114, v115
	ds_write_b128 v200, v[62:65]
	ds_write_b128 v200, v[58:61] offset:64
	ds_read_b128 v[58:61], v201
	ds_read_b128 v[62:65], v201 offset:1152
	v_lshl_add_u64 v[114:115], s[22:23], 0, v[122:123]
	s_waitcnt vmcnt(13) lgkmcnt(1)
	v_pk_fma_f32 v[58:59], v[50:51], v[58:59], v[94:95]
	v_pk_fma_f32 v[60:61], v[52:53], v[60:61], v[96:97]
	v_pk_mul_f32 v[96:97], v[176:177], v[58:59]
	global_store_dwordx4 v[112:113], v[58:61], off nt
	v_pk_mul_f32 v[94:95], v[174:175], v[60:61]
	v_cvt_pk_bf16_f32 v96, v96, v97
	s_waitcnt vmcnt(13) lgkmcnt(0)
	v_pk_fma_f32 v[62:63], v[50:51], v[62:63], v[90:91]
	v_cvt_pk_bf16_f32 v97, v94, v95
	ds_bpermute_b32 v90, v203, v96
	ds_bpermute_b32 v91, v203, v97
	v_pk_fma_f32 v[64:65], v[52:53], v[64:65], v[92:93]
	v_pk_mul_f32 v[92:93], v[176:177], v[62:63]
	v_pk_mul_f32 v[94:95], v[174:175], v[64:65]
	global_store_dwordx4 v[114:115], v[62:65], off nt
	v_cvt_pk_bf16_f32 v92, v92, v93
	v_cvt_pk_bf16_f32 v93, v94, v95
	v_lshlrev_b32_e32 v94, 1, v104
	s_waitcnt lgkmcnt(0)
	v_add_u32_e32 v250, 0xfffff040, v94
	v_cndmask_b32_e64 v250, v94, v250, s[38:39]
	v_cndmask_b32_e64 v248, v102, v90, s[38:39]
	v_cndmask_b32_e64 v249, v103, v91, s[38:39]
	global_store_dwordx2 v250, v[248:249], s[20:21]
	v_cndmask_b32_e64 v246, v90, v102, s[38:39]
	v_cndmask_b32_e64 v247, v91, v103, s[38:39]
	s_waitcnt lgkmcnt(1)
	v_add_u32_e32 v90, 0x1040, v94
	v_cndmask_b32_e64 v90, v94, v90, s[36:37]
	global_store_dwordx2 v90, v[246:247], s[20:21]
	ds_bpermute_b32 v90, v203, v92
	s_waitcnt lgkmcnt(1)
	ds_bpermute_b32 v91, v203, v93
	v_lshlrev_b32_e32 v92, 1, v100
	s_waitcnt lgkmcnt(0)
	v_add_u32_e32 v250, 0xfffff040, v92
	v_cndmask_b32_e64 v250, v92, v250, s[38:39]
	v_cndmask_b32_e64 v248, v98, v90, s[38:39]
	v_cndmask_b32_e64 v249, v99, v91, s[38:39]
	global_store_dwordx2 v250, v[248:249], s[20:21]
	v_cndmask_b32_e64 v246, v90, v98, s[38:39]
	v_cndmask_b32_e64 v247, v91, v99, s[38:39]
	v_mul_f32_e32 v59, v59, v59
	v_fmac_f32_e32 v59, v58, v58
	v_mul_f32_e32 v58, v61, v61
	v_mul_f32_e32 v69, v69, v69
	v_fmac_f32_e32 v58, v60, v60
	v_mul_f32_e32 v67, v67, v67
	v_fmac_f32_e32 v69, v68, v68
	v_mul_f32_e32 v68, v71, v71
	v_mul_f32_e32 v71, v73, v73
	v_add_f32_e32 v58, v59, v58
	v_mul_f32_e32 v59, v63, v63
	v_mul_f32_e32 v60, v65, v65
	v_fmac_f32_e32 v71, v72, v72
	v_fmac_f32_e32 v59, v62, v62
	v_fmac_f32_e32 v60, v64, v64
	v_fmac_f32_e32 v67, v66, v66
	v_fmac_f32_e32 v68, v70, v70
	v_add_f32_e32 v59, v59, v60
	v_add_f32_e32 v60, v67, v69
	v_add_f32_e32 v61, v68, v71
	v_add_f32_e32 v58, v60, v58
	v_add_f32_e32 v59, v61, v59
	ds_bpermute_b32 v60, v190, v58
	ds_bpermute_b32 v61, v190, v59
	s_waitcnt lgkmcnt(1)
	v_add_f32_e32 v58, v58, v60
	s_waitcnt lgkmcnt(0)
	v_add_f32_e32 v61, v59, v61
	ds_bpermute_b32 v60, v191, v58
	ds_bpermute_b32 v62, v191, v61
	s_waitcnt lgkmcnt(1)
	v_add_f32_e32 v58, v58, v60
	s_waitcnt lgkmcnt(0)
	v_add_f32_e32 v60, v61, v62
	ds_bpermute_b32 v59, v204, v58
	ds_bpermute_b32 v61, v204, v60
	v_add_u32_e32 v62, 0x1040, v92
	v_cndmask_b32_e64 v62, v92, v62, s[36:37]
	global_store_dwordx2 v62, v[246:247], s[20:21]
	s_and_saveexec_b64 s[24:25], s[40:41]
	s_cbranch_execz .LBB0_2819
	s_waitcnt lgkmcnt(1)
	v_add_f32_e32 v58, v58, v59
	s_waitcnt lgkmcnt(0)
	v_add_f32_e32 v59, v60, v61
	ds_write2_b32 v194, v58, v59 offset0:64 offset1:72
; #define LAS __attribute__((address_space(3)))
; __device__ __forceinline__ unsigned cvt_pk_bf16(float lo, float hi) { unsigned r; asm volatile("v_cvt_pk_bf16_f32 %0, %1, %2" : "=v"(r) : "v"(lo), "v"(hi)); return r; }
;     __device__ __forceinline__ void operator()(const f32x4 (&acc)[2][2][4][2], const Unit& u, int wr, int wc, int fr, int fq) const {
;     ...
;             if (g + 1 < 8) ERN_LOADX(g + 1);
;             float sq0 = 0.f, sq1 = 0.f; u32x2 hw[2][2];
; #pragma unroll
;             for (int bj = 0; bj < 2; ++bj) {
;                 *(LAS f32x4*)(st + wr_off) = acc[ai][bj][m][0]; *(LAS f32x4*)(st + wr_off + 64) = acc[ai][bj][m][1];
;                 const f32x4 a0 = *(const LAS f32x4*)(st + rd_off), a1 = *(const LAS f32x4*)(st + rd_off + 8 * 144);
;                 { const f32x4 xv = xb[g & 1][bj][0] + gv[bj] * a0; __builtin_nontemporal_store(xv, (f32x4*)((char*)xo + 4u * ERN_EOFF(g, bj, 0)));
;                   sq0 += (xv.x * xv.x + xv.y * xv.y) + (xv.z * xv.z + xv.w * xv.w);
;                   const f32x4 hv = xv * gsn[bj]; hw[bj][0].x = cvt_pk_bf16(hv.x, hv.y); hw[bj][0].y = cvt_pk_bf16(hv.z, hv.w); }
;                 { const f32x4 xv = xb[g & 1][bj][1] + gv[bj] * a1; __builtin_nontemporal_store(xv, (f32x4*)((char*)xo + 4u * ERN_EOFF(g, bj, 1)));
;                   sq1 += (xv.x * xv.x + xv.y * xv.y) + (xv.z * xv.z + xv.w * xv.w);
;                   const f32x4 hv = xv * gsn[bj]; hw[bj][1].x = cvt_pk_bf16(hv.x, hv.y); hw[bj][1].y = cvt_pk_bf16(hv.z, hv.w); }
;             }
;             if (!NOH && !PLAIN) {
; #pragma unroll
;                 for (int rh = 0; rh < 2; ++rh) { u32x2 rv; rv.x = __shfl_xor(hw[1][rh].x, 8); rv.y = __shfl_xor(hw[1][rh].y, 8);
;                     const unsigned e0 = ERN_EOFF(g, 0, rh);
;                     const unsigned ee = odd ? (e0 - DM + 32) : e0, eo2 = odd ? e0 : (e0 + DM + 32);
;                     *(u32x2*)((char*)ho + 2u * ee) = odd ? rv : hw[0][rh];
;                     *(u32x2*)((char*)ho + 2u * eo2) = odd ? hw[0][rh] : rv; }
;             }
;             if (!PLAIN) { sq0 += __shfl_xor(sq0, 1); sq0 += __shfl_xor(sq0, 2); sq0 += __shfl_xor(sq0, 4);
;             sq1 += __shfl_xor(sq1, 1); sq1 += __shfl_xor(sq1, 2); sq1 += __shfl_xor(sq1, 4); }
;             if (!PLAIN && pc == 0) { sst[g * 16 + rr] = sq0; sst[g * 16 + 8 + rr] = sq1; }
.LBB0_2819:
	s_or_b64 exec, exec, s[24:25]
	v_lshl_add_u64 v[96:97], s[22:23], 0, v[162:163]
	v_add_u32_e32 v162, 0x140000, v205
	v_add_u32_e32 v92, 0x140080, v205
	v_add_u32_e32 v94, 0x150000, v205
	global_load_dwordx4 v[70:73], v162, s[22:23]
	global_load_dwordx4 v[66:69], v94, s[22:23]
	v_add_u32_e32 v90, 0x150080, v205
	global_load_dwordx4 v[62:65], v92, s[22:23]
	s_waitcnt lgkmcnt(0)
	global_load_dwordx4 v[58:61], v90, s[22:23]
	ds_write_b128 v200, v[46:49]
	ds_write_b128 v200, v[42:45] offset:64
	ds_read_b128 v[42:45], v201
	ds_read_b128 v[46:49], v201 offset:1152
	v_mov_b32_e32 v111, v163
	v_lshl_add_u64 v[98:99], s[22:23], 0, v[110:111]
	v_mov_b32_e32 v109, v163
	s_waitcnt vmcnt(13) lgkmcnt(1)
	v_pk_fma_f32 v[42:43], v[54:55], v[42:43], v[86:87]
	s_waitcnt vmcnt(12) lgkmcnt(0)
	v_pk_fma_f32 v[46:47], v[54:55], v[46:47], v[82:83]
	v_pk_fma_f32 v[44:45], v[56:57], v[44:45], v[88:89]
	v_pk_mul_f32 v[86:87], v[180:181], v[42:43]
	v_pk_fma_f32 v[48:49], v[56:57], v[48:49], v[84:85]
	v_pk_mul_f32 v[82:83], v[180:181], v[46:47]
	global_store_dwordx4 v[96:97], v[42:45], off nt
	v_pk_mul_f32 v[88:89], v[178:179], v[44:45]
	v_cvt_pk_bf16_f32 v86, v86, v87
	v_pk_mul_f32 v[84:85], v[178:179], v[48:49]
	v_cvt_pk_bf16_f32 v87, v88, v89
	global_store_dwordx4 v[98:99], v[46:49], off nt
	v_cvt_pk_bf16_f32 v82, v82, v83
	v_cvt_pk_bf16_f32 v83, v84, v85
	ds_write_b128 v200, v[38:41]
	ds_write_b128 v200, v[34:37] offset:64
	ds_read_b128 v[34:37], v201
	ds_read_b128 v[38:41], v201 offset:1152
	v_lshl_add_u64 v[84:85], s[22:23], 0, v[108:109]
	v_mov_b32_e32 v107, v163
	v_lshl_add_u64 v[88:89], s[22:23], 0, v[106:107]
	s_waitcnt vmcnt(13) lgkmcnt(1)
	v_pk_fma_f32 v[34:35], v[50:51], v[34:35], v[78:79]
	v_pk_fma_f32 v[36:37], v[52:53], v[36:37], v[80:81]
	v_pk_mul_f32 v[80:81], v[176:177], v[34:35]
	global_store_dwordx4 v[84:85], v[34:37], off nt
	v_pk_mul_f32 v[78:79], v[174:175], v[36:37]
	v_cvt_pk_bf16_f32 v80, v80, v81
	s_waitcnt vmcnt(13) lgkmcnt(0)
	v_pk_fma_f32 v[38:39], v[50:51], v[38:39], v[74:75]
	v_cvt_pk_bf16_f32 v81, v78, v79
	ds_bpermute_b32 v74, v203, v80
	ds_bpermute_b32 v75, v203, v81
	v_pk_fma_f32 v[40:41], v[52:53], v[40:41], v[76:77]
	v_pk_mul_f32 v[76:77], v[176:177], v[38:39]
	v_pk_mul_f32 v[78:79], v[174:175], v[40:41]
	global_store_dwordx4 v[88:89], v[38:41], off nt
	v_cvt_pk_bf16_f32 v76, v76, v77
	v_cvt_pk_bf16_f32 v77, v78, v79
	v_add_u32_e32 v79, 0x48000, v202
	v_lshlrev_b32_e32 v78, 1, v79
	s_waitcnt lgkmcnt(0)
	v_add_u32_e32 v250, 0xfffff040, v78
	v_cndmask_b32_e64 v250, v78, v250, s[38:39]
	v_cndmask_b32_e64 v248, v86, v74, s[38:39]
	v_cndmask_b32_e64 v249, v87, v75, s[38:39]
	global_store_dwordx2 v250, v[248:249], s[20:21]
	v_cndmask_b32_e64 v246, v74, v86, s[38:39]
	v_cndmask_b32_e64 v247, v75, v87, s[38:39]
	s_waitcnt lgkmcnt(1)
	v_add_u32_e32 v74, 0x1040, v78
	v_cndmask_b32_e64 v74, v78, v74, s[36:37]
	global_store_dwordx2 v74, v[246:247], s[20:21]
	ds_bpermute_b32 v74, v203, v76
	s_waitcnt lgkmcnt(1)
	ds_bpermute_b32 v75, v203, v77
	v_add_u32_e32 v77, 0x4c000, v202
	v_lshlrev_b32_e32 v76, 1, v77
	s_waitcnt lgkmcnt(0)
	v_add_u32_e32 v250, 0xfffff040, v76
	v_cndmask_b32_e64 v250, v76, v250, s[38:39]
	v_cndmask_b32_e64 v248, v82, v74, s[38:39]
	v_cndmask_b32_e64 v249, v83, v75, s[38:39]
	global_store_dwordx2 v250, v[248:249], s[20:21]
	v_cndmask_b32_e64 v246, v74, v82, s[38:39]
	v_cndmask_b32_e64 v247, v75, v83, s[38:39]
	v_mul_f32_e32 v35, v35, v35
	v_fmac_f32_e32 v35, v34, v34
	v_mul_f32_e32 v34, v37, v37
	v_mul_f32_e32 v45, v45, v45
	v_fmac_f32_e32 v34, v36, v36
	v_mul_f32_e32 v43, v43, v43
	v_fmac_f32_e32 v45, v44, v44
	v_mul_f32_e32 v44, v47, v47
	v_mul_f32_e32 v47, v49, v49
	v_add_f32_e32 v34, v35, v34
	v_mul_f32_e32 v35, v39, v39
	v_mul_f32_e32 v36, v41, v41
	v_fmac_f32_e32 v47, v48, v48
	v_fmac_f32_e32 v35, v38, v38
	v_fmac_f32_e32 v36, v40, v40
	v_fmac_f32_e32 v43, v42, v42
	v_fmac_f32_e32 v44, v46, v46
	v_add_f32_e32 v35, v35, v36
	v_add_f32_e32 v36, v43, v45
	v_add_f32_e32 v37, v44, v47
	v_add_f32_e32 v34, v36, v34
	v_add_f32_e32 v35, v37, v35
	ds_bpermute_b32 v36, v190, v34
	ds_bpermute_b32 v37, v190, v35
	s_waitcnt lgkmcnt(1)
	v_add_f32_e32 v34, v34, v36
	s_waitcnt lgkmcnt(0)
	v_add_f32_e32 v37, v35, v37
	ds_bpermute_b32 v36, v191, v34
	ds_bpermute_b32 v38, v191, v37
	s_waitcnt lgkmcnt(1)
	v_add_f32_e32 v34, v34, v36
	s_waitcnt lgkmcnt(0)
	v_add_f32_e32 v36, v37, v38
	ds_bpermute_b32 v35, v204, v34
	ds_bpermute_b32 v37, v204, v36
	v_add_u32_e32 v38, 0x1040, v76
	v_cndmask_b32_e64 v38, v76, v38, s[36:37]
	global_store_dwordx2 v38, v[246:247], s[20:21]
	s_and_saveexec_b64 s[24:25], s[40:41]
	s_cbranch_execz .LBB0_2829
	s_waitcnt lgkmcnt(1)
	v_add_f32_e32 v34, v34, v35
	s_waitcnt lgkmcnt(0)
	v_add_f32_e32 v35, v36, v37
	ds_write2_b32 v194, v34, v35 offset0:80 offset1:88
; #define LAS __attribute__((address_space(3)))
; __device__ __forceinline__ unsigned cvt_pk_bf16(float lo, float hi) { unsigned r; asm volatile("v_cvt_pk_bf16_f32 %0, %1, %2" : "=v"(r) : "v"(lo), "v"(hi)); return r; }
;     __device__ __forceinline__ void operator()(const f32x4 (&acc)[2][2][4][2], const Unit& u, int wr, int wc, int fr, int fq) const {
;     ...
;             if (g + 1 < 8) ERN_LOADX(g + 1);
;             float sq0 = 0.f, sq1 = 0.f; u32x2 hw[2][2];
; #pragma unroll
;             for (int bj = 0; bj < 2; ++bj) {
;                 *(LAS f32x4*)(st + wr_off) = acc[ai][bj][m][0]; *(LAS f32x4*)(st + wr_off + 64) = acc[ai][bj][m][1];
;                 const f32x4 a0 = *(const LAS f32x4*)(st + rd_off), a1 = *(const LAS f32x4*)(st + rd_off + 8 * 144);
;                 { const f32x4 xv = xb[g & 1][bj][0] + gv[bj] * a0; __builtin_nontemporal_store(xv, (f32x4*)((char*)xo + 4u * ERN_EOFF(g, bj, 0)));
;                   sq0 += (xv.x * xv.x + xv.y * xv.y) + (xv.z * xv.z + xv.w * xv.w);
;                   const f32x4 hv = xv * gsn[bj]; hw[bj][0].x = cvt_pk_bf16(hv.x, hv.y); hw[bj][0].y = cvt_pk_bf16(hv.z, hv.w); }
;                 { const f32x4 xv = xb[g & 1][bj][1] + gv[bj] * a1; __builtin_nontemporal_store(xv, (f32x4*)((char*)xo + 4u * ERN_EOFF(g, bj, 1)));
;                   sq1 += (xv.x * xv.x + xv.y * xv.y) + (xv.z * xv.z + xv.w * xv.w);
;                   const f32x4 hv = xv * gsn[bj]; hw[bj][1].x = cvt_pk_bf16(hv.x, hv.y); hw[bj][1].y = cvt_pk_bf16(hv.z, hv.w); }
;             }
;             if (!NOH && !PLAIN) {
; #pragma unroll
;                 for (int rh = 0; rh < 2; ++rh) { u32x2 rv; rv.x = __shfl_xor(hw[1][rh].x, 8); rv.y = __shfl_xor(hw[1][rh].y, 8);
;                     const unsigned e0 = ERN_EOFF(g, 0, rh);
;                     const unsigned ee = odd ? (e0 - DM + 32) : e0, eo2 = odd ? e0 : (e0 + DM + 32);
;                     *(u32x2*)((char*)ho + 2u * ee) = odd ? rv : hw[0][rh];
;                     *(u32x2*)((char*)ho + 2u * eo2) = odd ? hw[0][rh] : rv; }
;             }
;             if (!PLAIN) { sq0 += __shfl_xor(sq0, 1); sq0 += __shfl_xor(sq0, 2); sq0 += __shfl_xor(sq0, 4);
;             sq1 += __shfl_xor(sq1, 1); sq1 += __shfl_xor(sq1, 2); sq1 += __shfl_xor(sq1, 4); }
;             if (!PLAIN && pc == 0) { sst[g * 16 + rr] = sq0; sst[g * 16 + 8 + rr] = sq1; }
.LBB0_2829:
	s_or_b64 exec, exec, s[24:25]
	v_lshl_add_u64 v[80:81], s[22:23], 0, v[162:163]
	v_add_u32_e32 v162, 0x160000, v205
	v_add_u32_e32 v76, 0x160080, v205
	v_add_u32_e32 v78, 0x170000, v205
	global_load_dwordx4 v[46:49], v162, s[22:23]
	global_load_dwordx4 v[42:45], v78, s[22:23]
	v_add_u32_e32 v74, 0x170080, v205
	global_load_dwordx4 v[38:41], v76, s[22:23]
	s_waitcnt lgkmcnt(0)
	global_load_dwordx4 v[34:37], v74, s[22:23]
	ds_write_b128 v200, v[30:33]
	ds_write_b128 v200, v[26:29] offset:64
	ds_read_b128 v[26:29], v201
	ds_read_b128 v[30:33], v201 offset:1152
	v_mov_b32_e32 v95, v163
	v_lshl_add_u64 v[82:83], s[22:23], 0, v[94:95]
	v_mov_b32_e32 v93, v163
	s_waitcnt vmcnt(13) lgkmcnt(1)
	v_pk_fma_f32 v[26:27], v[54:55], v[26:27], v[70:71]
	s_waitcnt vmcnt(12) lgkmcnt(0)
	v_pk_fma_f32 v[30:31], v[54:55], v[30:31], v[66:67]
	v_pk_fma_f32 v[28:29], v[56:57], v[28:29], v[72:73]
	v_pk_mul_f32 v[70:71], v[180:181], v[26:27]
	v_pk_fma_f32 v[32:33], v[56:57], v[32:33], v[68:69]
	v_pk_mul_f32 v[66:67], v[180:181], v[30:31]
	global_store_dwordx4 v[80:81], v[26:29], off nt
	v_pk_mul_f32 v[72:73], v[178:179], v[28:29]
	v_cvt_pk_bf16_f32 v70, v70, v71
	v_pk_mul_f32 v[68:69], v[178:179], v[32:33]
	v_cvt_pk_bf16_f32 v71, v72, v73
	global_store_dwordx4 v[82:83], v[30:33], off nt
	v_cvt_pk_bf16_f32 v66, v66, v67
	v_cvt_pk_bf16_f32 v67, v68, v69
	ds_write_b128 v200, v[22:25]
	ds_write_b128 v200, v[18:21] offset:64
	ds_read_b128 v[18:21], v201
	ds_read_b128 v[22:25], v201 offset:1152
	v_lshl_add_u64 v[68:69], s[22:23], 0, v[92:93]
	v_mov_b32_e32 v91, v163
	v_lshl_add_u64 v[72:73], s[22:23], 0, v[90:91]
	s_waitcnt vmcnt(13) lgkmcnt(1)
	v_pk_fma_f32 v[18:19], v[50:51], v[18:19], v[62:63]
	v_pk_fma_f32 v[20:21], v[52:53], v[20:21], v[64:65]
	v_pk_mul_f32 v[64:65], v[176:177], v[18:19]
	global_store_dwordx4 v[68:69], v[18:21], off nt
	v_pk_mul_f32 v[62:63], v[174:175], v[20:21]
	v_cvt_pk_bf16_f32 v64, v64, v65
	s_waitcnt vmcnt(13) lgkmcnt(0)
	v_pk_fma_f32 v[22:23], v[50:51], v[22:23], v[58:59]
	v_cvt_pk_bf16_f32 v65, v62, v63
	ds_bpermute_b32 v58, v203, v64
	ds_bpermute_b32 v59, v203, v65
	v_pk_fma_f32 v[24:25], v[52:53], v[24:25], v[60:61]
	v_pk_mul_f32 v[60:61], v[176:177], v[22:23]
	v_pk_mul_f32 v[62:63], v[174:175], v[24:25]
	global_store_dwordx4 v[72:73], v[22:25], off nt
	v_cvt_pk_bf16_f32 v60, v60, v61
	v_cvt_pk_bf16_f32 v61, v62, v63
	v_add_u32_e32 v63, 0x50000, v202
	v_lshlrev_b32_e32 v62, 1, v63
	s_waitcnt lgkmcnt(0)
	v_add_u32_e32 v250, 0xfffff040, v62
	v_cndmask_b32_e64 v250, v62, v250, s[38:39]
	v_cndmask_b32_e64 v248, v70, v58, s[38:39]
	v_cndmask_b32_e64 v249, v71, v59, s[38:39]
	global_store_dwordx2 v250, v[248:249], s[20:21]
	v_cndmask_b32_e64 v246, v58, v70, s[38:39]
	v_cndmask_b32_e64 v247, v59, v71, s[38:39]
	s_waitcnt lgkmcnt(1)
	v_add_u32_e32 v58, 0x1040, v62
	v_cndmask_b32_e64 v58, v62, v58, s[36:37]
	global_store_dwordx2 v58, v[246:247], s[20:21]
	ds_bpermute_b32 v58, v203, v60
	s_waitcnt lgkmcnt(1)
	ds_bpermute_b32 v59, v203, v61
	v_add_u32_e32 v61, 0x54000, v202
	v_lshlrev_b32_e32 v60, 1, v61
	s_waitcnt lgkmcnt(0)
	v_add_u32_e32 v250, 0xfffff040, v60
	v_cndmask_b32_e64 v250, v60, v250, s[38:39]
	v_cndmask_b32_e64 v248, v66, v58, s[38:39]
	v_cndmask_b32_e64 v249, v67, v59, s[38:39]
	global_store_dwordx2 v250, v[248:249], s[20:21]
	v_cndmask_b32_e64 v246, v58, v66, s[38:39]
	v_cndmask_b32_e64 v247, v59, v67, s[38:39]
	v_mul_f32_e32 v19, v19, v19
	v_fmac_f32_e32 v19, v18, v18
	v_mul_f32_e32 v18, v21, v21
	v_mul_f32_e32 v29, v29, v29
	v_fmac_f32_e32 v18, v20, v20
	v_mul_f32_e32 v27, v27, v27
	v_fmac_f32_e32 v29, v28, v28
	v_mul_f32_e32 v28, v31, v31
	v_mul_f32_e32 v31, v33, v33
	v_add_f32_e32 v18, v19, v18
	v_mul_f32_e32 v19, v23, v23
	v_mul_f32_e32 v20, v25, v25
	v_fmac_f32_e32 v31, v32, v32
	v_fmac_f32_e32 v19, v22, v22
	v_fmac_f32_e32 v20, v24, v24
	v_fmac_f32_e32 v27, v26, v26
	v_fmac_f32_e32 v28, v30, v30
	v_add_f32_e32 v19, v19, v20
	v_add_f32_e32 v20, v27, v29
	v_add_f32_e32 v21, v28, v31
	v_add_f32_e32 v18, v20, v18
	v_add_f32_e32 v19, v21, v19
	ds_bpermute_b32 v20, v190, v18
	ds_bpermute_b32 v21, v190, v19
	s_waitcnt lgkmcnt(1)
	v_add_f32_e32 v18, v18, v20
	s_waitcnt lgkmcnt(0)
	v_add_f32_e32 v21, v19, v21
	ds_bpermute_b32 v20, v191, v18
	ds_bpermute_b32 v22, v191, v21
	s_waitcnt lgkmcnt(1)
	v_add_f32_e32 v18, v18, v20
	s_waitcnt lgkmcnt(0)
	v_add_f32_e32 v20, v21, v22
	ds_bpermute_b32 v19, v204, v18
	ds_bpermute_b32 v21, v204, v20
	v_add_u32_e32 v22, 0x1040, v60
	v_cndmask_b32_e64 v22, v60, v22, s[36:37]
	global_store_dwordx2 v22, v[246:247], s[20:21]
	s_and_saveexec_b64 s[24:25], s[40:41]
	s_cbranch_execz .LBB0_2839
	s_waitcnt lgkmcnt(1)
	v_add_f32_e32 v18, v18, v19
	s_waitcnt lgkmcnt(0)
	v_add_f32_e32 v19, v20, v21
	ds_write2_b32 v194, v18, v19 offset0:96 offset1:104
; #define LAS __attribute__((address_space(3)))
; __device__ __forceinline__ unsigned cvt_pk_bf16(float lo, float hi) { unsigned r; asm volatile("v_cvt_pk_bf16_f32 %0, %1, %2" : "=v"(r) : "v"(lo), "v"(hi)); return r; }
; #define ERN_EOFF(q, m) (eb + (unsigned)((((q) & 1) * HALF + (m) * 16) * DM + ERN_COL((q) >> 1)))
;     __device__ __forceinline__ void operator()(const f32x4 (&acc)[2][2][4][2], const Unit& u, int wr, int wc, int fr, int fq) const {
;     ...
;             float sq0 = 0.f, sq1 = 0.f; u32x2 hw[2][2];
; #pragma unroll
;             for (int bj = 0; bj < 2; ++bj) {
;                 *(LAS f32x4*)(st + wr_off) = acc[ai][bj][m][0]; *(LAS f32x4*)(st + wr_off + 64) = acc[ai][bj][m][1];
;                 const f32x4 a0 = *(const LAS f32x4*)(st + rd_off), a1 = *(const LAS f32x4*)(st + rd_off + 8 * 144);
;                 { const f32x4 xv = xb[g & 1][bj][0] + gv[bj] * a0; __builtin_nontemporal_store(xv, (f32x4*)((char*)xo + 4u * ERN_EOFF(g, bj, 0)));
;                   sq0 += (xv.x * xv.x + xv.y * xv.y) + (xv.z * xv.z + xv.w * xv.w);
;                   const f32x4 hv = xv * gsn[bj]; hw[bj][0].x = cvt_pk_bf16(hv.x, hv.y); hw[bj][0].y = cvt_pk_bf16(hv.z, hv.w); }
;                 { const f32x4 xv = xb[g & 1][bj][1] + gv[bj] * a1; __builtin_nontemporal_store(xv, (f32x4*)((char*)xo + 4u * ERN_EOFF(g, bj, 1)));
;                   sq1 += (xv.x * xv.x + xv.y * xv.y) + (xv.z * xv.z + xv.w * xv.w);
;                   const f32x4 hv = xv * gsn[bj]; hw[bj][1].x = cvt_pk_bf16(hv.x, hv.y); hw[bj][1].y = cvt_pk_bf16(hv.z, hv.w); }
;             }
;             if (!NOH && !PLAIN) {
; #pragma unroll
;                 for (int rh = 0; rh < 2; ++rh) { u32x2 rv; rv.x = __shfl_xor(hw[1][rh].x, 8); rv.y = __shfl_xor(hw[1][rh].y, 8);
;                     const unsigned e0 = ERN_EOFF(g, 0, rh);
;                     const unsigned ee = odd ? (e0 - DM + 32) : e0, eo2 = odd ? e0 : (e0 + DM + 32);
;                     *(u32x2*)((char*)ho + 2u * ee) = odd ? rv : hw[0][rh];
;                     *(u32x2*)((char*)ho + 2u * eo2) = odd ? hw[0][rh] : rv; }
;             }
;             if (!PLAIN) { sq0 += __shfl_xor(sq0, 1); sq0 += __shfl_xor(sq0, 2); sq0 += __shfl_xor(sq0, 4);
;             sq1 += __shfl_xor(sq1, 1); sq1 += __shfl_xor(sq1, 2); sq1 += __shfl_xor(sq1, 4); }
;             if (!PLAIN && pc == 0) { sst[g * 16 + rr] = sq0; sst[g * 16 + 8 + rr] = sq1; }
.LBB0_2839:
	s_or_b64 exec, exec, s[24:25]
	ds_write_b128 v200, v[14:17]
	ds_write_b128 v200, v[10:13] offset:64
	ds_read_b128 v[10:13], v201
	ds_read_b128 v[14:17], v201 offset:1152
	s_waitcnt lgkmcnt(5)
	v_lshl_add_u64 v[18:19], s[22:23], 0, v[162:163]
	v_mov_b32_e32 v79, v163
	v_lshl_add_u64 v[22:23], s[22:23], 0, v[78:79]
	s_waitcnt vmcnt(9) lgkmcnt(1)
	v_pk_fma_f32 v[12:13], v[56:57], v[12:13], v[48:49]
	v_pk_fma_f32 v[10:11], v[54:55], v[10:11], v[46:47]
	global_store_dwordx4 v[18:19], v[10:13], off nt
	v_pk_mul_f32 v[18:19], v[178:179], v[12:13]
	v_pk_mul_f32 v[20:21], v[180:181], v[10:11]
	s_waitcnt vmcnt(9) lgkmcnt(0)
	v_pk_fma_f32 v[14:15], v[54:55], v[14:15], v[42:43]
	v_cvt_pk_bf16_f32 v20, v20, v21
	v_cvt_pk_bf16_f32 v21, v18, v19
	v_pk_fma_f32 v[16:17], v[56:57], v[16:17], v[44:45]
	v_pk_mul_f32 v[18:19], v[180:181], v[14:15]
	global_store_dwordx4 v[22:23], v[14:17], off nt
	v_pk_mul_f32 v[22:23], v[178:179], v[16:17]
	v_cvt_pk_bf16_f32 v18, v18, v19
	v_mov_b32_e32 v77, v163
	v_cvt_pk_bf16_f32 v19, v22, v23
	ds_write_b128 v200, v[6:9]
	ds_write_b128 v200, v[2:5] offset:64
	ds_read_b128 v[2:5], v201
	ds_read_b128 v[6:9], v201 offset:1152
	v_lshl_add_u64 v[22:23], s[22:23], 0, v[76:77]
	v_mov_b32_e32 v75, v163
	v_lshl_add_u64 v[24:25], s[22:23], 0, v[74:75]
	s_waitcnt vmcnt(9) lgkmcnt(1)
	v_pk_fma_f32 v[4:5], v[52:53], v[4:5], v[40:41]
	v_pk_fma_f32 v[2:3], v[50:51], v[2:3], v[38:39]
	global_store_dwordx4 v[22:23], v[2:5], off nt
	v_pk_mul_f32 v[22:23], v[174:175], v[4:5]
	v_pk_mul_f32 v[26:27], v[176:177], v[2:3]
	s_waitcnt vmcnt(9) lgkmcnt(0)
	v_pk_fma_f32 v[8:9], v[52:53], v[8:9], v[36:37]
	v_cvt_pk_bf16_f32 v28, v26, v27
	v_cvt_pk_bf16_f32 v23, v22, v23
	ds_bpermute_b32 v22, v203, v28
	ds_bpermute_b32 v23, v203, v23
	v_pk_fma_f32 v[6:7], v[50:51], v[6:7], v[34:35]
	global_store_dwordx4 v[24:25], v[6:9], off nt
	v_pk_mul_f32 v[26:27], v[174:175], v[8:9]
	v_pk_mul_f32 v[24:25], v[176:177], v[6:7]
	s_nop 0
	v_cvt_pk_bf16_f32 v24, v24, v25
	v_cvt_pk_bf16_f32 v25, v26, v27
	v_add_u32_e32 v27, 0x58000, v202
	v_lshlrev_b32_e32 v26, 1, v27
	s_waitcnt lgkmcnt(0)
	v_add_u32_e32 v250, 0xfffff040, v26
	v_cndmask_b32_e64 v250, v26, v250, s[38:39]
	v_cndmask_b32_e64 v248, v20, v22, s[38:39]
	v_cndmask_b32_e64 v249, v21, v23, s[38:39]
	global_store_dwordx2 v250, v[248:249], s[20:21]
	v_cndmask_b32_e64 v246, v22, v20, s[38:39]
	v_cndmask_b32_e64 v247, v23, v21, s[38:39]
	s_waitcnt lgkmcnt(1)
	v_add_u32_e32 v22, 0x1040, v26
	v_cndmask_b32_e64 v22, v26, v22, s[36:37]
	global_store_dwordx2 v22, v[246:247], s[20:21]
	ds_bpermute_b32 v20, v203, v24
	ds_bpermute_b32 v21, v203, v25
	s_waitcnt lgkmcnt(2)
	v_add_u32_e32 v23, 0x5c000, v202
	v_lshlrev_b32_e32 v22, 1, v23
	s_waitcnt lgkmcnt(0)
	v_add_u32_e32 v250, 0xfffff040, v22
	v_cndmask_b32_e64 v250, v22, v250, s[38:39]
	v_cndmask_b32_e64 v248, v18, v20, s[38:39]
	v_cndmask_b32_e64 v249, v19, v21, s[38:39]
	global_store_dwordx2 v250, v[248:249], s[20:21]
	v_cndmask_b32_e64 v246, v20, v18, s[38:39]
	v_cndmask_b32_e64 v247, v21, v19, s[38:39]
	v_mul_f32_e32 v3, v3, v3
	v_fmac_f32_e32 v3, v2, v2
	v_mul_f32_e32 v2, v5, v5
	v_mul_f32_e32 v13, v13, v13
	v_fmac_f32_e32 v2, v4, v4
	v_mul_f32_e32 v11, v11, v11
	v_fmac_f32_e32 v13, v12, v12
	v_mul_f32_e32 v12, v15, v15
	v_mul_f32_e32 v15, v17, v17
	v_add_f32_e32 v2, v3, v2
	v_mul_f32_e32 v3, v7, v7
	v_mul_f32_e32 v4, v9, v9
	v_fmac_f32_e32 v15, v16, v16
	v_fmac_f32_e32 v3, v6, v6
	v_fmac_f32_e32 v4, v8, v8
	v_fmac_f32_e32 v11, v10, v10
	v_fmac_f32_e32 v12, v14, v14
	v_add_f32_e32 v3, v3, v4
	v_add_f32_e32 v4, v11, v13
	v_add_f32_e32 v5, v12, v15
	v_add_f32_e32 v2, v4, v2
	v_add_f32_e32 v3, v5, v3
	ds_bpermute_b32 v4, v190, v2
	ds_bpermute_b32 v5, v190, v3
	s_waitcnt lgkmcnt(1)
	v_add_f32_e32 v2, v2, v4
	s_waitcnt lgkmcnt(0)
	v_add_f32_e32 v5, v3, v5
	ds_bpermute_b32 v4, v191, v2
	ds_bpermute_b32 v6, v191, v5
	s_waitcnt lgkmcnt(1)
	v_add_f32_e32 v2, v2, v4
	s_waitcnt lgkmcnt(0)
	v_add_f32_e32 v4, v5, v6
	ds_bpermute_b32 v3, v204, v2
	ds_bpermute_b32 v5, v204, v4
	v_add_u32_e32 v6, 0x1040, v22
	v_cndmask_b32_e64 v6, v22, v6, s[36:37]
	global_store_dwordx2 v6, v[246:247], s[20:21]
	s_and_saveexec_b64 s[20:21], s[40:41]
	s_cbranch_execz .LBB0_2849
	s_waitcnt lgkmcnt(1)
	v_add_f32_e32 v2, v2, v3
	s_waitcnt lgkmcnt(0)
	v_add_f32_e32 v3, v4, v5
	ds_write2_b32 v194, v2, v3 offset0:112 offset1:120
